# speedup vs baseline: 1.0206x; 1.0039x over previous
; #define WAIT_V(n) asm volatile("s_waitcnt vmcnt(" #n ")" ::: "memory")
; #define BAR __builtin_amdgcn_s_barrier()
; DEV void gemm_tile(const h16* __restrict__ A, const h16* __restrict__ Bt, int K, int ld, int brow, int bcol, h16* shm, Acc& acc) {
;     ...
;   int wid = TID >> 6, lane = TID & 63, wr = wid >> 2, wc = wid & 3, fr = lane & 15, fq = lane >> 4;
;   int vo0, vo1;
;   {
;     int r, c;
;     stage_rc(TID * 16, r, c);
;     vo0 = (r * ld + c) * 2;
;     stage_rc(TID * 16 + 8192, r, c);
;     vo1 = (r * ld + c) * 2;
;   }
;   __amdgpu_buffer_rsrc_t rsA = __builtin_amdgcn_make_buffer_rsrc((void*)A, (short)0, 0x7fffffff, 0x00020000);
;   __amdgpu_buffer_rsrc_t rsB = __builtin_amdgcn_make_buffer_rsrc((void*)Bt, (short)0, 0x7fffffff, 0x00020000);
; #pragma unroll
;   for (int a = 0; a < 2; ++a)
; #pragma unroll
;     for (int b = 0; b < 2; ++b)
; #pragma unroll
;       for (int m = 0; m < 4; ++m)
; #pragma unroll
;         for (int n = 0; n < 2; ++n) acc[a][b][m][n] = f32x4{0.f, 0.f, 0.f, 0.f};
;   h16x8 At[4][2], B0[2][2], B1[2][2];
;   int nt = K / BK;
;   STAGE(SB(0, 0), rsB, bcol, 0); STAGE(SA(0, 0), rsA, brow, 0);
;   STAGE(SB(0, 1), rsB, bcol + HALF_, 0); STAGE(SA(0, 1), rsA, brow + HALF_, 0);
;   if (wr == 1) BAR;
;   WAIT_V(4); BAR;
;   STAGE(SB(1, 0), rsB, bcol, 1); STAGE(SA(1, 0), rsA, brow, 1); STAGE(SB(1, 1), rsB, bcol + HALF_, 1);
;   WAIT_V(6); BAR;
; template <int EPI> __device__ __forceinline__ void gemm_phase(const h16* A, const h16* Bt, int M, int N, int K, const GE& e, h16* shm) {
;     ...
;       int q = nwg / NXCD, r = nwg % NXCD, xcd = wgid % NXCD, off = wgid / NXCD;
;       wgid = (xcd < r ? xcd * (q + 1) : r * (q + 1) + (xcd - r) * q) + off;
;     }
;     int nig = WGM * nN, gid = wgid / nig, fm = gid * WGM, gsz = min(nM - fm, WGM);
;     int pm = fm + ((wgid % nig) % gsz), pn = (wgid % nig) / gsz, brow = pm * BM, bcol = pn * BM;
.LBB0_140:
	s_ashr_i32 s4, s12, 31
	s_lshr_b32 s4, s4, 29
	s_add_i32 s4, s12, s4
	s_ashr_i32 s5, s4, 3
	s_and_b32 s4, s4, -8
	s_sub_i32 s4, s12, s4
	s_lshr_b32 s10, s4, 31
	s_or_b32 s10, s10, 16
	s_mul_i32 s15, s10, s4
	s_add_i32 s15, s15, s5
	s_ashr_i32 s4, s15, 31
	s_lshr_b32 s4, s4, 26
	s_add_i32 s4, s15, s4
	s_ashr_i32 s16, s4, 6
	s_lshl_b32 s10, s16, 3
	s_sub_i32 s5, 16, s10
	s_min_u32 s11, s5, 8
	s_andn2_b32 s4, s4, 63
	s_sub_i32 s13, s15, s4
	v_cvt_f32_ubyte0_e32 v2, s11
	v_cvt_f32_i32_e32 v0, s13
	v_rcp_iflag_f32_e32 v3, v2
	s_ashr_i32 s4, s13, 30
	s_or_b32 s14, s4, 1
	v_mul_f32_e32 v3, v0, v3
	v_trunc_f32_e32 v3, v3
	v_fma_f32 v0, -v3, v2, v0
	v_cmp_ge_f32_e64 s[4:5], |v0|, v2
	v_mov_b32_e32 v0, v172
	v_cvt_i32_f32_e32 v3, v3
	s_and_b64 s[4:5], s[4:5], exec
	v_bfe_i32 v4, v0, 27, 1
	v_lshlrev_b32_e32 v2, 4, v0
	v_lshrrev_b32_e32 v4, 22, v4
	v_add_u32_e32 v4, v2, v4
	v_and_b32_e32 v4, 0xfffffc00, v4
	v_readfirstlane_b32 s5, v3
	v_ashrrev_i32_e32 v3, 31, v0
	v_sub_u32_e32 v4, v2, v4
	v_lshrrev_b32_e32 v3, 26, v3
	v_lshrrev_b32_e32 v5, 4, v4
	v_add_u32_e32 v3, v0, v3
	v_bitop3_b32 v5, v5, v4, 32 bitop3:0x6c
	v_ashrrev_i32_e32 v4, 31, v4
	v_ashrrev_i32_e32 v3, 6, v3
	v_lshrrev_b32_e32 v4, 26, v4
	v_lshlrev_b32_e32 v6, 3, v3
	v_add_u32_e32 v4, v5, v4
	v_and_b32_e32 v6, 0xfffff0, v6
	v_ashrrev_i32_e32 v4, 6, v4
	v_add_u32_e32 v6, v4, v6
	v_lshlrev_b32_e32 v3, 5, v3
	v_mul_i32_i24_e32 v4, 64, v4
	v_and_b32_e32 v3, 32, v3
	v_sub_u32_e32 v4, v5, v4
	v_add_u32_e32 v5, 0x2000, v2
	v_lshl_or_b32 v3, v6, 7, v3
	v_ashrrev_i32_e32 v6, 31, v5
	v_lshrrev_b32_e32 v6, 22, v6
	v_add_u32_e32 v6, v5, v6
	v_ashrrev_i32_e32 v6, 10, v6
	v_mul_i32_i24_e32 v7, 0x400, v6
	v_sub_u32_e32 v5, v5, v7
	v_lshrrev_b32_e32 v7, 4, v5
	v_bitop3_b32 v5, v7, v5, 32 bitop3:0x6c
	v_ashrrev_i32_e32 v8, 31, v5
	v_lshrrev_b32_e32 v8, 26, v8
	v_add_u32_e32 v8, v5, v8
	s_cselect_b32 s4, s14, 0
	v_lshlrev_b32_e32 v7, 3, v6
	v_lshrrev_b32_e32 v9, 6, v8
	v_and_b32_e32 v8, 0xc0, v8
	s_add_i32 s17, s5, s4
	v_and_b32_e32 v7, 0xfffff0, v7
	v_lshlrev_b32_e32 v6, 5, v6
	v_sub_u32_e32 v5, v5, v8
	s_sext_i32_i8 s20, s17
	s_mul_i32 s17, s17, s11
	v_ashrrev_i16_sdwa v4, v187, sext(v4) dst_sel:DWORD dst_unused:UNUSED_PAD src0_sel:DWORD src1_sel:BYTE_0
	v_add_u32_e32 v7, v9, v7
	v_and_b32_e32 v6, 32, v6
	v_ashrrev_i16_sdwa v5, v187, sext(v5) dst_sel:DWORD dst_unused:UNUSED_PAD src0_sel:DWORD src1_sel:BYTE_0
	s_sub_i32 s4, s13, s17
	v_bfe_i32 v4, v4, 0, 16
	v_bfe_i32 v5, v5, 0, 16
	v_lshl_or_b32 v6, v7, 7, v6
	s_add_i32 s21, s68, 0x110
	s_sext_i32_i8 s4, s4
	v_add_lshl_u32 v4, v3, v4, 1
	v_add_lshl_u32 v3, v6, v5, 1
	v_add_u32_e32 v5, s21, v2
	s_add_i32 s10, s10, s4
	v_readfirstlane_b32 s4, v5
	v_add_u32_e32 v5, 0x2000, v5
	s_lshl_b32 s22, s20, 16
	s_mov_b32 m0, s4
	v_readfirstlane_b32 s4, v5
	v_add_u32_e32 v5, 0x110, v2
	buffer_load_dwordx4 v4, s[76:79], s22 offen lds
	s_mov_b32 m0, s4
	v_readfirstlane_b32 s4, v5
	v_add_u32_e32 v6, 0x2000, v5
	v_readlane_b32 s5, v254, 11
	s_lshl_b32 s13, s10, 8
	buffer_load_dwordx4 v3, s[76:79], s22 offen lds
	s_lshl_b32 s24, s10, 16
	s_mov_b32 s10, s78
	s_mov_b32 s11, s79
	s_mov_b32 m0, s4
	v_readfirstlane_b32 s4, v6
	v_add_u32_e32 v6, s5, v2
	buffer_load_dwordx4 v4, s[8:11], s24 offen lds
	s_mov_b32 m0, s4
	v_readfirstlane_b32 s5, v6
	v_add_u32_e32 v6, 0x2000, v6
	buffer_load_dwordx4 v3, s[8:11], s24 offen lds
	s_or_b32 s4, s22, 0x8000
	s_mov_b32 m0, s5
	v_readfirstlane_b32 s5, v6
	buffer_load_dwordx4 v4, s[76:79], s4 offen lds
	s_mov_b32 m0, s5
	v_add_u32_e32 v6, 0x4000, v5
	buffer_load_dwordx4 v3, s[76:79], s4 offen lds
	s_or_b32 s14, s13, 0x80
	v_readfirstlane_b32 s4, v6
	v_add_u32_e32 v6, 0x6000, v5
	s_lshl_b32 s23, s14, 8
	s_mov_b32 m0, s4
	v_readfirstlane_b32 s4, v6
	buffer_load_dwordx4 v4, s[8:11], s23 offen lds
	s_mov_b32 m0, s4
	v_ashrrev_i32_e32 v6, 8, v0
	buffer_load_dwordx4 v3, s[8:11], s23 offen lds
	v_cmp_eq_u32_e32 vcc, 1, v6
	s_and_saveexec_b64 s[4:5], vcc
	s_cbranch_execz .LBB0_142
	s_barrier
	s_setprio 1
.LBB0_142:
	s_or_b64 exec, exec, s[4:5]
	v_add_u32_e32 v9, s94, v2
	s_or_b32 s4, s22, 0x80
	v_readfirstlane_b32 s5, v9
	v_add_u32_e32 v9, 0x2000, v9
	s_mov_b32 m0, s5
	v_readfirstlane_b32 s5, v9
	s_waitcnt vmcnt(4)
	s_barrier
	buffer_load_dwordx4 v4, s[76:79], s4 offen lds
	s_mov_b32 m0, s5
	v_add_u32_e32 v9, 0x8000, v5
	buffer_load_dwordx4 v3, s[76:79], s4 offen lds
	v_readfirstlane_b32 s4, v9
	v_add_u32_e32 v9, 0xa000, v5
	s_bitset1_b32 s24, 7
	s_mov_b32 m0, s4
	v_readfirstlane_b32 s4, v9
	buffer_load_dwordx4 v4, s[8:11], s24 offen lds
	s_mov_b32 m0, s4
	s_or_b32 s4, s22, 0x8080
	v_readlane_b32 s22, v254, 12
	buffer_load_dwordx4 v3, s[8:11], s24 offen lds
	v_lshlrev_b32_e32 v9, 2, v0
	v_add_u32_e32 v2, s22, v2
	v_and_b32_e32 v8, 48, v0
	v_readfirstlane_b32 s5, v2
	v_add_u32_e32 v2, 0x2000, v2
	s_mov_b32 m0, s5
	v_readfirstlane_b32 s5, v2
	v_lshlrev_b32_e32 v2, 6, v0
	v_and_b32_e32 v170, 0x3000, v2
	v_and_b32_e32 v9, 32, v9
	v_and_b32_e32 v2, 0x3c0, v2
	v_and_b32_e32 v7, 15, v0
	s_waitcnt vmcnt(55)
	v_lshlrev_b32_e32 v30, 13, v6
	v_bitop3_b32 v2, v2, v9, v8 bitop3:0x36
	buffer_load_dwordx4 v4, s[76:79], s4 offen lds
	s_mov_b32 m0, s5
	v_lshlrev_b32_e32 v7, 6, v7
	v_add3_u32 v192, s85, v2, v30
	v_add_u32_e32 v2, 0xc000, v5
	buffer_load_dwordx4 v3, s[76:79], s4 offen lds
	v_bitop3_b32 v171, v7, v9, v8 bitop3:0x36
	v_readfirstlane_b32 s4, v2
	v_add_u32_e32 v2, 0xe000, v5
	v_add3_u32 v18, s21, v171, v170
	v_add3_u32 v197, s85, v171, v30
	s_bitset1_b32 s23, 7
	s_mov_b32 m0, s4
	v_readfirstlane_b32 s4, v2
	s_waitcnt vmcnt(6)
	s_barrier
; #define WAIT_V(n) asm volatile("s_waitcnt vmcnt(" #n ")" ::: "memory")
; #define WAIT_L(n) asm volatile("s_waitcnt lgkmcnt(" #n ")" ::: "memory")
; #define BAR __builtin_amdgcn_s_barrier()
; DEV void gemm_tile(const h16* __restrict__ A, const h16* __restrict__ Bt, int K, int ld, int brow, int bcol, h16* shm, Acc& acc) {
;     ...
;   { LDB(B0, 0, 0); LDA(At, 0, 0); STAGE(SA(1, 1), rsA, brow + HALF_, nt - 1);
;     BAR; WAIT_L(0); MMA(0, 0, At, B0); BAR;
;     LDB(B1, 0, 1); BAR; WAIT_L(0); MMA(0, 1, At, B1); BAR;
;     LDA(At, 0, 1); WAIT_V(4); BAR; WAIT_L(0); MMA(1, 0, At, B0); MMA(1, 1, At, B1); BAR; }
	ds_read_b128 v[6:9], v18
	ds_read_b128 v[10:13], v18 offset:1024
	s_waitcnt vmcnt(23)
	ds_read_b128 v[14:17], v18 offset:2048
	ds_read_b128 v[18:21], v18 offset:3072
	ds_read_b128 v[22:25], v197
	ds_read_b128 v[26:29], v197 offset:1024
	ds_read_b128 v[30:33], v192 offset:2048
	ds_read_b128 v[34:37], v192 offset:3072
	ds_read_b128 v[38:41], v192 offset:4096
	ds_read_b128 v[42:45], v192 offset:5120
	ds_read_b128 v[46:49], v192 offset:6144
	ds_read_b128 v[50:53], v192 offset:7168
	buffer_load_dwordx4 v4, s[8:11], s23 offen lds
	s_mov_b32 m0, s4
	s_nop 0
	buffer_load_dwordx4 v3, s[8:11], s23 offen lds
	s_barrier
	s_waitcnt lgkmcnt(0)
	s_waitcnt lgkmcnt(1)
	v_mfma_f32_16x16x32_f16 v[74:77], v[46:49], v[6:9], 0
	v_mfma_f32_16x16x32_f16 v[2:5], v[22:25], v[6:9], 0
	v_mfma_f32_16x16x32_f16 v[54:57], v[22:25], v[14:17], 0
	v_mfma_f32_16x16x32_f16 v[58:61], v[30:33], v[6:9], 0
	v_mfma_f32_16x16x32_f16 v[62:65], v[30:33], v[14:17], 0
	v_mfma_f32_16x16x32_f16 v[66:69], v[38:41], v[6:9], 0
	v_mfma_f32_16x16x32_f16 v[70:73], v[38:41], v[14:17], 0
	s_waitcnt lgkmcnt(0)
	v_mfma_f32_16x16x32_f16 v[82:85], v[50:53], v[10:13], v[74:77]
	v_mfma_f32_16x16x32_f16 v[74:77], v[46:49], v[14:17], 0
	v_mfma_f32_16x16x32_f16 v[2:5], v[26:29], v[10:13], v[2:5]
	v_mfma_f32_16x16x32_f16 v[54:57], v[26:29], v[18:21], v[54:57]
	v_mfma_f32_16x16x32_f16 v[58:61], v[34:37], v[10:13], v[58:61]
	v_mfma_f32_16x16x32_f16 v[62:65], v[34:37], v[18:21], v[62:65]
	v_mfma_f32_16x16x32_f16 v[66:69], v[42:45], v[10:13], v[66:69]
	v_mfma_f32_16x16x32_f16 v[70:73], v[42:45], v[18:21], v[70:73]
	v_mfma_f32_16x16x32_f16 v[86:89], v[50:53], v[18:21], v[74:77]
	v_readlane_b32 s4, v254, 11
	s_barrier
	s_nop 0
	v_add3_u32 v94, s4, v171, v170
	ds_read_b128 v[74:77], v94
	ds_read_b128 v[78:81], v94 offset:1024
	ds_read_b128 v[90:93], v94 offset:2048
	s_waitcnt vmcnt(23)
	ds_read_b128 v[94:97], v94 offset:3072
	s_barrier
	s_waitcnt lgkmcnt(0)
	s_waitcnt vmcnt(17) lgkmcnt(3)
	v_mfma_f32_16x16x32_f16 v[98:101], v[22:25], v[74:77], 0
	s_waitcnt lgkmcnt(1)
	v_mfma_f32_16x16x32_f16 v[22:25], v[22:25], v[90:93], 0
	v_mfma_f32_16x16x32_f16 v[114:117], v[26:29], v[78:81], v[98:101]
	s_waitcnt lgkmcnt(0)
	v_mfma_f32_16x16x32_f16 v[22:25], v[26:29], v[94:97], v[22:25]
	v_mfma_f32_16x16x32_f16 v[26:29], v[30:33], v[74:77], 0
	v_mfma_f32_16x16x32_f16 v[30:33], v[30:33], v[90:93], 0
	v_mfma_f32_16x16x32_f16 v[26:29], v[34:37], v[78:81], v[26:29]
	v_mfma_f32_16x16x32_f16 v[30:33], v[34:37], v[94:97], v[30:33]
	v_mfma_f32_16x16x32_f16 v[34:37], v[38:41], v[74:77], 0
	v_mfma_f32_16x16x32_f16 v[38:41], v[38:41], v[90:93], 0
	v_mfma_f32_16x16x32_f16 v[34:37], v[42:45], v[78:81], v[34:37]
	v_mfma_f32_16x16x32_f16 v[38:41], v[42:45], v[94:97], v[38:41]
	v_mfma_f32_16x16x32_f16 v[42:45], v[46:49], v[74:77], 0
	v_mfma_f32_16x16x32_f16 v[46:49], v[46:49], v[90:93], 0
	v_mfma_f32_16x16x32_f16 v[42:45], v[50:53], v[78:81], v[42:45]
	v_mfma_f32_16x16x32_f16 v[46:49], v[50:53], v[94:97], v[46:49]
	s_barrier
	ds_read_b128 v[50:53], v197 offset:16384
	ds_read_b128 v[98:101], v197 offset:17408
	s_waitcnt vmcnt(16)
	ds_read_b128 v[102:105], v192 offset:18432
	ds_read_b128 v[106:109], v192 offset:19456
	ds_read_b128 v[110:113], v192 offset:20480
	ds_read_b128 v[118:121], v192 offset:21504
	ds_read_b128 v[122:125], v192 offset:22528
	ds_read_b128 v[126:129], v192 offset:23552
	s_waitcnt vmcnt(4)
	s_barrier
	s_waitcnt lgkmcnt(0)
	s_waitcnt lgkmcnt(7)
	v_mfma_f32_16x16x32_f16 v[130:133], v[50:53], v[6:9], 0
	s_waitcnt lgkmcnt(5)
	v_mfma_f32_16x16x32_f16 v[138:141], v[102:105], v[6:9], 0
	s_waitcnt lgkmcnt(3)
	v_mfma_f32_16x16x32_f16 v[146:149], v[110:113], v[6:9], 0
	s_waitcnt lgkmcnt(1)
	v_mfma_f32_16x16x32_f16 v[6:9], v[122:125], v[6:9], 0
	v_mfma_f32_16x16x32_f16 v[130:133], v[98:101], v[10:13], v[130:133]
	v_mfma_f32_16x16x32_f16 v[134:137], v[50:53], v[14:17], 0
	v_mfma_f32_16x16x32_f16 v[138:141], v[106:109], v[10:13], v[138:141]
	v_mfma_f32_16x16x32_f16 v[142:145], v[102:105], v[14:17], 0
	v_mfma_f32_16x16x32_f16 v[146:149], v[118:121], v[10:13], v[146:149]
	v_mfma_f32_16x16x32_f16 v[150:153], v[110:113], v[14:17], 0
	s_waitcnt lgkmcnt(0)
	v_mfma_f32_16x16x32_f16 v[6:9], v[126:129], v[10:13], v[6:9]
	v_mfma_f32_16x16x32_f16 v[10:13], v[122:125], v[14:17], 0
	v_mfma_f32_16x16x32_f16 v[134:137], v[98:101], v[18:21], v[134:137]
	v_mfma_f32_16x16x32_f16 v[142:145], v[106:109], v[18:21], v[142:145]
	v_mfma_f32_16x16x32_f16 v[150:153], v[118:121], v[18:21], v[150:153]
	v_mfma_f32_16x16x32_f16 v[18:21], v[126:129], v[18:21], v[10:13]
	v_mfma_f32_16x16x32_f16 v[10:13], v[50:53], v[74:77], 0
	v_mfma_f32_16x16x32_f16 v[154:157], v[98:101], v[78:81], v[10:13]
	v_mfma_f32_16x16x32_f16 v[10:13], v[50:53], v[90:93], 0
	v_mfma_f32_16x16x32_f16 v[50:53], v[98:101], v[94:97], v[10:13]
	v_mfma_f32_16x16x32_f16 v[10:13], v[102:105], v[74:77], 0
	v_mfma_f32_16x16x32_f16 v[158:161], v[106:109], v[78:81], v[10:13]
	v_mfma_f32_16x16x32_f16 v[10:13], v[102:105], v[90:93], 0
	v_mfma_f32_16x16x32_f16 v[162:165], v[106:109], v[94:97], v[10:13]
	v_mfma_f32_16x16x32_f16 v[10:13], v[110:113], v[74:77], 0
	v_mfma_f32_16x16x32_f16 v[166:169], v[118:121], v[78:81], v[10:13]
	v_mfma_f32_16x16x32_f16 v[10:13], v[110:113], v[90:93], 0
	v_mfma_f32_16x16x32_f16 v[198:201], v[118:121], v[94:97], v[10:13]
	v_mfma_f32_16x16x32_f16 v[10:13], v[122:125], v[74:77], 0
	v_mfma_f32_16x16x32_f16 v[202:205], v[126:129], v[78:81], v[10:13]
	v_mfma_f32_16x16x32_f16 v[10:13], v[122:125], v[90:93], 0
	v_mfma_f32_16x16x32_f16 v[206:209], v[126:129], v[94:97], v[10:13]
	s_nop 5
	v_add3_u32 v10, s94, v171, v170
	s_barrier
; #define WAIT_V(n) asm volatile("s_waitcnt vmcnt(" #n ")" ::: "memory")
; #define WAIT_L(n) asm volatile("s_waitcnt lgkmcnt(" #n ")" ::: "memory")
; #define BAR __builtin_amdgcn_s_barrier()
; DEV void gemm_tile(const h16* __restrict__ A, const h16* __restrict__ Bt, int K, int ld, int brow, int bcol, h16* shm, Acc& acc) {
;     ...
;   { LDB(B0, 1, 0); LDA(At, 1, 0); WAIT_V(2); BAR; WAIT_L(0); MMA(0, 0, At, B0); BAR;
;     LDB(B1, 1, 1); WAIT_V(0); BAR; WAIT_L(0); MMA(0, 1, At, B1); BAR;
;     LDA(At, 1, 1); BAR; WAIT_L(0); MMA(1, 0, At, B0); MMA(1, 1, At, B1); BAR; }
;   if (wr == 0) BAR;
	ds_read_b128 v[210:213], v10
	ds_read_b128 v[214:217], v10 offset:1024
	ds_read_b128 v[218:221], v10 offset:2048
	ds_read_b128 v[222:225], v10 offset:3072
	ds_read_b128 v[10:13], v197 offset:32768
	ds_read_b128 v[14:17], v197 offset:33792
	ds_read_b128 v[90:93], v192 offset:34816
	ds_read_b128 v[94:97], v192 offset:35840
	ds_read_b128 v[226:229], v192 offset:36864
	ds_read_b128 v[230:233], v192 offset:37888
	ds_read_b128 v[234:237], v192 offset:38912
	ds_read_b128 v[238:241], v192 offset:39936
	s_waitcnt vmcnt(2)
	s_barrier
	s_waitcnt lgkmcnt(0)
	s_waitcnt lgkmcnt(7)
	v_mfma_f32_16x16x32_f16 v[2:5], v[10:13], v[210:213], v[2:5]
	s_waitcnt lgkmcnt(6)
	v_mfma_f32_16x16x32_f16 v[106:109], v[14:17], v[214:217], v[2:5]
	v_mfma_f32_16x16x32_f16 v[2:5], v[10:13], v[218:221], v[54:57]
	v_mfma_f32_16x16x32_f16 v[110:113], v[14:17], v[222:225], v[2:5]
	s_waitcnt lgkmcnt(5)
	v_mfma_f32_16x16x32_f16 v[2:5], v[90:93], v[210:213], v[58:61]
	s_waitcnt lgkmcnt(4)
	v_mfma_f32_16x16x32_f16 v[98:101], v[94:97], v[214:217], v[2:5]
	v_mfma_f32_16x16x32_f16 v[2:5], v[90:93], v[218:221], v[62:65]
	v_mfma_f32_16x16x32_f16 v[102:105], v[94:97], v[222:225], v[2:5]
	s_waitcnt lgkmcnt(3)
	v_mfma_f32_16x16x32_f16 v[2:5], v[226:229], v[210:213], v[66:69]
	s_waitcnt lgkmcnt(2)
	v_mfma_f32_16x16x32_f16 v[74:77], v[230:233], v[214:217], v[2:5]
	v_mfma_f32_16x16x32_f16 v[2:5], v[226:229], v[218:221], v[70:73]
	v_mfma_f32_16x16x32_f16 v[78:81], v[230:233], v[222:225], v[2:5]
	s_waitcnt lgkmcnt(1)
	v_mfma_f32_16x16x32_f16 v[2:5], v[234:237], v[210:213], v[82:85]
	s_waitcnt lgkmcnt(0)
	v_mfma_f32_16x16x32_f16 v[66:69], v[238:241], v[214:217], v[2:5]
	v_mfma_f32_16x16x32_f16 v[2:5], v[234:237], v[218:221], v[86:89]
	v_mfma_f32_16x16x32_f16 v[70:73], v[238:241], v[222:225], v[2:5]
	s_nop 5
	v_add3_u32 v2, s22, v171, v170
	s_barrier
	ds_read_b128 v[242:245], v2
	ds_read_b128 v[246:249], v2 offset:1024
	ds_read_b128 v[178:181], v2 offset:2048
	ds_read_b128 v[174:177], v2 offset:3072
	s_waitcnt vmcnt(0)
	s_barrier
	s_waitcnt lgkmcnt(0)
	s_waitcnt lgkmcnt(3)
	v_mfma_f32_16x16x32_f16 v[2:5], v[10:13], v[242:245], v[114:117]
	s_waitcnt lgkmcnt(2)
	v_mfma_f32_16x16x32_f16 v[122:125], v[14:17], v[246:249], v[2:5]
	s_waitcnt lgkmcnt(1)
	v_mfma_f32_16x16x32_f16 v[2:5], v[10:13], v[178:181], v[22:25]
	s_waitcnt lgkmcnt(0)
	v_mfma_f32_16x16x32_f16 v[126:129], v[14:17], v[174:177], v[2:5]
	v_mfma_f32_16x16x32_f16 v[2:5], v[90:93], v[242:245], v[26:29]
	v_mfma_f32_16x16x32_f16 v[114:117], v[94:97], v[246:249], v[2:5]
	v_mfma_f32_16x16x32_f16 v[2:5], v[90:93], v[178:181], v[30:33]
	v_mfma_f32_16x16x32_f16 v[118:121], v[94:97], v[174:177], v[2:5]
	v_mfma_f32_16x16x32_f16 v[2:5], v[226:229], v[242:245], v[34:37]
	v_mfma_f32_16x16x32_f16 v[90:93], v[230:233], v[246:249], v[2:5]
	v_mfma_f32_16x16x32_f16 v[2:5], v[226:229], v[178:181], v[38:41]
	v_mfma_f32_16x16x32_f16 v[94:97], v[230:233], v[174:177], v[2:5]
	v_mfma_f32_16x16x32_f16 v[2:5], v[234:237], v[242:245], v[42:45]
	v_mfma_f32_16x16x32_f16 v[82:85], v[238:241], v[246:249], v[2:5]
	v_mfma_f32_16x16x32_f16 v[2:5], v[234:237], v[178:181], v[46:49]
	v_mfma_f32_16x16x32_f16 v[86:89], v[238:241], v[174:177], v[2:5]
	s_barrier
	ds_read_b128 v[22:25], v197 offset:49152
	ds_read_b128 v[26:29], v197 offset:50176
	ds_read_b128 v[30:33], v192 offset:51200
	ds_read_b128 v[54:57], v192 offset:52224
	ds_read_b128 v[226:229], v192 offset:53248
	ds_read_b128 v[230:233], v192 offset:54272
	ds_read_b128 v[234:237], v192 offset:55296
	ds_read_b128 v[238:241], v192 offset:56320
	s_barrier
	s_waitcnt lgkmcnt(0)
	s_waitcnt lgkmcnt(7)
	v_mfma_f32_16x16x32_f16 v[2:5], v[22:25], v[210:213], v[130:133]
	s_waitcnt lgkmcnt(6)
	v_mfma_f32_16x16x32_f16 v[42:45], v[26:29], v[214:217], v[2:5]
	v_mfma_f32_16x16x32_f16 v[2:5], v[22:25], v[218:221], v[134:137]
	v_mfma_f32_16x16x32_f16 v[46:49], v[26:29], v[222:225], v[2:5]
	s_waitcnt lgkmcnt(5)
	v_mfma_f32_16x16x32_f16 v[2:5], v[30:33], v[210:213], v[138:141]
	s_waitcnt lgkmcnt(4)
	v_mfma_f32_16x16x32_f16 v[34:37], v[54:57], v[214:217], v[2:5]
	v_mfma_f32_16x16x32_f16 v[2:5], v[30:33], v[218:221], v[142:145]
	v_mfma_f32_16x16x32_f16 v[38:41], v[54:57], v[222:225], v[2:5]
	s_waitcnt lgkmcnt(3)
	v_mfma_f32_16x16x32_f16 v[2:5], v[226:229], v[210:213], v[146:149]
	s_waitcnt lgkmcnt(2)
	v_mfma_f32_16x16x32_f16 v[10:13], v[230:233], v[214:217], v[2:5]
	v_mfma_f32_16x16x32_f16 v[2:5], v[226:229], v[218:221], v[150:153]
	v_mfma_f32_16x16x32_f16 v[14:17], v[230:233], v[222:225], v[2:5]
	s_waitcnt lgkmcnt(1)
	v_mfma_f32_16x16x32_f16 v[2:5], v[234:237], v[210:213], v[6:9]
	v_mfma_f32_16x16x32_f16 v[6:9], v[234:237], v[218:221], v[18:21]
	s_waitcnt lgkmcnt(0)
	v_mfma_f32_16x16x32_f16 v[2:5], v[238:241], v[214:217], v[2:5]
	v_mfma_f32_16x16x32_f16 v[6:9], v[238:241], v[222:225], v[6:9]
	v_mfma_f32_16x16x32_f16 v[18:21], v[22:25], v[242:245], v[154:157]
	v_mfma_f32_16x16x32_f16 v[58:61], v[26:29], v[246:249], v[18:21]
	v_mfma_f32_16x16x32_f16 v[18:21], v[22:25], v[178:181], v[50:53]
	v_mfma_f32_16x16x32_f16 v[62:65], v[26:29], v[174:177], v[18:21]
	v_mfma_f32_16x16x32_f16 v[18:21], v[30:33], v[242:245], v[158:161]
	v_mfma_f32_16x16x32_f16 v[50:53], v[54:57], v[246:249], v[18:21]
	v_mfma_f32_16x16x32_f16 v[18:21], v[30:33], v[178:181], v[162:165]
	v_mfma_f32_16x16x32_f16 v[54:57], v[54:57], v[174:177], v[18:21]
	v_mfma_f32_16x16x32_f16 v[18:21], v[226:229], v[242:245], v[166:169]
	v_mfma_f32_16x16x32_f16 v[26:29], v[230:233], v[246:249], v[18:21]
	v_mfma_f32_16x16x32_f16 v[18:21], v[226:229], v[178:181], v[198:201]
	v_mfma_f32_16x16x32_f16 v[30:33], v[230:233], v[174:177], v[18:21]
	v_mfma_f32_16x16x32_f16 v[18:21], v[234:237], v[242:245], v[202:205]
	v_mfma_f32_16x16x32_f16 v[22:25], v[234:237], v[178:181], v[206:209]
	v_mfma_f32_16x16x32_f16 v[18:21], v[238:241], v[246:249], v[18:21]
	v_mfma_f32_16x16x32_f16 v[22:25], v[238:241], v[174:177], v[22:25]
	s_setprio 0
	s_movk_i32 s4, 0x100
	v_cmp_gt_u32_e32 vcc, s4, v0
	s_barrier
	s_and_saveexec_b64 s[4:5], vcc
	s_cbranch_execz .LBB0_144
	s_barrier

; #define WAIT_V(n) asm volatile("s_waitcnt vmcnt(" #n ")" ::: "memory")
; #define BAR __builtin_amdgcn_s_barrier()
; DEV void gemm_tile(const h16* __restrict__ A, const h16* __restrict__ Bt, int K, int ld, int brow, int bcol, h16* shm, Acc& acc) {
;     ...
;   int wid = TID >> 6, lane = TID & 63, wr = wid >> 2, wc = wid & 3, fr = lane & 15, fq = lane >> 4;
;   int vo0, vo1;
;   {
;     int r, c;
;     stage_rc(TID * 16, r, c);
;     vo0 = (r * ld + c) * 2;
;     stage_rc(TID * 16 + 8192, r, c);
;     vo1 = (r * ld + c) * 2;
;   }
;   __amdgpu_buffer_rsrc_t rsA = __builtin_amdgcn_make_buffer_rsrc((void*)A, (short)0, 0x7fffffff, 0x00020000);
;   __amdgpu_buffer_rsrc_t rsB = __builtin_amdgcn_make_buffer_rsrc((void*)Bt, (short)0, 0x7fffffff, 0x00020000);
; #pragma unroll
;   for (int a = 0; a < 2; ++a)
; #pragma unroll
;     for (int b = 0; b < 2; ++b)
; #pragma unroll
;       for (int m = 0; m < 4; ++m)
; #pragma unroll
;         for (int n = 0; n < 2; ++n) acc[a][b][m][n] = f32x4{0.f, 0.f, 0.f, 0.f};
;   h16x8 At[4][2], B0[2][2], B1[2][2];
;   int nt = K / BK;
;   STAGE(SB(0, 0), rsB, bcol, 0); STAGE(SA(0, 0), rsA, brow, 0);
;   STAGE(SB(0, 1), rsB, bcol + HALF_, 0); STAGE(SA(0, 1), rsA, brow + HALF_, 0);
;   if (wr == 1) BAR;
;   WAIT_V(4); BAR;
;   STAGE(SB(1, 0), rsB, bcol, 1); STAGE(SA(1, 0), rsA, brow, 1); STAGE(SB(1, 1), rsB, bcol + HALF_, 1);
;   WAIT_V(6); BAR;
; template <int EPI> __device__ __forceinline__ void gemm_phase(const h16* A, const h16* Bt, int M, int N, int K, const GE& e, h16* shm) {
;     ...
;       int q = nwg / NXCD, r = nwg % NXCD, xcd = wgid % NXCD, off = wgid / NXCD;
;       wgid = (xcd < r ? xcd * (q + 1) : r * (q + 1) + (xcd - r) * q) + off;
;     }
;     int nig = WGM * nN, gid = wgid / nig, fm = gid * WGM, gsz = min(nM - fm, WGM);
;     int pm = fm + ((wgid % nig) % gsz), pn = (wgid % nig) / gsz, brow = pm * BM, bcol = pn * BM;
.LBB0_155:
	s_ashr_i32 s4, s6, 31
	s_lshr_b32 s4, s4, 29
	s_add_i32 s4, s6, s4
	s_ashr_i32 s5, s4, 3
	s_and_b32 s4, s4, -8
	s_sub_i32 s4, s6, s4
	s_lshr_b32 s7, s4, 31
	s_or_b32 s7, s7, 32
	s_mul_i32 s13, s7, s4
	s_add_i32 s13, s13, s5
	s_ashr_i32 s4, s13, 31
	s_lshr_b32 s4, s4, 26
	s_add_i32 s4, s13, s4
	s_ashr_i32 s14, s4, 6
	s_lshl_b32 s7, s14, 3
	s_sub_i32 s5, 32, s7
	s_min_u32 s10, s5, 8
	s_andn2_b32 s4, s4, 63
	s_sub_i32 s11, s13, s4
	v_cvt_f32_ubyte0_e32 v2, s10
	v_cvt_f32_i32_e32 v0, s11
	v_rcp_iflag_f32_e32 v3, v2
	s_ashr_i32 s4, s11, 30
	s_or_b32 s12, s4, 1
	v_mul_f32_e32 v3, v0, v3
	v_trunc_f32_e32 v3, v3
	v_fma_f32 v0, -v3, v2, v0
	v_cmp_ge_f32_e64 s[4:5], |v0|, v2
	v_mov_b32_e32 v0, v172
	v_cvt_i32_f32_e32 v3, v3
	s_and_b64 s[4:5], s[4:5], exec
	v_bfe_i32 v4, v0, 27, 1
	v_lshlrev_b32_e32 v2, 4, v0
	v_lshrrev_b32_e32 v4, 22, v4
	v_add_u32_e32 v4, v2, v4
	v_and_b32_e32 v4, 0xfffffc00, v4
	v_readfirstlane_b32 s5, v3
	v_ashrrev_i32_e32 v3, 31, v0
	v_sub_u32_e32 v4, v2, v4
	v_lshrrev_b32_e32 v3, 26, v3
	v_lshrrev_b32_e32 v5, 4, v4
	v_add_u32_e32 v3, v0, v3
	v_bitop3_b32 v5, v5, v4, 32 bitop3:0x6c
	v_ashrrev_i32_e32 v4, 31, v4
	v_ashrrev_i32_e32 v3, 6, v3
	v_lshrrev_b32_e32 v4, 26, v4
	v_lshlrev_b32_e32 v6, 3, v3
	v_add_u32_e32 v4, v5, v4
	v_and_b32_e32 v6, 0xfffff0, v6
	v_ashrrev_i32_e32 v4, 6, v4
	v_add_u32_e32 v6, v4, v6
	v_lshlrev_b32_e32 v3, 5, v3
	v_mul_i32_i24_e32 v4, 64, v4
	v_and_b32_e32 v3, 32, v3
	v_sub_u32_e32 v4, v5, v4
	v_add_u32_e32 v5, 0x2000, v2
	v_lshl_or_b32 v3, v6, 7, v3
	v_ashrrev_i32_e32 v6, 31, v5
	v_lshrrev_b32_e32 v6, 22, v6
	v_add_u32_e32 v6, v5, v6
	v_ashrrev_i32_e32 v6, 10, v6
	v_mul_i32_i24_e32 v7, 0x400, v6
	v_sub_u32_e32 v5, v5, v7
	v_lshrrev_b32_e32 v7, 4, v5
	v_bitop3_b32 v5, v7, v5, 32 bitop3:0x6c
	v_ashrrev_i32_e32 v8, 31, v5
	v_lshrrev_b32_e32 v8, 26, v8
	v_add_u32_e32 v8, v5, v8
	v_lshlrev_b32_e32 v7, 3, v6
	v_lshrrev_b32_e32 v9, 6, v8
	v_and_b32_e32 v8, 0xc0, v8
	s_cselect_b32 s4, s12, 0
	v_and_b32_e32 v7, 0xfffff0, v7
	v_lshlrev_b32_e32 v6, 5, v6
	v_sub_u32_e32 v5, v5, v8
	s_add_i32 s15, s5, s4
	v_ashrrev_i16_sdwa v4, v187, sext(v4) dst_sel:DWORD dst_unused:UNUSED_PAD src0_sel:DWORD src1_sel:BYTE_0
	v_add_u32_e32 v7, v9, v7
	v_and_b32_e32 v6, 32, v6
	v_ashrrev_i16_sdwa v5, v187, sext(v5) dst_sel:DWORD dst_unused:UNUSED_PAD src0_sel:DWORD src1_sel:BYTE_0
	s_sext_i32_i8 s16, s15
	s_mul_i32 s15, s15, s10
	v_bfe_i32 v4, v4, 0, 16
	v_bfe_i32 v5, v5, 0, 16
	v_lshl_or_b32 v6, v7, 7, v6
	s_add_i32 s17, s68, 0x110
	s_sub_i32 s4, s11, s15
	v_add_lshl_u32 v4, v3, v4, 1
	v_add_lshl_u32 v3, v6, v5, 1
	v_add_u32_e32 v5, s17, v2
	s_sext_i32_i8 s4, s4
	v_readfirstlane_b32 s5, v5
	v_add_u32_e32 v5, 0x2000, v5
	s_add_i32 s4, s7, s4
	s_lshl_b32 s20, s16, 16
	s_mov_b32 m0, s5
	v_readfirstlane_b32 s5, v5
	v_add_u32_e32 v5, 0x110, v2
	s_lshl_b32 s7, s4, 8
	buffer_load_dwordx4 v4, s[76:79], s20 offen lds
	s_mov_b32 m0, s5
	s_lshl_b32 s22, s4, 16
	v_readfirstlane_b32 s4, v5
	v_add_u32_e32 v6, 0x2000, v5
	v_readlane_b32 s5, v254, 11
	buffer_load_dwordx4 v3, s[76:79], s20 offen lds
	s_mov_b32 s10, s78
	s_mov_b32 s11, s79
	s_mov_b32 m0, s4
	v_readfirstlane_b32 s4, v6
	v_add_u32_e32 v6, s5, v2
	buffer_load_dwordx4 v4, s[8:11], s22 offen lds
	s_mov_b32 m0, s4
	v_readfirstlane_b32 s5, v6
	v_add_u32_e32 v6, 0x2000, v6
	buffer_load_dwordx4 v3, s[8:11], s22 offen lds
	s_or_b32 s4, s20, 0x8000
	s_mov_b32 m0, s5
	v_readfirstlane_b32 s5, v6
	buffer_load_dwordx4 v4, s[76:79], s4 offen lds
	s_mov_b32 m0, s5
	v_add_u32_e32 v6, 0x4000, v5
	buffer_load_dwordx4 v3, s[76:79], s4 offen lds
	s_or_b32 s12, s7, 0x80
	v_readfirstlane_b32 s4, v6
	v_add_u32_e32 v6, 0x6000, v5
	s_lshl_b32 s21, s12, 8
	s_mov_b32 m0, s4
	v_readfirstlane_b32 s4, v6
	buffer_load_dwordx4 v4, s[8:11], s21 offen lds
	s_mov_b32 m0, s4
	v_ashrrev_i32_e32 v6, 8, v0
	buffer_load_dwordx4 v3, s[8:11], s21 offen lds
	v_cmp_eq_u32_e32 vcc, 1, v6
	s_and_saveexec_b64 s[4:5], vcc
	s_cbranch_execz .LBB0_157
	s_barrier
	s_setprio 1
.LBB0_157:
	s_or_b64 exec, exec, s[4:5]
	v_add_u32_e32 v9, s94, v2
	s_or_b32 s4, s20, 0x80
	v_readfirstlane_b32 s5, v9
	v_add_u32_e32 v9, 0x2000, v9
	s_mov_b32 m0, s5
	v_readfirstlane_b32 s5, v9
	s_waitcnt vmcnt(4)
	s_barrier
	buffer_load_dwordx4 v4, s[76:79], s4 offen lds
	s_mov_b32 m0, s5
	v_add_u32_e32 v9, 0x8000, v5
	buffer_load_dwordx4 v3, s[76:79], s4 offen lds
	v_readfirstlane_b32 s4, v9
	v_add_u32_e32 v9, 0xa000, v5
	s_bitset1_b32 s22, 7
	s_mov_b32 m0, s4
	v_readfirstlane_b32 s4, v9
	buffer_load_dwordx4 v4, s[8:11], s22 offen lds
	s_mov_b32 m0, s4
	s_or_b32 s4, s20, 0x8080
	v_readlane_b32 s20, v254, 12
	buffer_load_dwordx4 v3, s[8:11], s22 offen lds
	v_lshlrev_b32_e32 v9, 2, v0
	v_add_u32_e32 v2, s20, v2
	v_and_b32_e32 v8, 48, v0
	v_readfirstlane_b32 s5, v2
	v_add_u32_e32 v2, 0x2000, v2
	s_mov_b32 m0, s5
	v_readfirstlane_b32 s5, v2
	v_lshlrev_b32_e32 v2, 6, v0
	v_and_b32_e32 v170, 0x3000, v2
	v_and_b32_e32 v9, 32, v9
	v_and_b32_e32 v2, 0x3c0, v2
	v_and_b32_e32 v7, 15, v0
	s_waitcnt vmcnt(55)
	v_lshlrev_b32_e32 v30, 13, v6
	v_bitop3_b32 v2, v2, v9, v8 bitop3:0x36
	buffer_load_dwordx4 v4, s[76:79], s4 offen lds
	s_mov_b32 m0, s5
	v_lshlrev_b32_e32 v7, 6, v7
	v_add3_u32 v197, s85, v2, v30
	v_add_u32_e32 v2, 0xc000, v5
	buffer_load_dwordx4 v3, s[76:79], s4 offen lds
	v_bitop3_b32 v171, v7, v9, v8 bitop3:0x36
	v_readfirstlane_b32 s4, v2
	v_add_u32_e32 v2, 0xe000, v5
	v_add3_u32 v18, s17, v171, v170
	v_add3_u32 v192, s85, v171, v30
	s_bitset1_b32 s21, 7
	s_mov_b32 m0, s4
	v_readfirstlane_b32 s4, v2
	s_waitcnt vmcnt(6)
	s_barrier
; #define WAIT_V(n) asm volatile("s_waitcnt vmcnt(" #n ")" ::: "memory")
; #define WAIT_L(n) asm volatile("s_waitcnt lgkmcnt(" #n ")" ::: "memory")
; #define BAR __builtin_amdgcn_s_barrier()
; DEV void gemm_tile(const h16* __restrict__ A, const h16* __restrict__ Bt, int K, int ld, int brow, int bcol, h16* shm, Acc& acc) {
;     ...
;   { LDB(B0, 0, 0); LDA(At, 0, 0); STAGE(SA(1, 1), rsA, brow + HALF_, nt - 1);
;     BAR; WAIT_L(0); MMA(0, 0, At, B0); BAR;
;     LDB(B1, 0, 1); BAR; WAIT_L(0); MMA(0, 1, At, B1); BAR;
;     LDA(At, 0, 1); WAIT_V(4); BAR; WAIT_L(0); MMA(1, 0, At, B0); MMA(1, 1, At, B1); BAR; }
	ds_read_b128 v[6:9], v18
	ds_read_b128 v[10:13], v18 offset:1024
	s_waitcnt vmcnt(23)
	ds_read_b128 v[14:17], v18 offset:2048
	ds_read_b128 v[18:21], v18 offset:3072
	ds_read_b128 v[22:25], v192
	ds_read_b128 v[26:29], v192 offset:1024
	ds_read_b128 v[30:33], v197 offset:2048
	ds_read_b128 v[34:37], v197 offset:3072
	ds_read_b128 v[38:41], v197 offset:4096
	ds_read_b128 v[42:45], v197 offset:5120
	ds_read_b128 v[46:49], v197 offset:6144
	ds_read_b128 v[50:53], v197 offset:7168
	buffer_load_dwordx4 v4, s[8:11], s21 offen lds
	s_mov_b32 m0, s4
	s_nop 0
	buffer_load_dwordx4 v3, s[8:11], s21 offen lds
	s_barrier
	s_waitcnt lgkmcnt(0)
	s_waitcnt lgkmcnt(1)
	v_mfma_f32_16x16x32_f16 v[74:77], v[46:49], v[6:9], 0
	v_mfma_f32_16x16x32_f16 v[2:5], v[22:25], v[6:9], 0
	v_mfma_f32_16x16x32_f16 v[54:57], v[22:25], v[14:17], 0
	v_mfma_f32_16x16x32_f16 v[58:61], v[30:33], v[6:9], 0
	v_mfma_f32_16x16x32_f16 v[62:65], v[30:33], v[14:17], 0
	v_mfma_f32_16x16x32_f16 v[66:69], v[38:41], v[6:9], 0
	v_mfma_f32_16x16x32_f16 v[70:73], v[38:41], v[14:17], 0
	s_waitcnt lgkmcnt(0)
	v_mfma_f32_16x16x32_f16 v[82:85], v[50:53], v[10:13], v[74:77]
	v_mfma_f32_16x16x32_f16 v[74:77], v[46:49], v[14:17], 0
	v_mfma_f32_16x16x32_f16 v[2:5], v[26:29], v[10:13], v[2:5]
	v_mfma_f32_16x16x32_f16 v[54:57], v[26:29], v[18:21], v[54:57]
	v_mfma_f32_16x16x32_f16 v[58:61], v[34:37], v[10:13], v[58:61]
	v_mfma_f32_16x16x32_f16 v[62:65], v[34:37], v[18:21], v[62:65]
	v_mfma_f32_16x16x32_f16 v[66:69], v[42:45], v[10:13], v[66:69]
	v_mfma_f32_16x16x32_f16 v[70:73], v[42:45], v[18:21], v[70:73]
	v_mfma_f32_16x16x32_f16 v[86:89], v[50:53], v[18:21], v[74:77]
	v_readlane_b32 s4, v254, 11
	s_barrier
	s_nop 0
	v_add3_u32 v94, s4, v171, v170
	ds_read_b128 v[74:77], v94
	ds_read_b128 v[78:81], v94 offset:1024
	ds_read_b128 v[90:93], v94 offset:2048
	s_waitcnt vmcnt(23)
	ds_read_b128 v[94:97], v94 offset:3072
	s_barrier
	s_waitcnt lgkmcnt(0)
	s_waitcnt vmcnt(17) lgkmcnt(3)
	v_mfma_f32_16x16x32_f16 v[98:101], v[22:25], v[74:77], 0
	s_waitcnt lgkmcnt(1)
	v_mfma_f32_16x16x32_f16 v[22:25], v[22:25], v[90:93], 0
	v_mfma_f32_16x16x32_f16 v[114:117], v[26:29], v[78:81], v[98:101]
	s_waitcnt lgkmcnt(0)
	v_mfma_f32_16x16x32_f16 v[22:25], v[26:29], v[94:97], v[22:25]
	v_mfma_f32_16x16x32_f16 v[26:29], v[30:33], v[74:77], 0
	v_mfma_f32_16x16x32_f16 v[30:33], v[30:33], v[90:93], 0
	v_mfma_f32_16x16x32_f16 v[26:29], v[34:37], v[78:81], v[26:29]
	v_mfma_f32_16x16x32_f16 v[30:33], v[34:37], v[94:97], v[30:33]
	v_mfma_f32_16x16x32_f16 v[34:37], v[38:41], v[74:77], 0
	v_mfma_f32_16x16x32_f16 v[38:41], v[38:41], v[90:93], 0
	v_mfma_f32_16x16x32_f16 v[34:37], v[42:45], v[78:81], v[34:37]
	v_mfma_f32_16x16x32_f16 v[38:41], v[42:45], v[94:97], v[38:41]
	v_mfma_f32_16x16x32_f16 v[42:45], v[46:49], v[74:77], 0
	v_mfma_f32_16x16x32_f16 v[46:49], v[46:49], v[90:93], 0
	v_mfma_f32_16x16x32_f16 v[42:45], v[50:53], v[78:81], v[42:45]
	v_mfma_f32_16x16x32_f16 v[46:49], v[50:53], v[94:97], v[46:49]
	s_barrier
	ds_read_b128 v[50:53], v192 offset:16384
	ds_read_b128 v[98:101], v192 offset:17408
	s_waitcnt vmcnt(16)
	ds_read_b128 v[102:105], v197 offset:18432
	ds_read_b128 v[106:109], v197 offset:19456
	ds_read_b128 v[110:113], v197 offset:20480
	ds_read_b128 v[118:121], v197 offset:21504
	ds_read_b128 v[122:125], v197 offset:22528
	ds_read_b128 v[126:129], v197 offset:23552
	s_waitcnt vmcnt(4)
	s_barrier
	s_waitcnt lgkmcnt(0)
	s_waitcnt lgkmcnt(7)
	v_mfma_f32_16x16x32_f16 v[130:133], v[50:53], v[6:9], 0
	s_waitcnt lgkmcnt(5)
	v_mfma_f32_16x16x32_f16 v[138:141], v[102:105], v[6:9], 0
	s_waitcnt lgkmcnt(3)
	v_mfma_f32_16x16x32_f16 v[146:149], v[110:113], v[6:9], 0
	s_waitcnt lgkmcnt(1)
	v_mfma_f32_16x16x32_f16 v[6:9], v[122:125], v[6:9], 0
	v_mfma_f32_16x16x32_f16 v[130:133], v[98:101], v[10:13], v[130:133]
	v_mfma_f32_16x16x32_f16 v[134:137], v[50:53], v[14:17], 0
	v_mfma_f32_16x16x32_f16 v[138:141], v[106:109], v[10:13], v[138:141]
	v_mfma_f32_16x16x32_f16 v[142:145], v[102:105], v[14:17], 0
	v_mfma_f32_16x16x32_f16 v[146:149], v[118:121], v[10:13], v[146:149]
	v_mfma_f32_16x16x32_f16 v[150:153], v[110:113], v[14:17], 0
	s_waitcnt lgkmcnt(0)
	v_mfma_f32_16x16x32_f16 v[6:9], v[126:129], v[10:13], v[6:9]
	v_mfma_f32_16x16x32_f16 v[10:13], v[122:125], v[14:17], 0
	v_mfma_f32_16x16x32_f16 v[134:137], v[98:101], v[18:21], v[134:137]
	v_mfma_f32_16x16x32_f16 v[142:145], v[106:109], v[18:21], v[142:145]
	v_mfma_f32_16x16x32_f16 v[150:153], v[118:121], v[18:21], v[150:153]
	v_mfma_f32_16x16x32_f16 v[18:21], v[126:129], v[18:21], v[10:13]
	v_mfma_f32_16x16x32_f16 v[10:13], v[50:53], v[74:77], 0
	v_mfma_f32_16x16x32_f16 v[154:157], v[98:101], v[78:81], v[10:13]
	v_mfma_f32_16x16x32_f16 v[10:13], v[50:53], v[90:93], 0
	v_mfma_f32_16x16x32_f16 v[50:53], v[98:101], v[94:97], v[10:13]
	v_mfma_f32_16x16x32_f16 v[10:13], v[102:105], v[74:77], 0
	v_mfma_f32_16x16x32_f16 v[158:161], v[106:109], v[78:81], v[10:13]
	v_mfma_f32_16x16x32_f16 v[10:13], v[102:105], v[90:93], 0
	v_mfma_f32_16x16x32_f16 v[162:165], v[106:109], v[94:97], v[10:13]
	v_mfma_f32_16x16x32_f16 v[10:13], v[110:113], v[74:77], 0
	v_mfma_f32_16x16x32_f16 v[166:169], v[118:121], v[78:81], v[10:13]
	v_mfma_f32_16x16x32_f16 v[10:13], v[110:113], v[90:93], 0
	v_mfma_f32_16x16x32_f16 v[174:177], v[118:121], v[94:97], v[10:13]
	v_mfma_f32_16x16x32_f16 v[10:13], v[122:125], v[74:77], 0
	v_mfma_f32_16x16x32_f16 v[178:181], v[126:129], v[78:81], v[10:13]
	v_mfma_f32_16x16x32_f16 v[10:13], v[122:125], v[90:93], 0
	v_mfma_f32_16x16x32_f16 v[198:201], v[126:129], v[94:97], v[10:13]
	s_nop 5
	v_add3_u32 v10, s94, v171, v170
	s_barrier
; #define WAIT_V(n) asm volatile("s_waitcnt vmcnt(" #n ")" ::: "memory")
; #define WAIT_L(n) asm volatile("s_waitcnt lgkmcnt(" #n ")" ::: "memory")
; #define BAR __builtin_amdgcn_s_barrier()
; DEV void gemm_tile(const h16* __restrict__ A, const h16* __restrict__ Bt, int K, int ld, int brow, int bcol, h16* shm, Acc& acc) {
;     ...
;   { LDB(B0, 1, 0); LDA(At, 1, 0); WAIT_V(2); BAR; WAIT_L(0); MMA(0, 0, At, B0); BAR;
;     LDB(B1, 1, 1); WAIT_V(0); BAR; WAIT_L(0); MMA(0, 1, At, B1); BAR;
;     LDA(At, 1, 1); BAR; WAIT_L(0); MMA(1, 0, At, B0); MMA(1, 1, At, B1); BAR; }
;   if (wr == 0) BAR;
	ds_read_b128 v[202:205], v10
	ds_read_b128 v[206:209], v10 offset:1024
	ds_read_b128 v[210:213], v10 offset:2048
	ds_read_b128 v[214:217], v10 offset:3072
	ds_read_b128 v[10:13], v192 offset:32768
	ds_read_b128 v[14:17], v192 offset:33792
	ds_read_b128 v[90:93], v197 offset:34816
	ds_read_b128 v[94:97], v197 offset:35840
	ds_read_b128 v[218:221], v197 offset:36864
	ds_read_b128 v[222:225], v197 offset:37888
	ds_read_b128 v[226:229], v197 offset:38912
	ds_read_b128 v[230:233], v197 offset:39936
	s_waitcnt vmcnt(2)
	s_barrier
	s_waitcnt lgkmcnt(0)
	s_waitcnt lgkmcnt(7)
	v_mfma_f32_16x16x32_f16 v[2:5], v[10:13], v[202:205], v[2:5]
	s_waitcnt lgkmcnt(6)
	v_mfma_f32_16x16x32_f16 v[106:109], v[14:17], v[206:209], v[2:5]
	v_mfma_f32_16x16x32_f16 v[2:5], v[10:13], v[210:213], v[54:57]
	v_mfma_f32_16x16x32_f16 v[110:113], v[14:17], v[214:217], v[2:5]
	s_waitcnt lgkmcnt(5)
	v_mfma_f32_16x16x32_f16 v[2:5], v[90:93], v[202:205], v[58:61]
	s_waitcnt lgkmcnt(4)
	v_mfma_f32_16x16x32_f16 v[98:101], v[94:97], v[206:209], v[2:5]
	v_mfma_f32_16x16x32_f16 v[2:5], v[90:93], v[210:213], v[62:65]
	v_mfma_f32_16x16x32_f16 v[102:105], v[94:97], v[214:217], v[2:5]
	s_waitcnt lgkmcnt(3)
	v_mfma_f32_16x16x32_f16 v[2:5], v[218:221], v[202:205], v[66:69]
	s_waitcnt lgkmcnt(2)
	v_mfma_f32_16x16x32_f16 v[74:77], v[222:225], v[206:209], v[2:5]
	v_mfma_f32_16x16x32_f16 v[2:5], v[218:221], v[210:213], v[70:73]
	v_mfma_f32_16x16x32_f16 v[78:81], v[222:225], v[214:217], v[2:5]
	s_waitcnt lgkmcnt(1)
	v_mfma_f32_16x16x32_f16 v[2:5], v[226:229], v[202:205], v[82:85]
	s_waitcnt lgkmcnt(0)
	v_mfma_f32_16x16x32_f16 v[66:69], v[230:233], v[206:209], v[2:5]
	v_mfma_f32_16x16x32_f16 v[2:5], v[226:229], v[210:213], v[86:89]
	v_mfma_f32_16x16x32_f16 v[70:73], v[230:233], v[214:217], v[2:5]
	s_nop 5
	v_add3_u32 v2, s20, v171, v170
	s_barrier
	ds_read_b128 v[234:237], v2
	ds_read_b128 v[238:241], v2 offset:1024
	ds_read_b128 v[242:245], v2 offset:2048
	ds_read_b128 v[246:249], v2 offset:3072
	s_waitcnt vmcnt(0)
	s_barrier
	s_waitcnt lgkmcnt(0)
	s_waitcnt lgkmcnt(3)
	v_mfma_f32_16x16x32_f16 v[2:5], v[10:13], v[234:237], v[114:117]
	s_waitcnt lgkmcnt(2)
	v_mfma_f32_16x16x32_f16 v[122:125], v[14:17], v[238:241], v[2:5]
	s_waitcnt lgkmcnt(1)
	v_mfma_f32_16x16x32_f16 v[2:5], v[10:13], v[242:245], v[22:25]
	s_waitcnt lgkmcnt(0)
	v_mfma_f32_16x16x32_f16 v[126:129], v[14:17], v[246:249], v[2:5]
	v_mfma_f32_16x16x32_f16 v[2:5], v[90:93], v[234:237], v[26:29]
	v_mfma_f32_16x16x32_f16 v[114:117], v[94:97], v[238:241], v[2:5]
	v_mfma_f32_16x16x32_f16 v[2:5], v[90:93], v[242:245], v[30:33]
	v_mfma_f32_16x16x32_f16 v[118:121], v[94:97], v[246:249], v[2:5]
	v_mfma_f32_16x16x32_f16 v[2:5], v[218:221], v[234:237], v[34:37]
	v_mfma_f32_16x16x32_f16 v[90:93], v[222:225], v[238:241], v[2:5]
	v_mfma_f32_16x16x32_f16 v[2:5], v[218:221], v[242:245], v[38:41]
	v_mfma_f32_16x16x32_f16 v[94:97], v[222:225], v[246:249], v[2:5]
	v_mfma_f32_16x16x32_f16 v[2:5], v[226:229], v[234:237], v[42:45]
	v_mfma_f32_16x16x32_f16 v[82:85], v[230:233], v[238:241], v[2:5]
	v_mfma_f32_16x16x32_f16 v[2:5], v[226:229], v[242:245], v[46:49]
	v_mfma_f32_16x16x32_f16 v[86:89], v[230:233], v[246:249], v[2:5]
	s_barrier
	ds_read_b128 v[22:25], v192 offset:49152
	ds_read_b128 v[26:29], v192 offset:50176
	ds_read_b128 v[30:33], v197 offset:51200
	ds_read_b128 v[54:57], v197 offset:52224
	ds_read_b128 v[218:221], v197 offset:53248
	ds_read_b128 v[222:225], v197 offset:54272
	ds_read_b128 v[226:229], v197 offset:55296
	ds_read_b128 v[230:233], v197 offset:56320
	s_barrier
	s_waitcnt lgkmcnt(0)
	s_waitcnt lgkmcnt(7)
	v_mfma_f32_16x16x32_f16 v[2:5], v[22:25], v[202:205], v[130:133]
	s_waitcnt lgkmcnt(6)
	v_mfma_f32_16x16x32_f16 v[42:45], v[26:29], v[206:209], v[2:5]
	v_mfma_f32_16x16x32_f16 v[2:5], v[22:25], v[210:213], v[134:137]
	v_mfma_f32_16x16x32_f16 v[46:49], v[26:29], v[214:217], v[2:5]
	s_waitcnt lgkmcnt(5)
	v_mfma_f32_16x16x32_f16 v[2:5], v[30:33], v[202:205], v[138:141]
	s_waitcnt lgkmcnt(4)
	v_mfma_f32_16x16x32_f16 v[34:37], v[54:57], v[206:209], v[2:5]
	v_mfma_f32_16x16x32_f16 v[2:5], v[30:33], v[210:213], v[142:145]
	v_mfma_f32_16x16x32_f16 v[38:41], v[54:57], v[214:217], v[2:5]
	s_waitcnt lgkmcnt(3)
	v_mfma_f32_16x16x32_f16 v[2:5], v[218:221], v[202:205], v[146:149]
	s_waitcnt lgkmcnt(2)
	v_mfma_f32_16x16x32_f16 v[10:13], v[222:225], v[206:209], v[2:5]
	v_mfma_f32_16x16x32_f16 v[2:5], v[218:221], v[210:213], v[150:153]
	v_mfma_f32_16x16x32_f16 v[14:17], v[222:225], v[214:217], v[2:5]
	s_waitcnt lgkmcnt(1)
	v_mfma_f32_16x16x32_f16 v[2:5], v[226:229], v[202:205], v[6:9]
	v_mfma_f32_16x16x32_f16 v[6:9], v[226:229], v[210:213], v[18:21]
	s_waitcnt lgkmcnt(0)
	v_mfma_f32_16x16x32_f16 v[2:5], v[230:233], v[206:209], v[2:5]
	v_mfma_f32_16x16x32_f16 v[6:9], v[230:233], v[214:217], v[6:9]
	v_mfma_f32_16x16x32_f16 v[18:21], v[22:25], v[234:237], v[154:157]
	v_mfma_f32_16x16x32_f16 v[58:61], v[26:29], v[238:241], v[18:21]
	v_mfma_f32_16x16x32_f16 v[18:21], v[22:25], v[242:245], v[50:53]
	v_mfma_f32_16x16x32_f16 v[62:65], v[26:29], v[246:249], v[18:21]
	v_mfma_f32_16x16x32_f16 v[18:21], v[30:33], v[234:237], v[158:161]
	v_mfma_f32_16x16x32_f16 v[50:53], v[54:57], v[238:241], v[18:21]
	v_mfma_f32_16x16x32_f16 v[18:21], v[30:33], v[242:245], v[162:165]
	v_mfma_f32_16x16x32_f16 v[54:57], v[54:57], v[246:249], v[18:21]
	v_mfma_f32_16x16x32_f16 v[18:21], v[218:221], v[234:237], v[166:169]
	v_mfma_f32_16x16x32_f16 v[26:29], v[222:225], v[238:241], v[18:21]
	v_mfma_f32_16x16x32_f16 v[18:21], v[218:221], v[242:245], v[174:177]
	v_mfma_f32_16x16x32_f16 v[30:33], v[222:225], v[246:249], v[18:21]
	v_mfma_f32_16x16x32_f16 v[18:21], v[226:229], v[234:237], v[178:181]
	v_mfma_f32_16x16x32_f16 v[22:25], v[226:229], v[242:245], v[198:201]
	v_mfma_f32_16x16x32_f16 v[18:21], v[230:233], v[238:241], v[18:21]
	v_mfma_f32_16x16x32_f16 v[22:25], v[230:233], v[246:249], v[22:25]
	s_setprio 0
	s_movk_i32 s4, 0x100
	v_cmp_gt_u32_e32 vcc, s4, v0
	s_barrier
	s_and_saveexec_b64 s[4:5], vcc
	s_cbranch_execz .LBB0_159
	s_barrier

; #define BAR __builtin_amdgcn_s_barrier()
; DEV void gemm_tile(const h16* __restrict__ A, const h16* __restrict__ Bt, int K, int ld, int brow, int bcol, h16* shm, Acc& acc) {
;     ...
;   int wid = TID >> 6, lane = TID & 63, wr = wid >> 2, wc = wid & 3, fr = lane & 15, fq = lane >> 4;
;   int vo0, vo1;
;   {
;     int r, c;
;     stage_rc(TID * 16, r, c);
;     vo0 = (r * ld + c) * 2;
;     stage_rc(TID * 16 + 8192, r, c);
;     vo1 = (r * ld + c) * 2;
;   }
;   __amdgpu_buffer_rsrc_t rsA = __builtin_amdgcn_make_buffer_rsrc((void*)A, (short)0, 0x7fffffff, 0x00020000);
;   __amdgpu_buffer_rsrc_t rsB = __builtin_amdgcn_make_buffer_rsrc((void*)Bt, (short)0, 0x7fffffff, 0x00020000);
; #pragma unroll
;   for (int a = 0; a < 2; ++a)
; #pragma unroll
;     for (int b = 0; b < 2; ++b)
; #pragma unroll
;       for (int m = 0; m < 4; ++m)
; #pragma unroll
;         for (int n = 0; n < 2; ++n) acc[a][b][m][n] = f32x4{0.f, 0.f, 0.f, 0.f};
;   h16x8 At[4][2], B0[2][2], B1[2][2];
;   int nt = K / BK;
;   STAGE(SB(0, 0), rsB, bcol, 0); STAGE(SA(0, 0), rsA, brow, 0);
;   STAGE(SB(0, 1), rsB, bcol + HALF_, 0); STAGE(SA(0, 1), rsA, brow + HALF_, 0);
;   if (wr == 1) BAR;
; template <int EPI> __device__ __forceinline__ void gemm_phase(const h16* A, const h16* Bt, int M, int N, int K, const GE& e, h16* shm) {
;     ...
;       int q = nwg / NXCD, r = nwg % NXCD, xcd = wgid % NXCD, off = wgid / NXCD;
;       wgid = (xcd < r ? xcd * (q + 1) : r * (q + 1) + (xcd - r) * q) + off;
;     }
;     int nig = WGM * nN, gid = wgid / nig, fm = gid * WGM, gsz = min(nM - fm, WGM);
;     int pm = fm + ((wgid % nig) % gsz), pn = (wgid % nig) / gsz, brow = pm * BM, bcol = pn * BM;
.LBB0_213:
	v_mov_b32_e32 v0, v172
	s_ashr_i32 s4, s18, 31
	v_bfe_i32 v4, v0, 27, 1
	v_lshlrev_b32_e32 v2, 4, v0
	v_lshrrev_b32_e32 v4, 22, v4
	v_add_u32_e32 v4, v2, v4
	v_and_b32_e32 v4, 0xfffffc00, v4
	v_ashrrev_i32_e32 v3, 31, v0
	v_sub_u32_e32 v4, v2, v4
	s_lshr_b32 s4, s4, 29
	v_lshrrev_b32_e32 v3, 26, v3
	v_lshrrev_b32_e32 v5, 4, v4
	s_add_i32 s4, s18, s4
	v_add_u32_e32 v3, v0, v3
	v_bitop3_b32 v5, v5, v4, 32 bitop3:0x6c
	v_ashrrev_i32_e32 v4, 31, v4
	s_ashr_i32 s5, s4, 3
	s_and_b32 s4, s4, -8
	v_ashrrev_i32_e32 v3, 6, v3
	v_lshrrev_b32_e32 v4, 26, v4
	s_sub_i32 s4, s18, s4
	v_lshlrev_b32_e32 v6, 3, v3
	v_add_u32_e32 v4, v5, v4
	s_cmp_lt_i32 s4, 0
	s_movk_i32 s10, 0x211
	v_and_b32_e32 v6, 0x1ffff0, v6
	v_ashrrev_i32_e32 v4, 6, v4
	s_cselect_b32 s10, s10, 0x210
	v_add_u32_e32 v6, v4, v6
	v_lshlrev_b32_e32 v3, 5, v3
	v_mul_i32_i24_e32 v4, 64, v4
	s_mul_i32 s4, s10, s4
	v_and_b32_e32 v3, 32, v3
	v_sub_u32_e32 v4, v5, v4
	v_add_u32_e32 v5, 0x2000, v2
	s_add_i32 s4, s4, s5
	v_lshl_or_b32 v3, v6, 10, v3
	v_ashrrev_i32_e32 v6, 31, v5
	s_mul_hi_i32 s5, s4, 0x2e8ba2e9
	v_lshrrev_b32_e32 v6, 22, v6
	s_lshr_b32 s10, s5, 31
	s_ashr_i32 s24, s5, 5
	v_add_u32_e32 v6, v5, v6
	s_add_i32 s24, s24, s10
	v_ashrrev_i32_e32 v6, 10, v6
	s_mul_i32 s5, s24, 0xb0
	v_mul_i32_i24_e32 v7, 0x400, v6
	s_sub_i32 s4, s4, s5
	v_sub_u32_e32 v5, v5, v7
	s_sext_i32_i16 s5, s4
	v_lshrrev_b32_e32 v7, 4, v5
	s_bfe_u32 s5, s5, 0x3001c
	v_bitop3_b32 v5, v7, v5, 32 bitop3:0x6c
	s_add_i32 s5, s4, s5
	v_ashrrev_i32_e32 v8, 31, v5
	s_sext_i32_i16 s10, s5
	s_and_b32 s5, s5, 0xfff8
	v_lshrrev_b32_e32 v8, 26, v8
	s_sub_i32 s4, s4, s5
	v_add_u32_e32 v8, v5, v8
	s_sext_i32_i16 s25, s4
	v_lshlrev_b32_e32 v7, 3, v6
	v_lshrrev_b32_e32 v9, 6, v8
	v_and_b32_e32 v8, 0xc0, v8
	s_add_i32 s26, s68, 0x110
	s_lshl_b32 s4, s24, 11
	s_lshl_b32 s19, s25, 8
	v_ashrrev_i16_sdwa v4, v187, sext(v4) dst_sel:DWORD dst_unused:UNUSED_PAD src0_sel:DWORD src1_sel:BYTE_0
	v_and_b32_e32 v7, 0x1ffff0, v7
	v_lshlrev_b32_e32 v6, 5, v6
	v_sub_u32_e32 v5, v5, v8
	v_add_u32_e32 v137, s26, v2
	s_ashr_i32 s21, s10, 3
	s_add_i32 s19, s19, s4
	v_bfe_i32 v4, v4, 0, 16
	v_add_u32_e32 v7, v9, v7
	v_and_b32_e32 v6, 32, v6
	v_ashrrev_i16_sdwa v5, v187, sext(v5) dst_sel:DWORD dst_unused:UNUSED_PAD src0_sel:DWORD src1_sel:BYTE_0
	v_readfirstlane_b32 s4, v137
	v_add_u32_e32 v139, 0x2000, v137
	v_bfe_i32 v5, v5, 0, 16
	v_lshl_or_b32 v6, v7, 10, v6
	v_add_lshl_u32 v136, v3, v4, 1
	s_lshl_b32 s22, s21, 19
	s_mov_b32 s10, s78
	s_mov_b32 s11, s79
	s_mov_b32 m0, s4
	v_readfirstlane_b32 s4, v139
	v_add_u32_e32 v140, 0x110, v2
	v_add_lshl_u32 v135, v6, v5, 1
	buffer_load_dwordx4 v136, s[8:11], s22 offen lds
	s_mov_b32 m0, s4
	v_readfirstlane_b32 s4, v140
	v_add_u32_e32 v141, 0x2000, v140
	buffer_load_dwordx4 v135, s[8:11], s22 offen lds
	s_lshl_b32 s27, s19, 11
	s_mov_b32 m0, s4
	v_readfirstlane_b32 s4, v141
	buffer_load_dwordx4 v136, s[76:79], s27 offen lds
	s_mov_b32 m0, s4
	v_readlane_b32 s4, v254, 11
	buffer_load_dwordx4 v135, s[76:79], s27 offen lds
	s_or_b32 s28, s22, 0x40000
	v_add_u32_e32 v142, s4, v2
	v_add_u32_e32 v143, 0x2000, v142
	v_readfirstlane_b32 s4, v142
	s_mov_b32 m0, s4
	v_readfirstlane_b32 s4, v143
	v_add_u32_e32 v144, 0x4000, v140
	buffer_load_dwordx4 v136, s[8:11], s28 offen lds
	s_mov_b32 m0, s4
	s_or_b32 s20, s19, 0x80
	v_readfirstlane_b32 s4, v144
	v_add_u32_e32 v145, 0x6000, v140
	buffer_load_dwordx4 v135, s[8:11], s28 offen lds
	s_lshl_b32 s23, s20, 11
	s_mov_b32 m0, s4
	v_readfirstlane_b32 s4, v145
	buffer_load_dwordx4 v136, s[76:79], s23 offen lds
	s_mov_b32 m0, s4
	v_ashrrev_i32_e32 v3, 8, v0
	buffer_load_dwordx4 v135, s[76:79], s23 offen lds
	v_cmp_eq_u32_e32 vcc, 1, v3
	s_and_saveexec_b64 s[4:5], vcc
	s_cbranch_execz .LBB0_215
	s_barrier
	s_setprio 1

; #define WAIT_L(n) asm volatile("s_waitcnt lgkmcnt(" #n ")" ::: "memory")
; #define BAR __builtin_amdgcn_s_barrier()
; #define SCHED __builtin_amdgcn_sched_barrier(0)
; DEV void gemm_tile(const h16* __restrict__ A, const h16* __restrict__ Bt, int K, int ld, int brow, int bcol, h16* shm, Acc& acc) {
;     ...
;     LDB(B0, 0, 0); SCHED; LDA(At, 0, 0); STAGE(SA(1, 1), rsA, brow + HALF_, t + 1);
;     WAIT_L(8); BAR; WAIT_L(0); MMA(0, 0, At, B0); BAR; SCHED;
;     LDB(B1, 0, 1); STAGE(SB(0, 0), rsB, bcol, t + 2);
;     BAR; WAIT_L(0); MMA(0, 1, At, B1); BAR;
;     LDA(At, 0, 1); STAGE(SA(0, 0), rsA, brow, t + 2);
;     BAR; WAIT_L(0); MMA(1, 0, At, B0); BAR; SCHED;
.LBB0_216:
	ds_read_b128 v[156:159], v155
	ds_read_b128 v[160:163], v155 offset:1024
	ds_read_b128 v[164:167], v155 offset:2048
	ds_read_b128 v[168:171], v155 offset:3072
	s_add_i32 s25, s4, s24
	v_readfirstlane_b32 s11, v153
	s_add_i32 s10, s25, 0x40080
	s_mov_b32 m0, s11
	v_readfirstlane_b32 s11, v152
	ds_read_b128 v[174:177], v133
	ds_read_b128 v[178:181], v133 offset:1024
	ds_read_b128 v[198:201], v132
	ds_read_b128 v[202:205], v132 offset:1024
	ds_read_b128 v[206:209], v131
	ds_read_b128 v[210:213], v131 offset:1024
	ds_read_b128 v[214:217], v130
	ds_read_b128 v[218:221], v130 offset:1024
	buffer_load_dwordx4 v136, s[76:79], s10 offen lds
	s_mov_b32 m0, s11
	s_nop 0
	buffer_load_dwordx4 v135, s[76:79], s10 offen lds
	s_waitcnt lgkmcnt(8)
	s_barrier
	s_waitcnt lgkmcnt(0)
	s_waitcnt lgkmcnt(7)
	v_mfma_f32_16x16x32_f16 v[126:129], v[174:177], v[156:159], v[126:129]
	v_mfma_f32_16x16x32_f16 v[122:125], v[174:177], v[164:167], v[122:125]
	s_waitcnt lgkmcnt(5)
	v_mfma_f32_16x16x32_f16 v[118:121], v[198:201], v[156:159], v[118:121]
	v_mfma_f32_16x16x32_f16 v[114:117], v[198:201], v[164:167], v[114:117]
	s_waitcnt lgkmcnt(3)
	v_mfma_f32_16x16x32_f16 v[110:113], v[206:209], v[156:159], v[110:113]
	v_mfma_f32_16x16x32_f16 v[106:109], v[206:209], v[164:167], v[106:109]
	s_waitcnt lgkmcnt(1)
	v_mfma_f32_16x16x32_f16 v[102:105], v[214:217], v[156:159], v[102:105]
	v_mfma_f32_16x16x32_f16 v[98:101], v[214:217], v[164:167], v[98:101]
	v_mfma_f32_16x16x32_f16 v[126:129], v[178:181], v[160:163], v[126:129]
	v_mfma_f32_16x16x32_f16 v[122:125], v[178:181], v[168:171], v[122:125]
	v_mfma_f32_16x16x32_f16 v[118:121], v[202:205], v[160:163], v[118:121]
	v_mfma_f32_16x16x32_f16 v[114:117], v[202:205], v[168:171], v[114:117]
	v_mfma_f32_16x16x32_f16 v[110:113], v[210:213], v[160:163], v[110:113]
	v_mfma_f32_16x16x32_f16 v[106:109], v[210:213], v[168:171], v[106:109]
	s_waitcnt lgkmcnt(0)
	v_mfma_f32_16x16x32_f16 v[102:105], v[218:221], v[160:163], v[102:105]
	v_mfma_f32_16x16x32_f16 v[98:101], v[218:221], v[168:171], v[98:101]
	s_barrier
	s_add_i32 s26, s22, s24
	v_readfirstlane_b32 s28, v137
	s_add_i32 s27, s26, 0x100
	s_mov_b32 s10, s78
	s_mov_b32 s11, s79
	s_mov_b32 m0, s28
	v_readfirstlane_b32 s28, v139
	ds_read_b128 v[222:225], v150
	ds_read_b128 v[226:229], v150 offset:1024
	ds_read_b128 v[230:233], v150 offset:2048
	ds_read_b128 v[234:237], v150 offset:3072
	buffer_load_dwordx4 v136, s[8:11], s27 offen lds
	s_mov_b32 m0, s28
	s_nop 0
	buffer_load_dwordx4 v135, s[8:11], s27 offen lds
	s_barrier
	s_waitcnt lgkmcnt(0)
	s_waitcnt lgkmcnt(3)
	v_mfma_f32_16x16x32_f16 v[94:97], v[174:177], v[222:225], v[94:97]
	s_waitcnt lgkmcnt(1)
	v_mfma_f32_16x16x32_f16 v[90:93], v[174:177], v[230:233], v[90:93]
	v_mfma_f32_16x16x32_f16 v[86:89], v[198:201], v[222:225], v[86:89]
	v_mfma_f32_16x16x32_f16 v[82:85], v[198:201], v[230:233], v[82:85]
	v_mfma_f32_16x16x32_f16 v[78:81], v[206:209], v[222:225], v[78:81]
	v_mfma_f32_16x16x32_f16 v[74:77], v[206:209], v[230:233], v[74:77]
	v_mfma_f32_16x16x32_f16 v[70:73], v[214:217], v[222:225], v[70:73]
	v_mfma_f32_16x16x32_f16 v[66:69], v[214:217], v[230:233], v[66:69]
	v_mfma_f32_16x16x32_f16 v[94:97], v[178:181], v[226:229], v[94:97]
	s_waitcnt lgkmcnt(0)
	v_mfma_f32_16x16x32_f16 v[90:93], v[178:181], v[234:237], v[90:93]
	v_mfma_f32_16x16x32_f16 v[86:89], v[202:205], v[226:229], v[86:89]
	v_mfma_f32_16x16x32_f16 v[82:85], v[202:205], v[234:237], v[82:85]
	v_mfma_f32_16x16x32_f16 v[78:81], v[210:213], v[226:229], v[78:81]
	v_mfma_f32_16x16x32_f16 v[74:77], v[210:213], v[234:237], v[74:77]
	v_mfma_f32_16x16x32_f16 v[70:73], v[218:221], v[226:229], v[70:73]
	v_mfma_f32_16x16x32_f16 v[66:69], v[218:221], v[234:237], v[66:69]
	v_readfirstlane_b32 s28, v140
	s_add_i32 s27, s25, 0x100
	s_mov_b32 m0, s28
	v_readfirstlane_b32 s28, v141
	s_barrier
	ds_read_b128 v[174:177], v133 offset:16384
	ds_read_b128 v[178:181], v133 offset:17408
	ds_read_b128 v[198:201], v132 offset:16384
	ds_read_b128 v[202:205], v132 offset:17408
	ds_read_b128 v[206:209], v131 offset:16384
	ds_read_b128 v[210:213], v131 offset:17408
	ds_read_b128 v[214:217], v130 offset:16384
	ds_read_b128 v[218:221], v130 offset:17408
	buffer_load_dwordx4 v136, s[76:79], s27 offen lds
	s_mov_b32 m0, s28
	s_nop 0
	buffer_load_dwordx4 v135, s[76:79], s27 offen lds
	s_barrier
	s_waitcnt lgkmcnt(0)
	s_waitcnt lgkmcnt(7)
	v_mfma_f32_16x16x32_f16 v[62:65], v[174:177], v[156:159], v[62:65]
	v_mfma_f32_16x16x32_f16 v[58:61], v[174:177], v[164:167], v[58:61]
	s_waitcnt lgkmcnt(5)
	v_mfma_f32_16x16x32_f16 v[54:57], v[198:201], v[156:159], v[54:57]
	v_mfma_f32_16x16x32_f16 v[50:53], v[198:201], v[164:167], v[50:53]
	s_waitcnt lgkmcnt(3)
	v_mfma_f32_16x16x32_f16 v[46:49], v[206:209], v[156:159], v[46:49]
	v_mfma_f32_16x16x32_f16 v[42:45], v[206:209], v[164:167], v[42:45]
	s_waitcnt lgkmcnt(1)
	v_mfma_f32_16x16x32_f16 v[38:41], v[214:217], v[156:159], v[38:41]
	v_mfma_f32_16x16x32_f16 v[34:37], v[214:217], v[164:167], v[34:37]
	v_mfma_f32_16x16x32_f16 v[62:65], v[178:181], v[160:163], v[62:65]
	v_mfma_f32_16x16x32_f16 v[58:61], v[178:181], v[168:171], v[58:61]
	v_mfma_f32_16x16x32_f16 v[54:57], v[202:205], v[160:163], v[54:57]
	v_mfma_f32_16x16x32_f16 v[50:53], v[202:205], v[168:171], v[50:53]
	v_mfma_f32_16x16x32_f16 v[46:49], v[210:213], v[160:163], v[46:49]
	v_mfma_f32_16x16x32_f16 v[42:45], v[210:213], v[168:171], v[42:45]
	s_waitcnt lgkmcnt(0)
	v_mfma_f32_16x16x32_f16 v[38:41], v[218:221], v[160:163], v[38:41]
	v_mfma_f32_16x16x32_f16 v[34:37], v[218:221], v[168:171], v[34:37]
	s_barrier
; #define WAIT_V(n) asm volatile("s_waitcnt vmcnt(" #n ")" ::: "memory")
; #define WAIT_L(n) asm volatile("s_waitcnt lgkmcnt(" #n ")" ::: "memory")
; #define BAR __builtin_amdgcn_s_barrier()
; #define SCHED __builtin_amdgcn_sched_barrier(0)
; DEV void gemm_tile(const h16* __restrict__ A, const h16* __restrict__ Bt, int K, int ld, int brow, int bcol, h16* shm, Acc& acc) {
;     ...
;     STAGE(SB(0, 1), rsB, bcol + HALF_, t + 2);
;     WAIT_V(6); BAR; MMA(1, 1, At, B1); BAR;
;     LDB(B0, 1, 0); SCHED; LDA(At, 1, 0); STAGE(SA(0, 1), rsA, brow + HALF_, t + 2);
;     WAIT_L(8); BAR; WAIT_L(0); MMA(0, 0, At, B0); BAR; SCHED;
;     LDB(B1, 1, 1); STAGE(SB(1, 0), rsB, bcol, t + 3);
;     BAR; WAIT_L(0); MMA(0, 1, At, B1); BAR;
;     LDA(At, 1, 1); STAGE(SA(1, 0), rsA, brow, t + 3);
	v_readfirstlane_b32 s28, v142
	s_add_i32 s27, s26, 0x40100
	s_mov_b32 m0, s28
	v_readfirstlane_b32 s28, v143
	buffer_load_dwordx4 v136, s[8:11], s27 offen lds
	s_mov_b32 m0, s28
	s_nop 0
	buffer_load_dwordx4 v135, s[8:11], s27 offen lds
	s_waitcnt vmcnt(6)
	s_barrier
	v_mfma_f32_16x16x32_f16 v[30:33], v[174:177], v[222:225], v[30:33]
	v_mfma_f32_16x16x32_f16 v[26:29], v[174:177], v[230:233], v[26:29]
	v_mfma_f32_16x16x32_f16 v[22:25], v[198:201], v[222:225], v[22:25]
	v_mfma_f32_16x16x32_f16 v[18:21], v[198:201], v[230:233], v[18:21]
	v_mfma_f32_16x16x32_f16 v[14:17], v[206:209], v[222:225], v[14:17]
	v_mfma_f32_16x16x32_f16 v[10:13], v[206:209], v[230:233], v[10:13]
	v_mfma_f32_16x16x32_f16 v[6:9], v[214:217], v[222:225], v[6:9]
	v_mfma_f32_16x16x32_f16 v[2:5], v[214:217], v[230:233], v[2:5]
	v_mfma_f32_16x16x32_f16 v[30:33], v[178:181], v[226:229], v[30:33]
	v_mfma_f32_16x16x32_f16 v[26:29], v[178:181], v[234:237], v[26:29]
	v_mfma_f32_16x16x32_f16 v[22:25], v[202:205], v[226:229], v[22:25]
	v_mfma_f32_16x16x32_f16 v[18:21], v[202:205], v[234:237], v[18:21]
	v_mfma_f32_16x16x32_f16 v[14:17], v[210:213], v[226:229], v[14:17]
	v_mfma_f32_16x16x32_f16 v[10:13], v[210:213], v[234:237], v[10:13]
	v_mfma_f32_16x16x32_f16 v[6:9], v[218:221], v[226:229], v[6:9]
	v_mfma_f32_16x16x32_f16 v[2:5], v[218:221], v[234:237], v[2:5]
	s_barrier
	ds_read_b128 v[156:159], v138
	ds_read_b128 v[160:163], v138 offset:1024
	ds_read_b128 v[164:167], v138 offset:2048
	ds_read_b128 v[168:171], v138 offset:3072
	v_readfirstlane_b32 s28, v144
	s_add_i32 s27, s25, 0x40100
	s_mov_b32 m0, s28
	v_readfirstlane_b32 s28, v145
	ds_read_b128 v[174:177], v133 offset:32768
	ds_read_b128 v[178:181], v133 offset:33792
	ds_read_b128 v[198:201], v132 offset:32768
	ds_read_b128 v[202:205], v132 offset:33792
	ds_read_b128 v[206:209], v131 offset:32768
	ds_read_b128 v[210:213], v131 offset:33792
	ds_read_b128 v[214:217], v130 offset:32768
	ds_read_b128 v[218:221], v130 offset:33792
	buffer_load_dwordx4 v136, s[76:79], s27 offen lds
	s_mov_b32 m0, s28
	s_nop 0
	buffer_load_dwordx4 v135, s[76:79], s27 offen lds
	s_waitcnt lgkmcnt(8)
	s_barrier
	s_waitcnt lgkmcnt(0)
	s_waitcnt lgkmcnt(7)
	v_mfma_f32_16x16x32_f16 v[126:129], v[174:177], v[156:159], v[126:129]
	v_mfma_f32_16x16x32_f16 v[122:125], v[174:177], v[164:167], v[122:125]
	s_waitcnt lgkmcnt(5)
	v_mfma_f32_16x16x32_f16 v[118:121], v[198:201], v[156:159], v[118:121]
	v_mfma_f32_16x16x32_f16 v[114:117], v[198:201], v[164:167], v[114:117]
	s_waitcnt lgkmcnt(3)
	v_mfma_f32_16x16x32_f16 v[110:113], v[206:209], v[156:159], v[110:113]
	v_mfma_f32_16x16x32_f16 v[106:109], v[206:209], v[164:167], v[106:109]
	s_waitcnt lgkmcnt(1)
	v_mfma_f32_16x16x32_f16 v[102:105], v[214:217], v[156:159], v[102:105]
	v_mfma_f32_16x16x32_f16 v[98:101], v[214:217], v[164:167], v[98:101]
	v_mfma_f32_16x16x32_f16 v[126:129], v[178:181], v[160:163], v[126:129]
	v_mfma_f32_16x16x32_f16 v[122:125], v[178:181], v[168:171], v[122:125]
	v_mfma_f32_16x16x32_f16 v[118:121], v[202:205], v[160:163], v[118:121]
	v_mfma_f32_16x16x32_f16 v[114:117], v[202:205], v[168:171], v[114:117]
	v_mfma_f32_16x16x32_f16 v[110:113], v[210:213], v[160:163], v[110:113]
	v_mfma_f32_16x16x32_f16 v[106:109], v[210:213], v[168:171], v[106:109]
	s_waitcnt lgkmcnt(0)
	v_mfma_f32_16x16x32_f16 v[102:105], v[218:221], v[160:163], v[102:105]
	v_mfma_f32_16x16x32_f16 v[98:101], v[218:221], v[168:171], v[98:101]
	s_barrier
	v_readfirstlane_b32 s28, v146
	s_add_i32 s27, s26, 0x180
	s_mov_b32 m0, s28
	v_readfirstlane_b32 s28, v147
	ds_read_b128 v[222:225], v134
	ds_read_b128 v[226:229], v134 offset:1024
	ds_read_b128 v[230:233], v134 offset:2048
	ds_read_b128 v[234:237], v134 offset:3072
	buffer_load_dwordx4 v136, s[8:11], s27 offen lds
	s_mov_b32 m0, s28
	s_nop 0
	buffer_load_dwordx4 v135, s[8:11], s27 offen lds
	s_barrier
	s_waitcnt lgkmcnt(0)
	s_waitcnt lgkmcnt(3)
	v_mfma_f32_16x16x32_f16 v[94:97], v[174:177], v[222:225], v[94:97]
	s_waitcnt lgkmcnt(1)
	v_mfma_f32_16x16x32_f16 v[90:93], v[174:177], v[230:233], v[90:93]
	v_mfma_f32_16x16x32_f16 v[86:89], v[198:201], v[222:225], v[86:89]
	v_mfma_f32_16x16x32_f16 v[82:85], v[198:201], v[230:233], v[82:85]
	v_mfma_f32_16x16x32_f16 v[78:81], v[206:209], v[222:225], v[78:81]
	v_mfma_f32_16x16x32_f16 v[74:77], v[206:209], v[230:233], v[74:77]
	v_mfma_f32_16x16x32_f16 v[70:73], v[214:217], v[222:225], v[70:73]
	v_mfma_f32_16x16x32_f16 v[66:69], v[214:217], v[230:233], v[66:69]
	v_mfma_f32_16x16x32_f16 v[94:97], v[178:181], v[226:229], v[94:97]
	s_waitcnt lgkmcnt(0)
	v_mfma_f32_16x16x32_f16 v[90:93], v[178:181], v[234:237], v[90:93]
	v_mfma_f32_16x16x32_f16 v[86:89], v[202:205], v[226:229], v[86:89]
	v_mfma_f32_16x16x32_f16 v[82:85], v[202:205], v[234:237], v[82:85]
	v_mfma_f32_16x16x32_f16 v[78:81], v[210:213], v[226:229], v[78:81]
	v_mfma_f32_16x16x32_f16 v[74:77], v[210:213], v[234:237], v[74:77]
	v_mfma_f32_16x16x32_f16 v[70:73], v[218:221], v[226:229], v[70:73]
	v_mfma_f32_16x16x32_f16 v[66:69], v[218:221], v[234:237], v[66:69]
	v_readfirstlane_b32 s27, v148
	s_addk_i32 s25, 0x180
	s_mov_b32 m0, s27
	v_readfirstlane_b32 s27, v149
	s_barrier
	ds_read_b128 v[174:177], v133 offset:49152
	ds_read_b128 v[178:181], v133 offset:50176
	ds_read_b128 v[198:201], v132 offset:49152
	ds_read_b128 v[202:205], v132 offset:50176
	ds_read_b128 v[206:209], v131 offset:49152
	ds_read_b128 v[210:213], v131 offset:50176
	ds_read_b128 v[214:217], v130 offset:49152
	ds_read_b128 v[218:221], v130 offset:50176
	buffer_load_dwordx4 v136, s[76:79], s25 offen lds
	s_mov_b32 m0, s27
	s_nop 0
	buffer_load_dwordx4 v135, s[76:79], s25 offen lds
	s_barrier
; #define WAIT_V(n) asm volatile("s_waitcnt vmcnt(" #n ")" ::: "memory")
; #define WAIT_L(n) asm volatile("s_waitcnt lgkmcnt(" #n ")" ::: "memory")
; #define BAR __builtin_amdgcn_s_barrier()
; #define SCHED __builtin_amdgcn_sched_barrier(0)
; DEV void gemm_tile(const h16* __restrict__ A, const h16* __restrict__ Bt, int K, int ld, int brow, int bcol, h16* shm, Acc& acc) {
;     ...
;     BAR; WAIT_L(0); MMA(1, 0, At, B0); BAR; SCHED;
;     STAGE(SB(1, 1), rsB, bcol + HALF_, t + 3);
;     WAIT_V(6); BAR; MMA(1, 1, At, B1); BAR;
;   }
;   { LDB(B0, 0, 0); LDA(At, 0, 0); STAGE(SA(1, 1), rsA, brow + HALF_, nt - 1);
;     BAR; WAIT_L(0); MMA(0, 0, At, B0); BAR;
;     LDB(B1, 0, 1); BAR; WAIT_L(0); MMA(0, 1, At, B1); BAR;
	s_waitcnt lgkmcnt(0)
	s_waitcnt lgkmcnt(7)
	v_mfma_f32_16x16x32_f16 v[62:65], v[174:177], v[156:159], v[62:65]
	v_mfma_f32_16x16x32_f16 v[58:61], v[174:177], v[164:167], v[58:61]
	s_waitcnt lgkmcnt(5)
	v_mfma_f32_16x16x32_f16 v[54:57], v[198:201], v[156:159], v[54:57]
	v_mfma_f32_16x16x32_f16 v[50:53], v[198:201], v[164:167], v[50:53]
	s_waitcnt lgkmcnt(3)
	v_mfma_f32_16x16x32_f16 v[46:49], v[206:209], v[156:159], v[46:49]
	v_mfma_f32_16x16x32_f16 v[42:45], v[206:209], v[164:167], v[42:45]
	s_waitcnt lgkmcnt(1)
	v_mfma_f32_16x16x32_f16 v[38:41], v[214:217], v[156:159], v[38:41]
	v_mfma_f32_16x16x32_f16 v[34:37], v[214:217], v[164:167], v[34:37]
	v_mfma_f32_16x16x32_f16 v[62:65], v[178:181], v[160:163], v[62:65]
	v_mfma_f32_16x16x32_f16 v[58:61], v[178:181], v[168:171], v[58:61]
	v_mfma_f32_16x16x32_f16 v[54:57], v[202:205], v[160:163], v[54:57]
	v_mfma_f32_16x16x32_f16 v[50:53], v[202:205], v[168:171], v[50:53]
	v_mfma_f32_16x16x32_f16 v[46:49], v[210:213], v[160:163], v[46:49]
	v_mfma_f32_16x16x32_f16 v[42:45], v[210:213], v[168:171], v[42:45]
	s_waitcnt lgkmcnt(0)
	v_mfma_f32_16x16x32_f16 v[38:41], v[218:221], v[160:163], v[38:41]
	v_mfma_f32_16x16x32_f16 v[34:37], v[218:221], v[168:171], v[34:37]
	s_barrier
	v_readfirstlane_b32 s25, v151
	s_add_i32 s26, s26, 0x40180
	s_mov_b32 m0, s25
	v_readfirstlane_b32 s25, v154
	buffer_load_dwordx4 v136, s[8:11], s26 offen lds
	s_mov_b32 m0, s25
	s_nop 0
	buffer_load_dwordx4 v135, s[8:11], s26 offen lds
	s_waitcnt vmcnt(6)
	s_barrier
	v_mfma_f32_16x16x32_f16 v[30:33], v[174:177], v[222:225], v[30:33]
	v_mfma_f32_16x16x32_f16 v[26:29], v[174:177], v[230:233], v[26:29]
	v_mfma_f32_16x16x32_f16 v[22:25], v[198:201], v[222:225], v[22:25]
	v_mfma_f32_16x16x32_f16 v[18:21], v[198:201], v[230:233], v[18:21]
	v_mfma_f32_16x16x32_f16 v[14:17], v[206:209], v[222:225], v[14:17]
	v_mfma_f32_16x16x32_f16 v[10:13], v[206:209], v[230:233], v[10:13]
	v_mfma_f32_16x16x32_f16 v[6:9], v[214:217], v[222:225], v[6:9]
	v_mfma_f32_16x16x32_f16 v[2:5], v[214:217], v[230:233], v[2:5]
	v_mfma_f32_16x16x32_f16 v[30:33], v[178:181], v[226:229], v[30:33]
	v_mfma_f32_16x16x32_f16 v[26:29], v[178:181], v[234:237], v[26:29]
	v_mfma_f32_16x16x32_f16 v[22:25], v[202:205], v[226:229], v[22:25]
	v_mfma_f32_16x16x32_f16 v[18:21], v[202:205], v[234:237], v[18:21]
	v_mfma_f32_16x16x32_f16 v[14:17], v[210:213], v[226:229], v[14:17]
	v_mfma_f32_16x16x32_f16 v[10:13], v[210:213], v[234:237], v[10:13]
	v_mfma_f32_16x16x32_f16 v[6:9], v[218:221], v[226:229], v[6:9]
	v_mfma_f32_16x16x32_f16 v[2:5], v[218:221], v[234:237], v[2:5]
	s_add_i32 s5, s5, 2
	s_addk_i32 s24, 0x100
	s_cmp_lt_u32 s5, 12
	s_barrier
	s_cbranch_scc1 .LBB0_216
	v_readfirstlane_b32 s5, v153
	s_or_b32 s4, s23, 0x780
	s_mov_b32 m0, s5
	v_readfirstlane_b32 s5, v152
	ds_read_b128 v[140:143], v155
	ds_read_b128 v[144:147], v155 offset:1024
	ds_read_b128 v[156:159], v155 offset:2048
	ds_read_b128 v[160:163], v155 offset:3072
	ds_read_b128 v[164:167], v133
	ds_read_b128 v[168:171], v133 offset:1024
	ds_read_b128 v[174:177], v132
	ds_read_b128 v[178:181], v132 offset:1024
	ds_read_b128 v[198:201], v131
	ds_read_b128 v[202:205], v131 offset:1024
	ds_read_b128 v[206:209], v130
	ds_read_b128 v[210:213], v130 offset:1024
	buffer_load_dwordx4 v136, s[76:79], s4 offen lds
	s_mov_b32 m0, s5
	s_nop 0
	buffer_load_dwordx4 v135, s[76:79], s4 offen lds
	s_barrier
	s_waitcnt lgkmcnt(0)
	s_waitcnt lgkmcnt(7)
	v_mfma_f32_16x16x32_f16 v[126:129], v[164:167], v[140:143], v[126:129]
	v_mfma_f32_16x16x32_f16 v[122:125], v[164:167], v[156:159], v[122:125]
	s_waitcnt lgkmcnt(5)
	v_mfma_f32_16x16x32_f16 v[118:121], v[174:177], v[140:143], v[118:121]
	v_mfma_f32_16x16x32_f16 v[114:117], v[174:177], v[156:159], v[114:117]
	v_mfma_f32_16x16x32_f16 v[126:129], v[168:171], v[144:147], v[126:129]
	v_mfma_f32_16x16x32_f16 v[122:125], v[168:171], v[160:163], v[122:125]
	s_waitcnt lgkmcnt(4)
	v_mfma_f32_16x16x32_f16 v[118:121], v[178:181], v[144:147], v[118:121]
	v_mfma_f32_16x16x32_f16 v[114:117], v[178:181], v[160:163], v[114:117]
	s_waitcnt lgkmcnt(3)
	v_mfma_f32_16x16x32_f16 v[110:113], v[198:201], v[140:143], v[110:113]
	v_mfma_f32_16x16x32_f16 v[106:109], v[198:201], v[156:159], v[106:109]
	s_waitcnt lgkmcnt(1)
	v_mfma_f32_16x16x32_f16 v[102:105], v[206:209], v[140:143], v[102:105]
	v_mfma_f32_16x16x32_f16 v[98:101], v[206:209], v[156:159], v[98:101]
	v_mfma_f32_16x16x32_f16 v[152:155], v[202:205], v[144:147], v[110:113]
	v_mfma_f32_16x16x32_f16 v[214:217], v[202:205], v[160:163], v[106:109]
	s_waitcnt lgkmcnt(0)
	v_mfma_f32_16x16x32_f16 v[218:221], v[210:213], v[144:147], v[102:105]
	v_mfma_f32_16x16x32_f16 v[222:225], v[210:213], v[160:163], v[98:101]
	s_barrier
	s_nop 0
	ds_read_b128 v[98:101], v150
	ds_read_b128 v[102:105], v150 offset:1024
	ds_read_b128 v[106:109], v150 offset:2048
	ds_read_b128 v[110:113], v150 offset:3072
	s_barrier
	s_waitcnt lgkmcnt(0)
	s_waitcnt lgkmcnt(3)
	v_mfma_f32_16x16x32_f16 v[94:97], v[164:167], v[98:101], v[94:97]
	s_waitcnt lgkmcnt(1)
	v_mfma_f32_16x16x32_f16 v[90:93], v[164:167], v[106:109], v[90:93]
	v_mfma_f32_16x16x32_f16 v[86:89], v[174:177], v[98:101], v[86:89]
	v_mfma_f32_16x16x32_f16 v[82:85], v[174:177], v[106:109], v[82:85]
	v_mfma_f32_16x16x32_f16 v[94:97], v[168:171], v[102:105], v[94:97]
	s_waitcnt lgkmcnt(0)
	v_mfma_f32_16x16x32_f16 v[90:93], v[168:171], v[110:113], v[90:93]
	v_mfma_f32_16x16x32_f16 v[86:89], v[178:181], v[102:105], v[86:89]
	v_mfma_f32_16x16x32_f16 v[82:85], v[178:181], v[110:113], v[82:85]
	v_mfma_f32_16x16x32_f16 v[78:81], v[198:201], v[98:101], v[78:81]
	v_mfma_f32_16x16x32_f16 v[74:77], v[198:201], v[106:109], v[74:77]
	v_mfma_f32_16x16x32_f16 v[70:73], v[206:209], v[98:101], v[70:73]
	v_mfma_f32_16x16x32_f16 v[66:69], v[206:209], v[106:109], v[66:69]
	v_mfma_f32_16x16x32_f16 v[148:151], v[202:205], v[102:105], v[78:81]
	v_mfma_f32_16x16x32_f16 v[164:167], v[202:205], v[110:113], v[74:77]
	v_mfma_f32_16x16x32_f16 v[168:171], v[210:213], v[102:105], v[70:73]
	v_mfma_f32_16x16x32_f16 v[174:177], v[210:213], v[110:113], v[66:69]
	s_barrier
; #define WAIT_V(n) asm volatile("s_waitcnt vmcnt(" #n ")" ::: "memory")
; #define WAIT_L(n) asm volatile("s_waitcnt lgkmcnt(" #n ")" ::: "memory")
; #define BAR __builtin_amdgcn_s_barrier()
; DEV void gemm_tile(const h16* __restrict__ A, const h16* __restrict__ Bt, int K, int ld, int brow, int bcol, h16* shm, Acc& acc) {
;     ...
;     LDA(At, 0, 1); WAIT_V(4); BAR; WAIT_L(0); MMA(1, 0, At, B0); MMA(1, 1, At, B1); BAR; }
;   { LDB(B0, 1, 0); LDA(At, 1, 0); WAIT_V(2); BAR; WAIT_L(0); MMA(0, 0, At, B0); BAR;
	s_nop 1
	ds_read_b128 v[66:69], v133 offset:16384
	ds_read_b128 v[70:73], v133 offset:17408
	ds_read_b128 v[74:77], v132 offset:16384
	ds_read_b128 v[78:81], v132 offset:17408
	ds_read_b128 v[178:181], v131 offset:16384
	ds_read_b128 v[198:201], v131 offset:17408
	ds_read_b128 v[202:205], v130 offset:16384
	ds_read_b128 v[206:209], v130 offset:17408
	s_waitcnt vmcnt(4)
	s_barrier
	s_waitcnt lgkmcnt(0)
	s_waitcnt lgkmcnt(7)
	v_mfma_f32_16x16x32_f16 v[62:65], v[66:69], v[140:143], v[62:65]
	v_mfma_f32_16x16x32_f16 v[58:61], v[66:69], v[156:159], v[58:61]
	s_waitcnt lgkmcnt(5)
	v_mfma_f32_16x16x32_f16 v[54:57], v[74:77], v[140:143], v[54:57]
	v_mfma_f32_16x16x32_f16 v[50:53], v[74:77], v[156:159], v[50:53]
	v_mfma_f32_16x16x32_f16 v[62:65], v[70:73], v[144:147], v[62:65]
	v_mfma_f32_16x16x32_f16 v[58:61], v[70:73], v[160:163], v[58:61]
	s_waitcnt lgkmcnt(4)
	v_mfma_f32_16x16x32_f16 v[54:57], v[78:81], v[144:147], v[54:57]
	v_mfma_f32_16x16x32_f16 v[50:53], v[78:81], v[160:163], v[50:53]
	s_waitcnt lgkmcnt(3)
	v_mfma_f32_16x16x32_f16 v[46:49], v[178:181], v[140:143], v[46:49]
	v_mfma_f32_16x16x32_f16 v[42:45], v[178:181], v[156:159], v[42:45]
	s_waitcnt lgkmcnt(1)
	v_mfma_f32_16x16x32_f16 v[38:41], v[202:205], v[140:143], v[38:41]
	v_mfma_f32_16x16x32_f16 v[34:37], v[202:205], v[156:159], v[34:37]
	v_mfma_f32_16x16x32_f16 v[210:213], v[198:201], v[144:147], v[46:49]
	v_mfma_f32_16x16x32_f16 v[226:229], v[198:201], v[160:163], v[42:45]
	s_waitcnt lgkmcnt(0)
	v_mfma_f32_16x16x32_f16 v[140:143], v[206:209], v[144:147], v[38:41]
	v_mfma_f32_16x16x32_f16 v[144:147], v[206:209], v[160:163], v[34:37]
	v_mfma_f32_16x16x32_f16 v[30:33], v[66:69], v[98:101], v[30:33]
	v_mfma_f32_16x16x32_f16 v[26:29], v[66:69], v[106:109], v[26:29]
	v_mfma_f32_16x16x32_f16 v[22:25], v[74:77], v[98:101], v[22:25]
	v_mfma_f32_16x16x32_f16 v[18:21], v[74:77], v[106:109], v[18:21]
	v_mfma_f32_16x16x32_f16 v[30:33], v[70:73], v[102:105], v[30:33]
	v_mfma_f32_16x16x32_f16 v[26:29], v[70:73], v[110:113], v[26:29]
	v_mfma_f32_16x16x32_f16 v[22:25], v[78:81], v[102:105], v[22:25]
	v_mfma_f32_16x16x32_f16 v[18:21], v[78:81], v[110:113], v[18:21]
	v_mfma_f32_16x16x32_f16 v[14:17], v[178:181], v[98:101], v[14:17]
	v_mfma_f32_16x16x32_f16 v[10:13], v[178:181], v[106:109], v[10:13]
	v_mfma_f32_16x16x32_f16 v[6:9], v[202:205], v[98:101], v[6:9]
	v_mfma_f32_16x16x32_f16 v[2:5], v[202:205], v[106:109], v[2:5]
	v_mfma_f32_16x16x32_f16 v[156:159], v[198:201], v[102:105], v[14:17]
	v_mfma_f32_16x16x32_f16 v[160:163], v[198:201], v[110:113], v[10:13]
	v_mfma_f32_16x16x32_f16 v[178:181], v[206:209], v[102:105], v[6:9]
	v_mfma_f32_16x16x32_f16 v[198:201], v[206:209], v[110:113], v[2:5]
	s_barrier
	s_nop 1
	ds_read_b128 v[2:5], v138
	ds_read_b128 v[6:9], v138 offset:1024
	ds_read_b128 v[202:205], v138 offset:2048
	ds_read_b128 v[136:139], v138 offset:3072
	ds_read_b128 v[10:13], v133 offset:32768
	ds_read_b128 v[14:17], v133 offset:33792
	ds_read_b128 v[34:37], v132 offset:32768
	ds_read_b128 v[38:41], v132 offset:33792
	ds_read_b128 v[42:45], v131 offset:32768
	ds_read_b128 v[46:49], v131 offset:33792
	ds_read_b128 v[206:209], v130 offset:32768
	ds_read_b128 v[230:233], v130 offset:33792
	s_waitcnt vmcnt(2)
	s_barrier
	s_waitcnt lgkmcnt(0)
	s_waitcnt lgkmcnt(7)
	v_mfma_f32_16x16x32_f16 v[66:69], v[10:13], v[2:5], v[126:129]
	s_waitcnt lgkmcnt(6)
	v_mfma_f32_16x16x32_f16 v[106:109], v[14:17], v[6:9], v[66:69]
	v_mfma_f32_16x16x32_f16 v[66:69], v[10:13], v[202:205], v[122:125]
	v_mfma_f32_16x16x32_f16 v[110:113], v[14:17], v[136:139], v[66:69]
	s_waitcnt lgkmcnt(5)
	v_mfma_f32_16x16x32_f16 v[66:69], v[34:37], v[2:5], v[118:121]
	s_waitcnt lgkmcnt(4)
	v_mfma_f32_16x16x32_f16 v[98:101], v[38:41], v[6:9], v[66:69]
	v_mfma_f32_16x16x32_f16 v[66:69], v[34:37], v[202:205], v[114:117]
	v_mfma_f32_16x16x32_f16 v[102:105], v[38:41], v[136:139], v[66:69]
	s_waitcnt lgkmcnt(3)
	v_mfma_f32_16x16x32_f16 v[66:69], v[42:45], v[2:5], v[152:155]
	s_waitcnt lgkmcnt(2)
	v_mfma_f32_16x16x32_f16 v[74:77], v[46:49], v[6:9], v[66:69]
	v_mfma_f32_16x16x32_f16 v[66:69], v[42:45], v[202:205], v[214:217]
	v_mfma_f32_16x16x32_f16 v[78:81], v[46:49], v[136:139], v[66:69]
	s_waitcnt lgkmcnt(1)
	v_mfma_f32_16x16x32_f16 v[66:69], v[206:209], v[2:5], v[218:221]
	v_mfma_f32_16x16x32_f16 v[70:73], v[206:209], v[202:205], v[222:225]
	s_waitcnt lgkmcnt(0)
	v_mfma_f32_16x16x32_f16 v[66:69], v[230:233], v[6:9], v[66:69]
	v_mfma_f32_16x16x32_f16 v[70:73], v[230:233], v[136:139], v[70:73]
	s_barrier
; #define WAIT_V(n) asm volatile("s_waitcnt vmcnt(" #n ")" ::: "memory")
; #define WAIT_L(n) asm volatile("s_waitcnt lgkmcnt(" #n ")" ::: "memory")
; #define BAR __builtin_amdgcn_s_barrier()
; DEV void gemm_tile(const h16* __restrict__ A, const h16* __restrict__ Bt, int K, int ld, int brow, int bcol, h16* shm, Acc& acc) {
;     ...
;     LDB(B1, 1, 1); WAIT_V(0); BAR; WAIT_L(0); MMA(0, 1, At, B1); BAR;
;     LDA(At, 1, 1); BAR; WAIT_L(0); MMA(1, 0, At, B0); MMA(1, 1, At, B1); BAR; }
;   if (wr == 0) BAR;
	ds_read_b128 v[152:155], v134
	ds_read_b128 v[214:217], v134 offset:1024
	ds_read_b128 v[218:221], v134 offset:2048
	ds_read_b128 v[222:225], v134 offset:3072
	s_waitcnt vmcnt(0)
	s_barrier
	s_waitcnt lgkmcnt(0)
	s_waitcnt lgkmcnt(3)
	v_mfma_f32_16x16x32_f16 v[94:97], v[10:13], v[152:155], v[94:97]
	s_waitcnt lgkmcnt(1)
	v_mfma_f32_16x16x32_f16 v[10:13], v[10:13], v[218:221], v[90:93]
	s_waitcnt lgkmcnt(0)
	v_mfma_f32_16x16x32_f16 v[126:129], v[14:17], v[222:225], v[10:13]
	v_mfma_f32_16x16x32_f16 v[10:13], v[34:37], v[152:155], v[86:89]
	v_mfma_f32_16x16x32_f16 v[114:117], v[38:41], v[214:217], v[10:13]
	v_mfma_f32_16x16x32_f16 v[10:13], v[34:37], v[218:221], v[82:85]
	v_mfma_f32_16x16x32_f16 v[118:121], v[38:41], v[222:225], v[10:13]
	v_mfma_f32_16x16x32_f16 v[10:13], v[42:45], v[152:155], v[148:151]
	v_mfma_f32_16x16x32_f16 v[90:93], v[46:49], v[214:217], v[10:13]
	v_mfma_f32_16x16x32_f16 v[10:13], v[42:45], v[218:221], v[164:167]
	v_mfma_f32_16x16x32_f16 v[122:125], v[14:17], v[214:217], v[94:97]
	v_mfma_f32_16x16x32_f16 v[94:97], v[46:49], v[222:225], v[10:13]
	v_mfma_f32_16x16x32_f16 v[10:13], v[206:209], v[152:155], v[168:171]
	v_mfma_f32_16x16x32_f16 v[82:85], v[230:233], v[214:217], v[10:13]
	v_mfma_f32_16x16x32_f16 v[10:13], v[206:209], v[218:221], v[174:177]
	v_mfma_f32_16x16x32_f16 v[86:89], v[230:233], v[222:225], v[10:13]
	s_barrier
	ds_read_b128 v[148:151], v133 offset:49152
	ds_read_b128 v[164:167], v133 offset:50176
	ds_read_b128 v[168:171], v132 offset:49152
	ds_read_b128 v[132:135], v132 offset:50176
	ds_read_b128 v[174:177], v131 offset:49152
	ds_read_b128 v[206:209], v131 offset:50176
	ds_read_b128 v[230:233], v130 offset:49152
	ds_read_b128 v[234:237], v130 offset:50176
	s_barrier
	s_waitcnt lgkmcnt(0)
	s_waitcnt lgkmcnt(7)
	v_mfma_f32_16x16x32_f16 v[10:13], v[148:151], v[2:5], v[62:65]
	s_waitcnt lgkmcnt(6)
	v_mfma_f32_16x16x32_f16 v[42:45], v[164:167], v[6:9], v[10:13]
	v_mfma_f32_16x16x32_f16 v[10:13], v[148:151], v[202:205], v[58:61]
	v_mfma_f32_16x16x32_f16 v[46:49], v[164:167], v[136:139], v[10:13]
	s_waitcnt lgkmcnt(5)
	v_mfma_f32_16x16x32_f16 v[10:13], v[168:171], v[2:5], v[54:57]
	s_waitcnt lgkmcnt(4)
	v_mfma_f32_16x16x32_f16 v[34:37], v[132:135], v[6:9], v[10:13]
	v_mfma_f32_16x16x32_f16 v[10:13], v[168:171], v[202:205], v[50:53]
	v_mfma_f32_16x16x32_f16 v[38:41], v[132:135], v[136:139], v[10:13]
	s_waitcnt lgkmcnt(3)
	v_mfma_f32_16x16x32_f16 v[10:13], v[174:177], v[2:5], v[210:213]
	s_waitcnt lgkmcnt(1)
	v_mfma_f32_16x16x32_f16 v[2:5], v[230:233], v[2:5], v[140:143]
	v_mfma_f32_16x16x32_f16 v[10:13], v[206:209], v[6:9], v[10:13]
	v_mfma_f32_16x16x32_f16 v[14:17], v[174:177], v[202:205], v[226:229]
	s_waitcnt lgkmcnt(0)
	v_mfma_f32_16x16x32_f16 v[2:5], v[234:237], v[6:9], v[2:5]
	v_mfma_f32_16x16x32_f16 v[6:9], v[230:233], v[202:205], v[144:147]
	v_mfma_f32_16x16x32_f16 v[14:17], v[206:209], v[136:139], v[14:17]
	v_mfma_f32_16x16x32_f16 v[6:9], v[234:237], v[136:139], v[6:9]
	v_mfma_f32_16x16x32_f16 v[18:21], v[168:171], v[218:221], v[18:21]
	v_mfma_f32_16x16x32_f16 v[26:29], v[148:151], v[218:221], v[26:29]
	v_mfma_f32_16x16x32_f16 v[54:57], v[132:135], v[222:225], v[18:21]
	v_mfma_f32_16x16x32_f16 v[18:21], v[174:177], v[152:155], v[156:159]
	v_mfma_f32_16x16x32_f16 v[30:33], v[148:151], v[152:155], v[30:33]
	v_mfma_f32_16x16x32_f16 v[62:65], v[164:167], v[222:225], v[26:29]
	v_mfma_f32_16x16x32_f16 v[22:25], v[168:171], v[152:155], v[22:25]
	v_mfma_f32_16x16x32_f16 v[26:29], v[206:209], v[214:217], v[18:21]
	v_mfma_f32_16x16x32_f16 v[18:21], v[174:177], v[218:221], v[160:163]
	v_mfma_f32_16x16x32_f16 v[58:61], v[164:167], v[214:217], v[30:33]
	v_mfma_f32_16x16x32_f16 v[50:53], v[132:135], v[214:217], v[22:25]
	v_mfma_f32_16x16x32_f16 v[30:33], v[206:209], v[222:225], v[18:21]
	v_mfma_f32_16x16x32_f16 v[18:21], v[230:233], v[152:155], v[178:181]
	v_mfma_f32_16x16x32_f16 v[22:25], v[230:233], v[218:221], v[198:201]
	v_mfma_f32_16x16x32_f16 v[18:21], v[234:237], v[214:217], v[18:21]
	v_mfma_f32_16x16x32_f16 v[22:25], v[234:237], v[222:225], v[22:25]
	s_setprio 0
	s_movk_i32 s4, 0x100
	v_cmp_gt_u32_e32 vcc, s4, v0
	s_barrier
	s_and_saveexec_b64 s[4:5], vcc
	s_cbranch_execz .LBB0_219
	s_barrier

; #define BAR __builtin_amdgcn_s_barrier()
; DEV void gemm_tile(const h16* __restrict__ A, const h16* __restrict__ Bt, int K, int ld, int brow, int bcol, h16* shm, Acc& acc) {
;     ...
;   int wid = TID >> 6, lane = TID & 63, wr = wid >> 2, wc = wid & 3, fr = lane & 15, fq = lane >> 4;
;   int vo0, vo1;
;   {
;     int r, c;
;     stage_rc(TID * 16, r, c);
;     vo0 = (r * ld + c) * 2;
;     stage_rc(TID * 16 + 8192, r, c);
;     vo1 = (r * ld + c) * 2;
;   }
;   __amdgpu_buffer_rsrc_t rsA = __builtin_amdgcn_make_buffer_rsrc((void*)A, (short)0, 0x7fffffff, 0x00020000);
;   __amdgpu_buffer_rsrc_t rsB = __builtin_amdgcn_make_buffer_rsrc((void*)Bt, (short)0, 0x7fffffff, 0x00020000);
; #pragma unroll
;   for (int a = 0; a < 2; ++a)
; #pragma unroll
;     for (int b = 0; b < 2; ++b)
; #pragma unroll
;       for (int m = 0; m < 4; ++m)
; #pragma unroll
;         for (int n = 0; n < 2; ++n) acc[a][b][m][n] = f32x4{0.f, 0.f, 0.f, 0.f};
;   h16x8 At[4][2], B0[2][2], B1[2][2];
;   int nt = K / BK;
;   STAGE(SB(0, 0), rsB, bcol, 0); STAGE(SA(0, 0), rsA, brow, 0);
;   STAGE(SB(0, 1), rsB, bcol + HALF_, 0); STAGE(SA(0, 1), rsA, brow + HALF_, 0);
;   if (wr == 1) BAR;
; template <int EPI> __device__ __forceinline__ void gemm_phase(const h16* A, const h16* Bt, int M, int N, int K, const GE& e, h16* shm) {
;     ...
;       int q = nwg / NXCD, r = nwg % NXCD, xcd = wgid % NXCD, off = wgid / NXCD;
;       wgid = (xcd < r ? xcd * (q + 1) : r * (q + 1) + (xcd - r) * q) + off;
;     }
;     int nig = WGM * nN, gid = wgid / nig, fm = gid * WGM, gsz = min(nM - fm, WGM);
;     int pm = fm + ((wgid % nig) % gsz), pn = (wgid % nig) / gsz, brow = pm * BM, bcol = pn * BM;
.LBB0_240:
	s_ashr_i32 s4, s14, 31
	s_lshr_b32 s4, s4, 29
	s_add_i32 s4, s14, s4
	s_ashr_i32 s5, s4, 3
	s_and_b32 s4, s4, -8
	s_sub_i32 s4, s14, s4
	s_cmp_lt_i32 s4, 0
	s_movk_i32 s10, 0x61
	s_cselect_b32 s10, s10, 0x60
	s_mul_i32 s4, s10, s4
	s_add_i32 s4, s4, s5
	s_ashr_i32 s5, s4, 31
	s_lshr_b32 s5, s5, 27
	v_mov_b32_e32 v0, v172
	s_add_i32 s5, s4, s5
	s_ashr_i32 s21, s5, 5
	v_bfe_i32 v4, v0, 27, 1
	s_and_b32 s5, s5, 0xffe0
	v_lshlrev_b32_e32 v2, 4, v0
	v_lshrrev_b32_e32 v4, 22, v4
	s_sub_i32 s4, s4, s5
	v_add_u32_e32 v4, v2, v4
	s_bfe_i32 s5, s4, 0x80000
	v_and_b32_e32 v4, 0xfffffc00, v4
	s_bfe_u32 s5, s5, 0x3000c
	v_ashrrev_i32_e32 v3, 31, v0
	v_sub_u32_e32 v4, v2, v4
	s_add_i32 s5, s4, s5
	v_lshrrev_b32_e32 v3, 26, v3
	v_lshrrev_b32_e32 v5, 4, v4
	s_bfe_i32 s10, s5, 0x80000
	s_and_b32 s5, s5, 0xf8
	v_add_u32_e32 v3, v0, v3
	v_bitop3_b32 v5, v5, v4, 32 bitop3:0x6c
	v_ashrrev_i32_e32 v4, 31, v4
	s_sub_i32 s4, s4, s5
	v_ashrrev_i32_e32 v3, 6, v3
	v_lshrrev_b32_e32 v4, 26, v4
	s_sext_i32_i8 s22, s4
	v_lshlrev_b32_e32 v6, 3, v3
	v_add_u32_e32 v4, v5, v4
	s_lshl_b32 s4, s21, 11
	s_lshl_b32 s15, s22, 8
	v_and_b32_e32 v6, 0xfffff0, v6
	v_ashrrev_i32_e32 v4, 6, v4
	s_add_i32 s15, s15, s4
	v_add_u32_e32 v6, v4, v6
	v_mul_i32_i24_e32 v4, 64, v4
	s_movk_i32 s4, 0xb00
	v_lshlrev_b32_e32 v3, 5, v3
	v_sub_u32_e32 v4, v5, v4
	v_mul_lo_u32 v5, v6, s4
	v_and_or_b32 v3, v3, 32, v5
	v_add_u32_e32 v5, 0x2000, v2
	v_ashrrev_i32_e32 v6, 31, v5
	v_lshrrev_b32_e32 v6, 22, v6
	v_add_u32_e32 v6, v5, v6
	v_ashrrev_i32_e32 v6, 10, v6
	v_mul_i32_i24_e32 v7, 0x400, v6
	v_sub_u32_e32 v5, v5, v7
	v_lshrrev_b32_e32 v7, 4, v5
	v_bitop3_b32 v5, v7, v5, 32 bitop3:0x6c
	v_ashrrev_i32_e32 v8, 31, v5
	v_lshrrev_b32_e32 v8, 26, v8
	v_lshlrev_b32_e32 v7, 3, v6
	v_add_u32_e32 v8, v5, v8
	v_and_b32_e32 v7, 0xfffff0, v7
	v_lshrrev_b32_e32 v9, 6, v8
	v_and_b32_e32 v8, 0xc0, v8
	s_add_i32 s23, s68, 0x110
	s_sext_i32_i16 s10, s10
	v_ashrrev_i16_sdwa v4, v187, sext(v4) dst_sel:DWORD dst_unused:UNUSED_PAD src0_sel:DWORD src1_sel:BYTE_0
	v_add_u32_e32 v7, v9, v7
	v_sub_u32_e32 v5, v5, v8
	v_add_u32_e32 v137, s23, v2
	s_ashr_i32 s18, s10, 3
	v_bfe_i32 v4, v4, 0, 16
	v_lshlrev_b32_e32 v6, 5, v6
	v_ashrrev_i16_sdwa v5, v187, sext(v5) dst_sel:DWORD dst_unused:UNUSED_PAD src0_sel:DWORD src1_sel:BYTE_0
	v_mul_lo_u32 v7, v7, s4
	v_readfirstlane_b32 s4, v137
	v_add_u32_e32 v139, 0x2000, v137
	v_bfe_i32 v5, v5, 0, 16
	v_and_or_b32 v6, v6, 32, v7
	v_add_lshl_u32 v136, v3, v4, 1
	s_mul_i32 s19, s18, 0x160000
	s_mov_b32 s10, s78
	s_mov_b32 s11, s79
	s_mov_b32 m0, s4
	v_readfirstlane_b32 s4, v139
	v_add_u32_e32 v140, 0x110, v2
	v_add_lshl_u32 v135, v6, v5, 1
	buffer_load_dwordx4 v136, s[8:11], s19 offen lds
	s_mov_b32 m0, s4
	v_readfirstlane_b32 s4, v140
	v_add_u32_e32 v141, 0x2000, v140
	buffer_load_dwordx4 v135, s[8:11], s19 offen lds
	s_mul_i32 s24, s15, 0x1600
	s_mov_b32 m0, s4
	v_readfirstlane_b32 s4, v141
	buffer_load_dwordx4 v136, s[76:79], s24 offen lds
	s_mov_b32 m0, s4
	v_readlane_b32 s4, v254, 11
	buffer_load_dwordx4 v135, s[76:79], s24 offen lds
	s_add_i32 s25, s19, 0xb0000
	v_add_u32_e32 v142, s4, v2
	v_add_u32_e32 v143, 0x2000, v142
	v_readfirstlane_b32 s4, v142
	s_mov_b32 m0, s4
	v_readfirstlane_b32 s4, v143
	v_add_u32_e32 v144, 0x4000, v140
	buffer_load_dwordx4 v136, s[8:11], s25 offen lds
	s_mov_b32 m0, s4
	v_readfirstlane_b32 s4, v144
	v_add_u32_e32 v145, 0x6000, v140
	buffer_load_dwordx4 v135, s[8:11], s25 offen lds
	s_add_i32 s20, s24, 0xb0000
	s_mov_b32 m0, s4
	v_readfirstlane_b32 s4, v145
	buffer_load_dwordx4 v136, s[76:79], s20 offen lds
	s_mov_b32 m0, s4
	v_ashrrev_i32_e32 v3, 8, v0
	buffer_load_dwordx4 v135, s[76:79], s20 offen lds
	v_cmp_eq_u32_e32 vcc, 1, v3
	s_and_saveexec_b64 s[4:5], vcc
	s_cbranch_execz .LBB0_242
	s_barrier
	s_setprio 1

; #define WAIT_L(n) asm volatile("s_waitcnt lgkmcnt(" #n ")" ::: "memory")
; #define BAR __builtin_amdgcn_s_barrier()
; #define SCHED __builtin_amdgcn_sched_barrier(0)
; DEV void gemm_tile(const h16* __restrict__ A, const h16* __restrict__ Bt, int K, int ld, int brow, int bcol, h16* shm, Acc& acc) {
;     ...
;     LDB(B0, 0, 0); SCHED; LDA(At, 0, 0); STAGE(SA(1, 1), rsA, brow + HALF_, t + 1);
;     WAIT_L(8); BAR; WAIT_L(0); MMA(0, 0, At, B0); BAR; SCHED;
;     LDB(B1, 0, 1); STAGE(SB(0, 0), rsB, bcol, t + 2);
;     BAR; WAIT_L(0); MMA(0, 1, At, B1); BAR;
;     LDA(At, 0, 1); STAGE(SA(0, 0), rsA, brow, t + 2);
;     BAR; WAIT_L(0); MMA(1, 0, At, B0); BAR; SCHED;
.LBB0_243:
	ds_read_b128 v[156:159], v155
	ds_read_b128 v[160:163], v155 offset:1024
	ds_read_b128 v[164:167], v155 offset:2048
	ds_read_b128 v[168:171], v155 offset:3072
	s_add_i32 s22, s4, s21
	v_readfirstlane_b32 s11, v153
	s_add_i32 s10, s22, 0xb0080
	s_mov_b32 m0, s11
	v_readfirstlane_b32 s11, v152
	ds_read_b128 v[174:177], v133
	ds_read_b128 v[178:181], v133 offset:1024
	ds_read_b128 v[198:201], v132
	ds_read_b128 v[202:205], v132 offset:1024
	ds_read_b128 v[206:209], v131
	ds_read_b128 v[210:213], v131 offset:1024
	ds_read_b128 v[214:217], v130
	ds_read_b128 v[218:221], v130 offset:1024
	buffer_load_dwordx4 v136, s[76:79], s10 offen lds
	s_mov_b32 m0, s11
	s_nop 0
	buffer_load_dwordx4 v135, s[76:79], s10 offen lds
	s_waitcnt lgkmcnt(8)
	s_barrier
	s_waitcnt lgkmcnt(0)
	s_waitcnt lgkmcnt(7)
	v_mfma_f32_16x16x32_f16 v[126:129], v[174:177], v[156:159], v[126:129]
	v_mfma_f32_16x16x32_f16 v[122:125], v[174:177], v[164:167], v[122:125]
	s_waitcnt lgkmcnt(5)
	v_mfma_f32_16x16x32_f16 v[118:121], v[198:201], v[156:159], v[118:121]
	v_mfma_f32_16x16x32_f16 v[114:117], v[198:201], v[164:167], v[114:117]
	s_waitcnt lgkmcnt(3)
	v_mfma_f32_16x16x32_f16 v[110:113], v[206:209], v[156:159], v[110:113]
	v_mfma_f32_16x16x32_f16 v[106:109], v[206:209], v[164:167], v[106:109]
	s_waitcnt lgkmcnt(1)
	v_mfma_f32_16x16x32_f16 v[102:105], v[214:217], v[156:159], v[102:105]
	v_mfma_f32_16x16x32_f16 v[98:101], v[214:217], v[164:167], v[98:101]
	v_mfma_f32_16x16x32_f16 v[126:129], v[178:181], v[160:163], v[126:129]
	v_mfma_f32_16x16x32_f16 v[122:125], v[178:181], v[168:171], v[122:125]
	v_mfma_f32_16x16x32_f16 v[118:121], v[202:205], v[160:163], v[118:121]
	v_mfma_f32_16x16x32_f16 v[114:117], v[202:205], v[168:171], v[114:117]
	v_mfma_f32_16x16x32_f16 v[110:113], v[210:213], v[160:163], v[110:113]
	v_mfma_f32_16x16x32_f16 v[106:109], v[210:213], v[168:171], v[106:109]
	s_waitcnt lgkmcnt(0)
	v_mfma_f32_16x16x32_f16 v[102:105], v[218:221], v[160:163], v[102:105]
	v_mfma_f32_16x16x32_f16 v[98:101], v[218:221], v[168:171], v[98:101]
	s_barrier
	s_add_i32 s23, s19, s21
	v_readfirstlane_b32 s25, v137
	s_add_i32 s24, s23, 0x100
	s_mov_b32 s10, s78
	s_mov_b32 s11, s79
	s_mov_b32 m0, s25
	v_readfirstlane_b32 s25, v139
	ds_read_b128 v[222:225], v150
	ds_read_b128 v[226:229], v150 offset:1024
	ds_read_b128 v[230:233], v150 offset:2048
	ds_read_b128 v[234:237], v150 offset:3072
	buffer_load_dwordx4 v136, s[8:11], s24 offen lds
	s_mov_b32 m0, s25
	s_nop 0
	buffer_load_dwordx4 v135, s[8:11], s24 offen lds
	s_barrier
	s_waitcnt lgkmcnt(0)
	s_waitcnt lgkmcnt(3)
	v_mfma_f32_16x16x32_f16 v[94:97], v[174:177], v[222:225], v[94:97]
	s_waitcnt lgkmcnt(1)
	v_mfma_f32_16x16x32_f16 v[90:93], v[174:177], v[230:233], v[90:93]
	v_mfma_f32_16x16x32_f16 v[86:89], v[198:201], v[222:225], v[86:89]
	v_mfma_f32_16x16x32_f16 v[82:85], v[198:201], v[230:233], v[82:85]
	v_mfma_f32_16x16x32_f16 v[78:81], v[206:209], v[222:225], v[78:81]
	v_mfma_f32_16x16x32_f16 v[74:77], v[206:209], v[230:233], v[74:77]
	v_mfma_f32_16x16x32_f16 v[70:73], v[214:217], v[222:225], v[70:73]
	v_mfma_f32_16x16x32_f16 v[66:69], v[214:217], v[230:233], v[66:69]
	v_mfma_f32_16x16x32_f16 v[94:97], v[178:181], v[226:229], v[94:97]
	s_waitcnt lgkmcnt(0)
	v_mfma_f32_16x16x32_f16 v[90:93], v[178:181], v[234:237], v[90:93]
	v_mfma_f32_16x16x32_f16 v[86:89], v[202:205], v[226:229], v[86:89]
	v_mfma_f32_16x16x32_f16 v[82:85], v[202:205], v[234:237], v[82:85]
	v_mfma_f32_16x16x32_f16 v[78:81], v[210:213], v[226:229], v[78:81]
	v_mfma_f32_16x16x32_f16 v[74:77], v[210:213], v[234:237], v[74:77]
	v_mfma_f32_16x16x32_f16 v[70:73], v[218:221], v[226:229], v[70:73]
	v_mfma_f32_16x16x32_f16 v[66:69], v[218:221], v[234:237], v[66:69]
	v_readfirstlane_b32 s25, v140
	s_add_i32 s24, s22, 0x100
	s_mov_b32 m0, s25
	v_readfirstlane_b32 s25, v141
	s_barrier
	ds_read_b128 v[174:177], v133 offset:16384
	ds_read_b128 v[178:181], v133 offset:17408
	ds_read_b128 v[198:201], v132 offset:16384
	ds_read_b128 v[202:205], v132 offset:17408
	ds_read_b128 v[206:209], v131 offset:16384
	ds_read_b128 v[210:213], v131 offset:17408
	ds_read_b128 v[214:217], v130 offset:16384
	ds_read_b128 v[218:221], v130 offset:17408
	buffer_load_dwordx4 v136, s[76:79], s24 offen lds
	s_mov_b32 m0, s25
	s_nop 0
	buffer_load_dwordx4 v135, s[76:79], s24 offen lds
	s_barrier
	s_waitcnt lgkmcnt(0)
	s_waitcnt lgkmcnt(7)
	v_mfma_f32_16x16x32_f16 v[62:65], v[174:177], v[156:159], v[62:65]
	v_mfma_f32_16x16x32_f16 v[58:61], v[174:177], v[164:167], v[58:61]
	s_waitcnt lgkmcnt(5)
	v_mfma_f32_16x16x32_f16 v[54:57], v[198:201], v[156:159], v[54:57]
	v_mfma_f32_16x16x32_f16 v[50:53], v[198:201], v[164:167], v[50:53]
	s_waitcnt lgkmcnt(3)
	v_mfma_f32_16x16x32_f16 v[46:49], v[206:209], v[156:159], v[46:49]
	v_mfma_f32_16x16x32_f16 v[42:45], v[206:209], v[164:167], v[42:45]
	s_waitcnt lgkmcnt(1)
	v_mfma_f32_16x16x32_f16 v[38:41], v[214:217], v[156:159], v[38:41]
	v_mfma_f32_16x16x32_f16 v[34:37], v[214:217], v[164:167], v[34:37]
	v_mfma_f32_16x16x32_f16 v[62:65], v[178:181], v[160:163], v[62:65]
	v_mfma_f32_16x16x32_f16 v[58:61], v[178:181], v[168:171], v[58:61]
	v_mfma_f32_16x16x32_f16 v[54:57], v[202:205], v[160:163], v[54:57]
	v_mfma_f32_16x16x32_f16 v[50:53], v[202:205], v[168:171], v[50:53]
	v_mfma_f32_16x16x32_f16 v[46:49], v[210:213], v[160:163], v[46:49]
	v_mfma_f32_16x16x32_f16 v[42:45], v[210:213], v[168:171], v[42:45]
	s_waitcnt lgkmcnt(0)
	v_mfma_f32_16x16x32_f16 v[38:41], v[218:221], v[160:163], v[38:41]
	v_mfma_f32_16x16x32_f16 v[34:37], v[218:221], v[168:171], v[34:37]
	s_barrier
; #define WAIT_V(n) asm volatile("s_waitcnt vmcnt(" #n ")" ::: "memory")
; #define WAIT_L(n) asm volatile("s_waitcnt lgkmcnt(" #n ")" ::: "memory")
; #define BAR __builtin_amdgcn_s_barrier()
; #define SCHED __builtin_amdgcn_sched_barrier(0)
; DEV void gemm_tile(const h16* __restrict__ A, const h16* __restrict__ Bt, int K, int ld, int brow, int bcol, h16* shm, Acc& acc) {
;     ...
;     STAGE(SB(0, 1), rsB, bcol + HALF_, t + 2);
;     WAIT_V(6); BAR; MMA(1, 1, At, B1); BAR;
;     LDB(B0, 1, 0); SCHED; LDA(At, 1, 0); STAGE(SA(0, 1), rsA, brow + HALF_, t + 2);
;     WAIT_L(8); BAR; WAIT_L(0); MMA(0, 0, At, B0); BAR; SCHED;
;     LDB(B1, 1, 1); STAGE(SB(1, 0), rsB, bcol, t + 3);
;     BAR; WAIT_L(0); MMA(0, 1, At, B1); BAR;
;     LDA(At, 1, 1); STAGE(SA(1, 0), rsA, brow, t + 3);
	v_readfirstlane_b32 s25, v142
	s_add_i32 s24, s23, 0xb0100
	s_mov_b32 m0, s25
	v_readfirstlane_b32 s25, v143
	buffer_load_dwordx4 v136, s[8:11], s24 offen lds
	s_mov_b32 m0, s25
	s_nop 0
	buffer_load_dwordx4 v135, s[8:11], s24 offen lds
	s_waitcnt vmcnt(6)
	s_barrier
	v_mfma_f32_16x16x32_f16 v[30:33], v[174:177], v[222:225], v[30:33]
	v_mfma_f32_16x16x32_f16 v[26:29], v[174:177], v[230:233], v[26:29]
	v_mfma_f32_16x16x32_f16 v[22:25], v[198:201], v[222:225], v[22:25]
	v_mfma_f32_16x16x32_f16 v[18:21], v[198:201], v[230:233], v[18:21]
	v_mfma_f32_16x16x32_f16 v[14:17], v[206:209], v[222:225], v[14:17]
	v_mfma_f32_16x16x32_f16 v[10:13], v[206:209], v[230:233], v[10:13]
	v_mfma_f32_16x16x32_f16 v[6:9], v[214:217], v[222:225], v[6:9]
	v_mfma_f32_16x16x32_f16 v[2:5], v[214:217], v[230:233], v[2:5]
	v_mfma_f32_16x16x32_f16 v[30:33], v[178:181], v[226:229], v[30:33]
	v_mfma_f32_16x16x32_f16 v[26:29], v[178:181], v[234:237], v[26:29]
	v_mfma_f32_16x16x32_f16 v[22:25], v[202:205], v[226:229], v[22:25]
	v_mfma_f32_16x16x32_f16 v[18:21], v[202:205], v[234:237], v[18:21]
	v_mfma_f32_16x16x32_f16 v[14:17], v[210:213], v[226:229], v[14:17]
	v_mfma_f32_16x16x32_f16 v[10:13], v[210:213], v[234:237], v[10:13]
	v_mfma_f32_16x16x32_f16 v[6:9], v[218:221], v[226:229], v[6:9]
	v_mfma_f32_16x16x32_f16 v[2:5], v[218:221], v[234:237], v[2:5]
	s_barrier
	ds_read_b128 v[156:159], v138
	ds_read_b128 v[160:163], v138 offset:1024
	ds_read_b128 v[164:167], v138 offset:2048
	ds_read_b128 v[168:171], v138 offset:3072
	v_readfirstlane_b32 s25, v144
	s_add_i32 s24, s22, 0xb0100
	s_mov_b32 m0, s25
	v_readfirstlane_b32 s25, v145
	ds_read_b128 v[174:177], v133 offset:32768
	ds_read_b128 v[178:181], v133 offset:33792
	ds_read_b128 v[198:201], v132 offset:32768
	ds_read_b128 v[202:205], v132 offset:33792
	ds_read_b128 v[206:209], v131 offset:32768
	ds_read_b128 v[210:213], v131 offset:33792
	ds_read_b128 v[214:217], v130 offset:32768
	ds_read_b128 v[218:221], v130 offset:33792
	buffer_load_dwordx4 v136, s[76:79], s24 offen lds
	s_mov_b32 m0, s25
	s_nop 0
	buffer_load_dwordx4 v135, s[76:79], s24 offen lds
	s_waitcnt lgkmcnt(8)
	s_barrier
	s_waitcnt lgkmcnt(0)
	s_waitcnt lgkmcnt(7)
	v_mfma_f32_16x16x32_f16 v[126:129], v[174:177], v[156:159], v[126:129]
	v_mfma_f32_16x16x32_f16 v[122:125], v[174:177], v[164:167], v[122:125]
	s_waitcnt lgkmcnt(5)
	v_mfma_f32_16x16x32_f16 v[118:121], v[198:201], v[156:159], v[118:121]
	v_mfma_f32_16x16x32_f16 v[114:117], v[198:201], v[164:167], v[114:117]
	s_waitcnt lgkmcnt(3)
	v_mfma_f32_16x16x32_f16 v[110:113], v[206:209], v[156:159], v[110:113]
	v_mfma_f32_16x16x32_f16 v[106:109], v[206:209], v[164:167], v[106:109]
	s_waitcnt lgkmcnt(1)
	v_mfma_f32_16x16x32_f16 v[102:105], v[214:217], v[156:159], v[102:105]
	v_mfma_f32_16x16x32_f16 v[98:101], v[214:217], v[164:167], v[98:101]
	v_mfma_f32_16x16x32_f16 v[126:129], v[178:181], v[160:163], v[126:129]
	v_mfma_f32_16x16x32_f16 v[122:125], v[178:181], v[168:171], v[122:125]
	v_mfma_f32_16x16x32_f16 v[118:121], v[202:205], v[160:163], v[118:121]
	v_mfma_f32_16x16x32_f16 v[114:117], v[202:205], v[168:171], v[114:117]
	v_mfma_f32_16x16x32_f16 v[110:113], v[210:213], v[160:163], v[110:113]
	v_mfma_f32_16x16x32_f16 v[106:109], v[210:213], v[168:171], v[106:109]
	s_waitcnt lgkmcnt(0)
	v_mfma_f32_16x16x32_f16 v[102:105], v[218:221], v[160:163], v[102:105]
	v_mfma_f32_16x16x32_f16 v[98:101], v[218:221], v[168:171], v[98:101]
	s_barrier
	v_readfirstlane_b32 s25, v146
	s_add_i32 s24, s23, 0x180
	s_mov_b32 m0, s25
	v_readfirstlane_b32 s25, v147
	ds_read_b128 v[222:225], v134
	ds_read_b128 v[226:229], v134 offset:1024
	ds_read_b128 v[230:233], v134 offset:2048
	ds_read_b128 v[234:237], v134 offset:3072
	buffer_load_dwordx4 v136, s[8:11], s24 offen lds
	s_mov_b32 m0, s25
	s_nop 0
	buffer_load_dwordx4 v135, s[8:11], s24 offen lds
	s_barrier
	s_waitcnt lgkmcnt(0)
	s_waitcnt lgkmcnt(3)
	v_mfma_f32_16x16x32_f16 v[94:97], v[174:177], v[222:225], v[94:97]
	s_waitcnt lgkmcnt(1)
	v_mfma_f32_16x16x32_f16 v[90:93], v[174:177], v[230:233], v[90:93]
	v_mfma_f32_16x16x32_f16 v[86:89], v[198:201], v[222:225], v[86:89]
	v_mfma_f32_16x16x32_f16 v[82:85], v[198:201], v[230:233], v[82:85]
	v_mfma_f32_16x16x32_f16 v[78:81], v[206:209], v[222:225], v[78:81]
	v_mfma_f32_16x16x32_f16 v[74:77], v[206:209], v[230:233], v[74:77]
	v_mfma_f32_16x16x32_f16 v[70:73], v[214:217], v[222:225], v[70:73]
	v_mfma_f32_16x16x32_f16 v[66:69], v[214:217], v[230:233], v[66:69]
	v_mfma_f32_16x16x32_f16 v[94:97], v[178:181], v[226:229], v[94:97]
	s_waitcnt lgkmcnt(0)
	v_mfma_f32_16x16x32_f16 v[90:93], v[178:181], v[234:237], v[90:93]
	v_mfma_f32_16x16x32_f16 v[86:89], v[202:205], v[226:229], v[86:89]
	v_mfma_f32_16x16x32_f16 v[82:85], v[202:205], v[234:237], v[82:85]
	v_mfma_f32_16x16x32_f16 v[78:81], v[210:213], v[226:229], v[78:81]
	v_mfma_f32_16x16x32_f16 v[74:77], v[210:213], v[234:237], v[74:77]
	v_mfma_f32_16x16x32_f16 v[70:73], v[218:221], v[226:229], v[70:73]
	v_mfma_f32_16x16x32_f16 v[66:69], v[218:221], v[234:237], v[66:69]
	v_readfirstlane_b32 s24, v148
	s_addk_i32 s22, 0x180
	s_mov_b32 m0, s24
	v_readfirstlane_b32 s24, v149
	s_barrier
	ds_read_b128 v[174:177], v133 offset:49152
	ds_read_b128 v[178:181], v133 offset:50176
	ds_read_b128 v[198:201], v132 offset:49152
	ds_read_b128 v[202:205], v132 offset:50176
	ds_read_b128 v[206:209], v131 offset:49152
	ds_read_b128 v[210:213], v131 offset:50176
	ds_read_b128 v[214:217], v130 offset:49152
	ds_read_b128 v[218:221], v130 offset:50176
	buffer_load_dwordx4 v136, s[76:79], s22 offen lds
	s_mov_b32 m0, s24
	s_nop 0
	buffer_load_dwordx4 v135, s[76:79], s22 offen lds
	s_barrier
; #define WAIT_V(n) asm volatile("s_waitcnt vmcnt(" #n ")" ::: "memory")
; #define WAIT_L(n) asm volatile("s_waitcnt lgkmcnt(" #n ")" ::: "memory")
; #define BAR __builtin_amdgcn_s_barrier()
; #define SCHED __builtin_amdgcn_sched_barrier(0)
; DEV void gemm_tile(const h16* __restrict__ A, const h16* __restrict__ Bt, int K, int ld, int brow, int bcol, h16* shm, Acc& acc) {
;     ...
;     BAR; WAIT_L(0); MMA(1, 0, At, B0); BAR; SCHED;
;     STAGE(SB(1, 1), rsB, bcol + HALF_, t + 3);
;     WAIT_V(6); BAR; MMA(1, 1, At, B1); BAR;
;   }
;   { LDB(B0, 0, 0); LDA(At, 0, 0); STAGE(SA(1, 1), rsA, brow + HALF_, nt - 1);
;     BAR; WAIT_L(0); MMA(0, 0, At, B0); BAR;
;     LDB(B1, 0, 1); BAR; WAIT_L(0); MMA(0, 1, At, B1); BAR;
	s_waitcnt lgkmcnt(0)
	s_waitcnt lgkmcnt(7)
	v_mfma_f32_16x16x32_f16 v[62:65], v[174:177], v[156:159], v[62:65]
	v_mfma_f32_16x16x32_f16 v[58:61], v[174:177], v[164:167], v[58:61]
	s_waitcnt lgkmcnt(5)
	v_mfma_f32_16x16x32_f16 v[54:57], v[198:201], v[156:159], v[54:57]
	v_mfma_f32_16x16x32_f16 v[50:53], v[198:201], v[164:167], v[50:53]
	s_waitcnt lgkmcnt(3)
	v_mfma_f32_16x16x32_f16 v[46:49], v[206:209], v[156:159], v[46:49]
	v_mfma_f32_16x16x32_f16 v[42:45], v[206:209], v[164:167], v[42:45]
	s_waitcnt lgkmcnt(1)
	v_mfma_f32_16x16x32_f16 v[38:41], v[214:217], v[156:159], v[38:41]
	v_mfma_f32_16x16x32_f16 v[34:37], v[214:217], v[164:167], v[34:37]
	v_mfma_f32_16x16x32_f16 v[62:65], v[178:181], v[160:163], v[62:65]
	v_mfma_f32_16x16x32_f16 v[58:61], v[178:181], v[168:171], v[58:61]
	v_mfma_f32_16x16x32_f16 v[54:57], v[202:205], v[160:163], v[54:57]
	v_mfma_f32_16x16x32_f16 v[50:53], v[202:205], v[168:171], v[50:53]
	v_mfma_f32_16x16x32_f16 v[46:49], v[210:213], v[160:163], v[46:49]
	v_mfma_f32_16x16x32_f16 v[42:45], v[210:213], v[168:171], v[42:45]
	s_waitcnt lgkmcnt(0)
	v_mfma_f32_16x16x32_f16 v[38:41], v[218:221], v[160:163], v[38:41]
	v_mfma_f32_16x16x32_f16 v[34:37], v[218:221], v[168:171], v[34:37]
	s_barrier
	v_readfirstlane_b32 s22, v151
	s_add_i32 s23, s23, 0xb0180
	s_mov_b32 m0, s22
	v_readfirstlane_b32 s22, v154
	buffer_load_dwordx4 v136, s[8:11], s23 offen lds
	s_mov_b32 m0, s22
	s_nop 0
	buffer_load_dwordx4 v135, s[8:11], s23 offen lds
	s_waitcnt vmcnt(6)
	s_barrier
	v_mfma_f32_16x16x32_f16 v[30:33], v[174:177], v[222:225], v[30:33]
	v_mfma_f32_16x16x32_f16 v[26:29], v[174:177], v[230:233], v[26:29]
	v_mfma_f32_16x16x32_f16 v[22:25], v[198:201], v[222:225], v[22:25]
	v_mfma_f32_16x16x32_f16 v[18:21], v[198:201], v[230:233], v[18:21]
	v_mfma_f32_16x16x32_f16 v[14:17], v[206:209], v[222:225], v[14:17]
	v_mfma_f32_16x16x32_f16 v[10:13], v[206:209], v[230:233], v[10:13]
	v_mfma_f32_16x16x32_f16 v[6:9], v[214:217], v[222:225], v[6:9]
	v_mfma_f32_16x16x32_f16 v[2:5], v[214:217], v[230:233], v[2:5]
	v_mfma_f32_16x16x32_f16 v[30:33], v[178:181], v[226:229], v[30:33]
	v_mfma_f32_16x16x32_f16 v[26:29], v[178:181], v[234:237], v[26:29]
	v_mfma_f32_16x16x32_f16 v[22:25], v[202:205], v[226:229], v[22:25]
	v_mfma_f32_16x16x32_f16 v[18:21], v[202:205], v[234:237], v[18:21]
	v_mfma_f32_16x16x32_f16 v[14:17], v[210:213], v[226:229], v[14:17]
	v_mfma_f32_16x16x32_f16 v[10:13], v[210:213], v[234:237], v[10:13]
	v_mfma_f32_16x16x32_f16 v[6:9], v[218:221], v[226:229], v[6:9]
	v_mfma_f32_16x16x32_f16 v[2:5], v[218:221], v[234:237], v[2:5]
	s_add_i32 s5, s5, 2
	s_addk_i32 s21, 0x100
	s_cmp_lt_u32 s5, 40
	s_barrier
	s_cbranch_scc1 .LBB0_243
	v_readfirstlane_b32 s5, v153
	s_or_b32 s4, s20, 0x1580
	s_mov_b32 m0, s5
	v_readfirstlane_b32 s5, v152
	ds_read_b128 v[140:143], v155
	ds_read_b128 v[144:147], v155 offset:1024
	ds_read_b128 v[156:159], v155 offset:2048
	ds_read_b128 v[160:163], v155 offset:3072
	ds_read_b128 v[164:167], v133
	ds_read_b128 v[168:171], v133 offset:1024
	ds_read_b128 v[174:177], v132
	ds_read_b128 v[178:181], v132 offset:1024
	ds_read_b128 v[198:201], v131
	ds_read_b128 v[202:205], v131 offset:1024
	ds_read_b128 v[206:209], v130
	ds_read_b128 v[210:213], v130 offset:1024
	buffer_load_dwordx4 v136, s[76:79], s4 offen lds
	s_mov_b32 m0, s5
	s_nop 0
	buffer_load_dwordx4 v135, s[76:79], s4 offen lds
	s_barrier
	s_waitcnt lgkmcnt(0)
	s_waitcnt lgkmcnt(7)
	v_mfma_f32_16x16x32_f16 v[126:129], v[164:167], v[140:143], v[126:129]
	v_mfma_f32_16x16x32_f16 v[122:125], v[164:167], v[156:159], v[122:125]
	s_waitcnt lgkmcnt(5)
	v_mfma_f32_16x16x32_f16 v[118:121], v[174:177], v[140:143], v[118:121]
	v_mfma_f32_16x16x32_f16 v[114:117], v[174:177], v[156:159], v[114:117]
	v_mfma_f32_16x16x32_f16 v[126:129], v[168:171], v[144:147], v[126:129]
	v_mfma_f32_16x16x32_f16 v[122:125], v[168:171], v[160:163], v[122:125]
	s_waitcnt lgkmcnt(4)
	v_mfma_f32_16x16x32_f16 v[118:121], v[178:181], v[144:147], v[118:121]
	v_mfma_f32_16x16x32_f16 v[114:117], v[178:181], v[160:163], v[114:117]
	s_waitcnt lgkmcnt(3)
	v_mfma_f32_16x16x32_f16 v[110:113], v[198:201], v[140:143], v[110:113]
	v_mfma_f32_16x16x32_f16 v[106:109], v[198:201], v[156:159], v[106:109]
	s_waitcnt lgkmcnt(1)
	v_mfma_f32_16x16x32_f16 v[102:105], v[206:209], v[140:143], v[102:105]
	v_mfma_f32_16x16x32_f16 v[98:101], v[206:209], v[156:159], v[98:101]
	v_mfma_f32_16x16x32_f16 v[152:155], v[202:205], v[144:147], v[110:113]
	v_mfma_f32_16x16x32_f16 v[214:217], v[202:205], v[160:163], v[106:109]
	s_waitcnt lgkmcnt(0)
	v_mfma_f32_16x16x32_f16 v[218:221], v[210:213], v[144:147], v[102:105]
	v_mfma_f32_16x16x32_f16 v[222:225], v[210:213], v[160:163], v[98:101]
	s_barrier
	s_nop 0
	ds_read_b128 v[98:101], v150
	ds_read_b128 v[102:105], v150 offset:1024
	ds_read_b128 v[106:109], v150 offset:2048
	ds_read_b128 v[110:113], v150 offset:3072
	s_barrier
	s_waitcnt lgkmcnt(0)
	s_waitcnt lgkmcnt(3)
	v_mfma_f32_16x16x32_f16 v[94:97], v[164:167], v[98:101], v[94:97]
	s_waitcnt lgkmcnt(1)
	v_mfma_f32_16x16x32_f16 v[90:93], v[164:167], v[106:109], v[90:93]
	v_mfma_f32_16x16x32_f16 v[86:89], v[174:177], v[98:101], v[86:89]
	v_mfma_f32_16x16x32_f16 v[82:85], v[174:177], v[106:109], v[82:85]
	v_mfma_f32_16x16x32_f16 v[94:97], v[168:171], v[102:105], v[94:97]
	s_waitcnt lgkmcnt(0)
	v_mfma_f32_16x16x32_f16 v[90:93], v[168:171], v[110:113], v[90:93]
	v_mfma_f32_16x16x32_f16 v[86:89], v[178:181], v[102:105], v[86:89]
	v_mfma_f32_16x16x32_f16 v[82:85], v[178:181], v[110:113], v[82:85]
	v_mfma_f32_16x16x32_f16 v[78:81], v[198:201], v[98:101], v[78:81]
	v_mfma_f32_16x16x32_f16 v[74:77], v[198:201], v[106:109], v[74:77]
	v_mfma_f32_16x16x32_f16 v[70:73], v[206:209], v[98:101], v[70:73]
	v_mfma_f32_16x16x32_f16 v[66:69], v[206:209], v[106:109], v[66:69]
	v_mfma_f32_16x16x32_f16 v[148:151], v[202:205], v[102:105], v[78:81]
	v_mfma_f32_16x16x32_f16 v[164:167], v[202:205], v[110:113], v[74:77]
	v_mfma_f32_16x16x32_f16 v[168:171], v[210:213], v[102:105], v[70:73]
	v_mfma_f32_16x16x32_f16 v[174:177], v[210:213], v[110:113], v[66:69]
	s_barrier
; #define WAIT_V(n) asm volatile("s_waitcnt vmcnt(" #n ")" ::: "memory")
; #define WAIT_L(n) asm volatile("s_waitcnt lgkmcnt(" #n ")" ::: "memory")
; #define BAR __builtin_amdgcn_s_barrier()
; DEV void gemm_tile(const h16* __restrict__ A, const h16* __restrict__ Bt, int K, int ld, int brow, int bcol, h16* shm, Acc& acc) {
;     ...
;     LDA(At, 0, 1); WAIT_V(4); BAR; WAIT_L(0); MMA(1, 0, At, B0); MMA(1, 1, At, B1); BAR; }
;   { LDB(B0, 1, 0); LDA(At, 1, 0); WAIT_V(2); BAR; WAIT_L(0); MMA(0, 0, At, B0); BAR;
	s_nop 1
	ds_read_b128 v[66:69], v133 offset:16384
	ds_read_b128 v[70:73], v133 offset:17408
	ds_read_b128 v[74:77], v132 offset:16384
	ds_read_b128 v[78:81], v132 offset:17408
	ds_read_b128 v[178:181], v131 offset:16384
	ds_read_b128 v[198:201], v131 offset:17408
	ds_read_b128 v[202:205], v130 offset:16384
	ds_read_b128 v[206:209], v130 offset:17408
	s_waitcnt vmcnt(4)
	s_barrier
	s_waitcnt lgkmcnt(0)
	s_waitcnt lgkmcnt(7)
	v_mfma_f32_16x16x32_f16 v[62:65], v[66:69], v[140:143], v[62:65]
	v_mfma_f32_16x16x32_f16 v[58:61], v[66:69], v[156:159], v[58:61]
	s_waitcnt lgkmcnt(5)
	v_mfma_f32_16x16x32_f16 v[54:57], v[74:77], v[140:143], v[54:57]
	v_mfma_f32_16x16x32_f16 v[50:53], v[74:77], v[156:159], v[50:53]
	v_mfma_f32_16x16x32_f16 v[62:65], v[70:73], v[144:147], v[62:65]
	v_mfma_f32_16x16x32_f16 v[58:61], v[70:73], v[160:163], v[58:61]
	s_waitcnt lgkmcnt(4)
	v_mfma_f32_16x16x32_f16 v[54:57], v[78:81], v[144:147], v[54:57]
	v_mfma_f32_16x16x32_f16 v[50:53], v[78:81], v[160:163], v[50:53]
	s_waitcnt lgkmcnt(3)
	v_mfma_f32_16x16x32_f16 v[46:49], v[178:181], v[140:143], v[46:49]
	v_mfma_f32_16x16x32_f16 v[42:45], v[178:181], v[156:159], v[42:45]
	s_waitcnt lgkmcnt(1)
	v_mfma_f32_16x16x32_f16 v[38:41], v[202:205], v[140:143], v[38:41]
	v_mfma_f32_16x16x32_f16 v[34:37], v[202:205], v[156:159], v[34:37]
	v_mfma_f32_16x16x32_f16 v[210:213], v[198:201], v[144:147], v[46:49]
	v_mfma_f32_16x16x32_f16 v[226:229], v[198:201], v[160:163], v[42:45]
	s_waitcnt lgkmcnt(0)
	v_mfma_f32_16x16x32_f16 v[140:143], v[206:209], v[144:147], v[38:41]
	v_mfma_f32_16x16x32_f16 v[144:147], v[206:209], v[160:163], v[34:37]
	v_mfma_f32_16x16x32_f16 v[30:33], v[66:69], v[98:101], v[30:33]
	v_mfma_f32_16x16x32_f16 v[26:29], v[66:69], v[106:109], v[26:29]
	v_mfma_f32_16x16x32_f16 v[22:25], v[74:77], v[98:101], v[22:25]
	v_mfma_f32_16x16x32_f16 v[18:21], v[74:77], v[106:109], v[18:21]
	v_mfma_f32_16x16x32_f16 v[30:33], v[70:73], v[102:105], v[30:33]
	v_mfma_f32_16x16x32_f16 v[26:29], v[70:73], v[110:113], v[26:29]
	v_mfma_f32_16x16x32_f16 v[22:25], v[78:81], v[102:105], v[22:25]
	v_mfma_f32_16x16x32_f16 v[18:21], v[78:81], v[110:113], v[18:21]
	v_mfma_f32_16x16x32_f16 v[14:17], v[178:181], v[98:101], v[14:17]
	v_mfma_f32_16x16x32_f16 v[10:13], v[178:181], v[106:109], v[10:13]
	v_mfma_f32_16x16x32_f16 v[6:9], v[202:205], v[98:101], v[6:9]
	v_mfma_f32_16x16x32_f16 v[2:5], v[202:205], v[106:109], v[2:5]
	v_mfma_f32_16x16x32_f16 v[156:159], v[198:201], v[102:105], v[14:17]
	v_mfma_f32_16x16x32_f16 v[160:163], v[198:201], v[110:113], v[10:13]
	v_mfma_f32_16x16x32_f16 v[178:181], v[206:209], v[102:105], v[6:9]
	v_mfma_f32_16x16x32_f16 v[198:201], v[206:209], v[110:113], v[2:5]
	s_barrier
	s_nop 1
	ds_read_b128 v[2:5], v138
	ds_read_b128 v[6:9], v138 offset:1024
	ds_read_b128 v[202:205], v138 offset:2048
	ds_read_b128 v[136:139], v138 offset:3072
	ds_read_b128 v[10:13], v133 offset:32768
	ds_read_b128 v[14:17], v133 offset:33792
	ds_read_b128 v[34:37], v132 offset:32768
	ds_read_b128 v[38:41], v132 offset:33792
	ds_read_b128 v[42:45], v131 offset:32768
	ds_read_b128 v[46:49], v131 offset:33792
	ds_read_b128 v[206:209], v130 offset:32768
	ds_read_b128 v[230:233], v130 offset:33792
	s_waitcnt vmcnt(2)
	s_barrier
	s_waitcnt lgkmcnt(0)
	s_waitcnt lgkmcnt(7)
	v_mfma_f32_16x16x32_f16 v[66:69], v[10:13], v[2:5], v[126:129]
	s_waitcnt lgkmcnt(6)
	v_mfma_f32_16x16x32_f16 v[106:109], v[14:17], v[6:9], v[66:69]
	v_mfma_f32_16x16x32_f16 v[66:69], v[10:13], v[202:205], v[122:125]
	v_mfma_f32_16x16x32_f16 v[110:113], v[14:17], v[136:139], v[66:69]
	s_waitcnt lgkmcnt(5)
	v_mfma_f32_16x16x32_f16 v[66:69], v[34:37], v[2:5], v[118:121]
	s_waitcnt lgkmcnt(4)
	v_mfma_f32_16x16x32_f16 v[98:101], v[38:41], v[6:9], v[66:69]
	v_mfma_f32_16x16x32_f16 v[66:69], v[34:37], v[202:205], v[114:117]
	v_mfma_f32_16x16x32_f16 v[102:105], v[38:41], v[136:139], v[66:69]
	s_waitcnt lgkmcnt(3)
	v_mfma_f32_16x16x32_f16 v[66:69], v[42:45], v[2:5], v[152:155]
	s_waitcnt lgkmcnt(2)
	v_mfma_f32_16x16x32_f16 v[74:77], v[46:49], v[6:9], v[66:69]
	v_mfma_f32_16x16x32_f16 v[66:69], v[42:45], v[202:205], v[214:217]
	v_mfma_f32_16x16x32_f16 v[78:81], v[46:49], v[136:139], v[66:69]
	s_waitcnt lgkmcnt(1)
	v_mfma_f32_16x16x32_f16 v[66:69], v[206:209], v[2:5], v[218:221]
	v_mfma_f32_16x16x32_f16 v[70:73], v[206:209], v[202:205], v[222:225]
	s_waitcnt lgkmcnt(0)
	v_mfma_f32_16x16x32_f16 v[66:69], v[230:233], v[6:9], v[66:69]
	v_mfma_f32_16x16x32_f16 v[70:73], v[230:233], v[136:139], v[70:73]
	s_barrier
; #define WAIT_V(n) asm volatile("s_waitcnt vmcnt(" #n ")" ::: "memory")
; #define WAIT_L(n) asm volatile("s_waitcnt lgkmcnt(" #n ")" ::: "memory")
; #define BAR __builtin_amdgcn_s_barrier()
; DEV void gemm_tile(const h16* __restrict__ A, const h16* __restrict__ Bt, int K, int ld, int brow, int bcol, h16* shm, Acc& acc) {
;     ...
;     LDB(B1, 1, 1); WAIT_V(0); BAR; WAIT_L(0); MMA(0, 1, At, B1); BAR;
;     LDA(At, 1, 1); BAR; WAIT_L(0); MMA(1, 0, At, B0); MMA(1, 1, At, B1); BAR; }
;   if (wr == 0) BAR;
	ds_read_b128 v[152:155], v134
	ds_read_b128 v[214:217], v134 offset:1024
	ds_read_b128 v[218:221], v134 offset:2048
	ds_read_b128 v[222:225], v134 offset:3072
	s_waitcnt vmcnt(0)
	s_barrier
	s_waitcnt lgkmcnt(0)
	s_waitcnt lgkmcnt(3)
	v_mfma_f32_16x16x32_f16 v[94:97], v[10:13], v[152:155], v[94:97]
	s_waitcnt lgkmcnt(1)
	v_mfma_f32_16x16x32_f16 v[10:13], v[10:13], v[218:221], v[90:93]
	s_waitcnt lgkmcnt(0)
	v_mfma_f32_16x16x32_f16 v[126:129], v[14:17], v[222:225], v[10:13]
	v_mfma_f32_16x16x32_f16 v[10:13], v[34:37], v[152:155], v[86:89]
	v_mfma_f32_16x16x32_f16 v[114:117], v[38:41], v[214:217], v[10:13]
	v_mfma_f32_16x16x32_f16 v[10:13], v[34:37], v[218:221], v[82:85]
	v_mfma_f32_16x16x32_f16 v[118:121], v[38:41], v[222:225], v[10:13]
	v_mfma_f32_16x16x32_f16 v[10:13], v[42:45], v[152:155], v[148:151]
	v_mfma_f32_16x16x32_f16 v[90:93], v[46:49], v[214:217], v[10:13]
	v_mfma_f32_16x16x32_f16 v[10:13], v[42:45], v[218:221], v[164:167]
	v_mfma_f32_16x16x32_f16 v[122:125], v[14:17], v[214:217], v[94:97]
	v_mfma_f32_16x16x32_f16 v[94:97], v[46:49], v[222:225], v[10:13]
	v_mfma_f32_16x16x32_f16 v[10:13], v[206:209], v[152:155], v[168:171]
	v_mfma_f32_16x16x32_f16 v[82:85], v[230:233], v[214:217], v[10:13]
	v_mfma_f32_16x16x32_f16 v[10:13], v[206:209], v[218:221], v[174:177]
	v_mfma_f32_16x16x32_f16 v[86:89], v[230:233], v[222:225], v[10:13]
	s_barrier
	ds_read_b128 v[148:151], v133 offset:49152
	ds_read_b128 v[164:167], v133 offset:50176
	ds_read_b128 v[168:171], v132 offset:49152
	ds_read_b128 v[132:135], v132 offset:50176
	ds_read_b128 v[174:177], v131 offset:49152
	ds_read_b128 v[206:209], v131 offset:50176
	ds_read_b128 v[230:233], v130 offset:49152
	ds_read_b128 v[234:237], v130 offset:50176
	s_barrier
	s_waitcnt lgkmcnt(0)
	s_waitcnt lgkmcnt(7)
	v_mfma_f32_16x16x32_f16 v[10:13], v[148:151], v[2:5], v[62:65]
	s_waitcnt lgkmcnt(6)
	v_mfma_f32_16x16x32_f16 v[42:45], v[164:167], v[6:9], v[10:13]
	v_mfma_f32_16x16x32_f16 v[10:13], v[148:151], v[202:205], v[58:61]
	v_mfma_f32_16x16x32_f16 v[46:49], v[164:167], v[136:139], v[10:13]
	s_waitcnt lgkmcnt(5)
	v_mfma_f32_16x16x32_f16 v[10:13], v[168:171], v[2:5], v[54:57]
	s_waitcnt lgkmcnt(4)
	v_mfma_f32_16x16x32_f16 v[34:37], v[132:135], v[6:9], v[10:13]
	v_mfma_f32_16x16x32_f16 v[10:13], v[168:171], v[202:205], v[50:53]
	v_mfma_f32_16x16x32_f16 v[38:41], v[132:135], v[136:139], v[10:13]
	s_waitcnt lgkmcnt(3)
	v_mfma_f32_16x16x32_f16 v[10:13], v[174:177], v[2:5], v[210:213]
	s_waitcnt lgkmcnt(1)
	v_mfma_f32_16x16x32_f16 v[2:5], v[230:233], v[2:5], v[140:143]
	v_mfma_f32_16x16x32_f16 v[10:13], v[206:209], v[6:9], v[10:13]
	v_mfma_f32_16x16x32_f16 v[14:17], v[174:177], v[202:205], v[226:229]
	s_waitcnt lgkmcnt(0)
	v_mfma_f32_16x16x32_f16 v[2:5], v[234:237], v[6:9], v[2:5]
	v_mfma_f32_16x16x32_f16 v[6:9], v[230:233], v[202:205], v[144:147]
	v_mfma_f32_16x16x32_f16 v[14:17], v[206:209], v[136:139], v[14:17]
	v_mfma_f32_16x16x32_f16 v[6:9], v[234:237], v[136:139], v[6:9]
	v_mfma_f32_16x16x32_f16 v[18:21], v[168:171], v[218:221], v[18:21]
	v_mfma_f32_16x16x32_f16 v[26:29], v[148:151], v[218:221], v[26:29]
	v_mfma_f32_16x16x32_f16 v[54:57], v[132:135], v[222:225], v[18:21]
	v_mfma_f32_16x16x32_f16 v[18:21], v[174:177], v[152:155], v[156:159]
	v_mfma_f32_16x16x32_f16 v[30:33], v[148:151], v[152:155], v[30:33]
	v_mfma_f32_16x16x32_f16 v[62:65], v[164:167], v[222:225], v[26:29]
	v_mfma_f32_16x16x32_f16 v[22:25], v[168:171], v[152:155], v[22:25]
	v_mfma_f32_16x16x32_f16 v[26:29], v[206:209], v[214:217], v[18:21]
	v_mfma_f32_16x16x32_f16 v[18:21], v[174:177], v[218:221], v[160:163]
	v_mfma_f32_16x16x32_f16 v[58:61], v[164:167], v[214:217], v[30:33]
	v_mfma_f32_16x16x32_f16 v[50:53], v[132:135], v[214:217], v[22:25]
	v_mfma_f32_16x16x32_f16 v[30:33], v[206:209], v[222:225], v[18:21]
	v_mfma_f32_16x16x32_f16 v[18:21], v[230:233], v[152:155], v[178:181]
	v_mfma_f32_16x16x32_f16 v[22:25], v[230:233], v[218:221], v[198:201]
	v_mfma_f32_16x16x32_f16 v[18:21], v[234:237], v[214:217], v[18:21]
	v_mfma_f32_16x16x32_f16 v[22:25], v[234:237], v[222:225], v[22:25]
	s_setprio 0
	s_movk_i32 s4, 0x100
	v_cmp_gt_u32_e32 vcc, s4, v0
	s_barrier
	s_and_saveexec_b64 s[4:5], vcc
	s_cbranch_execz .LBB0_239
	s_barrier
	s_branch .LBB0_239

; #define BAR __builtin_amdgcn_s_barrier()
; DEV void gemm_tile(const h16* __restrict__ A, const h16* __restrict__ Bt, int K, int ld, int brow, int bcol, h16* shm, Acc& acc) {
;     ...
;   int wid = TID >> 6, lane = TID & 63, wr = wid >> 2, wc = wid & 3, fr = lane & 15, fq = lane >> 4;
;   int vo0, vo1;
;   {
;     int r, c;
;     stage_rc(TID * 16, r, c);
;     vo0 = (r * ld + c) * 2;
;     stage_rc(TID * 16 + 8192, r, c);
;     vo1 = (r * ld + c) * 2;
;   }
;   __amdgpu_buffer_rsrc_t rsA = __builtin_amdgcn_make_buffer_rsrc((void*)A, (short)0, 0x7fffffff, 0x00020000);
;   __amdgpu_buffer_rsrc_t rsB = __builtin_amdgcn_make_buffer_rsrc((void*)Bt, (short)0, 0x7fffffff, 0x00020000);
; #pragma unroll
;   for (int a = 0; a < 2; ++a)
; #pragma unroll
;     for (int b = 0; b < 2; ++b)
; #pragma unroll
;       for (int m = 0; m < 4; ++m)
; #pragma unroll
;         for (int n = 0; n < 2; ++n) acc[a][b][m][n] = f32x4{0.f, 0.f, 0.f, 0.f};
;   h16x8 At[4][2], B0[2][2], B1[2][2];
;   int nt = K / BK;
;   STAGE(SB(0, 0), rsB, bcol, 0); STAGE(SA(0, 0), rsA, brow, 0);
;   STAGE(SB(0, 1), rsB, bcol + HALF_, 0); STAGE(SA(0, 1), rsA, brow + HALF_, 0);
;   if (wr == 1) BAR;
; template <int EPI> __device__ __forceinline__ void gemm_phase(const h16* A, const h16* Bt, int M, int N, int K, const GE& e, h16* shm) {
;     ...
;       int q = nwg / NXCD, r = nwg % NXCD, xcd = wgid % NXCD, off = wgid / NXCD;
;       wgid = (xcd < r ? xcd * (q + 1) : r * (q + 1) + (xcd - r) * q) + off;
;     }
;     int nig = WGM * nN, gid = wgid / nig, fm = gid * WGM, gsz = min(nM - fm, WGM);
;     int pm = fm + ((wgid % nig) % gsz), pn = (wgid % nig) / gsz, brow = pm * BM, bcol = pn * BM;
.LBB0_274:
	v_mov_b32_e32 v0, v172
	s_ashr_i32 s4, s16, 31
	v_bfe_i32 v4, v0, 27, 1
	v_lshlrev_b32_e32 v2, 4, v0
	v_lshrrev_b32_e32 v4, 22, v4
	v_add_u32_e32 v4, v2, v4
	v_and_b32_e32 v4, 0xfffffc00, v4
	v_ashrrev_i32_e32 v3, 31, v0
	v_sub_u32_e32 v4, v2, v4
	s_lshr_b32 s4, s4, 29
	v_lshrrev_b32_e32 v3, 26, v3
	v_lshrrev_b32_e32 v5, 4, v4
	s_add_i32 s4, s16, s4
	v_add_u32_e32 v3, v0, v3
	v_bitop3_b32 v5, v5, v4, 32 bitop3:0x6c
	v_ashrrev_i32_e32 v4, 31, v4
	s_ashr_i32 s5, s4, 3
	s_and_b32 s4, s4, -8
	v_ashrrev_i32_e32 v3, 6, v3
	v_lshrrev_b32_e32 v4, 26, v4
	s_sub_i32 s4, s16, s4
	v_lshlrev_b32_e32 v6, 3, v3
	v_add_u32_e32 v4, v5, v4
	s_cmp_lt_i32 s4, 0
	s_movk_i32 s8, 0xf1
	v_and_b32_e32 v6, 0x1ffff0, v6
	v_ashrrev_i32_e32 v4, 6, v4
	s_cselect_b32 s8, s8, 0xf0
	v_add_u32_e32 v6, v4, v6
	v_lshlrev_b32_e32 v3, 5, v3
	v_mul_i32_i24_e32 v4, 64, v4
	s_mul_i32 s4, s8, s4
	v_and_b32_e32 v3, 32, v3
	v_sub_u32_e32 v4, v5, v4
	v_add_u32_e32 v5, 0x2000, v2
	s_add_i32 s4, s4, s5
	v_lshl_or_b32 v3, v6, 10, v3
	v_ashrrev_i32_e32 v6, 31, v5
	s_mul_hi_i32 s5, s4, 0x66666667
	v_lshrrev_b32_e32 v6, 22, v6
	s_lshr_b32 s8, s5, 31
	s_ashr_i32 s21, s5, 5
	v_add_u32_e32 v6, v5, v6
	s_add_i32 s21, s21, s8
	v_ashrrev_i32_e32 v6, 10, v6
	s_mul_i32 s5, s21, 0x50
	v_mul_i32_i24_e32 v7, 0x400, v6
	s_sub_i32 s8, s4, s5
	v_sub_u32_e32 v5, v5, v7
	s_bfe_i32 s4, s8, 0x80000
	v_lshrrev_b32_e32 v7, 4, v5
	s_bfe_u32 s4, s4, 0x3000c
	v_bitop3_b32 v5, v7, v5, 32 bitop3:0x6c
	s_add_i32 s4, s8, s4
	v_ashrrev_i32_e32 v8, 31, v5
	s_bfe_i32 s5, s4, 0x80000
	s_and_b32 s4, s4, 0xf8
	v_lshrrev_b32_e32 v8, 26, v8
	s_sub_i32 s4, s8, s4
	v_add_u32_e32 v8, v5, v8
	s_sext_i32_i8 s22, s4
	v_lshlrev_b32_e32 v7, 3, v6
	v_lshrrev_b32_e32 v9, 6, v8
	v_and_b32_e32 v8, 0xc0, v8
	s_add_i32 s23, s68, 0x110
	s_sext_i32_i16 s5, s5
	s_lshl_b32 s4, s21, 11
	s_lshl_b32 s17, s22, 8
	v_ashrrev_i16_sdwa v4, v187, sext(v4) dst_sel:DWORD dst_unused:UNUSED_PAD src0_sel:DWORD src1_sel:BYTE_0
	v_and_b32_e32 v7, 0x1ffff0, v7
	v_lshlrev_b32_e32 v6, 5, v6
	v_sub_u32_e32 v5, v5, v8
	v_add_u32_e32 v137, s23, v2
	s_ashr_i32 s9, s5, 3
	s_add_i32 s17, s17, s4
	v_bfe_i32 v4, v4, 0, 16
	v_add_u32_e32 v7, v9, v7
	v_and_b32_e32 v6, 32, v6
	v_ashrrev_i16_sdwa v5, v187, sext(v5) dst_sel:DWORD dst_unused:UNUSED_PAD src0_sel:DWORD src1_sel:BYTE_0
	v_readfirstlane_b32 s4, v137
	v_add_u32_e32 v139, 0x2000, v137
	v_bfe_i32 v5, v5, 0, 16
	v_lshl_or_b32 v6, v7, 10, v6
	v_add_lshl_u32 v136, v3, v4, 1
	s_lshl_b32 s19, s9, 19
	s_mov_b32 s14, s78
	s_mov_b32 s15, s79
	s_mov_b32 m0, s4
	v_readfirstlane_b32 s4, v139
	v_add_u32_e32 v140, 0x110, v2
	v_add_lshl_u32 v135, v6, v5, 1
	buffer_load_dwordx4 v136, s[12:15], s19 offen lds
	s_mov_b32 m0, s4
	v_readfirstlane_b32 s4, v140
	v_add_u32_e32 v141, 0x2000, v140
	buffer_load_dwordx4 v135, s[12:15], s19 offen lds
	s_lshl_b32 s24, s17, 11
	s_mov_b32 m0, s4
	v_readfirstlane_b32 s4, v141
	buffer_load_dwordx4 v136, s[76:79], s24 offen lds
	s_mov_b32 m0, s4
	v_readlane_b32 s4, v254, 11
	buffer_load_dwordx4 v135, s[76:79], s24 offen lds
	s_or_b32 s25, s19, 0x40000
	v_add_u32_e32 v142, s4, v2
	v_add_u32_e32 v143, 0x2000, v142
	v_readfirstlane_b32 s4, v142
	s_mov_b32 m0, s4
	v_readfirstlane_b32 s4, v143
	v_add_u32_e32 v144, 0x4000, v140
	buffer_load_dwordx4 v136, s[12:15], s25 offen lds
	s_mov_b32 m0, s4
	s_or_b32 s18, s17, 0x80
	v_readfirstlane_b32 s4, v144
	v_add_u32_e32 v145, 0x6000, v140
	buffer_load_dwordx4 v135, s[12:15], s25 offen lds
	s_lshl_b32 s20, s18, 11
	s_mov_b32 m0, s4
	v_readfirstlane_b32 s4, v145
	buffer_load_dwordx4 v136, s[76:79], s20 offen lds
	s_mov_b32 m0, s4
	v_ashrrev_i32_e32 v3, 8, v0
	buffer_load_dwordx4 v135, s[76:79], s20 offen lds
	v_cmp_eq_u32_e32 vcc, 1, v3
	s_and_saveexec_b64 s[4:5], vcc
	s_cbranch_execz .LBB0_276
	s_barrier
	s_setprio 1

; #define WAIT_L(n) asm volatile("s_waitcnt lgkmcnt(" #n ")" ::: "memory")
; #define BAR __builtin_amdgcn_s_barrier()
; #define SCHED __builtin_amdgcn_sched_barrier(0)
; DEV void gemm_tile(const h16* __restrict__ A, const h16* __restrict__ Bt, int K, int ld, int brow, int bcol, h16* shm, Acc& acc) {
;     ...
;     LDB(B0, 0, 0); SCHED; LDA(At, 0, 0); STAGE(SA(1, 1), rsA, brow + HALF_, t + 1);
;     WAIT_L(8); BAR; WAIT_L(0); MMA(0, 0, At, B0); BAR; SCHED;
;     LDB(B1, 0, 1); STAGE(SB(0, 0), rsB, bcol, t + 2);
;     BAR; WAIT_L(0); MMA(0, 1, At, B1); BAR;
;     LDA(At, 0, 1); STAGE(SA(0, 0), rsA, brow, t + 2);
;     BAR; WAIT_L(0); MMA(1, 0, At, B0); BAR; SCHED;
.LBB0_277:
	ds_read_b128 v[156:159], v155
	ds_read_b128 v[160:163], v155 offset:1024
	ds_read_b128 v[164:167], v155 offset:2048
	ds_read_b128 v[168:171], v155 offset:3072
	s_add_i32 s22, s4, s21
	v_readfirstlane_b32 s15, v153
	s_add_i32 s14, s22, 0x40080
	s_mov_b32 m0, s15
	v_readfirstlane_b32 s15, v152
	ds_read_b128 v[174:177], v133
	ds_read_b128 v[178:181], v133 offset:1024
	ds_read_b128 v[198:201], v132
	ds_read_b128 v[202:205], v132 offset:1024
	ds_read_b128 v[206:209], v131
	ds_read_b128 v[210:213], v131 offset:1024
	ds_read_b128 v[214:217], v130
	ds_read_b128 v[218:221], v130 offset:1024
	buffer_load_dwordx4 v136, s[76:79], s14 offen lds
	s_mov_b32 m0, s15
	s_nop 0
	buffer_load_dwordx4 v135, s[76:79], s14 offen lds
	s_waitcnt lgkmcnt(8)
	s_barrier
	s_waitcnt lgkmcnt(0)
	s_waitcnt lgkmcnt(7)
	v_mfma_f32_16x16x32_f16 v[126:129], v[174:177], v[156:159], v[126:129]
	v_mfma_f32_16x16x32_f16 v[122:125], v[174:177], v[164:167], v[122:125]
	s_waitcnt lgkmcnt(5)
	v_mfma_f32_16x16x32_f16 v[118:121], v[198:201], v[156:159], v[118:121]
	v_mfma_f32_16x16x32_f16 v[114:117], v[198:201], v[164:167], v[114:117]
	s_waitcnt lgkmcnt(3)
	v_mfma_f32_16x16x32_f16 v[110:113], v[206:209], v[156:159], v[110:113]
	v_mfma_f32_16x16x32_f16 v[106:109], v[206:209], v[164:167], v[106:109]
	s_waitcnt lgkmcnt(1)
	v_mfma_f32_16x16x32_f16 v[102:105], v[214:217], v[156:159], v[102:105]
	v_mfma_f32_16x16x32_f16 v[98:101], v[214:217], v[164:167], v[98:101]
	v_mfma_f32_16x16x32_f16 v[126:129], v[178:181], v[160:163], v[126:129]
	v_mfma_f32_16x16x32_f16 v[122:125], v[178:181], v[168:171], v[122:125]
	v_mfma_f32_16x16x32_f16 v[118:121], v[202:205], v[160:163], v[118:121]
	v_mfma_f32_16x16x32_f16 v[114:117], v[202:205], v[168:171], v[114:117]
	v_mfma_f32_16x16x32_f16 v[110:113], v[210:213], v[160:163], v[110:113]
	v_mfma_f32_16x16x32_f16 v[106:109], v[210:213], v[168:171], v[106:109]
	s_waitcnt lgkmcnt(0)
	v_mfma_f32_16x16x32_f16 v[102:105], v[218:221], v[160:163], v[102:105]
	v_mfma_f32_16x16x32_f16 v[98:101], v[218:221], v[168:171], v[98:101]
	s_barrier
	s_add_i32 s23, s19, s21
	v_readfirstlane_b32 s25, v137
	s_add_i32 s24, s23, 0x100
	s_mov_b32 s14, s78
	s_mov_b32 s15, s79
	s_mov_b32 m0, s25
	v_readfirstlane_b32 s25, v139
	ds_read_b128 v[222:225], v150
	ds_read_b128 v[226:229], v150 offset:1024
	ds_read_b128 v[230:233], v150 offset:2048
	ds_read_b128 v[234:237], v150 offset:3072
	buffer_load_dwordx4 v136, s[12:15], s24 offen lds
	s_mov_b32 m0, s25
	s_nop 0
	buffer_load_dwordx4 v135, s[12:15], s24 offen lds
	s_barrier
	s_waitcnt lgkmcnt(0)
	s_waitcnt lgkmcnt(3)
	v_mfma_f32_16x16x32_f16 v[94:97], v[174:177], v[222:225], v[94:97]
	s_waitcnt lgkmcnt(1)
	v_mfma_f32_16x16x32_f16 v[90:93], v[174:177], v[230:233], v[90:93]
	v_mfma_f32_16x16x32_f16 v[86:89], v[198:201], v[222:225], v[86:89]
	v_mfma_f32_16x16x32_f16 v[82:85], v[198:201], v[230:233], v[82:85]
	v_mfma_f32_16x16x32_f16 v[78:81], v[206:209], v[222:225], v[78:81]
	v_mfma_f32_16x16x32_f16 v[74:77], v[206:209], v[230:233], v[74:77]
	v_mfma_f32_16x16x32_f16 v[70:73], v[214:217], v[222:225], v[70:73]
	v_mfma_f32_16x16x32_f16 v[66:69], v[214:217], v[230:233], v[66:69]
	v_mfma_f32_16x16x32_f16 v[94:97], v[178:181], v[226:229], v[94:97]
	s_waitcnt lgkmcnt(0)
	v_mfma_f32_16x16x32_f16 v[90:93], v[178:181], v[234:237], v[90:93]
	v_mfma_f32_16x16x32_f16 v[86:89], v[202:205], v[226:229], v[86:89]
	v_mfma_f32_16x16x32_f16 v[82:85], v[202:205], v[234:237], v[82:85]
	v_mfma_f32_16x16x32_f16 v[78:81], v[210:213], v[226:229], v[78:81]
	v_mfma_f32_16x16x32_f16 v[74:77], v[210:213], v[234:237], v[74:77]
	v_mfma_f32_16x16x32_f16 v[70:73], v[218:221], v[226:229], v[70:73]
	v_mfma_f32_16x16x32_f16 v[66:69], v[218:221], v[234:237], v[66:69]
	v_readfirstlane_b32 s25, v140
	s_add_i32 s24, s22, 0x100
	s_mov_b32 m0, s25
	v_readfirstlane_b32 s25, v141
	s_barrier
	ds_read_b128 v[174:177], v133 offset:16384
	ds_read_b128 v[178:181], v133 offset:17408
	ds_read_b128 v[198:201], v132 offset:16384
	ds_read_b128 v[202:205], v132 offset:17408
	ds_read_b128 v[206:209], v131 offset:16384
	ds_read_b128 v[210:213], v131 offset:17408
	ds_read_b128 v[214:217], v130 offset:16384
	ds_read_b128 v[218:221], v130 offset:17408
	buffer_load_dwordx4 v136, s[76:79], s24 offen lds
	s_mov_b32 m0, s25
	s_nop 0
	buffer_load_dwordx4 v135, s[76:79], s24 offen lds
	s_barrier
	s_waitcnt lgkmcnt(0)
	s_waitcnt lgkmcnt(7)
	v_mfma_f32_16x16x32_f16 v[62:65], v[174:177], v[156:159], v[62:65]
	v_mfma_f32_16x16x32_f16 v[58:61], v[174:177], v[164:167], v[58:61]
	s_waitcnt lgkmcnt(5)
	v_mfma_f32_16x16x32_f16 v[54:57], v[198:201], v[156:159], v[54:57]
	v_mfma_f32_16x16x32_f16 v[50:53], v[198:201], v[164:167], v[50:53]
	s_waitcnt lgkmcnt(3)
	v_mfma_f32_16x16x32_f16 v[46:49], v[206:209], v[156:159], v[46:49]
	v_mfma_f32_16x16x32_f16 v[42:45], v[206:209], v[164:167], v[42:45]
	s_waitcnt lgkmcnt(1)
	v_mfma_f32_16x16x32_f16 v[38:41], v[214:217], v[156:159], v[38:41]
	v_mfma_f32_16x16x32_f16 v[34:37], v[214:217], v[164:167], v[34:37]
	v_mfma_f32_16x16x32_f16 v[62:65], v[178:181], v[160:163], v[62:65]
	v_mfma_f32_16x16x32_f16 v[58:61], v[178:181], v[168:171], v[58:61]
	v_mfma_f32_16x16x32_f16 v[54:57], v[202:205], v[160:163], v[54:57]
	v_mfma_f32_16x16x32_f16 v[50:53], v[202:205], v[168:171], v[50:53]
	v_mfma_f32_16x16x32_f16 v[46:49], v[210:213], v[160:163], v[46:49]
	v_mfma_f32_16x16x32_f16 v[42:45], v[210:213], v[168:171], v[42:45]
	s_waitcnt lgkmcnt(0)
	v_mfma_f32_16x16x32_f16 v[38:41], v[218:221], v[160:163], v[38:41]
	v_mfma_f32_16x16x32_f16 v[34:37], v[218:221], v[168:171], v[34:37]
	s_barrier
; #define WAIT_V(n) asm volatile("s_waitcnt vmcnt(" #n ")" ::: "memory")
; #define WAIT_L(n) asm volatile("s_waitcnt lgkmcnt(" #n ")" ::: "memory")
; #define BAR __builtin_amdgcn_s_barrier()
; #define SCHED __builtin_amdgcn_sched_barrier(0)
; DEV void gemm_tile(const h16* __restrict__ A, const h16* __restrict__ Bt, int K, int ld, int brow, int bcol, h16* shm, Acc& acc) {
;     ...
;     STAGE(SB(0, 1), rsB, bcol + HALF_, t + 2);
;     WAIT_V(6); BAR; MMA(1, 1, At, B1); BAR;
;     LDB(B0, 1, 0); SCHED; LDA(At, 1, 0); STAGE(SA(0, 1), rsA, brow + HALF_, t + 2);
;     WAIT_L(8); BAR; WAIT_L(0); MMA(0, 0, At, B0); BAR; SCHED;
;     LDB(B1, 1, 1); STAGE(SB(1, 0), rsB, bcol, t + 3);
;     BAR; WAIT_L(0); MMA(0, 1, At, B1); BAR;
;     LDA(At, 1, 1); STAGE(SA(1, 0), rsA, brow, t + 3);
	v_readfirstlane_b32 s25, v142
	s_add_i32 s24, s23, 0x40100
	s_mov_b32 m0, s25
	v_readfirstlane_b32 s25, v143
	buffer_load_dwordx4 v136, s[12:15], s24 offen lds
	s_mov_b32 m0, s25
	s_nop 0
	buffer_load_dwordx4 v135, s[12:15], s24 offen lds
	s_waitcnt vmcnt(6)
	s_barrier
	v_mfma_f32_16x16x32_f16 v[30:33], v[174:177], v[222:225], v[30:33]
	v_mfma_f32_16x16x32_f16 v[26:29], v[174:177], v[230:233], v[26:29]
	v_mfma_f32_16x16x32_f16 v[22:25], v[198:201], v[222:225], v[22:25]
	v_mfma_f32_16x16x32_f16 v[18:21], v[198:201], v[230:233], v[18:21]
	v_mfma_f32_16x16x32_f16 v[14:17], v[206:209], v[222:225], v[14:17]
	v_mfma_f32_16x16x32_f16 v[10:13], v[206:209], v[230:233], v[10:13]
	v_mfma_f32_16x16x32_f16 v[6:9], v[214:217], v[222:225], v[6:9]
	v_mfma_f32_16x16x32_f16 v[2:5], v[214:217], v[230:233], v[2:5]
	v_mfma_f32_16x16x32_f16 v[30:33], v[178:181], v[226:229], v[30:33]
	v_mfma_f32_16x16x32_f16 v[26:29], v[178:181], v[234:237], v[26:29]
	v_mfma_f32_16x16x32_f16 v[22:25], v[202:205], v[226:229], v[22:25]
	v_mfma_f32_16x16x32_f16 v[18:21], v[202:205], v[234:237], v[18:21]
	v_mfma_f32_16x16x32_f16 v[14:17], v[210:213], v[226:229], v[14:17]
	v_mfma_f32_16x16x32_f16 v[10:13], v[210:213], v[234:237], v[10:13]
	v_mfma_f32_16x16x32_f16 v[6:9], v[218:221], v[226:229], v[6:9]
	v_mfma_f32_16x16x32_f16 v[2:5], v[218:221], v[234:237], v[2:5]
	s_barrier
	ds_read_b128 v[156:159], v138
	ds_read_b128 v[160:163], v138 offset:1024
	ds_read_b128 v[164:167], v138 offset:2048
	ds_read_b128 v[168:171], v138 offset:3072
	v_readfirstlane_b32 s25, v144
	s_add_i32 s24, s22, 0x40100
	s_mov_b32 m0, s25
	v_readfirstlane_b32 s25, v145
	ds_read_b128 v[174:177], v133 offset:32768
	ds_read_b128 v[178:181], v133 offset:33792
	ds_read_b128 v[198:201], v132 offset:32768
	ds_read_b128 v[202:205], v132 offset:33792
	ds_read_b128 v[206:209], v131 offset:32768
	ds_read_b128 v[210:213], v131 offset:33792
	ds_read_b128 v[214:217], v130 offset:32768
	ds_read_b128 v[218:221], v130 offset:33792
	buffer_load_dwordx4 v136, s[76:79], s24 offen lds
	s_mov_b32 m0, s25
	s_nop 0
	buffer_load_dwordx4 v135, s[76:79], s24 offen lds
	s_waitcnt lgkmcnt(8)
	s_barrier
	s_waitcnt lgkmcnt(0)
	s_waitcnt lgkmcnt(7)
	v_mfma_f32_16x16x32_f16 v[126:129], v[174:177], v[156:159], v[126:129]
	v_mfma_f32_16x16x32_f16 v[122:125], v[174:177], v[164:167], v[122:125]
	s_waitcnt lgkmcnt(5)
	v_mfma_f32_16x16x32_f16 v[118:121], v[198:201], v[156:159], v[118:121]
	v_mfma_f32_16x16x32_f16 v[114:117], v[198:201], v[164:167], v[114:117]
	s_waitcnt lgkmcnt(3)
	v_mfma_f32_16x16x32_f16 v[110:113], v[206:209], v[156:159], v[110:113]
	v_mfma_f32_16x16x32_f16 v[106:109], v[206:209], v[164:167], v[106:109]
	s_waitcnt lgkmcnt(1)
	v_mfma_f32_16x16x32_f16 v[102:105], v[214:217], v[156:159], v[102:105]
	v_mfma_f32_16x16x32_f16 v[98:101], v[214:217], v[164:167], v[98:101]
	v_mfma_f32_16x16x32_f16 v[126:129], v[178:181], v[160:163], v[126:129]
	v_mfma_f32_16x16x32_f16 v[122:125], v[178:181], v[168:171], v[122:125]
	v_mfma_f32_16x16x32_f16 v[118:121], v[202:205], v[160:163], v[118:121]
	v_mfma_f32_16x16x32_f16 v[114:117], v[202:205], v[168:171], v[114:117]
	v_mfma_f32_16x16x32_f16 v[110:113], v[210:213], v[160:163], v[110:113]
	v_mfma_f32_16x16x32_f16 v[106:109], v[210:213], v[168:171], v[106:109]
	s_waitcnt lgkmcnt(0)
	v_mfma_f32_16x16x32_f16 v[102:105], v[218:221], v[160:163], v[102:105]
	v_mfma_f32_16x16x32_f16 v[98:101], v[218:221], v[168:171], v[98:101]
	s_barrier
	v_readfirstlane_b32 s25, v146
	s_add_i32 s24, s23, 0x180
	s_mov_b32 m0, s25
	v_readfirstlane_b32 s25, v147
	ds_read_b128 v[222:225], v134
	ds_read_b128 v[226:229], v134 offset:1024
	ds_read_b128 v[230:233], v134 offset:2048
	ds_read_b128 v[234:237], v134 offset:3072
	buffer_load_dwordx4 v136, s[12:15], s24 offen lds
	s_mov_b32 m0, s25
	s_nop 0
	buffer_load_dwordx4 v135, s[12:15], s24 offen lds
	s_barrier
	s_waitcnt lgkmcnt(0)
	s_waitcnt lgkmcnt(3)
	v_mfma_f32_16x16x32_f16 v[94:97], v[174:177], v[222:225], v[94:97]
	s_waitcnt lgkmcnt(1)
	v_mfma_f32_16x16x32_f16 v[90:93], v[174:177], v[230:233], v[90:93]
	v_mfma_f32_16x16x32_f16 v[86:89], v[198:201], v[222:225], v[86:89]
	v_mfma_f32_16x16x32_f16 v[82:85], v[198:201], v[230:233], v[82:85]
	v_mfma_f32_16x16x32_f16 v[78:81], v[206:209], v[222:225], v[78:81]
	v_mfma_f32_16x16x32_f16 v[74:77], v[206:209], v[230:233], v[74:77]
	v_mfma_f32_16x16x32_f16 v[70:73], v[214:217], v[222:225], v[70:73]
	v_mfma_f32_16x16x32_f16 v[66:69], v[214:217], v[230:233], v[66:69]
	v_mfma_f32_16x16x32_f16 v[94:97], v[178:181], v[226:229], v[94:97]
	s_waitcnt lgkmcnt(0)
	v_mfma_f32_16x16x32_f16 v[90:93], v[178:181], v[234:237], v[90:93]
	v_mfma_f32_16x16x32_f16 v[86:89], v[202:205], v[226:229], v[86:89]
	v_mfma_f32_16x16x32_f16 v[82:85], v[202:205], v[234:237], v[82:85]
	v_mfma_f32_16x16x32_f16 v[78:81], v[210:213], v[226:229], v[78:81]
	v_mfma_f32_16x16x32_f16 v[74:77], v[210:213], v[234:237], v[74:77]
	v_mfma_f32_16x16x32_f16 v[70:73], v[218:221], v[226:229], v[70:73]
	v_mfma_f32_16x16x32_f16 v[66:69], v[218:221], v[234:237], v[66:69]
	v_readfirstlane_b32 s24, v148
	s_addk_i32 s22, 0x180
	s_mov_b32 m0, s24
	v_readfirstlane_b32 s24, v149
	s_barrier
	ds_read_b128 v[174:177], v133 offset:49152
	ds_read_b128 v[178:181], v133 offset:50176
	ds_read_b128 v[198:201], v132 offset:49152
	ds_read_b128 v[202:205], v132 offset:50176
	ds_read_b128 v[206:209], v131 offset:49152
	ds_read_b128 v[210:213], v131 offset:50176
	ds_read_b128 v[214:217], v130 offset:49152
	ds_read_b128 v[218:221], v130 offset:50176
	buffer_load_dwordx4 v136, s[76:79], s22 offen lds
	s_mov_b32 m0, s24
	s_nop 0
	buffer_load_dwordx4 v135, s[76:79], s22 offen lds
	s_barrier
; #define WAIT_V(n) asm volatile("s_waitcnt vmcnt(" #n ")" ::: "memory")
; #define WAIT_L(n) asm volatile("s_waitcnt lgkmcnt(" #n ")" ::: "memory")
; #define BAR __builtin_amdgcn_s_barrier()
; #define SCHED __builtin_amdgcn_sched_barrier(0)
; DEV void gemm_tile(const h16* __restrict__ A, const h16* __restrict__ Bt, int K, int ld, int brow, int bcol, h16* shm, Acc& acc) {
;     ...
;     WAIT_L(8); BAR; WAIT_L(0); MMA(0, 0, At, B0); BAR; SCHED;
;     LDB(B1, 1, 1); STAGE(SB(1, 0), rsB, bcol, t + 3);
;     BAR; WAIT_L(0); MMA(0, 1, At, B1); BAR;
;     LDA(At, 1, 1); STAGE(SA(1, 0), rsA, brow, t + 3);
;     BAR; WAIT_L(0); MMA(1, 0, At, B0); BAR; SCHED;
;     STAGE(SB(1, 1), rsB, bcol + HALF_, t + 3);
;     WAIT_V(6); BAR; MMA(1, 1, At, B1); BAR;
;   }
;   { LDB(B0, 0, 0); LDA(At, 0, 0); STAGE(SA(1, 1), rsA, brow + HALF_, nt - 1);
;     BAR; WAIT_L(0); MMA(0, 0, At, B0); BAR;
;     LDB(B1, 0, 1); BAR; WAIT_L(0); MMA(0, 1, At, B1); BAR;
	s_waitcnt lgkmcnt(0)
	s_waitcnt lgkmcnt(7)
	v_mfma_f32_16x16x32_f16 v[62:65], v[174:177], v[156:159], v[62:65]
	v_mfma_f32_16x16x32_f16 v[58:61], v[174:177], v[164:167], v[58:61]
	s_waitcnt lgkmcnt(5)
	v_mfma_f32_16x16x32_f16 v[54:57], v[198:201], v[156:159], v[54:57]
	v_mfma_f32_16x16x32_f16 v[50:53], v[198:201], v[164:167], v[50:53]
	s_waitcnt lgkmcnt(3)
	v_mfma_f32_16x16x32_f16 v[46:49], v[206:209], v[156:159], v[46:49]
	v_mfma_f32_16x16x32_f16 v[42:45], v[206:209], v[164:167], v[42:45]
	s_waitcnt lgkmcnt(1)
	v_mfma_f32_16x16x32_f16 v[38:41], v[214:217], v[156:159], v[38:41]
	v_mfma_f32_16x16x32_f16 v[34:37], v[214:217], v[164:167], v[34:37]
	v_mfma_f32_16x16x32_f16 v[62:65], v[178:181], v[160:163], v[62:65]
	v_mfma_f32_16x16x32_f16 v[58:61], v[178:181], v[168:171], v[58:61]
	v_mfma_f32_16x16x32_f16 v[54:57], v[202:205], v[160:163], v[54:57]
	v_mfma_f32_16x16x32_f16 v[50:53], v[202:205], v[168:171], v[50:53]
	v_mfma_f32_16x16x32_f16 v[46:49], v[210:213], v[160:163], v[46:49]
	v_mfma_f32_16x16x32_f16 v[42:45], v[210:213], v[168:171], v[42:45]
	s_waitcnt lgkmcnt(0)
	v_mfma_f32_16x16x32_f16 v[38:41], v[218:221], v[160:163], v[38:41]
	v_mfma_f32_16x16x32_f16 v[34:37], v[218:221], v[168:171], v[34:37]
	s_barrier
	v_readfirstlane_b32 s22, v151
	s_add_i32 s23, s23, 0x40180
	s_mov_b32 m0, s22
	v_readfirstlane_b32 s22, v154
	buffer_load_dwordx4 v136, s[12:15], s23 offen lds
	s_mov_b32 m0, s22
	s_nop 0
	buffer_load_dwordx4 v135, s[12:15], s23 offen lds
	s_waitcnt vmcnt(6)
	s_barrier
	v_mfma_f32_16x16x32_f16 v[30:33], v[174:177], v[222:225], v[30:33]
	v_mfma_f32_16x16x32_f16 v[26:29], v[174:177], v[230:233], v[26:29]
	v_mfma_f32_16x16x32_f16 v[22:25], v[198:201], v[222:225], v[22:25]
	v_mfma_f32_16x16x32_f16 v[18:21], v[198:201], v[230:233], v[18:21]
	v_mfma_f32_16x16x32_f16 v[14:17], v[206:209], v[222:225], v[14:17]
	v_mfma_f32_16x16x32_f16 v[10:13], v[206:209], v[230:233], v[10:13]
	v_mfma_f32_16x16x32_f16 v[6:9], v[214:217], v[222:225], v[6:9]
	v_mfma_f32_16x16x32_f16 v[2:5], v[214:217], v[230:233], v[2:5]
	v_mfma_f32_16x16x32_f16 v[30:33], v[178:181], v[226:229], v[30:33]
	v_mfma_f32_16x16x32_f16 v[26:29], v[178:181], v[234:237], v[26:29]
	v_mfma_f32_16x16x32_f16 v[22:25], v[202:205], v[226:229], v[22:25]
	v_mfma_f32_16x16x32_f16 v[18:21], v[202:205], v[234:237], v[18:21]
	v_mfma_f32_16x16x32_f16 v[14:17], v[210:213], v[226:229], v[14:17]
	v_mfma_f32_16x16x32_f16 v[10:13], v[210:213], v[234:237], v[10:13]
	v_mfma_f32_16x16x32_f16 v[6:9], v[218:221], v[226:229], v[6:9]
	v_mfma_f32_16x16x32_f16 v[2:5], v[218:221], v[234:237], v[2:5]
	s_add_i32 s5, s5, 2
	s_addk_i32 s21, 0x100
	s_cmp_lt_u32 s5, 12
	s_barrier
	s_cbranch_scc1 .LBB0_277
	v_readfirstlane_b32 s5, v153
	s_or_b32 s4, s20, 0x780
	s_mov_b32 m0, s5
	v_readfirstlane_b32 s5, v152
	ds_read_b128 v[140:143], v155
	ds_read_b128 v[144:147], v155 offset:1024
	ds_read_b128 v[156:159], v155 offset:2048
	ds_read_b128 v[160:163], v155 offset:3072
	ds_read_b128 v[164:167], v133
	ds_read_b128 v[168:171], v133 offset:1024
	ds_read_b128 v[174:177], v132
	ds_read_b128 v[178:181], v132 offset:1024
	ds_read_b128 v[198:201], v131
	ds_read_b128 v[202:205], v131 offset:1024
	ds_read_b128 v[206:209], v130
	ds_read_b128 v[210:213], v130 offset:1024
	buffer_load_dwordx4 v136, s[76:79], s4 offen lds
	s_mov_b32 m0, s5
	s_nop 0
	buffer_load_dwordx4 v135, s[76:79], s4 offen lds
	s_barrier
	s_waitcnt lgkmcnt(0)
	s_waitcnt lgkmcnt(7)
	v_mfma_f32_16x16x32_f16 v[126:129], v[164:167], v[140:143], v[126:129]
	v_mfma_f32_16x16x32_f16 v[122:125], v[164:167], v[156:159], v[122:125]
	s_waitcnt lgkmcnt(5)
	v_mfma_f32_16x16x32_f16 v[118:121], v[174:177], v[140:143], v[118:121]
	v_mfma_f32_16x16x32_f16 v[114:117], v[174:177], v[156:159], v[114:117]
	v_mfma_f32_16x16x32_f16 v[126:129], v[168:171], v[144:147], v[126:129]
	v_mfma_f32_16x16x32_f16 v[122:125], v[168:171], v[160:163], v[122:125]
	s_waitcnt lgkmcnt(4)
	v_mfma_f32_16x16x32_f16 v[118:121], v[178:181], v[144:147], v[118:121]
	v_mfma_f32_16x16x32_f16 v[114:117], v[178:181], v[160:163], v[114:117]
	s_waitcnt lgkmcnt(3)
	v_mfma_f32_16x16x32_f16 v[110:113], v[198:201], v[140:143], v[110:113]
	v_mfma_f32_16x16x32_f16 v[106:109], v[198:201], v[156:159], v[106:109]
	s_waitcnt lgkmcnt(1)
	v_mfma_f32_16x16x32_f16 v[102:105], v[206:209], v[140:143], v[102:105]
	v_mfma_f32_16x16x32_f16 v[98:101], v[206:209], v[156:159], v[98:101]
	v_mfma_f32_16x16x32_f16 v[152:155], v[202:205], v[144:147], v[110:113]
	v_mfma_f32_16x16x32_f16 v[214:217], v[202:205], v[160:163], v[106:109]
	s_waitcnt lgkmcnt(0)
	v_mfma_f32_16x16x32_f16 v[218:221], v[210:213], v[144:147], v[102:105]
	v_mfma_f32_16x16x32_f16 v[222:225], v[210:213], v[160:163], v[98:101]
	s_barrier
	s_nop 0
	ds_read_b128 v[98:101], v150
	ds_read_b128 v[102:105], v150 offset:1024
	ds_read_b128 v[106:109], v150 offset:2048
	ds_read_b128 v[110:113], v150 offset:3072
	s_barrier
	s_waitcnt lgkmcnt(0)
	s_waitcnt lgkmcnt(3)
	v_mfma_f32_16x16x32_f16 v[94:97], v[164:167], v[98:101], v[94:97]
	s_waitcnt lgkmcnt(1)
	v_mfma_f32_16x16x32_f16 v[90:93], v[164:167], v[106:109], v[90:93]
	v_mfma_f32_16x16x32_f16 v[86:89], v[174:177], v[98:101], v[86:89]
	v_mfma_f32_16x16x32_f16 v[82:85], v[174:177], v[106:109], v[82:85]
	v_mfma_f32_16x16x32_f16 v[94:97], v[168:171], v[102:105], v[94:97]
	s_waitcnt lgkmcnt(0)
	v_mfma_f32_16x16x32_f16 v[90:93], v[168:171], v[110:113], v[90:93]
	v_mfma_f32_16x16x32_f16 v[86:89], v[178:181], v[102:105], v[86:89]
	v_mfma_f32_16x16x32_f16 v[82:85], v[178:181], v[110:113], v[82:85]
	v_mfma_f32_16x16x32_f16 v[78:81], v[198:201], v[98:101], v[78:81]
	v_mfma_f32_16x16x32_f16 v[74:77], v[198:201], v[106:109], v[74:77]
	v_mfma_f32_16x16x32_f16 v[70:73], v[206:209], v[98:101], v[70:73]
	v_mfma_f32_16x16x32_f16 v[66:69], v[206:209], v[106:109], v[66:69]
	v_mfma_f32_16x16x32_f16 v[148:151], v[202:205], v[102:105], v[78:81]
	v_mfma_f32_16x16x32_f16 v[164:167], v[202:205], v[110:113], v[74:77]
	v_mfma_f32_16x16x32_f16 v[168:171], v[210:213], v[102:105], v[70:73]
	v_mfma_f32_16x16x32_f16 v[174:177], v[210:213], v[110:113], v[66:69]
	s_barrier
; #define WAIT_V(n) asm volatile("s_waitcnt vmcnt(" #n ")" ::: "memory")
; #define WAIT_L(n) asm volatile("s_waitcnt lgkmcnt(" #n ")" ::: "memory")
; #define BAR __builtin_amdgcn_s_barrier()
; DEV void gemm_tile(const h16* __restrict__ A, const h16* __restrict__ Bt, int K, int ld, int brow, int bcol, h16* shm, Acc& acc) {
;     ...
;     LDA(At, 0, 1); WAIT_V(4); BAR; WAIT_L(0); MMA(1, 0, At, B0); MMA(1, 1, At, B1); BAR; }
;   { LDB(B0, 1, 0); LDA(At, 1, 0); WAIT_V(2); BAR; WAIT_L(0); MMA(0, 0, At, B0); BAR;
	s_nop 1
	ds_read_b128 v[66:69], v133 offset:16384
	ds_read_b128 v[70:73], v133 offset:17408
	ds_read_b128 v[74:77], v132 offset:16384
	ds_read_b128 v[78:81], v132 offset:17408
	ds_read_b128 v[178:181], v131 offset:16384
	ds_read_b128 v[198:201], v131 offset:17408
	ds_read_b128 v[202:205], v130 offset:16384
	ds_read_b128 v[206:209], v130 offset:17408
	s_waitcnt vmcnt(4)
	s_barrier
	s_waitcnt lgkmcnt(0)
	s_waitcnt lgkmcnt(7)
	v_mfma_f32_16x16x32_f16 v[62:65], v[66:69], v[140:143], v[62:65]
	v_mfma_f32_16x16x32_f16 v[58:61], v[66:69], v[156:159], v[58:61]
	s_waitcnt lgkmcnt(5)
	v_mfma_f32_16x16x32_f16 v[54:57], v[74:77], v[140:143], v[54:57]
	v_mfma_f32_16x16x32_f16 v[50:53], v[74:77], v[156:159], v[50:53]
	v_mfma_f32_16x16x32_f16 v[62:65], v[70:73], v[144:147], v[62:65]
	v_mfma_f32_16x16x32_f16 v[58:61], v[70:73], v[160:163], v[58:61]
	s_waitcnt lgkmcnt(4)
	v_mfma_f32_16x16x32_f16 v[54:57], v[78:81], v[144:147], v[54:57]
	v_mfma_f32_16x16x32_f16 v[50:53], v[78:81], v[160:163], v[50:53]
	s_waitcnt lgkmcnt(3)
	v_mfma_f32_16x16x32_f16 v[46:49], v[178:181], v[140:143], v[46:49]
	v_mfma_f32_16x16x32_f16 v[42:45], v[178:181], v[156:159], v[42:45]
	s_waitcnt lgkmcnt(1)
	v_mfma_f32_16x16x32_f16 v[38:41], v[202:205], v[140:143], v[38:41]
	v_mfma_f32_16x16x32_f16 v[34:37], v[202:205], v[156:159], v[34:37]
	v_mfma_f32_16x16x32_f16 v[210:213], v[198:201], v[144:147], v[46:49]
	v_mfma_f32_16x16x32_f16 v[226:229], v[198:201], v[160:163], v[42:45]
	s_waitcnt lgkmcnt(0)
	v_mfma_f32_16x16x32_f16 v[140:143], v[206:209], v[144:147], v[38:41]
	v_mfma_f32_16x16x32_f16 v[144:147], v[206:209], v[160:163], v[34:37]
	v_mfma_f32_16x16x32_f16 v[30:33], v[66:69], v[98:101], v[30:33]
	v_mfma_f32_16x16x32_f16 v[26:29], v[66:69], v[106:109], v[26:29]
	v_mfma_f32_16x16x32_f16 v[22:25], v[74:77], v[98:101], v[22:25]
	v_mfma_f32_16x16x32_f16 v[18:21], v[74:77], v[106:109], v[18:21]
	v_mfma_f32_16x16x32_f16 v[30:33], v[70:73], v[102:105], v[30:33]
	v_mfma_f32_16x16x32_f16 v[26:29], v[70:73], v[110:113], v[26:29]
	v_mfma_f32_16x16x32_f16 v[22:25], v[78:81], v[102:105], v[22:25]
	v_mfma_f32_16x16x32_f16 v[18:21], v[78:81], v[110:113], v[18:21]
	v_mfma_f32_16x16x32_f16 v[14:17], v[178:181], v[98:101], v[14:17]
	v_mfma_f32_16x16x32_f16 v[10:13], v[178:181], v[106:109], v[10:13]
	v_mfma_f32_16x16x32_f16 v[6:9], v[202:205], v[98:101], v[6:9]
	v_mfma_f32_16x16x32_f16 v[2:5], v[202:205], v[106:109], v[2:5]
	v_mfma_f32_16x16x32_f16 v[156:159], v[198:201], v[102:105], v[14:17]
	v_mfma_f32_16x16x32_f16 v[160:163], v[198:201], v[110:113], v[10:13]
	v_mfma_f32_16x16x32_f16 v[178:181], v[206:209], v[102:105], v[6:9]
	v_mfma_f32_16x16x32_f16 v[198:201], v[206:209], v[110:113], v[2:5]
	s_barrier
	s_nop 1
	ds_read_b128 v[2:5], v138
	ds_read_b128 v[6:9], v138 offset:1024
	ds_read_b128 v[202:205], v138 offset:2048
	ds_read_b128 v[136:139], v138 offset:3072
	ds_read_b128 v[10:13], v133 offset:32768
	ds_read_b128 v[14:17], v133 offset:33792
	ds_read_b128 v[34:37], v132 offset:32768
	ds_read_b128 v[38:41], v132 offset:33792
	ds_read_b128 v[42:45], v131 offset:32768
	ds_read_b128 v[46:49], v131 offset:33792
	ds_read_b128 v[206:209], v130 offset:32768
	ds_read_b128 v[230:233], v130 offset:33792
	s_waitcnt vmcnt(2)
	s_barrier
	s_waitcnt lgkmcnt(0)
	s_waitcnt lgkmcnt(7)
	v_mfma_f32_16x16x32_f16 v[66:69], v[10:13], v[2:5], v[126:129]
	s_waitcnt lgkmcnt(6)
	v_mfma_f32_16x16x32_f16 v[106:109], v[14:17], v[6:9], v[66:69]
	v_mfma_f32_16x16x32_f16 v[66:69], v[10:13], v[202:205], v[122:125]
	v_mfma_f32_16x16x32_f16 v[110:113], v[14:17], v[136:139], v[66:69]
	s_waitcnt lgkmcnt(5)
	v_mfma_f32_16x16x32_f16 v[66:69], v[34:37], v[2:5], v[118:121]
	s_waitcnt lgkmcnt(4)
	v_mfma_f32_16x16x32_f16 v[98:101], v[38:41], v[6:9], v[66:69]
	v_mfma_f32_16x16x32_f16 v[66:69], v[34:37], v[202:205], v[114:117]
	v_mfma_f32_16x16x32_f16 v[102:105], v[38:41], v[136:139], v[66:69]
	s_waitcnt lgkmcnt(3)
	v_mfma_f32_16x16x32_f16 v[66:69], v[42:45], v[2:5], v[152:155]
	s_waitcnt lgkmcnt(2)
	v_mfma_f32_16x16x32_f16 v[74:77], v[46:49], v[6:9], v[66:69]
	v_mfma_f32_16x16x32_f16 v[66:69], v[42:45], v[202:205], v[214:217]
	v_mfma_f32_16x16x32_f16 v[78:81], v[46:49], v[136:139], v[66:69]
	s_waitcnt lgkmcnt(1)
	v_mfma_f32_16x16x32_f16 v[66:69], v[206:209], v[2:5], v[218:221]
	v_mfma_f32_16x16x32_f16 v[70:73], v[206:209], v[202:205], v[222:225]
	s_waitcnt lgkmcnt(0)
	v_mfma_f32_16x16x32_f16 v[66:69], v[230:233], v[6:9], v[66:69]
	v_mfma_f32_16x16x32_f16 v[70:73], v[230:233], v[136:139], v[70:73]
	s_barrier
; #define WAIT_V(n) asm volatile("s_waitcnt vmcnt(" #n ")" ::: "memory")
; #define WAIT_L(n) asm volatile("s_waitcnt lgkmcnt(" #n ")" ::: "memory")
; #define BAR __builtin_amdgcn_s_barrier()
; DEV void gemm_tile(const h16* __restrict__ A, const h16* __restrict__ Bt, int K, int ld, int brow, int bcol, h16* shm, Acc& acc) {
;     ...
;     LDB(B1, 1, 1); WAIT_V(0); BAR; WAIT_L(0); MMA(0, 1, At, B1); BAR;
;     LDA(At, 1, 1); BAR; WAIT_L(0); MMA(1, 0, At, B0); MMA(1, 1, At, B1); BAR; }
;   if (wr == 0) BAR;
	ds_read_b128 v[152:155], v134
	ds_read_b128 v[214:217], v134 offset:1024
	ds_read_b128 v[218:221], v134 offset:2048
	ds_read_b128 v[222:225], v134 offset:3072
	s_waitcnt vmcnt(0)
	s_barrier
	s_waitcnt lgkmcnt(0)
	s_waitcnt lgkmcnt(3)
	v_mfma_f32_16x16x32_f16 v[94:97], v[10:13], v[152:155], v[94:97]
	s_waitcnt lgkmcnt(1)
	v_mfma_f32_16x16x32_f16 v[10:13], v[10:13], v[218:221], v[90:93]
	s_waitcnt lgkmcnt(0)
	v_mfma_f32_16x16x32_f16 v[126:129], v[14:17], v[222:225], v[10:13]
	v_mfma_f32_16x16x32_f16 v[10:13], v[34:37], v[152:155], v[86:89]
	v_mfma_f32_16x16x32_f16 v[114:117], v[38:41], v[214:217], v[10:13]
	v_mfma_f32_16x16x32_f16 v[10:13], v[34:37], v[218:221], v[82:85]
	v_mfma_f32_16x16x32_f16 v[118:121], v[38:41], v[222:225], v[10:13]
	v_mfma_f32_16x16x32_f16 v[10:13], v[42:45], v[152:155], v[148:151]
	v_mfma_f32_16x16x32_f16 v[90:93], v[46:49], v[214:217], v[10:13]
	v_mfma_f32_16x16x32_f16 v[10:13], v[42:45], v[218:221], v[164:167]
	v_mfma_f32_16x16x32_f16 v[122:125], v[14:17], v[214:217], v[94:97]
	v_mfma_f32_16x16x32_f16 v[94:97], v[46:49], v[222:225], v[10:13]
	v_mfma_f32_16x16x32_f16 v[10:13], v[206:209], v[152:155], v[168:171]
	v_mfma_f32_16x16x32_f16 v[82:85], v[230:233], v[214:217], v[10:13]
	v_mfma_f32_16x16x32_f16 v[10:13], v[206:209], v[218:221], v[174:177]
	v_mfma_f32_16x16x32_f16 v[86:89], v[230:233], v[222:225], v[10:13]
	s_barrier
	ds_read_b128 v[148:151], v133 offset:49152
	ds_read_b128 v[164:167], v133 offset:50176
	ds_read_b128 v[168:171], v132 offset:49152
	ds_read_b128 v[132:135], v132 offset:50176
	ds_read_b128 v[174:177], v131 offset:49152
	ds_read_b128 v[206:209], v131 offset:50176
	ds_read_b128 v[230:233], v130 offset:49152
	ds_read_b128 v[234:237], v130 offset:50176
	s_barrier
	s_waitcnt lgkmcnt(0)
	s_waitcnt lgkmcnt(7)
	v_mfma_f32_16x16x32_f16 v[10:13], v[148:151], v[2:5], v[62:65]
	s_waitcnt lgkmcnt(6)
	v_mfma_f32_16x16x32_f16 v[42:45], v[164:167], v[6:9], v[10:13]
	v_mfma_f32_16x16x32_f16 v[10:13], v[148:151], v[202:205], v[58:61]
	v_mfma_f32_16x16x32_f16 v[46:49], v[164:167], v[136:139], v[10:13]
	s_waitcnt lgkmcnt(5)
	v_mfma_f32_16x16x32_f16 v[10:13], v[168:171], v[2:5], v[54:57]
	s_waitcnt lgkmcnt(4)
	v_mfma_f32_16x16x32_f16 v[34:37], v[132:135], v[6:9], v[10:13]
	v_mfma_f32_16x16x32_f16 v[10:13], v[168:171], v[202:205], v[50:53]
	v_mfma_f32_16x16x32_f16 v[38:41], v[132:135], v[136:139], v[10:13]
	s_waitcnt lgkmcnt(3)
	v_mfma_f32_16x16x32_f16 v[10:13], v[174:177], v[2:5], v[210:213]
	s_waitcnt lgkmcnt(1)
	v_mfma_f32_16x16x32_f16 v[2:5], v[230:233], v[2:5], v[140:143]
	v_mfma_f32_16x16x32_f16 v[10:13], v[206:209], v[6:9], v[10:13]
	v_mfma_f32_16x16x32_f16 v[14:17], v[174:177], v[202:205], v[226:229]
	s_waitcnt lgkmcnt(0)
	v_mfma_f32_16x16x32_f16 v[2:5], v[234:237], v[6:9], v[2:5]
	v_mfma_f32_16x16x32_f16 v[6:9], v[230:233], v[202:205], v[144:147]
	v_mfma_f32_16x16x32_f16 v[14:17], v[206:209], v[136:139], v[14:17]
	v_mfma_f32_16x16x32_f16 v[6:9], v[234:237], v[136:139], v[6:9]
	v_mfma_f32_16x16x32_f16 v[18:21], v[168:171], v[218:221], v[18:21]
	v_mfma_f32_16x16x32_f16 v[26:29], v[148:151], v[218:221], v[26:29]
	v_mfma_f32_16x16x32_f16 v[54:57], v[132:135], v[222:225], v[18:21]
	v_mfma_f32_16x16x32_f16 v[18:21], v[174:177], v[152:155], v[156:159]
	v_mfma_f32_16x16x32_f16 v[30:33], v[148:151], v[152:155], v[30:33]
	v_mfma_f32_16x16x32_f16 v[62:65], v[164:167], v[222:225], v[26:29]
	v_mfma_f32_16x16x32_f16 v[22:25], v[168:171], v[152:155], v[22:25]
	v_mfma_f32_16x16x32_f16 v[26:29], v[206:209], v[214:217], v[18:21]
	v_mfma_f32_16x16x32_f16 v[18:21], v[174:177], v[218:221], v[160:163]
	v_mfma_f32_16x16x32_f16 v[58:61], v[164:167], v[214:217], v[30:33]
	v_mfma_f32_16x16x32_f16 v[50:53], v[132:135], v[214:217], v[22:25]
	v_mfma_f32_16x16x32_f16 v[30:33], v[206:209], v[222:225], v[18:21]
	v_mfma_f32_16x16x32_f16 v[18:21], v[230:233], v[152:155], v[178:181]
	v_mfma_f32_16x16x32_f16 v[22:25], v[230:233], v[218:221], v[198:201]
	v_mfma_f32_16x16x32_f16 v[18:21], v[234:237], v[214:217], v[18:21]
	v_mfma_f32_16x16x32_f16 v[22:25], v[234:237], v[222:225], v[22:25]
	s_setprio 0
	s_movk_i32 s4, 0x100
	v_cmp_gt_u32_e32 vcc, s4, v0
	s_barrier
	s_and_saveexec_b64 s[4:5], vcc
	s_cbranch_execz .LBB0_280
	s_barrier

; #define WAIT_V(n) asm volatile("s_waitcnt vmcnt(" #n ")" ::: "memory")
; #define BAR __builtin_amdgcn_s_barrier()
; DEV void gemm_tile(const h16* __restrict__ A, const h16* __restrict__ Bt, int K, int ld, int brow, int bcol, h16* shm, Acc& acc) {
;     ...
;   int wid = TID >> 6, lane = TID & 63, wr = wid >> 2, wc = wid & 3, fr = lane & 15, fq = lane >> 4;
;   int vo0, vo1;
;   {
;     int r, c;
;     stage_rc(TID * 16, r, c);
;     vo0 = (r * ld + c) * 2;
;     stage_rc(TID * 16 + 8192, r, c);
;     vo1 = (r * ld + c) * 2;
;   }
;   __amdgpu_buffer_rsrc_t rsA = __builtin_amdgcn_make_buffer_rsrc((void*)A, (short)0, 0x7fffffff, 0x00020000);
;   __amdgpu_buffer_rsrc_t rsB = __builtin_amdgcn_make_buffer_rsrc((void*)Bt, (short)0, 0x7fffffff, 0x00020000);
; #pragma unroll
;   for (int a = 0; a < 2; ++a)
; #pragma unroll
;     for (int b = 0; b < 2; ++b)
; #pragma unroll
;       for (int m = 0; m < 4; ++m)
; #pragma unroll
;         for (int n = 0; n < 2; ++n) acc[a][b][m][n] = f32x4{0.f, 0.f, 0.f, 0.f};
;   h16x8 At[4][2], B0[2][2], B1[2][2];
;   int nt = K / BK;
;   STAGE(SB(0, 0), rsB, bcol, 0); STAGE(SA(0, 0), rsA, brow, 0);
;   STAGE(SB(0, 1), rsB, bcol + HALF_, 0); STAGE(SA(0, 1), rsA, brow + HALF_, 0);
;   if (wr == 1) BAR;
;   WAIT_V(4); BAR;
;   STAGE(SB(1, 0), rsB, bcol, 1); STAGE(SA(1, 0), rsA, brow, 1); STAGE(SB(1, 1), rsB, bcol + HALF_, 1);
;   WAIT_V(6); BAR;
; template <int EPI> __device__ __forceinline__ void gemm_phase(const h16* A, const h16* Bt, int M, int N, int K, const GE& e, h16* shm) {
;     ...
;       int q = nwg / NXCD, r = nwg % NXCD, xcd = wgid % NXCD, off = wgid / NXCD;
;       wgid = (xcd < r ? xcd * (q + 1) : r * (q + 1) + (xcd - r) * q) + off;
;     }
;     int nig = WGM * nN, gid = wgid / nig, fm = gid * WGM, gsz = min(nM - fm, WGM);
;     int pm = fm + ((wgid % nig) % gsz), pn = (wgid % nig) / gsz, brow = pm * BM, bcol = pn * BM;
;     Acc acc;
;     if constexpr (EPI == E_LRU) {
;       int koff = ((bcol >> 8) & 3) * 128;
;       gemm_tile(A + koff, Bt + koff, 128, K, brow, bcol, shm, acc);
.LBB0_340:
	v_mov_b32_e32 v0, v172
	s_ashr_i32 s4, s24, 31
	s_lshr_b32 s4, s4, 29
	v_bfe_i32 v4, v0, 27, 1
	v_lshlrev_b32_e32 v2, 4, v0
	v_lshrrev_b32_e32 v4, 22, v4
	s_add_i32 s4, s24, s4
	v_add_u32_e32 v4, v2, v4
	s_ashr_i32 s5, s4, 3
	s_and_b32 s4, s4, -8
	v_and_b32_e32 v4, 0xfffffc00, v4
	s_sub_i32 s4, s24, s4
	v_ashrrev_i32_e32 v3, 31, v0
	v_sub_u32_e32 v4, v2, v4
	s_cmp_lt_i32 s4, 0
	s_movk_i32 s6, 0xc1
	v_lshrrev_b32_e32 v3, 26, v3
	v_lshrrev_b32_e32 v5, 4, v4
	s_cselect_b32 s6, s6, 0xc0
	v_add_u32_e32 v3, v0, v3
	v_bitop3_b32 v5, v5, v4, 32 bitop3:0x6c
	v_ashrrev_i32_e32 v4, 31, v4
	s_mul_i32 s4, s6, s4
	v_ashrrev_i32_e32 v3, 6, v3
	v_lshrrev_b32_e32 v4, 26, v4
	s_add_i32 s4, s4, s5
	v_lshlrev_b32_e32 v6, 3, v3
	v_add_u32_e32 v4, v5, v4
	s_ashr_i32 s5, s4, 31
	v_and_b32_e32 v6, 0x3ffff0, v6
	v_ashrrev_i32_e32 v4, 6, v4
	s_lshr_b32 s5, s5, 26
	v_add_u32_e32 v6, v4, v6
	v_lshlrev_b32_e32 v3, 5, v3
	v_mul_i32_i24_e32 v4, 64, v4
	s_add_i32 s5, s4, s5
	v_and_b32_e32 v3, 32, v3
	v_sub_u32_e32 v4, v5, v4
	v_add_u32_e32 v5, 0x2000, v2
	s_and_b32 s6, s5, 0xffc0
	v_lshl_or_b32 v3, v6, 9, v3
	v_ashrrev_i32_e32 v6, 31, v5
	s_sub_i32 s4, s4, s6
	v_lshrrev_b32_e32 v6, 22, v6
	s_bfe_i32 s6, s4, 0x80000
	v_add_u32_e32 v6, v5, v6
	s_bfe_u32 s6, s6, 0x3000c
	v_ashrrev_i32_e32 v6, 10, v6
	s_add_i32 s6, s4, s6
	v_mul_i32_i24_e32 v7, 0x400, v6
	s_bfe_i32 s7, s6, 0x80000
	s_and_b32 s6, s6, 0xf8
	v_sub_u32_e32 v5, v5, v7
	s_sext_i32_i16 s7, s7
	s_sub_i32 s4, s4, s6
	v_lshrrev_b32_e32 v7, 4, v5
	s_sext_i32_i8 s4, s4
	s_ashr_i32 s6, s7, 3
	v_bitop3_b32 v5, v7, v5, 32 bitop3:0x6c
	s_lshl_b32 s5, s5, 5
	s_lshl_b32 s25, s4, 8
	s_lshl_b32 s4, s6, 7
	v_ashrrev_i32_e32 v8, 31, v5
	s_and_b32 s5, s5, 0xfffff800
	s_and_b32 s26, s4, 0x180
	v_lshrrev_b32_e32 v8, 26, v8
	s_add_i32 s25, s25, s5
	s_lshl_b32 s4, s26, 1
	v_add_u32_e32 v8, v5, v8
	s_add_u32 s76, s20, s4
	v_lshlrev_b32_e32 v7, 3, v6
	v_lshrrev_b32_e32 v9, 6, v8
	v_and_b32_e32 v8, 0xc0, v8
	s_addc_u32 s5, s21, 0
	v_and_b32_e32 v7, 0x3ffff0, v7
	v_lshlrev_b32_e32 v6, 5, v6
	v_sub_u32_e32 v5, v5, v8
	s_add_u32 s8, s22, s4
	v_ashrrev_i16_sdwa v4, v187, sext(v4) dst_sel:DWORD dst_unused:UNUSED_PAD src0_sel:DWORD src1_sel:BYTE_0
	v_add_u32_e32 v7, v9, v7
	v_and_b32_e32 v6, 32, v6
	v_ashrrev_i16_sdwa v5, v187, sext(v5) dst_sel:DWORD dst_unused:UNUSED_PAD src0_sel:DWORD src1_sel:BYTE_0
	s_addc_u32 s4, s23, 0
	v_bfe_i32 v4, v4, 0, 16
	v_bfe_i32 v5, v5, 0, 16
	v_lshl_or_b32 v6, v7, 9, v6
	s_add_i32 s7, s68, 0x110
	v_add_lshl_u32 v4, v3, v4, 1
	v_add_lshl_u32 v3, v6, v5, 1
	v_add_u32_e32 v5, s7, v2
	s_and_b32 s9, s4, 0xffff
	v_readfirstlane_b32 s4, v5
	v_add_u32_e32 v5, 0x2000, v5
	s_mov_b32 s10, s78
	s_mov_b32 s11, s79
	s_lshl_b32 s13, s6, 18
	s_mov_b32 m0, s4
	v_readfirstlane_b32 s4, v5
	v_add_u32_e32 v5, 0x110, v2
	s_and_b32 s77, s5, 0xffff
	buffer_load_dwordx4 v4, s[8:11], s13 offen lds
	s_mov_b32 m0, s4
	v_readfirstlane_b32 s4, v5
	v_add_u32_e32 v6, 0x2000, v5
	v_readlane_b32 s5, v254, 11
	buffer_load_dwordx4 v3, s[8:11], s13 offen lds
	s_lshl_b32 s14, s25, 10
	s_mov_b32 m0, s4
	v_readfirstlane_b32 s4, v6
	v_add_u32_e32 v6, s5, v2
	buffer_load_dwordx4 v4, s[76:79], s14 offen lds
	s_mov_b32 m0, s4
	v_readfirstlane_b32 s5, v6
	v_add_u32_e32 v6, 0x2000, v6
	buffer_load_dwordx4 v3, s[76:79], s14 offen lds
	s_or_b32 s4, s13, 0x20000
	s_mov_b32 m0, s5
	v_readfirstlane_b32 s5, v6
	buffer_load_dwordx4 v4, s[8:11], s4 offen lds
	s_mov_b32 m0, s5
	v_add_u32_e32 v6, 0x4000, v5
	buffer_load_dwordx4 v3, s[8:11], s4 offen lds
	s_or_b32 s27, s25, 0x80
	v_readfirstlane_b32 s4, v6
	v_add_u32_e32 v6, 0x6000, v5
	s_lshl_b32 s12, s27, 10
	s_mov_b32 m0, s4
	v_readfirstlane_b32 s4, v6
	buffer_load_dwordx4 v4, s[76:79], s12 offen lds
	s_mov_b32 m0, s4
	v_ashrrev_i32_e32 v6, 8, v0
	buffer_load_dwordx4 v3, s[76:79], s12 offen lds
	v_cmp_eq_u32_e32 vcc, 1, v6
	s_and_saveexec_b64 s[4:5], vcc
	s_cbranch_execz .LBB0_342
	s_barrier
	s_setprio 1
.LBB0_342:
	s_or_b64 exec, exec, s[4:5]
	v_add_u32_e32 v9, s94, v2
	s_or_b32 s4, s13, 0x80
	v_readfirstlane_b32 s5, v9
	v_add_u32_e32 v9, 0x2000, v9
	s_mov_b32 s10, s78
	s_mov_b32 s11, s79
	s_mov_b32 m0, s5
	v_readfirstlane_b32 s5, v9
	s_waitcnt vmcnt(4)
	s_barrier
	buffer_load_dwordx4 v4, s[8:11], s4 offen lds
	s_mov_b32 m0, s5
	v_add_u32_e32 v9, 0x8000, v5
	buffer_load_dwordx4 v3, s[8:11], s4 offen lds
	v_readfirstlane_b32 s4, v9
	v_add_u32_e32 v9, 0xa000, v5
	s_bitset1_b32 s14, 7
	s_mov_b32 m0, s4
	v_readfirstlane_b32 s4, v9
	buffer_load_dwordx4 v4, s[76:79], s14 offen lds
	s_mov_b32 m0, s4
	s_or_b32 s4, s13, 0x20080
	v_readlane_b32 s13, v254, 12
	buffer_load_dwordx4 v3, s[76:79], s14 offen lds
	v_lshlrev_b32_e32 v9, 2, v0
	v_add_u32_e32 v2, s13, v2
	v_and_b32_e32 v8, 48, v0
	v_readfirstlane_b32 s5, v2
	v_add_u32_e32 v2, 0x2000, v2
	s_mov_b32 m0, s5
	v_readfirstlane_b32 s5, v2
	v_lshlrev_b32_e32 v2, 6, v0
	v_and_b32_e32 v170, 0x3000, v2
	v_and_b32_e32 v9, 32, v9
	v_and_b32_e32 v2, 0x3c0, v2
	v_and_b32_e32 v7, 15, v0
	v_lshlrev_b32_e32 v30, 13, v6
	v_bitop3_b32 v2, v2, v9, v8 bitop3:0x36
	buffer_load_dwordx4 v4, s[8:11], s4 offen lds
	s_mov_b32 m0, s5
	v_lshlrev_b32_e32 v7, 6, v7
	v_add3_u32 v197, s85, v2, v30
	v_add_u32_e32 v2, 0xc000, v5
	buffer_load_dwordx4 v3, s[8:11], s4 offen lds
	v_bitop3_b32 v171, v7, v9, v8 bitop3:0x36
	v_readfirstlane_b32 s4, v2
	v_add_u32_e32 v2, 0xe000, v5
	v_add3_u32 v18, s7, v171, v170
	v_add3_u32 v192, s85, v171, v30
	s_bitset1_b32 s12, 7
	s_mov_b32 m0, s4
	v_readfirstlane_b32 s4, v2
	s_waitcnt vmcnt(6)
	s_barrier
; #define WAIT_V(n) asm volatile("s_waitcnt vmcnt(" #n ")" ::: "memory")
; #define WAIT_L(n) asm volatile("s_waitcnt lgkmcnt(" #n ")" ::: "memory")
; #define BAR __builtin_amdgcn_s_barrier()
; DEV void gemm_tile(const h16* __restrict__ A, const h16* __restrict__ Bt, int K, int ld, int brow, int bcol, h16* shm, Acc& acc) {
;     ...
;   { LDB(B0, 0, 0); LDA(At, 0, 0); STAGE(SA(1, 1), rsA, brow + HALF_, nt - 1);
;     BAR; WAIT_L(0); MMA(0, 0, At, B0); BAR;
;     LDB(B1, 0, 1); BAR; WAIT_L(0); MMA(0, 1, At, B1); BAR;
;     LDA(At, 0, 1); WAIT_V(4); BAR; WAIT_L(0); MMA(1, 0, At, B0); MMA(1, 1, At, B1); BAR; }
;   { LDB(B0, 1, 0); LDA(At, 1, 0); WAIT_V(2); BAR; WAIT_L(0); MMA(0, 0, At, B0); BAR;
	ds_read_b128 v[6:9], v18
	ds_read_b128 v[10:13], v18 offset:1024
	ds_read_b128 v[14:17], v18 offset:2048
	ds_read_b128 v[18:21], v18 offset:3072
	ds_read_b128 v[22:25], v192
	ds_read_b128 v[26:29], v192 offset:1024
	ds_read_b128 v[30:33], v197 offset:2048
	ds_read_b128 v[34:37], v197 offset:3072
	ds_read_b128 v[38:41], v197 offset:4096
	ds_read_b128 v[42:45], v197 offset:5120
	ds_read_b128 v[46:49], v197 offset:6144
	ds_read_b128 v[50:53], v197 offset:7168
	buffer_load_dwordx4 v4, s[76:79], s12 offen lds
	s_mov_b32 m0, s4
	s_nop 0
	buffer_load_dwordx4 v3, s[76:79], s12 offen lds
	s_barrier
	s_waitcnt lgkmcnt(0)
	s_waitcnt lgkmcnt(1)
	v_mfma_f32_16x16x32_f16 v[74:77], v[46:49], v[6:9], 0
	v_mfma_f32_16x16x32_f16 v[2:5], v[22:25], v[6:9], 0
	v_mfma_f32_16x16x32_f16 v[54:57], v[22:25], v[14:17], 0
	v_mfma_f32_16x16x32_f16 v[58:61], v[30:33], v[6:9], 0
	v_mfma_f32_16x16x32_f16 v[62:65], v[30:33], v[14:17], 0
	v_mfma_f32_16x16x32_f16 v[66:69], v[38:41], v[6:9], 0
	v_mfma_f32_16x16x32_f16 v[70:73], v[38:41], v[14:17], 0
	s_waitcnt lgkmcnt(0)
	v_mfma_f32_16x16x32_f16 v[82:85], v[50:53], v[10:13], v[74:77]
	v_mfma_f32_16x16x32_f16 v[74:77], v[46:49], v[14:17], 0
	v_mfma_f32_16x16x32_f16 v[2:5], v[26:29], v[10:13], v[2:5]
	v_mfma_f32_16x16x32_f16 v[54:57], v[26:29], v[18:21], v[54:57]
	v_mfma_f32_16x16x32_f16 v[58:61], v[34:37], v[10:13], v[58:61]
	v_mfma_f32_16x16x32_f16 v[62:65], v[34:37], v[18:21], v[62:65]
	v_mfma_f32_16x16x32_f16 v[66:69], v[42:45], v[10:13], v[66:69]
	v_mfma_f32_16x16x32_f16 v[70:73], v[42:45], v[18:21], v[70:73]
	v_mfma_f32_16x16x32_f16 v[86:89], v[50:53], v[18:21], v[74:77]
	v_readlane_b32 s4, v254, 11
	s_barrier
	s_nop 0
	v_add3_u32 v94, s4, v171, v170
	ds_read_b128 v[74:77], v94
	ds_read_b128 v[78:81], v94 offset:1024
	ds_read_b128 v[90:93], v94 offset:2048
	ds_read_b128 v[94:97], v94 offset:3072
	s_barrier
	s_waitcnt lgkmcnt(0)
	s_waitcnt lgkmcnt(3)
	v_mfma_f32_16x16x32_f16 v[98:101], v[22:25], v[74:77], 0
	s_waitcnt lgkmcnt(1)
	v_mfma_f32_16x16x32_f16 v[22:25], v[22:25], v[90:93], 0
	v_mfma_f32_16x16x32_f16 v[114:117], v[26:29], v[78:81], v[98:101]
	s_waitcnt lgkmcnt(0)
	v_mfma_f32_16x16x32_f16 v[22:25], v[26:29], v[94:97], v[22:25]
	v_mfma_f32_16x16x32_f16 v[26:29], v[30:33], v[74:77], 0
	v_mfma_f32_16x16x32_f16 v[30:33], v[30:33], v[90:93], 0
	v_mfma_f32_16x16x32_f16 v[26:29], v[34:37], v[78:81], v[26:29]
	v_mfma_f32_16x16x32_f16 v[30:33], v[34:37], v[94:97], v[30:33]
	v_mfma_f32_16x16x32_f16 v[34:37], v[38:41], v[74:77], 0
	v_mfma_f32_16x16x32_f16 v[38:41], v[38:41], v[90:93], 0
	v_mfma_f32_16x16x32_f16 v[34:37], v[42:45], v[78:81], v[34:37]
	v_mfma_f32_16x16x32_f16 v[38:41], v[42:45], v[94:97], v[38:41]
	v_mfma_f32_16x16x32_f16 v[42:45], v[46:49], v[74:77], 0
	v_mfma_f32_16x16x32_f16 v[46:49], v[46:49], v[90:93], 0
	v_mfma_f32_16x16x32_f16 v[42:45], v[50:53], v[78:81], v[42:45]
	v_mfma_f32_16x16x32_f16 v[46:49], v[50:53], v[94:97], v[46:49]
	s_barrier
	ds_read_b128 v[50:53], v192 offset:16384
	ds_read_b128 v[98:101], v192 offset:17408
	ds_read_b128 v[102:105], v197 offset:18432
	ds_read_b128 v[106:109], v197 offset:19456
	ds_read_b128 v[110:113], v197 offset:20480
	ds_read_b128 v[118:121], v197 offset:21504
	ds_read_b128 v[122:125], v197 offset:22528
	ds_read_b128 v[126:129], v197 offset:23552
	s_waitcnt vmcnt(4)
	s_barrier
	s_waitcnt lgkmcnt(0)
	s_waitcnt lgkmcnt(7)
	v_mfma_f32_16x16x32_f16 v[130:133], v[50:53], v[6:9], 0
	s_waitcnt lgkmcnt(5)
	v_mfma_f32_16x16x32_f16 v[138:141], v[102:105], v[6:9], 0
	s_waitcnt lgkmcnt(3)
	v_mfma_f32_16x16x32_f16 v[146:149], v[110:113], v[6:9], 0
	s_waitcnt lgkmcnt(1)
	v_mfma_f32_16x16x32_f16 v[6:9], v[122:125], v[6:9], 0
	v_mfma_f32_16x16x32_f16 v[130:133], v[98:101], v[10:13], v[130:133]
	v_mfma_f32_16x16x32_f16 v[134:137], v[50:53], v[14:17], 0
	v_mfma_f32_16x16x32_f16 v[138:141], v[106:109], v[10:13], v[138:141]
	v_mfma_f32_16x16x32_f16 v[142:145], v[102:105], v[14:17], 0
	v_mfma_f32_16x16x32_f16 v[146:149], v[118:121], v[10:13], v[146:149]
	v_mfma_f32_16x16x32_f16 v[150:153], v[110:113], v[14:17], 0
	s_waitcnt lgkmcnt(0)
	v_mfma_f32_16x16x32_f16 v[6:9], v[126:129], v[10:13], v[6:9]
	v_mfma_f32_16x16x32_f16 v[10:13], v[122:125], v[14:17], 0
	v_mfma_f32_16x16x32_f16 v[134:137], v[98:101], v[18:21], v[134:137]
	v_mfma_f32_16x16x32_f16 v[142:145], v[106:109], v[18:21], v[142:145]
	v_mfma_f32_16x16x32_f16 v[150:153], v[118:121], v[18:21], v[150:153]
	v_mfma_f32_16x16x32_f16 v[18:21], v[126:129], v[18:21], v[10:13]
	v_mfma_f32_16x16x32_f16 v[10:13], v[50:53], v[74:77], 0
	v_mfma_f32_16x16x32_f16 v[154:157], v[98:101], v[78:81], v[10:13]
	v_mfma_f32_16x16x32_f16 v[10:13], v[50:53], v[90:93], 0
	v_mfma_f32_16x16x32_f16 v[50:53], v[98:101], v[94:97], v[10:13]
	v_mfma_f32_16x16x32_f16 v[10:13], v[102:105], v[74:77], 0
	v_mfma_f32_16x16x32_f16 v[158:161], v[106:109], v[78:81], v[10:13]
	v_mfma_f32_16x16x32_f16 v[10:13], v[102:105], v[90:93], 0
	v_mfma_f32_16x16x32_f16 v[162:165], v[106:109], v[94:97], v[10:13]
	v_mfma_f32_16x16x32_f16 v[10:13], v[110:113], v[74:77], 0
	v_mfma_f32_16x16x32_f16 v[166:169], v[118:121], v[78:81], v[10:13]
	v_mfma_f32_16x16x32_f16 v[10:13], v[110:113], v[90:93], 0
	v_mfma_f32_16x16x32_f16 v[174:177], v[118:121], v[94:97], v[10:13]
	v_mfma_f32_16x16x32_f16 v[10:13], v[122:125], v[74:77], 0
	v_mfma_f32_16x16x32_f16 v[178:181], v[126:129], v[78:81], v[10:13]
	v_mfma_f32_16x16x32_f16 v[10:13], v[122:125], v[90:93], 0
	v_mfma_f32_16x16x32_f16 v[198:201], v[126:129], v[94:97], v[10:13]
	s_nop 5
	v_add3_u32 v10, s94, v171, v170
	s_barrier
; #define WAIT_V(n) asm volatile("s_waitcnt vmcnt(" #n ")" ::: "memory")
; #define WAIT_L(n) asm volatile("s_waitcnt lgkmcnt(" #n ")" ::: "memory")
; #define BAR __builtin_amdgcn_s_barrier()
; DEV void gemm_tile(const h16* __restrict__ A, const h16* __restrict__ Bt, int K, int ld, int brow, int bcol, h16* shm, Acc& acc) {
;     ...
;   { LDB(B0, 1, 0); LDA(At, 1, 0); WAIT_V(2); BAR; WAIT_L(0); MMA(0, 0, At, B0); BAR;
;     LDB(B1, 1, 1); WAIT_V(0); BAR; WAIT_L(0); MMA(0, 1, At, B1); BAR;
;     LDA(At, 1, 1); BAR; WAIT_L(0); MMA(1, 0, At, B0); MMA(1, 1, At, B1); BAR; }
;   if (wr == 0) BAR;
	ds_read_b128 v[202:205], v10
	ds_read_b128 v[206:209], v10 offset:1024
	ds_read_b128 v[210:213], v10 offset:2048
	ds_read_b128 v[214:217], v10 offset:3072
	ds_read_b128 v[10:13], v192 offset:32768
	ds_read_b128 v[14:17], v192 offset:33792
	ds_read_b128 v[90:93], v197 offset:34816
	ds_read_b128 v[94:97], v197 offset:35840
	ds_read_b128 v[218:221], v197 offset:36864
	ds_read_b128 v[222:225], v197 offset:37888
	ds_read_b128 v[226:229], v197 offset:38912
	ds_read_b128 v[230:233], v197 offset:39936
	s_waitcnt vmcnt(2)
	s_barrier
	s_waitcnt lgkmcnt(0)
	s_waitcnt lgkmcnt(7)
	v_mfma_f32_16x16x32_f16 v[2:5], v[10:13], v[202:205], v[2:5]
	s_waitcnt lgkmcnt(6)
	v_mfma_f32_16x16x32_f16 v[106:109], v[14:17], v[206:209], v[2:5]
	v_mfma_f32_16x16x32_f16 v[2:5], v[10:13], v[210:213], v[54:57]
	v_mfma_f32_16x16x32_f16 v[110:113], v[14:17], v[214:217], v[2:5]
	s_waitcnt lgkmcnt(5)
	v_mfma_f32_16x16x32_f16 v[2:5], v[90:93], v[202:205], v[58:61]
	s_waitcnt lgkmcnt(4)
	v_mfma_f32_16x16x32_f16 v[98:101], v[94:97], v[206:209], v[2:5]
	v_mfma_f32_16x16x32_f16 v[2:5], v[90:93], v[210:213], v[62:65]
	v_mfma_f32_16x16x32_f16 v[102:105], v[94:97], v[214:217], v[2:5]
	s_waitcnt lgkmcnt(3)
	v_mfma_f32_16x16x32_f16 v[2:5], v[218:221], v[202:205], v[66:69]
	s_waitcnt lgkmcnt(2)
	v_mfma_f32_16x16x32_f16 v[74:77], v[222:225], v[206:209], v[2:5]
	v_mfma_f32_16x16x32_f16 v[2:5], v[218:221], v[210:213], v[70:73]
	v_mfma_f32_16x16x32_f16 v[78:81], v[222:225], v[214:217], v[2:5]
	s_waitcnt lgkmcnt(1)
	v_mfma_f32_16x16x32_f16 v[2:5], v[226:229], v[202:205], v[82:85]
	s_waitcnt lgkmcnt(0)
	v_mfma_f32_16x16x32_f16 v[66:69], v[230:233], v[206:209], v[2:5]
	v_mfma_f32_16x16x32_f16 v[2:5], v[226:229], v[210:213], v[86:89]
	v_mfma_f32_16x16x32_f16 v[70:73], v[230:233], v[214:217], v[2:5]
	s_nop 5
	v_add3_u32 v2, s13, v171, v170
	s_barrier
	ds_read_b128 v[234:237], v2
	ds_read_b128 v[238:241], v2 offset:1024
	ds_read_b128 v[242:245], v2 offset:2048
	ds_read_b128 v[246:249], v2 offset:3072
	s_waitcnt vmcnt(0)
	s_barrier
	s_waitcnt lgkmcnt(0)
	s_waitcnt lgkmcnt(3)
	v_mfma_f32_16x16x32_f16 v[2:5], v[10:13], v[234:237], v[114:117]
	s_waitcnt lgkmcnt(2)
	v_mfma_f32_16x16x32_f16 v[122:125], v[14:17], v[238:241], v[2:5]
	s_waitcnt lgkmcnt(1)
	v_mfma_f32_16x16x32_f16 v[2:5], v[10:13], v[242:245], v[22:25]
	s_waitcnt lgkmcnt(0)
	v_mfma_f32_16x16x32_f16 v[126:129], v[14:17], v[246:249], v[2:5]
	v_mfma_f32_16x16x32_f16 v[2:5], v[90:93], v[234:237], v[26:29]
	v_mfma_f32_16x16x32_f16 v[114:117], v[94:97], v[238:241], v[2:5]
	v_mfma_f32_16x16x32_f16 v[2:5], v[90:93], v[242:245], v[30:33]
	v_mfma_f32_16x16x32_f16 v[118:121], v[94:97], v[246:249], v[2:5]
	v_mfma_f32_16x16x32_f16 v[2:5], v[218:221], v[234:237], v[34:37]
	v_mfma_f32_16x16x32_f16 v[90:93], v[222:225], v[238:241], v[2:5]
	v_mfma_f32_16x16x32_f16 v[2:5], v[218:221], v[242:245], v[38:41]
	v_mfma_f32_16x16x32_f16 v[94:97], v[222:225], v[246:249], v[2:5]
	v_mfma_f32_16x16x32_f16 v[2:5], v[226:229], v[234:237], v[42:45]
	v_mfma_f32_16x16x32_f16 v[82:85], v[230:233], v[238:241], v[2:5]
	v_mfma_f32_16x16x32_f16 v[2:5], v[226:229], v[242:245], v[46:49]
	v_mfma_f32_16x16x32_f16 v[86:89], v[230:233], v[246:249], v[2:5]
	s_barrier
	ds_read_b128 v[22:25], v192 offset:49152
	ds_read_b128 v[26:29], v192 offset:50176
	ds_read_b128 v[30:33], v197 offset:51200
	ds_read_b128 v[54:57], v197 offset:52224
	ds_read_b128 v[218:221], v197 offset:53248
	ds_read_b128 v[222:225], v197 offset:54272
	ds_read_b128 v[226:229], v197 offset:55296
	ds_read_b128 v[230:233], v197 offset:56320
	s_barrier
	s_waitcnt lgkmcnt(0)
	s_waitcnt lgkmcnt(7)
	v_mfma_f32_16x16x32_f16 v[2:5], v[22:25], v[202:205], v[130:133]
	s_waitcnt lgkmcnt(6)
	v_mfma_f32_16x16x32_f16 v[42:45], v[26:29], v[206:209], v[2:5]
	v_mfma_f32_16x16x32_f16 v[2:5], v[22:25], v[210:213], v[134:137]
	v_mfma_f32_16x16x32_f16 v[46:49], v[26:29], v[214:217], v[2:5]
	s_waitcnt lgkmcnt(5)
	v_mfma_f32_16x16x32_f16 v[2:5], v[30:33], v[202:205], v[138:141]
	s_waitcnt lgkmcnt(4)
	v_mfma_f32_16x16x32_f16 v[34:37], v[54:57], v[206:209], v[2:5]
	v_mfma_f32_16x16x32_f16 v[2:5], v[30:33], v[210:213], v[142:145]
	v_mfma_f32_16x16x32_f16 v[38:41], v[54:57], v[214:217], v[2:5]
	s_waitcnt lgkmcnt(3)
	v_mfma_f32_16x16x32_f16 v[2:5], v[218:221], v[202:205], v[146:149]
	s_waitcnt lgkmcnt(2)
	v_mfma_f32_16x16x32_f16 v[10:13], v[222:225], v[206:209], v[2:5]
	v_mfma_f32_16x16x32_f16 v[2:5], v[218:221], v[210:213], v[150:153]
	v_mfma_f32_16x16x32_f16 v[14:17], v[222:225], v[214:217], v[2:5]
	s_waitcnt lgkmcnt(1)
	v_mfma_f32_16x16x32_f16 v[2:5], v[226:229], v[202:205], v[6:9]
	v_mfma_f32_16x16x32_f16 v[6:9], v[226:229], v[210:213], v[18:21]
	s_waitcnt lgkmcnt(0)
	v_mfma_f32_16x16x32_f16 v[2:5], v[230:233], v[206:209], v[2:5]
	v_mfma_f32_16x16x32_f16 v[6:9], v[230:233], v[214:217], v[6:9]
	v_mfma_f32_16x16x32_f16 v[18:21], v[22:25], v[234:237], v[154:157]
	v_mfma_f32_16x16x32_f16 v[58:61], v[26:29], v[238:241], v[18:21]
	v_mfma_f32_16x16x32_f16 v[18:21], v[22:25], v[242:245], v[50:53]
	v_mfma_f32_16x16x32_f16 v[62:65], v[26:29], v[246:249], v[18:21]
	v_mfma_f32_16x16x32_f16 v[18:21], v[30:33], v[234:237], v[158:161]
	v_mfma_f32_16x16x32_f16 v[50:53], v[54:57], v[238:241], v[18:21]
	v_mfma_f32_16x16x32_f16 v[18:21], v[30:33], v[242:245], v[162:165]
	v_mfma_f32_16x16x32_f16 v[54:57], v[54:57], v[246:249], v[18:21]
	v_mfma_f32_16x16x32_f16 v[18:21], v[218:221], v[234:237], v[166:169]
	v_mfma_f32_16x16x32_f16 v[26:29], v[222:225], v[238:241], v[18:21]
	v_mfma_f32_16x16x32_f16 v[18:21], v[218:221], v[242:245], v[174:177]
	v_mfma_f32_16x16x32_f16 v[30:33], v[222:225], v[246:249], v[18:21]
	v_mfma_f32_16x16x32_f16 v[18:21], v[226:229], v[234:237], v[178:181]
	v_mfma_f32_16x16x32_f16 v[22:25], v[226:229], v[242:245], v[198:201]
	v_mfma_f32_16x16x32_f16 v[18:21], v[230:233], v[238:241], v[18:21]
	v_mfma_f32_16x16x32_f16 v[22:25], v[230:233], v[246:249], v[22:25]
	s_setprio 0
	s_movk_i32 s4, 0x100
	v_cmp_gt_u32_e32 vcc, s4, v0
	s_barrier
	s_and_saveexec_b64 s[4:5], vcc
	s_cbranch_execz .LBB0_339
	s_barrier
	s_branch .LBB0_339

; #define WAIT_V(n) asm volatile("s_waitcnt vmcnt(" #n ")" ::: "memory")
; #define BAR __builtin_amdgcn_s_barrier()
; DEV void gemm_tile(const h16* __restrict__ A, const h16* __restrict__ Bt, int K, int ld, int brow, int bcol, h16* shm, Acc& acc) {
;     ...
;   int wid = TID >> 6, lane = TID & 63, wr = wid >> 2, wc = wid & 3, fr = lane & 15, fq = lane >> 4;
;   int vo0, vo1;
;   {
;     int r, c;
;     stage_rc(TID * 16, r, c);
;     vo0 = (r * ld + c) * 2;
;     stage_rc(TID * 16 + 8192, r, c);
;     vo1 = (r * ld + c) * 2;
;   }
;   __amdgpu_buffer_rsrc_t rsA = __builtin_amdgcn_make_buffer_rsrc((void*)A, (short)0, 0x7fffffff, 0x00020000);
;   __amdgpu_buffer_rsrc_t rsB = __builtin_amdgcn_make_buffer_rsrc((void*)Bt, (short)0, 0x7fffffff, 0x00020000);
; #pragma unroll
;   for (int a = 0; a < 2; ++a)
; #pragma unroll
;     for (int b = 0; b < 2; ++b)
; #pragma unroll
;       for (int m = 0; m < 4; ++m)
; #pragma unroll
;         for (int n = 0; n < 2; ++n) acc[a][b][m][n] = f32x4{0.f, 0.f, 0.f, 0.f};
;   h16x8 At[4][2], B0[2][2], B1[2][2];
;   int nt = K / BK;
;   STAGE(SB(0, 0), rsB, bcol, 0); STAGE(SA(0, 0), rsA, brow, 0);
;   STAGE(SB(0, 1), rsB, bcol + HALF_, 0); STAGE(SA(0, 1), rsA, brow + HALF_, 0);
;   if (wr == 1) BAR;
;   WAIT_V(4); BAR;
; template <int EPI> __device__ __forceinline__ void gemm_phase(const h16* A, const h16* Bt, int M, int N, int K, const GE& e, h16* shm) {
;     ...
;       int q = nwg / NXCD, r = nwg % NXCD, xcd = wgid % NXCD, off = wgid / NXCD;
;       wgid = (xcd < r ? xcd * (q + 1) : r * (q + 1) + (xcd - r) * q) + off;
;     }
;     int nig = WGM * nN, gid = wgid / nig, fm = gid * WGM, gsz = min(nM - fm, WGM);
;     int pm = fm + ((wgid % nig) % gsz), pn = (wgid % nig) / gsz, brow = pm * BM, bcol = pn * BM;
.LBB0_1362:
	v_mov_b32_e32 v0, v172
	s_ashr_i32 s6, s16, 31
	s_waitcnt lgkmcnt(0)
	v_bfe_i32 v4, v0, 27, 1
	v_lshlrev_b32_e32 v2, 4, v0
	v_lshrrev_b32_e32 v4, 22, v4
	v_add_u32_e32 v4, v2, v4
	v_and_b32_e32 v4, 0xfffffc00, v4
	v_ashrrev_i32_e32 v3, 31, v0
	v_sub_u32_e32 v4, v2, v4
	s_lshr_b32 s6, s6, 29
	v_lshrrev_b32_e32 v3, 26, v3
	v_lshrrev_b32_e32 v5, 4, v4
	s_add_i32 s6, s16, s6
	v_add_u32_e32 v3, v0, v3
	v_bitop3_b32 v5, v5, v4, 32 bitop3:0x6c
	v_ashrrev_i32_e32 v4, 31, v4
	s_ashr_i32 s7, s6, 3
	s_and_b32 s6, s6, -8
	v_ashrrev_i32_e32 v3, 6, v3
	v_lshrrev_b32_e32 v4, 26, v4
	s_sub_i32 s6, s16, s6
	v_lshlrev_b32_e32 v6, 3, v3
	v_add_u32_e32 v4, v5, v4
	s_cmp_lt_i32 s6, 0
	s_movk_i32 s8, 0xd9
	v_and_b32_e32 v6, 0x1ffff0, v6
	v_ashrrev_i32_e32 v4, 6, v4
	s_cselect_b32 s8, s8, 0xd8
	v_add_u32_e32 v6, v4, v6
	v_lshlrev_b32_e32 v3, 5, v3
	v_mul_i32_i24_e32 v4, 64, v4
	s_mul_i32 s6, s8, s6
	v_and_b32_e32 v3, 32, v3
	v_sub_u32_e32 v4, v5, v4
	v_add_u32_e32 v5, 0x2000, v2
	s_add_i32 s6, s6, s7
	v_lshl_or_b32 v3, v6, 10, v3
	v_ashrrev_i32_e32 v6, 31, v5
	s_mul_hi_i32 s7, s6, 0x38e38e39
	v_lshrrev_b32_e32 v6, 22, v6
	s_lshr_b32 s8, s7, 31
	s_ashr_i32 s11, s7, 4
	v_add_u32_e32 v6, v5, v6
	s_add_i32 s11, s11, s8
	v_ashrrev_i32_e32 v6, 10, v6
	s_mul_i32 s7, s11, 0x48
	v_mul_i32_i24_e32 v7, 0x400, v6
	s_sub_i32 s6, s6, s7
	v_sub_u32_e32 v5, v5, v7
	s_bfe_i32 s7, s6, 0x80000
	v_lshrrev_b32_e32 v7, 4, v5
	s_bfe_u32 s7, s7, 0x3000c
	v_bitop3_b32 v5, v7, v5, 32 bitop3:0x6c
	s_add_i32 s7, s6, s7
	v_ashrrev_i32_e32 v8, 31, v5
	s_bfe_i32 s8, s7, 0x80000
	s_and_b32 s7, s7, 0xf8
	v_lshrrev_b32_e32 v8, 26, v8
	s_sub_i32 s6, s6, s7
	v_add_u32_e32 v8, v5, v8
	s_sext_i32_i8 s19, s6
	v_lshlrev_b32_e32 v7, 3, v6
	v_lshrrev_b32_e32 v9, 6, v8
	v_and_b32_e32 v8, 0xc0, v8
	s_add_i32 s20, s68, 0x110
	s_sext_i32_i16 s8, s8
	s_lshl_b32 s6, s11, 11
	s_lshl_b32 s17, s19, 8
	v_ashrrev_i16_sdwa v4, v187, sext(v4) dst_sel:DWORD dst_unused:UNUSED_PAD src0_sel:DWORD src1_sel:BYTE_0
	v_and_b32_e32 v7, 0x1ffff0, v7
	v_lshlrev_b32_e32 v6, 5, v6
	v_sub_u32_e32 v5, v5, v8
	v_add_u32_e32 v137, s20, v2
	s_ashr_i32 s8, s8, 3
	s_add_i32 s17, s17, s6
	v_bfe_i32 v4, v4, 0, 16
	v_add_u32_e32 v7, v9, v7
	v_and_b32_e32 v6, 32, v6
	v_ashrrev_i16_sdwa v5, v187, sext(v5) dst_sel:DWORD dst_unused:UNUSED_PAD src0_sel:DWORD src1_sel:BYTE_0
	v_readfirstlane_b32 s6, v137
	v_add_u32_e32 v139, 0x2000, v137
	v_bfe_i32 v5, v5, 0, 16
	v_lshl_or_b32 v6, v7, 10, v6
	v_add_lshl_u32 v136, v3, v4, 1
	s_lshl_b32 s9, s8, 19
	s_mov_b32 s14, s78
	s_mov_b32 s15, s79
	s_mov_b32 m0, s6
	v_readfirstlane_b32 s6, v139
	v_add_u32_e32 v140, 0x110, v2
	v_add_lshl_u32 v135, v6, v5, 1
	buffer_load_dwordx4 v136, s[12:15], s9 offen lds
	s_mov_b32 m0, s6
	v_readfirstlane_b32 s6, v140
	v_add_u32_e32 v141, 0x2000, v140
	buffer_load_dwordx4 v135, s[12:15], s9 offen lds
	s_lshl_b32 s21, s17, 11
	s_mov_b32 m0, s6
	v_readfirstlane_b32 s6, v141
	buffer_load_dwordx4 v136, s[76:79], s21 offen lds
	s_mov_b32 m0, s6
	v_readlane_b32 s6, v254, 11
	buffer_load_dwordx4 v135, s[76:79], s21 offen lds
	s_or_b32 s22, s9, 0x40000
	v_add_u32_e32 v142, s6, v2
	v_add_u32_e32 v143, 0x2000, v142
	v_readfirstlane_b32 s6, v142
	s_mov_b32 m0, s6
	v_readfirstlane_b32 s6, v143
	v_add_u32_e32 v144, 0x4000, v140
	buffer_load_dwordx4 v136, s[12:15], s22 offen lds
	s_mov_b32 m0, s6
	s_or_b32 s18, s17, 0x80
	v_readfirstlane_b32 s6, v144
	v_add_u32_e32 v145, 0x6000, v140
	buffer_load_dwordx4 v135, s[12:15], s22 offen lds
	s_lshl_b32 s10, s18, 11
	s_mov_b32 m0, s6
	v_readfirstlane_b32 s6, v145
	buffer_load_dwordx4 v136, s[76:79], s10 offen lds
	s_mov_b32 m0, s6
	v_ashrrev_i32_e32 v3, 8, v0
	buffer_load_dwordx4 v135, s[76:79], s10 offen lds
	v_cmp_eq_u32_e32 vcc, 1, v3
	s_and_saveexec_b64 s[6:7], vcc
	s_cbranch_execz .LBB0_1364
	s_barrier
	s_setprio 1

; #define WAIT_L(n) asm volatile("s_waitcnt lgkmcnt(" #n ")" ::: "memory")
; #define BAR __builtin_amdgcn_s_barrier()
; #define SCHED __builtin_amdgcn_sched_barrier(0)
; DEV void gemm_tile(const h16* __restrict__ A, const h16* __restrict__ Bt, int K, int ld, int brow, int bcol, h16* shm, Acc& acc) {
;     ...
;     LDB(B0, 0, 0); SCHED; LDA(At, 0, 0); STAGE(SA(1, 1), rsA, brow + HALF_, t + 1);
;     WAIT_L(8); BAR; WAIT_L(0); MMA(0, 0, At, B0); BAR; SCHED;
;     LDB(B1, 0, 1); STAGE(SB(0, 0), rsB, bcol, t + 2);
;     BAR; WAIT_L(0); MMA(0, 1, At, B1); BAR;
;     LDA(At, 0, 1); STAGE(SA(0, 0), rsA, brow, t + 2);
;     BAR; WAIT_L(0); MMA(1, 0, At, B0); BAR; SCHED;
.LBB0_1365:
	ds_read_b128 v[156:159], v155
	ds_read_b128 v[160:163], v155 offset:1024
	ds_read_b128 v[164:167], v155 offset:2048
	ds_read_b128 v[168:171], v155 offset:3072
	s_add_i32 s19, s6, s11
	v_readfirstlane_b32 s15, v153
	s_add_i32 s14, s19, 0x40080
	s_mov_b32 m0, s15
	v_readfirstlane_b32 s15, v152
	ds_read_b128 v[174:177], v133
	ds_read_b128 v[178:181], v133 offset:1024
	ds_read_b128 v[198:201], v132
	ds_read_b128 v[202:205], v132 offset:1024
	ds_read_b128 v[206:209], v131
	ds_read_b128 v[210:213], v131 offset:1024
	ds_read_b128 v[214:217], v130
	ds_read_b128 v[218:221], v130 offset:1024
	buffer_load_dwordx4 v136, s[76:79], s14 offen lds
	s_mov_b32 m0, s15
	s_nop 0
	buffer_load_dwordx4 v135, s[76:79], s14 offen lds
	s_waitcnt lgkmcnt(8)
	s_barrier
	s_waitcnt lgkmcnt(0)
	s_waitcnt lgkmcnt(7)
	v_mfma_f32_16x16x32_f16 v[126:129], v[174:177], v[156:159], v[126:129]
	v_mfma_f32_16x16x32_f16 v[122:125], v[174:177], v[164:167], v[122:125]
	s_waitcnt lgkmcnt(5)
	v_mfma_f32_16x16x32_f16 v[118:121], v[198:201], v[156:159], v[118:121]
	v_mfma_f32_16x16x32_f16 v[114:117], v[198:201], v[164:167], v[114:117]
	s_waitcnt lgkmcnt(3)
	v_mfma_f32_16x16x32_f16 v[110:113], v[206:209], v[156:159], v[110:113]
	v_mfma_f32_16x16x32_f16 v[106:109], v[206:209], v[164:167], v[106:109]
	s_waitcnt lgkmcnt(1)
	v_mfma_f32_16x16x32_f16 v[102:105], v[214:217], v[156:159], v[102:105]
	v_mfma_f32_16x16x32_f16 v[98:101], v[214:217], v[164:167], v[98:101]
	v_mfma_f32_16x16x32_f16 v[126:129], v[178:181], v[160:163], v[126:129]
	v_mfma_f32_16x16x32_f16 v[122:125], v[178:181], v[168:171], v[122:125]
	v_mfma_f32_16x16x32_f16 v[118:121], v[202:205], v[160:163], v[118:121]
	v_mfma_f32_16x16x32_f16 v[114:117], v[202:205], v[168:171], v[114:117]
	v_mfma_f32_16x16x32_f16 v[110:113], v[210:213], v[160:163], v[110:113]
	v_mfma_f32_16x16x32_f16 v[106:109], v[210:213], v[168:171], v[106:109]
	s_waitcnt lgkmcnt(0)
	v_mfma_f32_16x16x32_f16 v[102:105], v[218:221], v[160:163], v[102:105]
	v_mfma_f32_16x16x32_f16 v[98:101], v[218:221], v[168:171], v[98:101]
	s_barrier
	s_add_i32 s20, s9, s11
	v_readfirstlane_b32 s22, v137
	s_add_i32 s21, s20, 0x100
	s_mov_b32 s14, s78
	s_mov_b32 s15, s79
	s_mov_b32 m0, s22
	v_readfirstlane_b32 s22, v139
	ds_read_b128 v[222:225], v150
	ds_read_b128 v[226:229], v150 offset:1024
	ds_read_b128 v[230:233], v150 offset:2048
	ds_read_b128 v[234:237], v150 offset:3072
	buffer_load_dwordx4 v136, s[12:15], s21 offen lds
	s_mov_b32 m0, s22
	s_nop 0
	buffer_load_dwordx4 v135, s[12:15], s21 offen lds
	s_barrier
	s_waitcnt lgkmcnt(0)
	s_waitcnt lgkmcnt(3)
	v_mfma_f32_16x16x32_f16 v[94:97], v[174:177], v[222:225], v[94:97]
	s_waitcnt lgkmcnt(1)
	v_mfma_f32_16x16x32_f16 v[90:93], v[174:177], v[230:233], v[90:93]
	v_mfma_f32_16x16x32_f16 v[86:89], v[198:201], v[222:225], v[86:89]
	v_mfma_f32_16x16x32_f16 v[82:85], v[198:201], v[230:233], v[82:85]
	v_mfma_f32_16x16x32_f16 v[78:81], v[206:209], v[222:225], v[78:81]
	v_mfma_f32_16x16x32_f16 v[74:77], v[206:209], v[230:233], v[74:77]
	v_mfma_f32_16x16x32_f16 v[70:73], v[214:217], v[222:225], v[70:73]
	v_mfma_f32_16x16x32_f16 v[66:69], v[214:217], v[230:233], v[66:69]
	v_mfma_f32_16x16x32_f16 v[94:97], v[178:181], v[226:229], v[94:97]
	s_waitcnt lgkmcnt(0)
	v_mfma_f32_16x16x32_f16 v[90:93], v[178:181], v[234:237], v[90:93]
	v_mfma_f32_16x16x32_f16 v[86:89], v[202:205], v[226:229], v[86:89]
	v_mfma_f32_16x16x32_f16 v[82:85], v[202:205], v[234:237], v[82:85]
	v_mfma_f32_16x16x32_f16 v[78:81], v[210:213], v[226:229], v[78:81]
	v_mfma_f32_16x16x32_f16 v[74:77], v[210:213], v[234:237], v[74:77]
	v_mfma_f32_16x16x32_f16 v[70:73], v[218:221], v[226:229], v[70:73]
	v_mfma_f32_16x16x32_f16 v[66:69], v[218:221], v[234:237], v[66:69]
	v_readfirstlane_b32 s22, v140
	s_add_i32 s21, s19, 0x100
	s_mov_b32 m0, s22
	v_readfirstlane_b32 s22, v141
	s_barrier
	ds_read_b128 v[174:177], v133 offset:16384
	ds_read_b128 v[178:181], v133 offset:17408
	ds_read_b128 v[198:201], v132 offset:16384
	ds_read_b128 v[202:205], v132 offset:17408
	ds_read_b128 v[206:209], v131 offset:16384
	ds_read_b128 v[210:213], v131 offset:17408
	ds_read_b128 v[214:217], v130 offset:16384
	ds_read_b128 v[218:221], v130 offset:17408
	buffer_load_dwordx4 v136, s[76:79], s21 offen lds
	s_mov_b32 m0, s22
	s_nop 0
	buffer_load_dwordx4 v135, s[76:79], s21 offen lds
	s_barrier
	s_waitcnt lgkmcnt(0)
	s_waitcnt lgkmcnt(7)
	v_mfma_f32_16x16x32_f16 v[62:65], v[174:177], v[156:159], v[62:65]
	v_mfma_f32_16x16x32_f16 v[58:61], v[174:177], v[164:167], v[58:61]
	s_waitcnt lgkmcnt(5)
	v_mfma_f32_16x16x32_f16 v[54:57], v[198:201], v[156:159], v[54:57]
	v_mfma_f32_16x16x32_f16 v[50:53], v[198:201], v[164:167], v[50:53]
	s_waitcnt lgkmcnt(3)
	v_mfma_f32_16x16x32_f16 v[46:49], v[206:209], v[156:159], v[46:49]
	v_mfma_f32_16x16x32_f16 v[42:45], v[206:209], v[164:167], v[42:45]
	s_waitcnt lgkmcnt(1)
	v_mfma_f32_16x16x32_f16 v[38:41], v[214:217], v[156:159], v[38:41]
	v_mfma_f32_16x16x32_f16 v[34:37], v[214:217], v[164:167], v[34:37]
	v_mfma_f32_16x16x32_f16 v[62:65], v[178:181], v[160:163], v[62:65]
	v_mfma_f32_16x16x32_f16 v[58:61], v[178:181], v[168:171], v[58:61]
	v_mfma_f32_16x16x32_f16 v[54:57], v[202:205], v[160:163], v[54:57]
	v_mfma_f32_16x16x32_f16 v[50:53], v[202:205], v[168:171], v[50:53]
	v_mfma_f32_16x16x32_f16 v[46:49], v[210:213], v[160:163], v[46:49]
	v_mfma_f32_16x16x32_f16 v[42:45], v[210:213], v[168:171], v[42:45]
	s_waitcnt lgkmcnt(0)
	v_mfma_f32_16x16x32_f16 v[38:41], v[218:221], v[160:163], v[38:41]
	v_mfma_f32_16x16x32_f16 v[34:37], v[218:221], v[168:171], v[34:37]
	s_barrier
; #define WAIT_V(n) asm volatile("s_waitcnt vmcnt(" #n ")" ::: "memory")
; #define WAIT_L(n) asm volatile("s_waitcnt lgkmcnt(" #n ")" ::: "memory")
; #define BAR __builtin_amdgcn_s_barrier()
; #define SCHED __builtin_amdgcn_sched_barrier(0)
; DEV void gemm_tile(const h16* __restrict__ A, const h16* __restrict__ Bt, int K, int ld, int brow, int bcol, h16* shm, Acc& acc) {
;     ...
;     STAGE(SB(0, 1), rsB, bcol + HALF_, t + 2);
;     WAIT_V(6); BAR; MMA(1, 1, At, B1); BAR;
;     LDB(B0, 1, 0); SCHED; LDA(At, 1, 0); STAGE(SA(0, 1), rsA, brow + HALF_, t + 2);
;     WAIT_L(8); BAR; WAIT_L(0); MMA(0, 0, At, B0); BAR; SCHED;
;     LDB(B1, 1, 1); STAGE(SB(1, 0), rsB, bcol, t + 3);
;     BAR; WAIT_L(0); MMA(0, 1, At, B1); BAR;
;     LDA(At, 1, 1); STAGE(SA(1, 0), rsA, brow, t + 3);
	v_readfirstlane_b32 s22, v142
	s_add_i32 s21, s20, 0x40100
	s_mov_b32 m0, s22
	v_readfirstlane_b32 s22, v143
	buffer_load_dwordx4 v136, s[12:15], s21 offen lds
	s_mov_b32 m0, s22
	s_nop 0
	buffer_load_dwordx4 v135, s[12:15], s21 offen lds
	s_waitcnt vmcnt(6)
	s_barrier
	v_mfma_f32_16x16x32_f16 v[30:33], v[174:177], v[222:225], v[30:33]
	v_mfma_f32_16x16x32_f16 v[26:29], v[174:177], v[230:233], v[26:29]
	v_mfma_f32_16x16x32_f16 v[22:25], v[198:201], v[222:225], v[22:25]
	v_mfma_f32_16x16x32_f16 v[18:21], v[198:201], v[230:233], v[18:21]
	v_mfma_f32_16x16x32_f16 v[14:17], v[206:209], v[222:225], v[14:17]
	v_mfma_f32_16x16x32_f16 v[10:13], v[206:209], v[230:233], v[10:13]
	v_mfma_f32_16x16x32_f16 v[6:9], v[214:217], v[222:225], v[6:9]
	v_mfma_f32_16x16x32_f16 v[2:5], v[214:217], v[230:233], v[2:5]
	v_mfma_f32_16x16x32_f16 v[30:33], v[178:181], v[226:229], v[30:33]
	v_mfma_f32_16x16x32_f16 v[26:29], v[178:181], v[234:237], v[26:29]
	v_mfma_f32_16x16x32_f16 v[22:25], v[202:205], v[226:229], v[22:25]
	v_mfma_f32_16x16x32_f16 v[18:21], v[202:205], v[234:237], v[18:21]
	v_mfma_f32_16x16x32_f16 v[14:17], v[210:213], v[226:229], v[14:17]
	v_mfma_f32_16x16x32_f16 v[10:13], v[210:213], v[234:237], v[10:13]
	v_mfma_f32_16x16x32_f16 v[6:9], v[218:221], v[226:229], v[6:9]
	v_mfma_f32_16x16x32_f16 v[2:5], v[218:221], v[234:237], v[2:5]
	s_barrier
	ds_read_b128 v[156:159], v138
	ds_read_b128 v[160:163], v138 offset:1024
	ds_read_b128 v[164:167], v138 offset:2048
	ds_read_b128 v[168:171], v138 offset:3072
	v_readfirstlane_b32 s22, v144
	s_add_i32 s21, s19, 0x40100
	s_mov_b32 m0, s22
	v_readfirstlane_b32 s22, v145
	ds_read_b128 v[174:177], v133 offset:32768
	ds_read_b128 v[178:181], v133 offset:33792
	ds_read_b128 v[198:201], v132 offset:32768
	ds_read_b128 v[202:205], v132 offset:33792
	ds_read_b128 v[206:209], v131 offset:32768
	ds_read_b128 v[210:213], v131 offset:33792
	ds_read_b128 v[214:217], v130 offset:32768
	ds_read_b128 v[218:221], v130 offset:33792
	buffer_load_dwordx4 v136, s[76:79], s21 offen lds
	s_mov_b32 m0, s22
	s_nop 0
	buffer_load_dwordx4 v135, s[76:79], s21 offen lds
	s_waitcnt lgkmcnt(8)
	s_barrier
	s_waitcnt lgkmcnt(0)
	s_waitcnt lgkmcnt(7)
	v_mfma_f32_16x16x32_f16 v[126:129], v[174:177], v[156:159], v[126:129]
	v_mfma_f32_16x16x32_f16 v[122:125], v[174:177], v[164:167], v[122:125]
	s_waitcnt lgkmcnt(5)
	v_mfma_f32_16x16x32_f16 v[118:121], v[198:201], v[156:159], v[118:121]
	v_mfma_f32_16x16x32_f16 v[114:117], v[198:201], v[164:167], v[114:117]
	s_waitcnt lgkmcnt(3)
	v_mfma_f32_16x16x32_f16 v[110:113], v[206:209], v[156:159], v[110:113]
	v_mfma_f32_16x16x32_f16 v[106:109], v[206:209], v[164:167], v[106:109]
	s_waitcnt lgkmcnt(1)
	v_mfma_f32_16x16x32_f16 v[102:105], v[214:217], v[156:159], v[102:105]
	v_mfma_f32_16x16x32_f16 v[98:101], v[214:217], v[164:167], v[98:101]
	v_mfma_f32_16x16x32_f16 v[126:129], v[178:181], v[160:163], v[126:129]
	v_mfma_f32_16x16x32_f16 v[122:125], v[178:181], v[168:171], v[122:125]
	v_mfma_f32_16x16x32_f16 v[118:121], v[202:205], v[160:163], v[118:121]
	v_mfma_f32_16x16x32_f16 v[114:117], v[202:205], v[168:171], v[114:117]
	v_mfma_f32_16x16x32_f16 v[110:113], v[210:213], v[160:163], v[110:113]
	v_mfma_f32_16x16x32_f16 v[106:109], v[210:213], v[168:171], v[106:109]
	s_waitcnt lgkmcnt(0)
	v_mfma_f32_16x16x32_f16 v[102:105], v[218:221], v[160:163], v[102:105]
	v_mfma_f32_16x16x32_f16 v[98:101], v[218:221], v[168:171], v[98:101]
	s_barrier
	v_readfirstlane_b32 s22, v146
	s_add_i32 s21, s20, 0x180
	s_mov_b32 m0, s22
	v_readfirstlane_b32 s22, v147
	ds_read_b128 v[222:225], v134
	ds_read_b128 v[226:229], v134 offset:1024
	ds_read_b128 v[230:233], v134 offset:2048
	ds_read_b128 v[234:237], v134 offset:3072
	buffer_load_dwordx4 v136, s[12:15], s21 offen lds
	s_mov_b32 m0, s22
	s_nop 0
	buffer_load_dwordx4 v135, s[12:15], s21 offen lds
	s_barrier
	s_waitcnt lgkmcnt(0)
	s_waitcnt lgkmcnt(3)
	v_mfma_f32_16x16x32_f16 v[94:97], v[174:177], v[222:225], v[94:97]
	s_waitcnt lgkmcnt(1)
	v_mfma_f32_16x16x32_f16 v[90:93], v[174:177], v[230:233], v[90:93]
	v_mfma_f32_16x16x32_f16 v[86:89], v[198:201], v[222:225], v[86:89]
	v_mfma_f32_16x16x32_f16 v[82:85], v[198:201], v[230:233], v[82:85]
	v_mfma_f32_16x16x32_f16 v[78:81], v[206:209], v[222:225], v[78:81]
	v_mfma_f32_16x16x32_f16 v[74:77], v[206:209], v[230:233], v[74:77]
	v_mfma_f32_16x16x32_f16 v[70:73], v[214:217], v[222:225], v[70:73]
	v_mfma_f32_16x16x32_f16 v[66:69], v[214:217], v[230:233], v[66:69]
	v_mfma_f32_16x16x32_f16 v[94:97], v[178:181], v[226:229], v[94:97]
	s_waitcnt lgkmcnt(0)
	v_mfma_f32_16x16x32_f16 v[90:93], v[178:181], v[234:237], v[90:93]
	v_mfma_f32_16x16x32_f16 v[86:89], v[202:205], v[226:229], v[86:89]
	v_mfma_f32_16x16x32_f16 v[82:85], v[202:205], v[234:237], v[82:85]
	v_mfma_f32_16x16x32_f16 v[78:81], v[210:213], v[226:229], v[78:81]
	v_mfma_f32_16x16x32_f16 v[74:77], v[210:213], v[234:237], v[74:77]
	v_mfma_f32_16x16x32_f16 v[70:73], v[218:221], v[226:229], v[70:73]
	v_mfma_f32_16x16x32_f16 v[66:69], v[218:221], v[234:237], v[66:69]
	v_readfirstlane_b32 s21, v148
	s_addk_i32 s19, 0x180
	s_mov_b32 m0, s21
	v_readfirstlane_b32 s21, v149
	s_barrier
	ds_read_b128 v[174:177], v133 offset:49152
	ds_read_b128 v[178:181], v133 offset:50176
	ds_read_b128 v[198:201], v132 offset:49152
	ds_read_b128 v[202:205], v132 offset:50176
	ds_read_b128 v[206:209], v131 offset:49152
	ds_read_b128 v[210:213], v131 offset:50176
	ds_read_b128 v[214:217], v130 offset:49152
	ds_read_b128 v[218:221], v130 offset:50176
	buffer_load_dwordx4 v136, s[76:79], s19 offen lds
	s_mov_b32 m0, s21
	s_nop 0
	buffer_load_dwordx4 v135, s[76:79], s19 offen lds
	s_barrier
; #define WAIT_V(n) asm volatile("s_waitcnt vmcnt(" #n ")" ::: "memory")
; #define WAIT_L(n) asm volatile("s_waitcnt lgkmcnt(" #n ")" ::: "memory")
; #define BAR __builtin_amdgcn_s_barrier()
; #define SCHED __builtin_amdgcn_sched_barrier(0)
; DEV void gemm_tile(const h16* __restrict__ A, const h16* __restrict__ Bt, int K, int ld, int brow, int bcol, h16* shm, Acc& acc) {
;     ...
;     BAR; WAIT_L(0); MMA(1, 0, At, B0); BAR; SCHED;
;     STAGE(SB(1, 1), rsB, bcol + HALF_, t + 3);
;     WAIT_V(6); BAR; MMA(1, 1, At, B1); BAR;
;   }
;   { LDB(B0, 0, 0); LDA(At, 0, 0); STAGE(SA(1, 1), rsA, brow + HALF_, nt - 1);
;     BAR; WAIT_L(0); MMA(0, 0, At, B0); BAR;
;     LDB(B1, 0, 1); BAR; WAIT_L(0); MMA(0, 1, At, B1); BAR;
	s_waitcnt lgkmcnt(0)
	s_waitcnt lgkmcnt(7)
	v_mfma_f32_16x16x32_f16 v[62:65], v[174:177], v[156:159], v[62:65]
	v_mfma_f32_16x16x32_f16 v[58:61], v[174:177], v[164:167], v[58:61]
	s_waitcnt lgkmcnt(5)
	v_mfma_f32_16x16x32_f16 v[54:57], v[198:201], v[156:159], v[54:57]
	v_mfma_f32_16x16x32_f16 v[50:53], v[198:201], v[164:167], v[50:53]
	s_waitcnt lgkmcnt(3)
	v_mfma_f32_16x16x32_f16 v[46:49], v[206:209], v[156:159], v[46:49]
	v_mfma_f32_16x16x32_f16 v[42:45], v[206:209], v[164:167], v[42:45]
	s_waitcnt lgkmcnt(1)
	v_mfma_f32_16x16x32_f16 v[38:41], v[214:217], v[156:159], v[38:41]
	v_mfma_f32_16x16x32_f16 v[34:37], v[214:217], v[164:167], v[34:37]
	v_mfma_f32_16x16x32_f16 v[62:65], v[178:181], v[160:163], v[62:65]
	v_mfma_f32_16x16x32_f16 v[58:61], v[178:181], v[168:171], v[58:61]
	v_mfma_f32_16x16x32_f16 v[54:57], v[202:205], v[160:163], v[54:57]
	v_mfma_f32_16x16x32_f16 v[50:53], v[202:205], v[168:171], v[50:53]
	v_mfma_f32_16x16x32_f16 v[46:49], v[210:213], v[160:163], v[46:49]
	v_mfma_f32_16x16x32_f16 v[42:45], v[210:213], v[168:171], v[42:45]
	s_waitcnt lgkmcnt(0)
	v_mfma_f32_16x16x32_f16 v[38:41], v[218:221], v[160:163], v[38:41]
	v_mfma_f32_16x16x32_f16 v[34:37], v[218:221], v[168:171], v[34:37]
	s_barrier
	v_readfirstlane_b32 s19, v151
	s_add_i32 s20, s20, 0x40180
	s_mov_b32 m0, s19
	v_readfirstlane_b32 s19, v154
	buffer_load_dwordx4 v136, s[12:15], s20 offen lds
	s_mov_b32 m0, s19
	s_nop 0
	buffer_load_dwordx4 v135, s[12:15], s20 offen lds
	s_waitcnt vmcnt(6)
	s_barrier
	v_mfma_f32_16x16x32_f16 v[30:33], v[174:177], v[222:225], v[30:33]
	v_mfma_f32_16x16x32_f16 v[26:29], v[174:177], v[230:233], v[26:29]
	v_mfma_f32_16x16x32_f16 v[22:25], v[198:201], v[222:225], v[22:25]
	v_mfma_f32_16x16x32_f16 v[18:21], v[198:201], v[230:233], v[18:21]
	v_mfma_f32_16x16x32_f16 v[14:17], v[206:209], v[222:225], v[14:17]
	v_mfma_f32_16x16x32_f16 v[10:13], v[206:209], v[230:233], v[10:13]
	v_mfma_f32_16x16x32_f16 v[6:9], v[214:217], v[222:225], v[6:9]
	v_mfma_f32_16x16x32_f16 v[2:5], v[214:217], v[230:233], v[2:5]
	v_mfma_f32_16x16x32_f16 v[30:33], v[178:181], v[226:229], v[30:33]
	v_mfma_f32_16x16x32_f16 v[26:29], v[178:181], v[234:237], v[26:29]
	v_mfma_f32_16x16x32_f16 v[22:25], v[202:205], v[226:229], v[22:25]
	v_mfma_f32_16x16x32_f16 v[18:21], v[202:205], v[234:237], v[18:21]
	v_mfma_f32_16x16x32_f16 v[14:17], v[210:213], v[226:229], v[14:17]
	v_mfma_f32_16x16x32_f16 v[10:13], v[210:213], v[234:237], v[10:13]
	v_mfma_f32_16x16x32_f16 v[6:9], v[218:221], v[226:229], v[6:9]
	v_mfma_f32_16x16x32_f16 v[2:5], v[218:221], v[234:237], v[2:5]
	s_add_i32 s7, s7, 2
	s_addk_i32 s11, 0x100
	s_cmp_lt_u32 s7, 12
	s_barrier
	s_cbranch_scc1 .LBB0_1365
	v_readfirstlane_b32 s7, v153
	s_or_b32 s6, s10, 0x780
	s_mov_b32 m0, s7
	v_readfirstlane_b32 s7, v152
	ds_read_b128 v[140:143], v155
	ds_read_b128 v[144:147], v155 offset:1024
	ds_read_b128 v[156:159], v155 offset:2048
	ds_read_b128 v[160:163], v155 offset:3072
	ds_read_b128 v[164:167], v133
	ds_read_b128 v[168:171], v133 offset:1024
	ds_read_b128 v[174:177], v132
	ds_read_b128 v[178:181], v132 offset:1024
	ds_read_b128 v[198:201], v131
	ds_read_b128 v[202:205], v131 offset:1024
	ds_read_b128 v[206:209], v130
	ds_read_b128 v[210:213], v130 offset:1024
	buffer_load_dwordx4 v136, s[76:79], s6 offen lds
	s_mov_b32 m0, s7
	s_nop 0
	buffer_load_dwordx4 v135, s[76:79], s6 offen lds
	s_barrier
	s_waitcnt lgkmcnt(0)
	s_waitcnt lgkmcnt(7)
	v_mfma_f32_16x16x32_f16 v[126:129], v[164:167], v[140:143], v[126:129]
	v_mfma_f32_16x16x32_f16 v[122:125], v[164:167], v[156:159], v[122:125]
	s_waitcnt lgkmcnt(5)
	v_mfma_f32_16x16x32_f16 v[118:121], v[174:177], v[140:143], v[118:121]
	v_mfma_f32_16x16x32_f16 v[114:117], v[174:177], v[156:159], v[114:117]
	v_mfma_f32_16x16x32_f16 v[126:129], v[168:171], v[144:147], v[126:129]
	v_mfma_f32_16x16x32_f16 v[122:125], v[168:171], v[160:163], v[122:125]
	s_waitcnt lgkmcnt(4)
	v_mfma_f32_16x16x32_f16 v[118:121], v[178:181], v[144:147], v[118:121]
	v_mfma_f32_16x16x32_f16 v[114:117], v[178:181], v[160:163], v[114:117]
	s_waitcnt lgkmcnt(3)
	v_mfma_f32_16x16x32_f16 v[110:113], v[198:201], v[140:143], v[110:113]
	v_mfma_f32_16x16x32_f16 v[106:109], v[198:201], v[156:159], v[106:109]
	s_waitcnt lgkmcnt(1)
	v_mfma_f32_16x16x32_f16 v[102:105], v[206:209], v[140:143], v[102:105]
	v_mfma_f32_16x16x32_f16 v[98:101], v[206:209], v[156:159], v[98:101]
	v_mfma_f32_16x16x32_f16 v[152:155], v[202:205], v[144:147], v[110:113]
	v_mfma_f32_16x16x32_f16 v[214:217], v[202:205], v[160:163], v[106:109]
	s_waitcnt lgkmcnt(0)
	v_mfma_f32_16x16x32_f16 v[218:221], v[210:213], v[144:147], v[102:105]
	v_mfma_f32_16x16x32_f16 v[222:225], v[210:213], v[160:163], v[98:101]
	s_barrier
	s_nop 0
	ds_read_b128 v[98:101], v150
	ds_read_b128 v[102:105], v150 offset:1024
	ds_read_b128 v[106:109], v150 offset:2048
	ds_read_b128 v[110:113], v150 offset:3072
	s_barrier
	s_waitcnt lgkmcnt(0)
	s_waitcnt lgkmcnt(3)
	v_mfma_f32_16x16x32_f16 v[94:97], v[164:167], v[98:101], v[94:97]
	s_waitcnt lgkmcnt(1)
	v_mfma_f32_16x16x32_f16 v[90:93], v[164:167], v[106:109], v[90:93]
	v_mfma_f32_16x16x32_f16 v[86:89], v[174:177], v[98:101], v[86:89]
	v_mfma_f32_16x16x32_f16 v[82:85], v[174:177], v[106:109], v[82:85]
	v_mfma_f32_16x16x32_f16 v[94:97], v[168:171], v[102:105], v[94:97]
	s_waitcnt lgkmcnt(0)
	v_mfma_f32_16x16x32_f16 v[90:93], v[168:171], v[110:113], v[90:93]
	v_mfma_f32_16x16x32_f16 v[86:89], v[178:181], v[102:105], v[86:89]
	v_mfma_f32_16x16x32_f16 v[82:85], v[178:181], v[110:113], v[82:85]
	v_mfma_f32_16x16x32_f16 v[78:81], v[198:201], v[98:101], v[78:81]
	v_mfma_f32_16x16x32_f16 v[74:77], v[198:201], v[106:109], v[74:77]
	v_mfma_f32_16x16x32_f16 v[70:73], v[206:209], v[98:101], v[70:73]
	v_mfma_f32_16x16x32_f16 v[66:69], v[206:209], v[106:109], v[66:69]
	v_mfma_f32_16x16x32_f16 v[148:151], v[202:205], v[102:105], v[78:81]
	v_mfma_f32_16x16x32_f16 v[164:167], v[202:205], v[110:113], v[74:77]
	v_mfma_f32_16x16x32_f16 v[168:171], v[210:213], v[102:105], v[70:73]
	v_mfma_f32_16x16x32_f16 v[174:177], v[210:213], v[110:113], v[66:69]
	s_barrier
; #define WAIT_V(n) asm volatile("s_waitcnt vmcnt(" #n ")" ::: "memory")
; #define WAIT_L(n) asm volatile("s_waitcnt lgkmcnt(" #n ")" ::: "memory")
; #define BAR __builtin_amdgcn_s_barrier()
; DEV void gemm_tile(const h16* __restrict__ A, const h16* __restrict__ Bt, int K, int ld, int brow, int bcol, h16* shm, Acc& acc) {
;     ...
;     LDA(At, 0, 1); WAIT_V(4); BAR; WAIT_L(0); MMA(1, 0, At, B0); MMA(1, 1, At, B1); BAR; }
;   { LDB(B0, 1, 0); LDA(At, 1, 0); WAIT_V(2); BAR; WAIT_L(0); MMA(0, 0, At, B0); BAR;
	s_nop 1
	ds_read_b128 v[66:69], v133 offset:16384
	ds_read_b128 v[70:73], v133 offset:17408
	ds_read_b128 v[74:77], v132 offset:16384
	ds_read_b128 v[78:81], v132 offset:17408
	ds_read_b128 v[178:181], v131 offset:16384
	ds_read_b128 v[198:201], v131 offset:17408
	ds_read_b128 v[202:205], v130 offset:16384
	ds_read_b128 v[206:209], v130 offset:17408
	s_waitcnt vmcnt(4)
	s_barrier
	s_waitcnt lgkmcnt(0)
	s_waitcnt lgkmcnt(7)
	v_mfma_f32_16x16x32_f16 v[62:65], v[66:69], v[140:143], v[62:65]
	v_mfma_f32_16x16x32_f16 v[58:61], v[66:69], v[156:159], v[58:61]
	s_waitcnt lgkmcnt(5)
	v_mfma_f32_16x16x32_f16 v[54:57], v[74:77], v[140:143], v[54:57]
	v_mfma_f32_16x16x32_f16 v[50:53], v[74:77], v[156:159], v[50:53]
	v_mfma_f32_16x16x32_f16 v[62:65], v[70:73], v[144:147], v[62:65]
	v_mfma_f32_16x16x32_f16 v[58:61], v[70:73], v[160:163], v[58:61]
	s_waitcnt lgkmcnt(4)
	v_mfma_f32_16x16x32_f16 v[54:57], v[78:81], v[144:147], v[54:57]
	v_mfma_f32_16x16x32_f16 v[50:53], v[78:81], v[160:163], v[50:53]
	s_waitcnt lgkmcnt(3)
	v_mfma_f32_16x16x32_f16 v[46:49], v[178:181], v[140:143], v[46:49]
	v_mfma_f32_16x16x32_f16 v[42:45], v[178:181], v[156:159], v[42:45]
	s_waitcnt lgkmcnt(1)
	v_mfma_f32_16x16x32_f16 v[38:41], v[202:205], v[140:143], v[38:41]
	v_mfma_f32_16x16x32_f16 v[34:37], v[202:205], v[156:159], v[34:37]
	v_mfma_f32_16x16x32_f16 v[210:213], v[198:201], v[144:147], v[46:49]
	v_mfma_f32_16x16x32_f16 v[226:229], v[198:201], v[160:163], v[42:45]
	s_waitcnt lgkmcnt(0)
	v_mfma_f32_16x16x32_f16 v[140:143], v[206:209], v[144:147], v[38:41]
	v_mfma_f32_16x16x32_f16 v[144:147], v[206:209], v[160:163], v[34:37]
	v_mfma_f32_16x16x32_f16 v[30:33], v[66:69], v[98:101], v[30:33]
	v_mfma_f32_16x16x32_f16 v[26:29], v[66:69], v[106:109], v[26:29]
	v_mfma_f32_16x16x32_f16 v[22:25], v[74:77], v[98:101], v[22:25]
	v_mfma_f32_16x16x32_f16 v[18:21], v[74:77], v[106:109], v[18:21]
	v_mfma_f32_16x16x32_f16 v[30:33], v[70:73], v[102:105], v[30:33]
	v_mfma_f32_16x16x32_f16 v[26:29], v[70:73], v[110:113], v[26:29]
	v_mfma_f32_16x16x32_f16 v[22:25], v[78:81], v[102:105], v[22:25]
	v_mfma_f32_16x16x32_f16 v[18:21], v[78:81], v[110:113], v[18:21]
	v_mfma_f32_16x16x32_f16 v[14:17], v[178:181], v[98:101], v[14:17]
	v_mfma_f32_16x16x32_f16 v[10:13], v[178:181], v[106:109], v[10:13]
	v_mfma_f32_16x16x32_f16 v[6:9], v[202:205], v[98:101], v[6:9]
	v_mfma_f32_16x16x32_f16 v[2:5], v[202:205], v[106:109], v[2:5]
	v_mfma_f32_16x16x32_f16 v[156:159], v[198:201], v[102:105], v[14:17]
	v_mfma_f32_16x16x32_f16 v[160:163], v[198:201], v[110:113], v[10:13]
	v_mfma_f32_16x16x32_f16 v[178:181], v[206:209], v[102:105], v[6:9]
	v_mfma_f32_16x16x32_f16 v[198:201], v[206:209], v[110:113], v[2:5]
	s_barrier
	s_nop 1
	ds_read_b128 v[2:5], v138
	ds_read_b128 v[6:9], v138 offset:1024
	ds_read_b128 v[202:205], v138 offset:2048
	ds_read_b128 v[136:139], v138 offset:3072
	ds_read_b128 v[10:13], v133 offset:32768
	ds_read_b128 v[14:17], v133 offset:33792
	ds_read_b128 v[34:37], v132 offset:32768
	ds_read_b128 v[38:41], v132 offset:33792
	ds_read_b128 v[42:45], v131 offset:32768
	ds_read_b128 v[46:49], v131 offset:33792
	ds_read_b128 v[206:209], v130 offset:32768
	ds_read_b128 v[230:233], v130 offset:33792
	s_waitcnt vmcnt(2)
	s_barrier
	s_waitcnt lgkmcnt(0)
	s_waitcnt lgkmcnt(7)
	v_mfma_f32_16x16x32_f16 v[66:69], v[10:13], v[2:5], v[126:129]
	s_waitcnt lgkmcnt(6)
	v_mfma_f32_16x16x32_f16 v[106:109], v[14:17], v[6:9], v[66:69]
	v_mfma_f32_16x16x32_f16 v[66:69], v[10:13], v[202:205], v[122:125]
	v_mfma_f32_16x16x32_f16 v[110:113], v[14:17], v[136:139], v[66:69]
	s_waitcnt lgkmcnt(5)
	v_mfma_f32_16x16x32_f16 v[66:69], v[34:37], v[2:5], v[118:121]
	s_waitcnt lgkmcnt(4)
	v_mfma_f32_16x16x32_f16 v[98:101], v[38:41], v[6:9], v[66:69]
	v_mfma_f32_16x16x32_f16 v[66:69], v[34:37], v[202:205], v[114:117]
	v_mfma_f32_16x16x32_f16 v[102:105], v[38:41], v[136:139], v[66:69]
	s_waitcnt lgkmcnt(3)
	v_mfma_f32_16x16x32_f16 v[66:69], v[42:45], v[2:5], v[152:155]
	s_waitcnt lgkmcnt(2)
	v_mfma_f32_16x16x32_f16 v[74:77], v[46:49], v[6:9], v[66:69]
	v_mfma_f32_16x16x32_f16 v[66:69], v[42:45], v[202:205], v[214:217]
	v_mfma_f32_16x16x32_f16 v[78:81], v[46:49], v[136:139], v[66:69]
	s_waitcnt lgkmcnt(1)
	v_mfma_f32_16x16x32_f16 v[66:69], v[206:209], v[2:5], v[218:221]
	v_mfma_f32_16x16x32_f16 v[70:73], v[206:209], v[202:205], v[222:225]
	s_waitcnt lgkmcnt(0)
	v_mfma_f32_16x16x32_f16 v[66:69], v[230:233], v[6:9], v[66:69]
	v_mfma_f32_16x16x32_f16 v[70:73], v[230:233], v[136:139], v[70:73]
	s_barrier
; #define WAIT_V(n) asm volatile("s_waitcnt vmcnt(" #n ")" ::: "memory")
; #define WAIT_L(n) asm volatile("s_waitcnt lgkmcnt(" #n ")" ::: "memory")
; #define BAR __builtin_amdgcn_s_barrier()
; DEV void gemm_tile(const h16* __restrict__ A, const h16* __restrict__ Bt, int K, int ld, int brow, int bcol, h16* shm, Acc& acc) {
;     ...
;     LDB(B1, 1, 1); WAIT_V(0); BAR; WAIT_L(0); MMA(0, 1, At, B1); BAR;
;     LDA(At, 1, 1); BAR; WAIT_L(0); MMA(1, 0, At, B0); MMA(1, 1, At, B1); BAR; }
;   if (wr == 0) BAR;
	ds_read_b128 v[152:155], v134
	ds_read_b128 v[214:217], v134 offset:1024
	ds_read_b128 v[218:221], v134 offset:2048
	ds_read_b128 v[222:225], v134 offset:3072
	s_waitcnt vmcnt(0)
	s_barrier
	s_waitcnt lgkmcnt(0)
	s_waitcnt lgkmcnt(3)
	v_mfma_f32_16x16x32_f16 v[94:97], v[10:13], v[152:155], v[94:97]
	s_waitcnt lgkmcnt(1)
	v_mfma_f32_16x16x32_f16 v[10:13], v[10:13], v[218:221], v[90:93]
	s_waitcnt lgkmcnt(0)
	v_mfma_f32_16x16x32_f16 v[126:129], v[14:17], v[222:225], v[10:13]
	v_mfma_f32_16x16x32_f16 v[10:13], v[34:37], v[152:155], v[86:89]
	v_mfma_f32_16x16x32_f16 v[114:117], v[38:41], v[214:217], v[10:13]
	v_mfma_f32_16x16x32_f16 v[10:13], v[34:37], v[218:221], v[82:85]
	v_mfma_f32_16x16x32_f16 v[118:121], v[38:41], v[222:225], v[10:13]
	v_mfma_f32_16x16x32_f16 v[10:13], v[42:45], v[152:155], v[148:151]
	v_mfma_f32_16x16x32_f16 v[90:93], v[46:49], v[214:217], v[10:13]
	v_mfma_f32_16x16x32_f16 v[10:13], v[42:45], v[218:221], v[164:167]
	v_mfma_f32_16x16x32_f16 v[122:125], v[14:17], v[214:217], v[94:97]
	v_mfma_f32_16x16x32_f16 v[94:97], v[46:49], v[222:225], v[10:13]
	v_mfma_f32_16x16x32_f16 v[10:13], v[206:209], v[152:155], v[168:171]
	v_mfma_f32_16x16x32_f16 v[82:85], v[230:233], v[214:217], v[10:13]
	v_mfma_f32_16x16x32_f16 v[10:13], v[206:209], v[218:221], v[174:177]
	v_mfma_f32_16x16x32_f16 v[86:89], v[230:233], v[222:225], v[10:13]
	s_barrier
	ds_read_b128 v[148:151], v133 offset:49152
	ds_read_b128 v[164:167], v133 offset:50176
	ds_read_b128 v[168:171], v132 offset:49152
	ds_read_b128 v[132:135], v132 offset:50176
	ds_read_b128 v[174:177], v131 offset:49152
	ds_read_b128 v[206:209], v131 offset:50176
	ds_read_b128 v[230:233], v130 offset:49152
	ds_read_b128 v[234:237], v130 offset:50176
	s_barrier
	s_waitcnt lgkmcnt(0)
	s_waitcnt lgkmcnt(7)
	v_mfma_f32_16x16x32_f16 v[10:13], v[148:151], v[2:5], v[62:65]
	s_waitcnt lgkmcnt(6)
	v_mfma_f32_16x16x32_f16 v[42:45], v[164:167], v[6:9], v[10:13]
	v_mfma_f32_16x16x32_f16 v[10:13], v[148:151], v[202:205], v[58:61]
	v_mfma_f32_16x16x32_f16 v[46:49], v[164:167], v[136:139], v[10:13]
	s_waitcnt lgkmcnt(5)
	v_mfma_f32_16x16x32_f16 v[10:13], v[168:171], v[2:5], v[54:57]
	s_waitcnt lgkmcnt(4)
	v_mfma_f32_16x16x32_f16 v[34:37], v[132:135], v[6:9], v[10:13]
	v_mfma_f32_16x16x32_f16 v[10:13], v[168:171], v[202:205], v[50:53]
	v_mfma_f32_16x16x32_f16 v[38:41], v[132:135], v[136:139], v[10:13]
	s_waitcnt lgkmcnt(3)
	v_mfma_f32_16x16x32_f16 v[10:13], v[174:177], v[2:5], v[210:213]
	s_waitcnt lgkmcnt(1)
	v_mfma_f32_16x16x32_f16 v[2:5], v[230:233], v[2:5], v[140:143]
	v_mfma_f32_16x16x32_f16 v[10:13], v[206:209], v[6:9], v[10:13]
	v_mfma_f32_16x16x32_f16 v[14:17], v[174:177], v[202:205], v[226:229]
	s_waitcnt lgkmcnt(0)
	v_mfma_f32_16x16x32_f16 v[2:5], v[234:237], v[6:9], v[2:5]
	v_mfma_f32_16x16x32_f16 v[6:9], v[230:233], v[202:205], v[144:147]
	v_mfma_f32_16x16x32_f16 v[14:17], v[206:209], v[136:139], v[14:17]
	v_mfma_f32_16x16x32_f16 v[6:9], v[234:237], v[136:139], v[6:9]
	v_mfma_f32_16x16x32_f16 v[18:21], v[168:171], v[218:221], v[18:21]
	v_mfma_f32_16x16x32_f16 v[26:29], v[148:151], v[218:221], v[26:29]
	v_mfma_f32_16x16x32_f16 v[54:57], v[132:135], v[222:225], v[18:21]
	v_mfma_f32_16x16x32_f16 v[18:21], v[174:177], v[152:155], v[156:159]
	v_mfma_f32_16x16x32_f16 v[30:33], v[148:151], v[152:155], v[30:33]
	v_mfma_f32_16x16x32_f16 v[62:65], v[164:167], v[222:225], v[26:29]
	v_mfma_f32_16x16x32_f16 v[22:25], v[168:171], v[152:155], v[22:25]
	v_mfma_f32_16x16x32_f16 v[26:29], v[206:209], v[214:217], v[18:21]
	v_mfma_f32_16x16x32_f16 v[18:21], v[174:177], v[218:221], v[160:163]
	v_mfma_f32_16x16x32_f16 v[58:61], v[164:167], v[214:217], v[30:33]
	v_mfma_f32_16x16x32_f16 v[50:53], v[132:135], v[214:217], v[22:25]
	v_mfma_f32_16x16x32_f16 v[30:33], v[206:209], v[222:225], v[18:21]
	v_mfma_f32_16x16x32_f16 v[18:21], v[230:233], v[152:155], v[178:181]
	v_mfma_f32_16x16x32_f16 v[22:25], v[230:233], v[218:221], v[198:201]
	v_mfma_f32_16x16x32_f16 v[18:21], v[234:237], v[214:217], v[18:21]
	v_mfma_f32_16x16x32_f16 v[22:25], v[234:237], v[222:225], v[22:25]
	s_setprio 0
	s_movk_i32 s6, 0x100
	v_cmp_gt_u32_e32 vcc, s6, v0
	s_barrier
	s_and_saveexec_b64 s[6:7], vcc
	s_cbranch_execz .LBB0_1368
	s_barrier

; #define WAIT_V(n) asm volatile("s_waitcnt vmcnt(" #n ")" ::: "memory")
; #define BAR __builtin_amdgcn_s_barrier()
; DEV void gemm_tile(const h16* __restrict__ A, const h16* __restrict__ Bt, int K, int ld, int brow, int bcol, h16* shm, Acc& acc) {
;     ...
;   int wid = TID >> 6, lane = TID & 63, wr = wid >> 2, wc = wid & 3, fr = lane & 15, fq = lane >> 4;
;   int vo0, vo1;
;   {
;     int r, c;
;     stage_rc(TID * 16, r, c);
;     vo0 = (r * ld + c) * 2;
;     stage_rc(TID * 16 + 8192, r, c);
;     vo1 = (r * ld + c) * 2;
;   }
;   __amdgpu_buffer_rsrc_t rsA = __builtin_amdgcn_make_buffer_rsrc((void*)A, (short)0, 0x7fffffff, 0x00020000);
;   __amdgpu_buffer_rsrc_t rsB = __builtin_amdgcn_make_buffer_rsrc((void*)Bt, (short)0, 0x7fffffff, 0x00020000);
; #pragma unroll
;   for (int a = 0; a < 2; ++a)
; #pragma unroll
;     for (int b = 0; b < 2; ++b)
; #pragma unroll
;       for (int m = 0; m < 4; ++m)
; #pragma unroll
;         for (int n = 0; n < 2; ++n) acc[a][b][m][n] = f32x4{0.f, 0.f, 0.f, 0.f};
;   h16x8 At[4][2], B0[2][2], B1[2][2];
;   int nt = K / BK;
;   STAGE(SB(0, 0), rsB, bcol, 0); STAGE(SA(0, 0), rsA, brow, 0);
;   STAGE(SB(0, 1), rsB, bcol + HALF_, 0); STAGE(SA(0, 1), rsA, brow + HALF_, 0);
;   if (wr == 1) BAR;
;   WAIT_V(4); BAR;
;   STAGE(SB(1, 0), rsB, bcol, 1); STAGE(SA(1, 0), rsA, brow, 1); STAGE(SB(1, 1), rsB, bcol + HALF_, 1);
;   WAIT_V(6); BAR;
;     ...
;   { LDB(B0, 0, 0); LDA(At, 0, 0); STAGE(SA(1, 1), rsA, brow + HALF_, nt - 1);
.LBB0_1454:
	v_mov_b32_e32 v0, v172
	s_ashr_i32 s2, s20, 31
	v_bfe_i32 v4, v0, 27, 1
	v_lshlrev_b32_e32 v2, 4, v0
	v_lshrrev_b32_e32 v4, 22, v4
	v_add_u32_e32 v4, v2, v4
	v_and_b32_e32 v4, 0xfffffc00, v4
	v_ashrrev_i32_e32 v3, 31, v0
	v_sub_u32_e32 v4, v2, v4
	v_lshrrev_b32_e32 v3, 26, v3
	v_lshrrev_b32_e32 v5, 4, v4
	v_add_u32_e32 v3, v0, v3
	v_bitop3_b32 v5, v5, v4, 32 bitop3:0x6c
	v_ashrrev_i32_e32 v4, 31, v4
	v_ashrrev_i32_e32 v3, 6, v3
	v_lshrrev_b32_e32 v4, 26, v4
	v_lshlrev_b32_e32 v6, 3, v3
	v_add_u32_e32 v4, v5, v4
	s_lshr_b32 s2, s2, 29
	v_and_b32_e32 v6, 0xfffff0, v6
	v_ashrrev_i32_e32 v4, 6, v4
	s_add_i32 s2, s20, s2
	v_add_u32_e32 v6, v4, v6
	v_lshlrev_b32_e32 v3, 5, v3
	v_mul_i32_i24_e32 v4, 64, v4
	s_ashr_i32 s3, s2, 3
	s_and_b32 s2, s2, -8
	v_and_b32_e32 v3, 32, v3
	v_sub_u32_e32 v4, v5, v4
	v_add_u32_e32 v5, 0x2000, v2
	s_sub_i32 s2, s20, s2
	v_lshl_or_b32 v3, v6, 7, v3
	v_ashrrev_i32_e32 v6, 31, v5
	s_cmp_lt_i32 s2, 0
	s_movk_i32 s4, 0x91
	v_lshrrev_b32_e32 v6, 22, v6
	s_cselect_b32 s4, s4, 0x90
	v_add_u32_e32 v6, v5, v6
	s_mul_i32 s2, s4, s2
	v_ashrrev_i32_e32 v6, 10, v6
	s_add_i32 s2, s2, s3
	v_mul_i32_i24_e32 v7, 0x400, v6
	s_mul_hi_i32 s3, s2, 0x2aaaaaab
	v_sub_u32_e32 v5, v5, v7
	s_lshr_b32 s4, s3, 31
	s_ashr_i32 s3, s3, 3
	v_lshrrev_b32_e32 v7, 4, v5
	s_add_i32 s3, s3, s4
	v_bitop3_b32 v5, v7, v5, 32 bitop3:0x6c
	s_mul_i32 s4, s3, 48
	v_ashrrev_i32_e32 v8, 31, v5
	s_sub_i32 s2, s2, s4
	v_lshrrev_b32_e32 v8, 26, v8
	s_bfe_i32 s4, s2, 0x80000
	v_add_u32_e32 v8, v5, v8
	s_bfe_u32 s4, s4, 0x3000c
	v_lshlrev_b32_e32 v7, 3, v6
	v_lshrrev_b32_e32 v9, 6, v8
	v_and_b32_e32 v8, 0xc0, v8
	s_add_i32 s5, s2, s4
	v_and_b32_e32 v7, 0xfffff0, v7
	v_lshlrev_b32_e32 v6, 5, v6
	v_sub_u32_e32 v5, v5, v8
	s_bfe_i32 s4, s5, 0x80000
	s_and_b32 s5, s5, 0xf8
	v_ashrrev_i16_sdwa v4, v187, sext(v4) dst_sel:DWORD dst_unused:UNUSED_PAD src0_sel:DWORD src1_sel:BYTE_0
	v_add_u32_e32 v7, v9, v7
	v_and_b32_e32 v6, 32, v6
	v_ashrrev_i16_sdwa v5, v187, sext(v5) dst_sel:DWORD dst_unused:UNUSED_PAD src0_sel:DWORD src1_sel:BYTE_0
	s_sub_i32 s2, s2, s5
	v_bfe_i32 v4, v4, 0, 16
	v_bfe_i32 v5, v5, 0, 16
	v_lshl_or_b32 v6, v7, 7, v6
	s_add_i32 s5, s68, 0x110
	s_sext_i32_i16 s4, s4
	s_sext_i32_i8 s2, s2
	v_add_lshl_u32 v4, v3, v4, 1
	v_add_lshl_u32 v3, v6, v5, 1
	v_add_u32_e32 v5, s5, v2
	s_lshr_b32 s6, s4, 3
	s_lshl_b32 s21, s2, 8
	v_readfirstlane_b32 s2, v5
	v_add_u32_e32 v5, 0x2000, v5
	s_lshl_b32 s3, s3, 11
	s_lshl_b32 s6, s6, 16
	s_mov_b32 m0, s2
	v_readfirstlane_b32 s2, v5
	v_add_u32_e32 v5, 0x110, v2
	s_add_i32 s21, s21, s3
	buffer_load_dwordx4 v4, s[76:79], s6 offen lds
	s_mov_b32 m0, s2
	v_readfirstlane_b32 s2, v5
	v_add_u32_e32 v6, 0x2000, v5
	v_readlane_b32 s3, v254, 11
	buffer_load_dwordx4 v3, s[76:79], s6 offen lds
	s_lshl_b32 s8, s21, 8
	s_mov_b32 s14, s78
	s_mov_b32 s15, s79
	s_mov_b32 m0, s2
	v_readfirstlane_b32 s2, v6
	v_add_u32_e32 v6, s3, v2
	buffer_load_dwordx4 v4, s[12:15], s8 offen lds
	s_mov_b32 m0, s2
	v_readfirstlane_b32 s3, v6
	v_add_u32_e32 v6, 0x2000, v6
	buffer_load_dwordx4 v3, s[12:15], s8 offen lds
	s_or_b32 s2, s6, 0x8000
	s_mov_b32 m0, s3
	v_readfirstlane_b32 s3, v6
	buffer_load_dwordx4 v4, s[76:79], s2 offen lds
	s_mov_b32 m0, s3
	v_add_u32_e32 v6, 0x4000, v5
	buffer_load_dwordx4 v3, s[76:79], s2 offen lds
	s_or_b32 s22, s21, 0x80
	v_readfirstlane_b32 s2, v6
	v_add_u32_e32 v6, 0x6000, v5
	s_lshl_b32 s7, s22, 8
	s_mov_b32 m0, s2
	v_readfirstlane_b32 s2, v6
	buffer_load_dwordx4 v4, s[12:15], s7 offen lds
	s_mov_b32 m0, s2
	v_ashrrev_i32_e32 v6, 8, v0
	buffer_load_dwordx4 v3, s[12:15], s7 offen lds
	v_cmp_eq_u32_e32 vcc, 1, v6
	s_and_saveexec_b64 s[2:3], vcc
	s_cbranch_execz .LBB0_1456
	s_barrier
	s_setprio 1
.LBB0_1456:
	s_or_b64 exec, exec, s[2:3]
	v_add_u32_e32 v9, s94, v2
	s_or_b32 s2, s6, 0x80
	v_readfirstlane_b32 s3, v9
	v_add_u32_e32 v9, 0x2000, v9
	s_mov_b32 m0, s3
	v_readfirstlane_b32 s3, v9
	s_waitcnt vmcnt(4)
	s_barrier
	buffer_load_dwordx4 v4, s[76:79], s2 offen lds
	s_mov_b32 m0, s3
	v_add_u32_e32 v9, 0x8000, v5
	buffer_load_dwordx4 v3, s[76:79], s2 offen lds
	v_readfirstlane_b32 s2, v9
	v_add_u32_e32 v9, 0xa000, v5
	s_bitset1_b32 s8, 7
	s_mov_b32 m0, s2
	v_readfirstlane_b32 s2, v9
	buffer_load_dwordx4 v4, s[12:15], s8 offen lds
	s_mov_b32 m0, s2
	s_or_b32 s2, s6, 0x8080
	v_readlane_b32 s6, v254, 12
	buffer_load_dwordx4 v3, s[12:15], s8 offen lds
	v_lshlrev_b32_e32 v9, 2, v0
	v_add_u32_e32 v2, s6, v2
	v_and_b32_e32 v8, 48, v0
	v_readfirstlane_b32 s3, v2
	v_add_u32_e32 v2, 0x2000, v2
	s_mov_b32 m0, s3
	v_readfirstlane_b32 s3, v2
	v_lshlrev_b32_e32 v2, 6, v0
	v_and_b32_e32 v170, 0x3000, v2
	v_and_b32_e32 v9, 32, v9
	v_and_b32_e32 v2, 0x3c0, v2
	v_and_b32_e32 v7, 15, v0
	v_lshlrev_b32_e32 v30, 13, v6
	v_bitop3_b32 v2, v2, v9, v8 bitop3:0x36
	buffer_load_dwordx4 v4, s[76:79], s2 offen lds
	s_mov_b32 m0, s3
	v_lshlrev_b32_e32 v7, 6, v7
	v_add3_u32 v197, s85, v2, v30
	v_add_u32_e32 v2, 0xc000, v5
	buffer_load_dwordx4 v3, s[76:79], s2 offen lds
	v_bitop3_b32 v171, v7, v9, v8 bitop3:0x36
	v_readfirstlane_b32 s2, v2
	v_add_u32_e32 v2, 0xe000, v5
	v_add3_u32 v18, s5, v171, v170
	v_add3_u32 v192, s85, v171, v30
	s_bitset1_b32 s7, 7
	s_mov_b32 m0, s2
	v_readfirstlane_b32 s2, v2
	s_waitcnt vmcnt(6)
	s_barrier
	ds_read_b128 v[6:9], v18
	ds_read_b128 v[10:13], v18 offset:1024
	ds_read_b128 v[14:17], v18 offset:2048
	ds_read_b128 v[18:21], v18 offset:3072
	ds_read_b128 v[22:25], v192
	ds_read_b128 v[26:29], v192 offset:1024
	ds_read_b128 v[30:33], v197 offset:2048
	ds_read_b128 v[34:37], v197 offset:3072
	ds_read_b128 v[38:41], v197 offset:4096
	ds_read_b128 v[42:45], v197 offset:5120
	ds_read_b128 v[46:49], v197 offset:6144
	ds_read_b128 v[50:53], v197 offset:7168
	buffer_load_dwordx4 v4, s[12:15], s7 offen lds
	s_mov_b32 m0, s2
	s_ashr_i32 s4, s4, 3
	buffer_load_dwordx4 v3, s[12:15], s7 offen lds
	s_barrier
; #define WAIT_V(n) asm volatile("s_waitcnt vmcnt(" #n ")" ::: "memory")
; #define WAIT_L(n) asm volatile("s_waitcnt lgkmcnt(" #n ")" ::: "memory")
; #define BAR __builtin_amdgcn_s_barrier()
; DEV void gemm_tile(const h16* __restrict__ A, const h16* __restrict__ Bt, int K, int ld, int brow, int bcol, h16* shm, Acc& acc) {
;     ...
;     BAR; WAIT_L(0); MMA(0, 0, At, B0); BAR;
;     LDB(B1, 0, 1); BAR; WAIT_L(0); MMA(0, 1, At, B1); BAR;
;     LDA(At, 0, 1); WAIT_V(4); BAR; WAIT_L(0); MMA(1, 0, At, B0); MMA(1, 1, At, B1); BAR; }
;   { LDB(B0, 1, 0); LDA(At, 1, 0); WAIT_V(2); BAR; WAIT_L(0); MMA(0, 0, At, B0); BAR;
	s_waitcnt lgkmcnt(0)
	s_waitcnt lgkmcnt(1)
	v_mfma_f32_16x16x32_f16 v[74:77], v[46:49], v[6:9], 0
	v_mfma_f32_16x16x32_f16 v[2:5], v[22:25], v[6:9], 0
	v_mfma_f32_16x16x32_f16 v[54:57], v[22:25], v[14:17], 0
	v_mfma_f32_16x16x32_f16 v[58:61], v[30:33], v[6:9], 0
	v_mfma_f32_16x16x32_f16 v[62:65], v[30:33], v[14:17], 0
	v_mfma_f32_16x16x32_f16 v[66:69], v[38:41], v[6:9], 0
	v_mfma_f32_16x16x32_f16 v[70:73], v[38:41], v[14:17], 0
	s_waitcnt lgkmcnt(0)
	v_mfma_f32_16x16x32_f16 v[82:85], v[50:53], v[10:13], v[74:77]
	v_mfma_f32_16x16x32_f16 v[74:77], v[46:49], v[14:17], 0
	v_mfma_f32_16x16x32_f16 v[2:5], v[26:29], v[10:13], v[2:5]
	v_mfma_f32_16x16x32_f16 v[54:57], v[26:29], v[18:21], v[54:57]
	v_mfma_f32_16x16x32_f16 v[58:61], v[34:37], v[10:13], v[58:61]
	v_mfma_f32_16x16x32_f16 v[62:65], v[34:37], v[18:21], v[62:65]
	v_mfma_f32_16x16x32_f16 v[66:69], v[42:45], v[10:13], v[66:69]
	v_mfma_f32_16x16x32_f16 v[70:73], v[42:45], v[18:21], v[70:73]
	v_mfma_f32_16x16x32_f16 v[86:89], v[50:53], v[18:21], v[74:77]
	v_readlane_b32 s2, v254, 11
	s_barrier
	s_nop 0
	v_add3_u32 v94, s2, v171, v170
	ds_read_b128 v[74:77], v94
	ds_read_b128 v[78:81], v94 offset:1024
	ds_read_b128 v[90:93], v94 offset:2048
	ds_read_b128 v[94:97], v94 offset:3072
	s_barrier
	s_waitcnt lgkmcnt(0)
	s_waitcnt lgkmcnt(3)
	v_mfma_f32_16x16x32_f16 v[98:101], v[22:25], v[74:77], 0
	s_waitcnt lgkmcnt(1)
	v_mfma_f32_16x16x32_f16 v[22:25], v[22:25], v[90:93], 0
	v_mfma_f32_16x16x32_f16 v[114:117], v[26:29], v[78:81], v[98:101]
	s_waitcnt lgkmcnt(0)
	v_mfma_f32_16x16x32_f16 v[22:25], v[26:29], v[94:97], v[22:25]
	v_mfma_f32_16x16x32_f16 v[26:29], v[30:33], v[74:77], 0
	v_mfma_f32_16x16x32_f16 v[30:33], v[30:33], v[90:93], 0
	v_mfma_f32_16x16x32_f16 v[26:29], v[34:37], v[78:81], v[26:29]
	v_mfma_f32_16x16x32_f16 v[30:33], v[34:37], v[94:97], v[30:33]
	v_mfma_f32_16x16x32_f16 v[34:37], v[38:41], v[74:77], 0
	v_mfma_f32_16x16x32_f16 v[38:41], v[38:41], v[90:93], 0
	v_mfma_f32_16x16x32_f16 v[34:37], v[42:45], v[78:81], v[34:37]
	v_mfma_f32_16x16x32_f16 v[38:41], v[42:45], v[94:97], v[38:41]
	v_mfma_f32_16x16x32_f16 v[42:45], v[46:49], v[74:77], 0
	v_mfma_f32_16x16x32_f16 v[46:49], v[46:49], v[90:93], 0
	v_mfma_f32_16x16x32_f16 v[42:45], v[50:53], v[78:81], v[42:45]
	v_mfma_f32_16x16x32_f16 v[46:49], v[50:53], v[94:97], v[46:49]
	s_barrier
	ds_read_b128 v[50:53], v192 offset:16384
	ds_read_b128 v[98:101], v192 offset:17408
	ds_read_b128 v[102:105], v197 offset:18432
	ds_read_b128 v[106:109], v197 offset:19456
	ds_read_b128 v[110:113], v197 offset:20480
	ds_read_b128 v[118:121], v197 offset:21504
	ds_read_b128 v[122:125], v197 offset:22528
	ds_read_b128 v[126:129], v197 offset:23552
	s_waitcnt vmcnt(4)
	s_barrier
	s_waitcnt lgkmcnt(0)
	s_waitcnt lgkmcnt(7)
	v_mfma_f32_16x16x32_f16 v[130:133], v[50:53], v[6:9], 0
	s_waitcnt lgkmcnt(5)
	v_mfma_f32_16x16x32_f16 v[138:141], v[102:105], v[6:9], 0
	s_waitcnt lgkmcnt(3)
	v_mfma_f32_16x16x32_f16 v[146:149], v[110:113], v[6:9], 0
	s_waitcnt lgkmcnt(1)
	v_mfma_f32_16x16x32_f16 v[6:9], v[122:125], v[6:9], 0
	v_mfma_f32_16x16x32_f16 v[130:133], v[98:101], v[10:13], v[130:133]
	v_mfma_f32_16x16x32_f16 v[134:137], v[50:53], v[14:17], 0
	v_mfma_f32_16x16x32_f16 v[138:141], v[106:109], v[10:13], v[138:141]
	v_mfma_f32_16x16x32_f16 v[142:145], v[102:105], v[14:17], 0
	v_mfma_f32_16x16x32_f16 v[146:149], v[118:121], v[10:13], v[146:149]
	v_mfma_f32_16x16x32_f16 v[150:153], v[110:113], v[14:17], 0
	s_waitcnt lgkmcnt(0)
	v_mfma_f32_16x16x32_f16 v[6:9], v[126:129], v[10:13], v[6:9]
	v_mfma_f32_16x16x32_f16 v[10:13], v[122:125], v[14:17], 0
	v_mfma_f32_16x16x32_f16 v[134:137], v[98:101], v[18:21], v[134:137]
	v_mfma_f32_16x16x32_f16 v[142:145], v[106:109], v[18:21], v[142:145]
	v_mfma_f32_16x16x32_f16 v[150:153], v[118:121], v[18:21], v[150:153]
	v_mfma_f32_16x16x32_f16 v[18:21], v[126:129], v[18:21], v[10:13]
	v_mfma_f32_16x16x32_f16 v[10:13], v[50:53], v[74:77], 0
	v_mfma_f32_16x16x32_f16 v[154:157], v[98:101], v[78:81], v[10:13]
	v_mfma_f32_16x16x32_f16 v[10:13], v[50:53], v[90:93], 0
	v_mfma_f32_16x16x32_f16 v[50:53], v[98:101], v[94:97], v[10:13]
	v_mfma_f32_16x16x32_f16 v[10:13], v[102:105], v[74:77], 0
	v_mfma_f32_16x16x32_f16 v[158:161], v[106:109], v[78:81], v[10:13]
	v_mfma_f32_16x16x32_f16 v[10:13], v[102:105], v[90:93], 0
	v_mfma_f32_16x16x32_f16 v[162:165], v[106:109], v[94:97], v[10:13]
	v_mfma_f32_16x16x32_f16 v[10:13], v[110:113], v[74:77], 0
	v_mfma_f32_16x16x32_f16 v[166:169], v[118:121], v[78:81], v[10:13]
	v_mfma_f32_16x16x32_f16 v[10:13], v[110:113], v[90:93], 0
	v_mfma_f32_16x16x32_f16 v[174:177], v[118:121], v[94:97], v[10:13]
	v_mfma_f32_16x16x32_f16 v[10:13], v[122:125], v[74:77], 0
	v_mfma_f32_16x16x32_f16 v[178:181], v[126:129], v[78:81], v[10:13]
	v_mfma_f32_16x16x32_f16 v[10:13], v[122:125], v[90:93], 0
	v_mfma_f32_16x16x32_f16 v[198:201], v[126:129], v[94:97], v[10:13]
	s_nop 5
	v_add3_u32 v10, s94, v171, v170
	s_barrier
	ds_read_b128 v[202:205], v10
	ds_read_b128 v[206:209], v10 offset:1024
	ds_read_b128 v[210:213], v10 offset:2048
	ds_read_b128 v[214:217], v10 offset:3072
	ds_read_b128 v[10:13], v192 offset:32768
	ds_read_b128 v[14:17], v192 offset:33792
	ds_read_b128 v[90:93], v197 offset:34816
	ds_read_b128 v[94:97], v197 offset:35840
	ds_read_b128 v[218:221], v197 offset:36864
	ds_read_b128 v[222:225], v197 offset:37888
	ds_read_b128 v[226:229], v197 offset:38912
	ds_read_b128 v[230:233], v197 offset:39936
	s_waitcnt vmcnt(2)
	s_barrier
; #define WAIT_V(n) asm volatile("s_waitcnt vmcnt(" #n ")" ::: "memory")
; #define WAIT_L(n) asm volatile("s_waitcnt lgkmcnt(" #n ")" ::: "memory")
; #define BAR __builtin_amdgcn_s_barrier()
; DEV void gemm_tile(const h16* __restrict__ A, const h16* __restrict__ Bt, int K, int ld, int brow, int bcol, h16* shm, Acc& acc) {
;     ...
;   { LDB(B0, 1, 0); LDA(At, 1, 0); WAIT_V(2); BAR; WAIT_L(0); MMA(0, 0, At, B0); BAR;
;     LDB(B1, 1, 1); WAIT_V(0); BAR; WAIT_L(0); MMA(0, 1, At, B1); BAR;
;     LDA(At, 1, 1); BAR; WAIT_L(0); MMA(1, 0, At, B0); MMA(1, 1, At, B1); BAR; }
;   if (wr == 0) BAR;
	s_waitcnt lgkmcnt(0)
	s_waitcnt lgkmcnt(7)
	v_mfma_f32_16x16x32_f16 v[2:5], v[10:13], v[202:205], v[2:5]
	s_waitcnt lgkmcnt(6)
	v_mfma_f32_16x16x32_f16 v[106:109], v[14:17], v[206:209], v[2:5]
	v_mfma_f32_16x16x32_f16 v[2:5], v[10:13], v[210:213], v[54:57]
	v_mfma_f32_16x16x32_f16 v[110:113], v[14:17], v[214:217], v[2:5]
	s_waitcnt lgkmcnt(5)
	v_mfma_f32_16x16x32_f16 v[2:5], v[90:93], v[202:205], v[58:61]
	s_waitcnt lgkmcnt(4)
	v_mfma_f32_16x16x32_f16 v[98:101], v[94:97], v[206:209], v[2:5]
	v_mfma_f32_16x16x32_f16 v[2:5], v[90:93], v[210:213], v[62:65]
	v_mfma_f32_16x16x32_f16 v[102:105], v[94:97], v[214:217], v[2:5]
	s_waitcnt lgkmcnt(3)
	v_mfma_f32_16x16x32_f16 v[2:5], v[218:221], v[202:205], v[66:69]
	s_waitcnt lgkmcnt(2)
	v_mfma_f32_16x16x32_f16 v[74:77], v[222:225], v[206:209], v[2:5]
	v_mfma_f32_16x16x32_f16 v[2:5], v[218:221], v[210:213], v[70:73]
	v_mfma_f32_16x16x32_f16 v[78:81], v[222:225], v[214:217], v[2:5]
	s_waitcnt lgkmcnt(1)
	v_mfma_f32_16x16x32_f16 v[2:5], v[226:229], v[202:205], v[82:85]
	s_waitcnt lgkmcnt(0)
	v_mfma_f32_16x16x32_f16 v[66:69], v[230:233], v[206:209], v[2:5]
	v_mfma_f32_16x16x32_f16 v[2:5], v[226:229], v[210:213], v[86:89]
	v_mfma_f32_16x16x32_f16 v[70:73], v[230:233], v[214:217], v[2:5]
	s_nop 5
	v_add3_u32 v2, s6, v171, v170
	s_barrier
	ds_read_b128 v[234:237], v2
	ds_read_b128 v[238:241], v2 offset:1024
	ds_read_b128 v[242:245], v2 offset:2048
	ds_read_b128 v[246:249], v2 offset:3072
	s_waitcnt vmcnt(0)
	s_barrier
	s_waitcnt lgkmcnt(0)
	s_waitcnt lgkmcnt(3)
	v_mfma_f32_16x16x32_f16 v[2:5], v[10:13], v[234:237], v[114:117]
	s_waitcnt lgkmcnt(2)
	v_mfma_f32_16x16x32_f16 v[122:125], v[14:17], v[238:241], v[2:5]
	s_waitcnt lgkmcnt(1)
	v_mfma_f32_16x16x32_f16 v[2:5], v[10:13], v[242:245], v[22:25]
	s_waitcnt lgkmcnt(0)
	v_mfma_f32_16x16x32_f16 v[126:129], v[14:17], v[246:249], v[2:5]
	v_mfma_f32_16x16x32_f16 v[2:5], v[90:93], v[234:237], v[26:29]
	v_mfma_f32_16x16x32_f16 v[114:117], v[94:97], v[238:241], v[2:5]
	v_mfma_f32_16x16x32_f16 v[2:5], v[90:93], v[242:245], v[30:33]
	v_mfma_f32_16x16x32_f16 v[118:121], v[94:97], v[246:249], v[2:5]
	v_mfma_f32_16x16x32_f16 v[2:5], v[218:221], v[234:237], v[34:37]
	v_mfma_f32_16x16x32_f16 v[90:93], v[222:225], v[238:241], v[2:5]
	v_mfma_f32_16x16x32_f16 v[2:5], v[218:221], v[242:245], v[38:41]
	v_mfma_f32_16x16x32_f16 v[94:97], v[222:225], v[246:249], v[2:5]
	v_mfma_f32_16x16x32_f16 v[2:5], v[226:229], v[234:237], v[42:45]
	v_mfma_f32_16x16x32_f16 v[82:85], v[230:233], v[238:241], v[2:5]
	v_mfma_f32_16x16x32_f16 v[2:5], v[226:229], v[242:245], v[46:49]
	v_mfma_f32_16x16x32_f16 v[86:89], v[230:233], v[246:249], v[2:5]
	s_barrier
	ds_read_b128 v[22:25], v192 offset:49152
	ds_read_b128 v[26:29], v192 offset:50176
	ds_read_b128 v[30:33], v197 offset:51200
	ds_read_b128 v[54:57], v197 offset:52224
	ds_read_b128 v[218:221], v197 offset:53248
	ds_read_b128 v[222:225], v197 offset:54272
	ds_read_b128 v[226:229], v197 offset:55296
	ds_read_b128 v[230:233], v197 offset:56320
	s_barrier
	s_waitcnt lgkmcnt(0)
	s_waitcnt lgkmcnt(7)
	v_mfma_f32_16x16x32_f16 v[2:5], v[22:25], v[202:205], v[130:133]
	s_waitcnt lgkmcnt(6)
	v_mfma_f32_16x16x32_f16 v[42:45], v[26:29], v[206:209], v[2:5]
	v_mfma_f32_16x16x32_f16 v[2:5], v[22:25], v[210:213], v[134:137]
	v_mfma_f32_16x16x32_f16 v[46:49], v[26:29], v[214:217], v[2:5]
	s_waitcnt lgkmcnt(5)
	v_mfma_f32_16x16x32_f16 v[2:5], v[30:33], v[202:205], v[138:141]
	s_waitcnt lgkmcnt(4)
	v_mfma_f32_16x16x32_f16 v[34:37], v[54:57], v[206:209], v[2:5]
	v_mfma_f32_16x16x32_f16 v[2:5], v[30:33], v[210:213], v[142:145]
	v_mfma_f32_16x16x32_f16 v[38:41], v[54:57], v[214:217], v[2:5]
	s_waitcnt lgkmcnt(3)
	v_mfma_f32_16x16x32_f16 v[2:5], v[218:221], v[202:205], v[146:149]
	s_waitcnt lgkmcnt(2)
	v_mfma_f32_16x16x32_f16 v[10:13], v[222:225], v[206:209], v[2:5]
	v_mfma_f32_16x16x32_f16 v[2:5], v[218:221], v[210:213], v[150:153]
	v_mfma_f32_16x16x32_f16 v[14:17], v[222:225], v[214:217], v[2:5]
	s_waitcnt lgkmcnt(1)
	v_mfma_f32_16x16x32_f16 v[2:5], v[226:229], v[202:205], v[6:9]
	v_mfma_f32_16x16x32_f16 v[6:9], v[226:229], v[210:213], v[18:21]
	s_waitcnt lgkmcnt(0)
	v_mfma_f32_16x16x32_f16 v[2:5], v[230:233], v[206:209], v[2:5]
	v_mfma_f32_16x16x32_f16 v[6:9], v[230:233], v[214:217], v[6:9]
	v_mfma_f32_16x16x32_f16 v[18:21], v[22:25], v[234:237], v[154:157]
	v_mfma_f32_16x16x32_f16 v[58:61], v[26:29], v[238:241], v[18:21]
	v_mfma_f32_16x16x32_f16 v[18:21], v[22:25], v[242:245], v[50:53]
	v_mfma_f32_16x16x32_f16 v[62:65], v[26:29], v[246:249], v[18:21]
	v_mfma_f32_16x16x32_f16 v[18:21], v[30:33], v[234:237], v[158:161]
	v_mfma_f32_16x16x32_f16 v[50:53], v[54:57], v[238:241], v[18:21]
	v_mfma_f32_16x16x32_f16 v[18:21], v[30:33], v[242:245], v[162:165]
	v_mfma_f32_16x16x32_f16 v[54:57], v[54:57], v[246:249], v[18:21]
	v_mfma_f32_16x16x32_f16 v[18:21], v[218:221], v[234:237], v[166:169]
	v_mfma_f32_16x16x32_f16 v[26:29], v[222:225], v[238:241], v[18:21]
	v_mfma_f32_16x16x32_f16 v[18:21], v[218:221], v[242:245], v[174:177]
	v_mfma_f32_16x16x32_f16 v[30:33], v[222:225], v[246:249], v[18:21]
	v_mfma_f32_16x16x32_f16 v[18:21], v[226:229], v[234:237], v[178:181]
	v_mfma_f32_16x16x32_f16 v[22:25], v[226:229], v[242:245], v[198:201]
	v_mfma_f32_16x16x32_f16 v[18:21], v[230:233], v[238:241], v[18:21]
	v_mfma_f32_16x16x32_f16 v[22:25], v[230:233], v[246:249], v[22:25]
	s_setprio 0
	s_movk_i32 s2, 0x100
	v_cmp_gt_u32_e32 vcc, s2, v0
	s_barrier
	s_and_saveexec_b64 s[2:3], vcc
	s_cbranch_execz .LBB0_1458
	s_barrier

; #define WAIT_V(n) asm volatile("s_waitcnt vmcnt(" #n ")" ::: "memory")
; #define BAR __builtin_amdgcn_s_barrier()
; DEV void gemm_tile(const h16* __restrict__ A, const h16* __restrict__ Bt, int K, int ld, int brow, int bcol, h16* shm, Acc& acc) {
;     ...
;   int wid = TID >> 6, lane = TID & 63, wr = wid >> 2, wc = wid & 3, fr = lane & 15, fq = lane >> 4;
;   int vo0, vo1;
;   {
;     int r, c;
;     stage_rc(TID * 16, r, c);
;     vo0 = (r * ld + c) * 2;
;     stage_rc(TID * 16 + 8192, r, c);
;     vo1 = (r * ld + c) * 2;
;   }
;   __amdgpu_buffer_rsrc_t rsA = __builtin_amdgcn_make_buffer_rsrc((void*)A, (short)0, 0x7fffffff, 0x00020000);
;   __amdgpu_buffer_rsrc_t rsB = __builtin_amdgcn_make_buffer_rsrc((void*)Bt, (short)0, 0x7fffffff, 0x00020000);
; #pragma unroll
;   for (int a = 0; a < 2; ++a)
; #pragma unroll
;     for (int b = 0; b < 2; ++b)
; #pragma unroll
;       for (int m = 0; m < 4; ++m)
; #pragma unroll
;         for (int n = 0; n < 2; ++n) acc[a][b][m][n] = f32x4{0.f, 0.f, 0.f, 0.f};
;   h16x8 At[4][2], B0[2][2], B1[2][2];
;   int nt = K / BK;
;   STAGE(SB(0, 0), rsB, bcol, 0); STAGE(SA(0, 0), rsA, brow, 0);
;   STAGE(SB(0, 1), rsB, bcol + HALF_, 0); STAGE(SA(0, 1), rsA, brow + HALF_, 0);
;   if (wr == 1) BAR;
;   WAIT_V(4); BAR;
;   STAGE(SB(1, 0), rsB, bcol, 1); STAGE(SA(1, 0), rsA, brow, 1); STAGE(SB(1, 1), rsB, bcol + HALF_, 1);
;   WAIT_V(6); BAR;
; template <int EPI> __device__ __forceinline__ void gemm_phase(const h16* A, const h16* Bt, int M, int N, int K, const GE& e, h16* shm) {
;     ...
;       int q = nwg / NXCD, r = nwg % NXCD, xcd = wgid % NXCD, off = wgid / NXCD;
;       wgid = (xcd < r ? xcd * (q + 1) : r * (q + 1) + (xcd - r) * q) + off;
;     }
;     int nig = WGM * nN, gid = wgid / nig, fm = gid * WGM, gsz = min(nM - fm, WGM);
;     int pm = fm + ((wgid % nig) % gsz), pn = (wgid % nig) / gsz, brow = pm * BM, bcol = pn * BM;
.LBB0_2156:
	v_mov_b32_e32 v0, v172
	s_ashr_i32 s4, s12, 31
	v_bfe_i32 v4, v0, 27, 1
	v_lshlrev_b32_e32 v2, 4, v0
	v_lshrrev_b32_e32 v4, 22, v4
	v_add_u32_e32 v4, v2, v4
	v_and_b32_e32 v4, 0xfffffc00, v4
	v_ashrrev_i32_e32 v3, 31, v0
	v_sub_u32_e32 v4, v2, v4
	s_lshr_b32 s4, s4, 29
	v_lshrrev_b32_e32 v3, 26, v3
	v_lshrrev_b32_e32 v5, 4, v4
	s_add_i32 s4, s12, s4
	v_add_u32_e32 v3, v0, v3
	v_bitop3_b32 v5, v5, v4, 32 bitop3:0x6c
	v_ashrrev_i32_e32 v4, 31, v4
	s_ashr_i32 s5, s4, 3
	s_and_b32 s4, s4, -8
	v_ashrrev_i32_e32 v3, 6, v3
	v_lshrrev_b32_e32 v4, 26, v4
	s_sub_i32 s4, s12, s4
	v_lshlrev_b32_e32 v6, 3, v3
	v_add_u32_e32 v4, v5, v4
	s_cmp_lt_i32 s4, 0
	v_and_b32_e32 v6, 0x3ffff0, v6
	v_ashrrev_i32_e32 v4, 6, v4
	s_cselect_b32 s10, 49, 48
	v_add_u32_e32 v6, v4, v6
	v_lshlrev_b32_e32 v3, 5, v3
	v_mul_i32_i24_e32 v4, 64, v4
	s_mul_i32 s4, s10, s4
	v_and_b32_e32 v3, 32, v3
	v_sub_u32_e32 v4, v5, v4
	v_add_u32_e32 v5, 0x2000, v2
	s_add_i32 s4, s4, s5
	v_lshl_or_b32 v3, v6, 9, v3
	v_ashrrev_i32_e32 v6, 31, v5
	s_ashr_i32 s5, s4, 31
	v_lshrrev_b32_e32 v6, 22, v6
	s_lshr_b32 s5, s5, 28
	v_add_u32_e32 v6, v5, v6
	s_add_i32 s5, s4, s5
	v_ashrrev_i32_e32 v6, 10, v6
	s_ashr_i32 s18, s5, 4
	s_and_b32 s5, s5, 0xfff0
	v_mul_i32_i24_e32 v7, 0x400, v6
	s_sub_i32 s4, s4, s5
	v_sub_u32_e32 v5, v5, v7
	s_bfe_i32 s5, s4, 0x80000
	v_lshrrev_b32_e32 v7, 4, v5
	s_bfe_u32 s5, s5, 0x3000c
	v_bitop3_b32 v5, v7, v5, 32 bitop3:0x6c
	s_add_i32 s5, s4, s5
	v_ashrrev_i32_e32 v8, 31, v5
	s_bfe_i32 s10, s5, 0x80000
	s_and_b32 s5, s5, 0xf8
	v_lshrrev_b32_e32 v8, 26, v8
	s_sub_i32 s4, s4, s5
	v_add_u32_e32 v8, v5, v8
	s_sext_i32_i8 s19, s4
	v_lshlrev_b32_e32 v7, 3, v6
	v_lshrrev_b32_e32 v9, 6, v8
	v_and_b32_e32 v8, 0xc0, v8
	s_add_i32 s20, s68, 0x110
	s_sext_i32_i16 s10, s10
	s_lshl_b32 s4, s18, 11
	s_lshl_b32 s13, s19, 8
	v_ashrrev_i16_sdwa v4, v187, sext(v4) dst_sel:DWORD dst_unused:UNUSED_PAD src0_sel:DWORD src1_sel:BYTE_0
	v_and_b32_e32 v7, 0x3ffff0, v7
	v_lshlrev_b32_e32 v6, 5, v6
	v_sub_u32_e32 v5, v5, v8
	v_add_u32_e32 v137, s20, v2
	s_ashr_i32 s15, s10, 3
	s_add_i32 s13, s13, s4
	v_bfe_i32 v4, v4, 0, 16
	v_add_u32_e32 v7, v9, v7
	v_and_b32_e32 v6, 32, v6
	v_ashrrev_i16_sdwa v5, v187, sext(v5) dst_sel:DWORD dst_unused:UNUSED_PAD src0_sel:DWORD src1_sel:BYTE_0
	v_readfirstlane_b32 s4, v137
	v_add_u32_e32 v139, 0x2000, v137
	v_bfe_i32 v5, v5, 0, 16
	v_lshl_or_b32 v6, v7, 9, v6
	v_add_lshl_u32 v136, v3, v4, 1
	s_lshl_b32 s16, s15, 18
	s_mov_b32 s10, s78
	s_mov_b32 s11, s79
	s_mov_b32 m0, s4
	v_readfirstlane_b32 s4, v139
	v_add_u32_e32 v140, 0x110, v2
	v_add_lshl_u32 v135, v6, v5, 1
	buffer_load_dwordx4 v136, s[8:11], s16 offen lds
	s_mov_b32 m0, s4
	v_readfirstlane_b32 s4, v140
	v_add_u32_e32 v141, 0x2000, v140
	buffer_load_dwordx4 v135, s[8:11], s16 offen lds
	s_lshl_b32 s21, s13, 10
	s_mov_b32 m0, s4
	v_readfirstlane_b32 s4, v141
	buffer_load_dwordx4 v136, s[76:79], s21 offen lds
	s_mov_b32 m0, s4
	v_readlane_b32 s4, v254, 11
	buffer_load_dwordx4 v135, s[76:79], s21 offen lds
	s_or_b32 s22, s16, 0x20000
	v_add_u32_e32 v142, s4, v2
	v_add_u32_e32 v143, 0x2000, v142
	v_readfirstlane_b32 s4, v142
	s_mov_b32 m0, s4
	v_readfirstlane_b32 s4, v143
	v_add_u32_e32 v144, 0x4000, v140
	buffer_load_dwordx4 v136, s[8:11], s22 offen lds
	s_mov_b32 m0, s4
	s_or_b32 s14, s13, 0x80
	v_readfirstlane_b32 s4, v144
	v_add_u32_e32 v145, 0x6000, v140
	buffer_load_dwordx4 v135, s[8:11], s22 offen lds
	s_lshl_b32 s17, s14, 10
	s_mov_b32 m0, s4
	v_readfirstlane_b32 s4, v145
	buffer_load_dwordx4 v136, s[76:79], s17 offen lds
	s_mov_b32 m0, s4
	v_ashrrev_i32_e32 v3, 8, v0
	buffer_load_dwordx4 v135, s[76:79], s17 offen lds
	v_cmp_eq_u32_e32 vcc, 1, v3
	s_and_saveexec_b64 s[4:5], vcc
	s_cbranch_execz .LBB0_2158
	s_barrier
	s_setprio 1

; #define WAIT_L(n) asm volatile("s_waitcnt lgkmcnt(" #n ")" ::: "memory")
; #define BAR __builtin_amdgcn_s_barrier()
; #define SCHED __builtin_amdgcn_sched_barrier(0)
; DEV void gemm_tile(const h16* __restrict__ A, const h16* __restrict__ Bt, int K, int ld, int brow, int bcol, h16* shm, Acc& acc) {
;     ...
;     LDB(B0, 0, 0); SCHED; LDA(At, 0, 0); STAGE(SA(1, 1), rsA, brow + HALF_, t + 1);
;     WAIT_L(8); BAR; WAIT_L(0); MMA(0, 0, At, B0); BAR; SCHED;
;     LDB(B1, 0, 1); STAGE(SB(0, 0), rsB, bcol, t + 2);
;     BAR; WAIT_L(0); MMA(0, 1, At, B1); BAR;
;     LDA(At, 0, 1); STAGE(SA(0, 0), rsA, brow, t + 2);
;     BAR; WAIT_L(0); MMA(1, 0, At, B0); BAR; SCHED;
.LBB0_2159:
	ds_read_b128 v[156:159], v155
	ds_read_b128 v[160:163], v155 offset:1024
	ds_read_b128 v[164:167], v155 offset:2048
	ds_read_b128 v[168:171], v155 offset:3072
	s_add_i32 s19, s4, s18
	v_readfirstlane_b32 s11, v153
	s_add_i32 s10, s19, 0x20080
	s_mov_b32 m0, s11
	v_readfirstlane_b32 s11, v152
	ds_read_b128 v[174:177], v133
	ds_read_b128 v[178:181], v133 offset:1024
	ds_read_b128 v[198:201], v132
	ds_read_b128 v[202:205], v132 offset:1024
	ds_read_b128 v[206:209], v131
	ds_read_b128 v[210:213], v131 offset:1024
	ds_read_b128 v[214:217], v130
	ds_read_b128 v[218:221], v130 offset:1024
	buffer_load_dwordx4 v136, s[76:79], s10 offen lds
	s_mov_b32 m0, s11
	s_nop 0
	buffer_load_dwordx4 v135, s[76:79], s10 offen lds
	s_waitcnt lgkmcnt(8)
	s_barrier
	s_waitcnt lgkmcnt(0)
	s_waitcnt lgkmcnt(7)
	v_mfma_f32_16x16x32_f16 v[126:129], v[174:177], v[156:159], v[126:129]
	v_mfma_f32_16x16x32_f16 v[122:125], v[174:177], v[164:167], v[122:125]
	s_waitcnt lgkmcnt(5)
	v_mfma_f32_16x16x32_f16 v[118:121], v[198:201], v[156:159], v[118:121]
	v_mfma_f32_16x16x32_f16 v[114:117], v[198:201], v[164:167], v[114:117]
	s_waitcnt lgkmcnt(3)
	v_mfma_f32_16x16x32_f16 v[110:113], v[206:209], v[156:159], v[110:113]
	v_mfma_f32_16x16x32_f16 v[106:109], v[206:209], v[164:167], v[106:109]
	s_waitcnt lgkmcnt(1)
	v_mfma_f32_16x16x32_f16 v[102:105], v[214:217], v[156:159], v[102:105]
	v_mfma_f32_16x16x32_f16 v[98:101], v[214:217], v[164:167], v[98:101]
	v_mfma_f32_16x16x32_f16 v[126:129], v[178:181], v[160:163], v[126:129]
	v_mfma_f32_16x16x32_f16 v[122:125], v[178:181], v[168:171], v[122:125]
	v_mfma_f32_16x16x32_f16 v[118:121], v[202:205], v[160:163], v[118:121]
	v_mfma_f32_16x16x32_f16 v[114:117], v[202:205], v[168:171], v[114:117]
	v_mfma_f32_16x16x32_f16 v[110:113], v[210:213], v[160:163], v[110:113]
	v_mfma_f32_16x16x32_f16 v[106:109], v[210:213], v[168:171], v[106:109]
	s_waitcnt lgkmcnt(0)
	v_mfma_f32_16x16x32_f16 v[102:105], v[218:221], v[160:163], v[102:105]
	v_mfma_f32_16x16x32_f16 v[98:101], v[218:221], v[168:171], v[98:101]
	s_barrier
	s_add_i32 s20, s16, s18
	v_readfirstlane_b32 s22, v137
	s_add_i32 s21, s20, 0x100
	s_mov_b32 s10, s78
	s_mov_b32 s11, s79
	s_mov_b32 m0, s22
	v_readfirstlane_b32 s22, v139
	ds_read_b128 v[222:225], v150
	ds_read_b128 v[226:229], v150 offset:1024
	ds_read_b128 v[230:233], v150 offset:2048
	ds_read_b128 v[234:237], v150 offset:3072
	buffer_load_dwordx4 v136, s[8:11], s21 offen lds
	s_mov_b32 m0, s22
	s_nop 0
	buffer_load_dwordx4 v135, s[8:11], s21 offen lds
	s_barrier
	s_waitcnt lgkmcnt(0)
	s_waitcnt lgkmcnt(3)
	v_mfma_f32_16x16x32_f16 v[94:97], v[174:177], v[222:225], v[94:97]
	s_waitcnt lgkmcnt(1)
	v_mfma_f32_16x16x32_f16 v[90:93], v[174:177], v[230:233], v[90:93]
	v_mfma_f32_16x16x32_f16 v[86:89], v[198:201], v[222:225], v[86:89]
	v_mfma_f32_16x16x32_f16 v[82:85], v[198:201], v[230:233], v[82:85]
	v_mfma_f32_16x16x32_f16 v[78:81], v[206:209], v[222:225], v[78:81]
	v_mfma_f32_16x16x32_f16 v[74:77], v[206:209], v[230:233], v[74:77]
	v_mfma_f32_16x16x32_f16 v[70:73], v[214:217], v[222:225], v[70:73]
	v_mfma_f32_16x16x32_f16 v[66:69], v[214:217], v[230:233], v[66:69]
	v_mfma_f32_16x16x32_f16 v[94:97], v[178:181], v[226:229], v[94:97]
	s_waitcnt lgkmcnt(0)
	v_mfma_f32_16x16x32_f16 v[90:93], v[178:181], v[234:237], v[90:93]
	v_mfma_f32_16x16x32_f16 v[86:89], v[202:205], v[226:229], v[86:89]
	v_mfma_f32_16x16x32_f16 v[82:85], v[202:205], v[234:237], v[82:85]
	v_mfma_f32_16x16x32_f16 v[78:81], v[210:213], v[226:229], v[78:81]
	v_mfma_f32_16x16x32_f16 v[74:77], v[210:213], v[234:237], v[74:77]
	v_mfma_f32_16x16x32_f16 v[70:73], v[218:221], v[226:229], v[70:73]
	v_mfma_f32_16x16x32_f16 v[66:69], v[218:221], v[234:237], v[66:69]
	v_readfirstlane_b32 s22, v140
	s_add_i32 s21, s19, 0x100
	s_mov_b32 m0, s22
	v_readfirstlane_b32 s22, v141
	s_barrier
	ds_read_b128 v[174:177], v133 offset:16384
	ds_read_b128 v[178:181], v133 offset:17408
	ds_read_b128 v[198:201], v132 offset:16384
	ds_read_b128 v[202:205], v132 offset:17408
	ds_read_b128 v[206:209], v131 offset:16384
	ds_read_b128 v[210:213], v131 offset:17408
	ds_read_b128 v[214:217], v130 offset:16384
	ds_read_b128 v[218:221], v130 offset:17408
	buffer_load_dwordx4 v136, s[76:79], s21 offen lds
	s_mov_b32 m0, s22
	s_nop 0
	buffer_load_dwordx4 v135, s[76:79], s21 offen lds
	s_barrier
	s_waitcnt lgkmcnt(0)
	s_waitcnt lgkmcnt(7)
	v_mfma_f32_16x16x32_f16 v[62:65], v[174:177], v[156:159], v[62:65]
	v_mfma_f32_16x16x32_f16 v[58:61], v[174:177], v[164:167], v[58:61]
	s_waitcnt lgkmcnt(5)
	v_mfma_f32_16x16x32_f16 v[54:57], v[198:201], v[156:159], v[54:57]
	v_mfma_f32_16x16x32_f16 v[50:53], v[198:201], v[164:167], v[50:53]
	s_waitcnt lgkmcnt(3)
	v_mfma_f32_16x16x32_f16 v[46:49], v[206:209], v[156:159], v[46:49]
	v_mfma_f32_16x16x32_f16 v[42:45], v[206:209], v[164:167], v[42:45]
	s_waitcnt lgkmcnt(1)
	v_mfma_f32_16x16x32_f16 v[38:41], v[214:217], v[156:159], v[38:41]
	v_mfma_f32_16x16x32_f16 v[34:37], v[214:217], v[164:167], v[34:37]
	v_mfma_f32_16x16x32_f16 v[62:65], v[178:181], v[160:163], v[62:65]
	v_mfma_f32_16x16x32_f16 v[58:61], v[178:181], v[168:171], v[58:61]
	v_mfma_f32_16x16x32_f16 v[54:57], v[202:205], v[160:163], v[54:57]
	v_mfma_f32_16x16x32_f16 v[50:53], v[202:205], v[168:171], v[50:53]
	v_mfma_f32_16x16x32_f16 v[46:49], v[210:213], v[160:163], v[46:49]
	v_mfma_f32_16x16x32_f16 v[42:45], v[210:213], v[168:171], v[42:45]
	s_waitcnt lgkmcnt(0)
	v_mfma_f32_16x16x32_f16 v[38:41], v[218:221], v[160:163], v[38:41]
	v_mfma_f32_16x16x32_f16 v[34:37], v[218:221], v[168:171], v[34:37]
	s_barrier
; #define WAIT_V(n) asm volatile("s_waitcnt vmcnt(" #n ")" ::: "memory")
; #define WAIT_L(n) asm volatile("s_waitcnt lgkmcnt(" #n ")" ::: "memory")
; #define BAR __builtin_amdgcn_s_barrier()
; #define SCHED __builtin_amdgcn_sched_barrier(0)
; DEV void gemm_tile(const h16* __restrict__ A, const h16* __restrict__ Bt, int K, int ld, int brow, int bcol, h16* shm, Acc& acc) {
;     ...
;     STAGE(SB(0, 1), rsB, bcol + HALF_, t + 2);
;     WAIT_V(6); BAR; MMA(1, 1, At, B1); BAR;
;     LDB(B0, 1, 0); SCHED; LDA(At, 1, 0); STAGE(SA(0, 1), rsA, brow + HALF_, t + 2);
;     WAIT_L(8); BAR; WAIT_L(0); MMA(0, 0, At, B0); BAR; SCHED;
;     LDB(B1, 1, 1); STAGE(SB(1, 0), rsB, bcol, t + 3);
;     BAR; WAIT_L(0); MMA(0, 1, At, B1); BAR;
;     LDA(At, 1, 1); STAGE(SA(1, 0), rsA, brow, t + 3);
	v_readfirstlane_b32 s22, v142
	s_add_i32 s21, s20, 0x20100
	s_mov_b32 m0, s22
	v_readfirstlane_b32 s22, v143
	buffer_load_dwordx4 v136, s[8:11], s21 offen lds
	s_mov_b32 m0, s22
	s_nop 0
	buffer_load_dwordx4 v135, s[8:11], s21 offen lds
	s_waitcnt vmcnt(6)
	s_barrier
	v_mfma_f32_16x16x32_f16 v[30:33], v[174:177], v[222:225], v[30:33]
	v_mfma_f32_16x16x32_f16 v[26:29], v[174:177], v[230:233], v[26:29]
	v_mfma_f32_16x16x32_f16 v[22:25], v[198:201], v[222:225], v[22:25]
	v_mfma_f32_16x16x32_f16 v[18:21], v[198:201], v[230:233], v[18:21]
	v_mfma_f32_16x16x32_f16 v[14:17], v[206:209], v[222:225], v[14:17]
	v_mfma_f32_16x16x32_f16 v[10:13], v[206:209], v[230:233], v[10:13]
	v_mfma_f32_16x16x32_f16 v[6:9], v[214:217], v[222:225], v[6:9]
	v_mfma_f32_16x16x32_f16 v[2:5], v[214:217], v[230:233], v[2:5]
	v_mfma_f32_16x16x32_f16 v[30:33], v[178:181], v[226:229], v[30:33]
	v_mfma_f32_16x16x32_f16 v[26:29], v[178:181], v[234:237], v[26:29]
	v_mfma_f32_16x16x32_f16 v[22:25], v[202:205], v[226:229], v[22:25]
	v_mfma_f32_16x16x32_f16 v[18:21], v[202:205], v[234:237], v[18:21]
	v_mfma_f32_16x16x32_f16 v[14:17], v[210:213], v[226:229], v[14:17]
	v_mfma_f32_16x16x32_f16 v[10:13], v[210:213], v[234:237], v[10:13]
	v_mfma_f32_16x16x32_f16 v[6:9], v[218:221], v[226:229], v[6:9]
	v_mfma_f32_16x16x32_f16 v[2:5], v[218:221], v[234:237], v[2:5]
	s_barrier
	ds_read_b128 v[156:159], v138
	ds_read_b128 v[160:163], v138 offset:1024
	ds_read_b128 v[164:167], v138 offset:2048
	ds_read_b128 v[168:171], v138 offset:3072
	v_readfirstlane_b32 s22, v144
	s_add_i32 s21, s19, 0x20100
	s_mov_b32 m0, s22
	v_readfirstlane_b32 s22, v145
	ds_read_b128 v[174:177], v133 offset:32768
	ds_read_b128 v[178:181], v133 offset:33792
	ds_read_b128 v[198:201], v132 offset:32768
	ds_read_b128 v[202:205], v132 offset:33792
	ds_read_b128 v[206:209], v131 offset:32768
	ds_read_b128 v[210:213], v131 offset:33792
	ds_read_b128 v[214:217], v130 offset:32768
	ds_read_b128 v[218:221], v130 offset:33792
	buffer_load_dwordx4 v136, s[76:79], s21 offen lds
	s_mov_b32 m0, s22
	s_nop 0
	buffer_load_dwordx4 v135, s[76:79], s21 offen lds
	s_waitcnt lgkmcnt(8)
	s_barrier
	s_waitcnt lgkmcnt(0)
	s_waitcnt lgkmcnt(7)
	v_mfma_f32_16x16x32_f16 v[126:129], v[174:177], v[156:159], v[126:129]
	v_mfma_f32_16x16x32_f16 v[122:125], v[174:177], v[164:167], v[122:125]
	s_waitcnt lgkmcnt(5)
	v_mfma_f32_16x16x32_f16 v[118:121], v[198:201], v[156:159], v[118:121]
	v_mfma_f32_16x16x32_f16 v[114:117], v[198:201], v[164:167], v[114:117]
	s_waitcnt lgkmcnt(3)
	v_mfma_f32_16x16x32_f16 v[110:113], v[206:209], v[156:159], v[110:113]
	v_mfma_f32_16x16x32_f16 v[106:109], v[206:209], v[164:167], v[106:109]
	s_waitcnt lgkmcnt(1)
	v_mfma_f32_16x16x32_f16 v[102:105], v[214:217], v[156:159], v[102:105]
	v_mfma_f32_16x16x32_f16 v[98:101], v[214:217], v[164:167], v[98:101]
	v_mfma_f32_16x16x32_f16 v[126:129], v[178:181], v[160:163], v[126:129]
	v_mfma_f32_16x16x32_f16 v[122:125], v[178:181], v[168:171], v[122:125]
	v_mfma_f32_16x16x32_f16 v[118:121], v[202:205], v[160:163], v[118:121]
	v_mfma_f32_16x16x32_f16 v[114:117], v[202:205], v[168:171], v[114:117]
	v_mfma_f32_16x16x32_f16 v[110:113], v[210:213], v[160:163], v[110:113]
	v_mfma_f32_16x16x32_f16 v[106:109], v[210:213], v[168:171], v[106:109]
	s_waitcnt lgkmcnt(0)
	v_mfma_f32_16x16x32_f16 v[102:105], v[218:221], v[160:163], v[102:105]
	v_mfma_f32_16x16x32_f16 v[98:101], v[218:221], v[168:171], v[98:101]
	s_barrier
	v_readfirstlane_b32 s22, v146
	s_add_i32 s21, s20, 0x180
	s_mov_b32 m0, s22
	v_readfirstlane_b32 s22, v147
	ds_read_b128 v[222:225], v134
	ds_read_b128 v[226:229], v134 offset:1024
	ds_read_b128 v[230:233], v134 offset:2048
	ds_read_b128 v[234:237], v134 offset:3072
	buffer_load_dwordx4 v136, s[8:11], s21 offen lds
	s_mov_b32 m0, s22
	s_nop 0
	buffer_load_dwordx4 v135, s[8:11], s21 offen lds
	s_barrier
	s_waitcnt lgkmcnt(0)
	s_waitcnt lgkmcnt(3)
	v_mfma_f32_16x16x32_f16 v[94:97], v[174:177], v[222:225], v[94:97]
	s_waitcnt lgkmcnt(1)
	v_mfma_f32_16x16x32_f16 v[90:93], v[174:177], v[230:233], v[90:93]
	v_mfma_f32_16x16x32_f16 v[86:89], v[198:201], v[222:225], v[86:89]
	v_mfma_f32_16x16x32_f16 v[82:85], v[198:201], v[230:233], v[82:85]
	v_mfma_f32_16x16x32_f16 v[78:81], v[206:209], v[222:225], v[78:81]
	v_mfma_f32_16x16x32_f16 v[74:77], v[206:209], v[230:233], v[74:77]
	v_mfma_f32_16x16x32_f16 v[70:73], v[214:217], v[222:225], v[70:73]
	v_mfma_f32_16x16x32_f16 v[66:69], v[214:217], v[230:233], v[66:69]
	v_mfma_f32_16x16x32_f16 v[94:97], v[178:181], v[226:229], v[94:97]
	s_waitcnt lgkmcnt(0)
	v_mfma_f32_16x16x32_f16 v[90:93], v[178:181], v[234:237], v[90:93]
	v_mfma_f32_16x16x32_f16 v[86:89], v[202:205], v[226:229], v[86:89]
	v_mfma_f32_16x16x32_f16 v[82:85], v[202:205], v[234:237], v[82:85]
	v_mfma_f32_16x16x32_f16 v[78:81], v[210:213], v[226:229], v[78:81]
	v_mfma_f32_16x16x32_f16 v[74:77], v[210:213], v[234:237], v[74:77]
	v_mfma_f32_16x16x32_f16 v[70:73], v[218:221], v[226:229], v[70:73]
	v_mfma_f32_16x16x32_f16 v[66:69], v[218:221], v[234:237], v[66:69]
	v_readfirstlane_b32 s21, v148
	s_addk_i32 s19, 0x180
	s_mov_b32 m0, s21
	v_readfirstlane_b32 s21, v149
	s_barrier
	ds_read_b128 v[174:177], v133 offset:49152
	ds_read_b128 v[178:181], v133 offset:50176
	ds_read_b128 v[198:201], v132 offset:49152
	ds_read_b128 v[202:205], v132 offset:50176
	ds_read_b128 v[206:209], v131 offset:49152
	ds_read_b128 v[210:213], v131 offset:50176
	ds_read_b128 v[214:217], v130 offset:49152
	ds_read_b128 v[218:221], v130 offset:50176
	buffer_load_dwordx4 v136, s[76:79], s19 offen lds
	s_mov_b32 m0, s21
	s_nop 0
	buffer_load_dwordx4 v135, s[76:79], s19 offen lds
	s_barrier
; #define WAIT_V(n) asm volatile("s_waitcnt vmcnt(" #n ")" ::: "memory")
; #define WAIT_L(n) asm volatile("s_waitcnt lgkmcnt(" #n ")" ::: "memory")
; #define BAR __builtin_amdgcn_s_barrier()
; #define SCHED __builtin_amdgcn_sched_barrier(0)
; DEV void gemm_tile(const h16* __restrict__ A, const h16* __restrict__ Bt, int K, int ld, int brow, int bcol, h16* shm, Acc& acc) {
;     ...
;     BAR; WAIT_L(0); MMA(1, 0, At, B0); BAR; SCHED;
;     STAGE(SB(1, 1), rsB, bcol + HALF_, t + 3);
;     WAIT_V(6); BAR; MMA(1, 1, At, B1); BAR;
;   }
;   { LDB(B0, 0, 0); LDA(At, 0, 0); STAGE(SA(1, 1), rsA, brow + HALF_, nt - 1);
;     BAR; WAIT_L(0); MMA(0, 0, At, B0); BAR;
;     LDB(B1, 0, 1); BAR; WAIT_L(0); MMA(0, 1, At, B1); BAR;
	s_waitcnt lgkmcnt(0)
	s_waitcnt lgkmcnt(7)
	v_mfma_f32_16x16x32_f16 v[62:65], v[174:177], v[156:159], v[62:65]
	v_mfma_f32_16x16x32_f16 v[58:61], v[174:177], v[164:167], v[58:61]
	s_waitcnt lgkmcnt(5)
	v_mfma_f32_16x16x32_f16 v[54:57], v[198:201], v[156:159], v[54:57]
	v_mfma_f32_16x16x32_f16 v[50:53], v[198:201], v[164:167], v[50:53]
	s_waitcnt lgkmcnt(3)
	v_mfma_f32_16x16x32_f16 v[46:49], v[206:209], v[156:159], v[46:49]
	v_mfma_f32_16x16x32_f16 v[42:45], v[206:209], v[164:167], v[42:45]
	s_waitcnt lgkmcnt(1)
	v_mfma_f32_16x16x32_f16 v[38:41], v[214:217], v[156:159], v[38:41]
	v_mfma_f32_16x16x32_f16 v[34:37], v[214:217], v[164:167], v[34:37]
	v_mfma_f32_16x16x32_f16 v[62:65], v[178:181], v[160:163], v[62:65]
	v_mfma_f32_16x16x32_f16 v[58:61], v[178:181], v[168:171], v[58:61]
	v_mfma_f32_16x16x32_f16 v[54:57], v[202:205], v[160:163], v[54:57]
	v_mfma_f32_16x16x32_f16 v[50:53], v[202:205], v[168:171], v[50:53]
	v_mfma_f32_16x16x32_f16 v[46:49], v[210:213], v[160:163], v[46:49]
	v_mfma_f32_16x16x32_f16 v[42:45], v[210:213], v[168:171], v[42:45]
	s_waitcnt lgkmcnt(0)
	v_mfma_f32_16x16x32_f16 v[38:41], v[218:221], v[160:163], v[38:41]
	v_mfma_f32_16x16x32_f16 v[34:37], v[218:221], v[168:171], v[34:37]
	s_barrier
	v_readfirstlane_b32 s19, v151
	s_add_i32 s20, s20, 0x20180
	s_mov_b32 m0, s19
	v_readfirstlane_b32 s19, v154
	buffer_load_dwordx4 v136, s[8:11], s20 offen lds
	s_mov_b32 m0, s19
	s_nop 0
	buffer_load_dwordx4 v135, s[8:11], s20 offen lds
	s_waitcnt vmcnt(6)
	s_barrier
	v_mfma_f32_16x16x32_f16 v[30:33], v[174:177], v[222:225], v[30:33]
	v_mfma_f32_16x16x32_f16 v[26:29], v[174:177], v[230:233], v[26:29]
	v_mfma_f32_16x16x32_f16 v[22:25], v[198:201], v[222:225], v[22:25]
	v_mfma_f32_16x16x32_f16 v[18:21], v[198:201], v[230:233], v[18:21]
	v_mfma_f32_16x16x32_f16 v[14:17], v[206:209], v[222:225], v[14:17]
	v_mfma_f32_16x16x32_f16 v[10:13], v[206:209], v[230:233], v[10:13]
	v_mfma_f32_16x16x32_f16 v[6:9], v[214:217], v[222:225], v[6:9]
	v_mfma_f32_16x16x32_f16 v[2:5], v[214:217], v[230:233], v[2:5]
	v_mfma_f32_16x16x32_f16 v[30:33], v[178:181], v[226:229], v[30:33]
	v_mfma_f32_16x16x32_f16 v[26:29], v[178:181], v[234:237], v[26:29]
	v_mfma_f32_16x16x32_f16 v[22:25], v[202:205], v[226:229], v[22:25]
	v_mfma_f32_16x16x32_f16 v[18:21], v[202:205], v[234:237], v[18:21]
	v_mfma_f32_16x16x32_f16 v[14:17], v[210:213], v[226:229], v[14:17]
	v_mfma_f32_16x16x32_f16 v[10:13], v[210:213], v[234:237], v[10:13]
	v_mfma_f32_16x16x32_f16 v[6:9], v[218:221], v[226:229], v[6:9]
	v_mfma_f32_16x16x32_f16 v[2:5], v[218:221], v[234:237], v[2:5]
	s_add_i32 s5, s5, 2
	s_addk_i32 s18, 0x100
	s_cmp_lt_u32 s5, 4
	s_barrier
	s_cbranch_scc1 .LBB0_2159
	v_readfirstlane_b32 s5, v153
	s_or_b32 s4, s17, 0x380
	s_mov_b32 m0, s5
	v_readfirstlane_b32 s5, v152
	ds_read_b128 v[140:143], v155
	ds_read_b128 v[144:147], v155 offset:1024
	ds_read_b128 v[156:159], v155 offset:2048
	ds_read_b128 v[160:163], v155 offset:3072
	ds_read_b128 v[164:167], v133
	ds_read_b128 v[168:171], v133 offset:1024
	ds_read_b128 v[174:177], v132
	ds_read_b128 v[178:181], v132 offset:1024
	ds_read_b128 v[198:201], v131
	ds_read_b128 v[202:205], v131 offset:1024
	ds_read_b128 v[206:209], v130
	ds_read_b128 v[210:213], v130 offset:1024
	buffer_load_dwordx4 v136, s[76:79], s4 offen lds
	s_mov_b32 m0, s5
	s_nop 0
	buffer_load_dwordx4 v135, s[76:79], s4 offen lds
	s_barrier
	s_waitcnt lgkmcnt(0)
	s_waitcnt lgkmcnt(7)
	v_mfma_f32_16x16x32_f16 v[126:129], v[164:167], v[140:143], v[126:129]
	v_mfma_f32_16x16x32_f16 v[122:125], v[164:167], v[156:159], v[122:125]
	s_waitcnt lgkmcnt(5)
	v_mfma_f32_16x16x32_f16 v[118:121], v[174:177], v[140:143], v[118:121]
	v_mfma_f32_16x16x32_f16 v[114:117], v[174:177], v[156:159], v[114:117]
	v_mfma_f32_16x16x32_f16 v[126:129], v[168:171], v[144:147], v[126:129]
	v_mfma_f32_16x16x32_f16 v[122:125], v[168:171], v[160:163], v[122:125]
	s_waitcnt lgkmcnt(4)
	v_mfma_f32_16x16x32_f16 v[118:121], v[178:181], v[144:147], v[118:121]
	v_mfma_f32_16x16x32_f16 v[114:117], v[178:181], v[160:163], v[114:117]
	s_waitcnt lgkmcnt(3)
	v_mfma_f32_16x16x32_f16 v[110:113], v[198:201], v[140:143], v[110:113]
	v_mfma_f32_16x16x32_f16 v[106:109], v[198:201], v[156:159], v[106:109]
	s_waitcnt lgkmcnt(1)
	v_mfma_f32_16x16x32_f16 v[102:105], v[206:209], v[140:143], v[102:105]
	v_mfma_f32_16x16x32_f16 v[98:101], v[206:209], v[156:159], v[98:101]
	v_mfma_f32_16x16x32_f16 v[152:155], v[202:205], v[144:147], v[110:113]
	v_mfma_f32_16x16x32_f16 v[214:217], v[202:205], v[160:163], v[106:109]
	s_waitcnt lgkmcnt(0)
	v_mfma_f32_16x16x32_f16 v[218:221], v[210:213], v[144:147], v[102:105]
	v_mfma_f32_16x16x32_f16 v[222:225], v[210:213], v[160:163], v[98:101]
	s_barrier
	s_nop 0
	ds_read_b128 v[98:101], v150
	ds_read_b128 v[102:105], v150 offset:1024
	ds_read_b128 v[106:109], v150 offset:2048
	ds_read_b128 v[110:113], v150 offset:3072
	s_barrier
	s_waitcnt lgkmcnt(0)
	s_waitcnt lgkmcnt(3)
	v_mfma_f32_16x16x32_f16 v[94:97], v[164:167], v[98:101], v[94:97]
	s_waitcnt lgkmcnt(1)
	v_mfma_f32_16x16x32_f16 v[90:93], v[164:167], v[106:109], v[90:93]
	v_mfma_f32_16x16x32_f16 v[86:89], v[174:177], v[98:101], v[86:89]
	v_mfma_f32_16x16x32_f16 v[82:85], v[174:177], v[106:109], v[82:85]
	v_mfma_f32_16x16x32_f16 v[94:97], v[168:171], v[102:105], v[94:97]
	s_waitcnt lgkmcnt(0)
	v_mfma_f32_16x16x32_f16 v[90:93], v[168:171], v[110:113], v[90:93]
	v_mfma_f32_16x16x32_f16 v[86:89], v[178:181], v[102:105], v[86:89]
	v_mfma_f32_16x16x32_f16 v[82:85], v[178:181], v[110:113], v[82:85]
	v_mfma_f32_16x16x32_f16 v[78:81], v[198:201], v[98:101], v[78:81]
	v_mfma_f32_16x16x32_f16 v[74:77], v[198:201], v[106:109], v[74:77]
	v_mfma_f32_16x16x32_f16 v[70:73], v[206:209], v[98:101], v[70:73]
	v_mfma_f32_16x16x32_f16 v[66:69], v[206:209], v[106:109], v[66:69]
	v_mfma_f32_16x16x32_f16 v[148:151], v[202:205], v[102:105], v[78:81]
	v_mfma_f32_16x16x32_f16 v[164:167], v[202:205], v[110:113], v[74:77]
	v_mfma_f32_16x16x32_f16 v[168:171], v[210:213], v[102:105], v[70:73]
	v_mfma_f32_16x16x32_f16 v[174:177], v[210:213], v[110:113], v[66:69]
	s_barrier
; #define WAIT_V(n) asm volatile("s_waitcnt vmcnt(" #n ")" ::: "memory")
; #define WAIT_L(n) asm volatile("s_waitcnt lgkmcnt(" #n ")" ::: "memory")
; #define BAR __builtin_amdgcn_s_barrier()
; DEV void gemm_tile(const h16* __restrict__ A, const h16* __restrict__ Bt, int K, int ld, int brow, int bcol, h16* shm, Acc& acc) {
;     ...
;     LDA(At, 0, 1); WAIT_V(4); BAR; WAIT_L(0); MMA(1, 0, At, B0); MMA(1, 1, At, B1); BAR; }
;   { LDB(B0, 1, 0); LDA(At, 1, 0); WAIT_V(2); BAR; WAIT_L(0); MMA(0, 0, At, B0); BAR;
	s_nop 1
	ds_read_b128 v[66:69], v133 offset:16384
	ds_read_b128 v[70:73], v133 offset:17408
	ds_read_b128 v[74:77], v132 offset:16384
	ds_read_b128 v[78:81], v132 offset:17408
	ds_read_b128 v[178:181], v131 offset:16384
	ds_read_b128 v[198:201], v131 offset:17408
	ds_read_b128 v[202:205], v130 offset:16384
	ds_read_b128 v[206:209], v130 offset:17408
	s_waitcnt vmcnt(4)
	s_barrier
	s_waitcnt lgkmcnt(0)
	s_waitcnt lgkmcnt(7)
	v_mfma_f32_16x16x32_f16 v[62:65], v[66:69], v[140:143], v[62:65]
	v_mfma_f32_16x16x32_f16 v[58:61], v[66:69], v[156:159], v[58:61]
	s_waitcnt lgkmcnt(5)
	v_mfma_f32_16x16x32_f16 v[54:57], v[74:77], v[140:143], v[54:57]
	v_mfma_f32_16x16x32_f16 v[50:53], v[74:77], v[156:159], v[50:53]
	v_mfma_f32_16x16x32_f16 v[62:65], v[70:73], v[144:147], v[62:65]
	v_mfma_f32_16x16x32_f16 v[58:61], v[70:73], v[160:163], v[58:61]
	s_waitcnt lgkmcnt(4)
	v_mfma_f32_16x16x32_f16 v[54:57], v[78:81], v[144:147], v[54:57]
	v_mfma_f32_16x16x32_f16 v[50:53], v[78:81], v[160:163], v[50:53]
	s_waitcnt lgkmcnt(3)
	v_mfma_f32_16x16x32_f16 v[46:49], v[178:181], v[140:143], v[46:49]
	v_mfma_f32_16x16x32_f16 v[42:45], v[178:181], v[156:159], v[42:45]
	s_waitcnt lgkmcnt(1)
	v_mfma_f32_16x16x32_f16 v[38:41], v[202:205], v[140:143], v[38:41]
	v_mfma_f32_16x16x32_f16 v[34:37], v[202:205], v[156:159], v[34:37]
	v_mfma_f32_16x16x32_f16 v[210:213], v[198:201], v[144:147], v[46:49]
	v_mfma_f32_16x16x32_f16 v[226:229], v[198:201], v[160:163], v[42:45]
	s_waitcnt lgkmcnt(0)
	v_mfma_f32_16x16x32_f16 v[140:143], v[206:209], v[144:147], v[38:41]
	v_mfma_f32_16x16x32_f16 v[144:147], v[206:209], v[160:163], v[34:37]
	v_mfma_f32_16x16x32_f16 v[30:33], v[66:69], v[98:101], v[30:33]
	v_mfma_f32_16x16x32_f16 v[26:29], v[66:69], v[106:109], v[26:29]
	v_mfma_f32_16x16x32_f16 v[22:25], v[74:77], v[98:101], v[22:25]
	v_mfma_f32_16x16x32_f16 v[18:21], v[74:77], v[106:109], v[18:21]
	v_mfma_f32_16x16x32_f16 v[30:33], v[70:73], v[102:105], v[30:33]
	v_mfma_f32_16x16x32_f16 v[26:29], v[70:73], v[110:113], v[26:29]
	v_mfma_f32_16x16x32_f16 v[22:25], v[78:81], v[102:105], v[22:25]
	v_mfma_f32_16x16x32_f16 v[18:21], v[78:81], v[110:113], v[18:21]
	v_mfma_f32_16x16x32_f16 v[14:17], v[178:181], v[98:101], v[14:17]
	v_mfma_f32_16x16x32_f16 v[10:13], v[178:181], v[106:109], v[10:13]
	v_mfma_f32_16x16x32_f16 v[6:9], v[202:205], v[98:101], v[6:9]
	v_mfma_f32_16x16x32_f16 v[2:5], v[202:205], v[106:109], v[2:5]
	v_mfma_f32_16x16x32_f16 v[156:159], v[198:201], v[102:105], v[14:17]
	v_mfma_f32_16x16x32_f16 v[160:163], v[198:201], v[110:113], v[10:13]
	v_mfma_f32_16x16x32_f16 v[178:181], v[206:209], v[102:105], v[6:9]
	v_mfma_f32_16x16x32_f16 v[198:201], v[206:209], v[110:113], v[2:5]
	s_barrier
	s_nop 1
	ds_read_b128 v[2:5], v138
	ds_read_b128 v[6:9], v138 offset:1024
	ds_read_b128 v[202:205], v138 offset:2048
	ds_read_b128 v[136:139], v138 offset:3072
	ds_read_b128 v[10:13], v133 offset:32768
	ds_read_b128 v[14:17], v133 offset:33792
	ds_read_b128 v[34:37], v132 offset:32768
	ds_read_b128 v[38:41], v132 offset:33792
	ds_read_b128 v[42:45], v131 offset:32768
	ds_read_b128 v[46:49], v131 offset:33792
	ds_read_b128 v[206:209], v130 offset:32768
	ds_read_b128 v[230:233], v130 offset:33792
	s_waitcnt vmcnt(2)
	s_barrier
	s_waitcnt lgkmcnt(0)
	s_waitcnt lgkmcnt(7)
	v_mfma_f32_16x16x32_f16 v[66:69], v[10:13], v[2:5], v[126:129]
	s_waitcnt lgkmcnt(6)
	v_mfma_f32_16x16x32_f16 v[106:109], v[14:17], v[6:9], v[66:69]
	v_mfma_f32_16x16x32_f16 v[66:69], v[10:13], v[202:205], v[122:125]
	v_mfma_f32_16x16x32_f16 v[110:113], v[14:17], v[136:139], v[66:69]
	s_waitcnt lgkmcnt(5)
	v_mfma_f32_16x16x32_f16 v[66:69], v[34:37], v[2:5], v[118:121]
	s_waitcnt lgkmcnt(4)
	v_mfma_f32_16x16x32_f16 v[98:101], v[38:41], v[6:9], v[66:69]
	v_mfma_f32_16x16x32_f16 v[66:69], v[34:37], v[202:205], v[114:117]
	v_mfma_f32_16x16x32_f16 v[102:105], v[38:41], v[136:139], v[66:69]
	s_waitcnt lgkmcnt(3)
	v_mfma_f32_16x16x32_f16 v[66:69], v[42:45], v[2:5], v[152:155]
	s_waitcnt lgkmcnt(2)
	v_mfma_f32_16x16x32_f16 v[74:77], v[46:49], v[6:9], v[66:69]
	v_mfma_f32_16x16x32_f16 v[66:69], v[42:45], v[202:205], v[214:217]
	v_mfma_f32_16x16x32_f16 v[78:81], v[46:49], v[136:139], v[66:69]
	s_waitcnt lgkmcnt(1)
	v_mfma_f32_16x16x32_f16 v[66:69], v[206:209], v[2:5], v[218:221]
	v_mfma_f32_16x16x32_f16 v[70:73], v[206:209], v[202:205], v[222:225]
	s_waitcnt lgkmcnt(0)
	v_mfma_f32_16x16x32_f16 v[66:69], v[230:233], v[6:9], v[66:69]
	v_mfma_f32_16x16x32_f16 v[70:73], v[230:233], v[136:139], v[70:73]
	s_barrier
; #define WAIT_V(n) asm volatile("s_waitcnt vmcnt(" #n ")" ::: "memory")
; #define WAIT_L(n) asm volatile("s_waitcnt lgkmcnt(" #n ")" ::: "memory")
; #define BAR __builtin_amdgcn_s_barrier()
; DEV void gemm_tile(const h16* __restrict__ A, const h16* __restrict__ Bt, int K, int ld, int brow, int bcol, h16* shm, Acc& acc) {
;     ...
;     LDB(B1, 1, 1); WAIT_V(0); BAR; WAIT_L(0); MMA(0, 1, At, B1); BAR;
;     LDA(At, 1, 1); BAR; WAIT_L(0); MMA(1, 0, At, B0); MMA(1, 1, At, B1); BAR; }
;   if (wr == 0) BAR;
	ds_read_b128 v[152:155], v134
	ds_read_b128 v[214:217], v134 offset:1024
	ds_read_b128 v[218:221], v134 offset:2048
	ds_read_b128 v[222:225], v134 offset:3072
	s_waitcnt vmcnt(0)
	s_barrier
	s_waitcnt lgkmcnt(0)
	s_waitcnt lgkmcnt(3)
	v_mfma_f32_16x16x32_f16 v[94:97], v[10:13], v[152:155], v[94:97]
	s_waitcnt lgkmcnt(1)
	v_mfma_f32_16x16x32_f16 v[10:13], v[10:13], v[218:221], v[90:93]
	s_waitcnt lgkmcnt(0)
	v_mfma_f32_16x16x32_f16 v[126:129], v[14:17], v[222:225], v[10:13]
	v_mfma_f32_16x16x32_f16 v[10:13], v[34:37], v[152:155], v[86:89]
	v_mfma_f32_16x16x32_f16 v[114:117], v[38:41], v[214:217], v[10:13]
	v_mfma_f32_16x16x32_f16 v[10:13], v[34:37], v[218:221], v[82:85]
	v_mfma_f32_16x16x32_f16 v[118:121], v[38:41], v[222:225], v[10:13]
	v_mfma_f32_16x16x32_f16 v[10:13], v[42:45], v[152:155], v[148:151]
	v_mfma_f32_16x16x32_f16 v[90:93], v[46:49], v[214:217], v[10:13]
	v_mfma_f32_16x16x32_f16 v[10:13], v[42:45], v[218:221], v[164:167]
	v_mfma_f32_16x16x32_f16 v[122:125], v[14:17], v[214:217], v[94:97]
	v_mfma_f32_16x16x32_f16 v[94:97], v[46:49], v[222:225], v[10:13]
	v_mfma_f32_16x16x32_f16 v[10:13], v[206:209], v[152:155], v[168:171]
	v_mfma_f32_16x16x32_f16 v[82:85], v[230:233], v[214:217], v[10:13]
	v_mfma_f32_16x16x32_f16 v[10:13], v[206:209], v[218:221], v[174:177]
	v_mfma_f32_16x16x32_f16 v[86:89], v[230:233], v[222:225], v[10:13]
	s_barrier
	ds_read_b128 v[148:151], v133 offset:49152
	ds_read_b128 v[164:167], v133 offset:50176
	ds_read_b128 v[168:171], v132 offset:49152
	ds_read_b128 v[132:135], v132 offset:50176
	ds_read_b128 v[174:177], v131 offset:49152
	ds_read_b128 v[206:209], v131 offset:50176
	ds_read_b128 v[230:233], v130 offset:49152
	ds_read_b128 v[234:237], v130 offset:50176
	s_barrier
	s_waitcnt lgkmcnt(0)
	s_waitcnt lgkmcnt(7)
	v_mfma_f32_16x16x32_f16 v[10:13], v[148:151], v[2:5], v[62:65]
	s_waitcnt lgkmcnt(6)
	v_mfma_f32_16x16x32_f16 v[42:45], v[164:167], v[6:9], v[10:13]
	v_mfma_f32_16x16x32_f16 v[10:13], v[148:151], v[202:205], v[58:61]
	v_mfma_f32_16x16x32_f16 v[46:49], v[164:167], v[136:139], v[10:13]
	s_waitcnt lgkmcnt(5)
	v_mfma_f32_16x16x32_f16 v[10:13], v[168:171], v[2:5], v[54:57]
	s_waitcnt lgkmcnt(4)
	v_mfma_f32_16x16x32_f16 v[34:37], v[132:135], v[6:9], v[10:13]
	v_mfma_f32_16x16x32_f16 v[10:13], v[168:171], v[202:205], v[50:53]
	v_mfma_f32_16x16x32_f16 v[38:41], v[132:135], v[136:139], v[10:13]
	s_waitcnt lgkmcnt(3)
	v_mfma_f32_16x16x32_f16 v[10:13], v[174:177], v[2:5], v[210:213]
	s_waitcnt lgkmcnt(1)
	v_mfma_f32_16x16x32_f16 v[2:5], v[230:233], v[2:5], v[140:143]
	v_mfma_f32_16x16x32_f16 v[10:13], v[206:209], v[6:9], v[10:13]
	v_mfma_f32_16x16x32_f16 v[14:17], v[174:177], v[202:205], v[226:229]
	s_waitcnt lgkmcnt(0)
	v_mfma_f32_16x16x32_f16 v[2:5], v[234:237], v[6:9], v[2:5]
	v_mfma_f32_16x16x32_f16 v[6:9], v[230:233], v[202:205], v[144:147]
	v_mfma_f32_16x16x32_f16 v[14:17], v[206:209], v[136:139], v[14:17]
	v_mfma_f32_16x16x32_f16 v[6:9], v[234:237], v[136:139], v[6:9]
	v_mfma_f32_16x16x32_f16 v[18:21], v[168:171], v[218:221], v[18:21]
	v_mfma_f32_16x16x32_f16 v[26:29], v[148:151], v[218:221], v[26:29]
	v_mfma_f32_16x16x32_f16 v[54:57], v[132:135], v[222:225], v[18:21]
	v_mfma_f32_16x16x32_f16 v[18:21], v[174:177], v[152:155], v[156:159]
	v_mfma_f32_16x16x32_f16 v[30:33], v[148:151], v[152:155], v[30:33]
	v_mfma_f32_16x16x32_f16 v[62:65], v[164:167], v[222:225], v[26:29]
	v_mfma_f32_16x16x32_f16 v[22:25], v[168:171], v[152:155], v[22:25]
	v_mfma_f32_16x16x32_f16 v[26:29], v[206:209], v[214:217], v[18:21]
	v_mfma_f32_16x16x32_f16 v[18:21], v[174:177], v[218:221], v[160:163]
	v_mfma_f32_16x16x32_f16 v[58:61], v[164:167], v[214:217], v[30:33]
	v_mfma_f32_16x16x32_f16 v[50:53], v[132:135], v[214:217], v[22:25]
	v_mfma_f32_16x16x32_f16 v[30:33], v[206:209], v[222:225], v[18:21]
	v_mfma_f32_16x16x32_f16 v[18:21], v[230:233], v[152:155], v[178:181]
	v_mfma_f32_16x16x32_f16 v[22:25], v[230:233], v[218:221], v[198:201]
	v_mfma_f32_16x16x32_f16 v[18:21], v[234:237], v[214:217], v[18:21]
	v_mfma_f32_16x16x32_f16 v[22:25], v[234:237], v[222:225], v[22:25]
	s_setprio 0
	s_movk_i32 s4, 0x100
	v_cmp_gt_u32_e32 vcc, s4, v0
	s_barrier
	s_and_saveexec_b64 s[4:5], vcc
	s_cbranch_execz .LBB0_2155
	s_barrier
	s_branch .LBB0_2155

; #define WAIT_V(n) asm volatile("s_waitcnt vmcnt(" #n ")" ::: "memory")
; #define BAR __builtin_amdgcn_s_barrier()
; DEV void gemm_tile(const h16* __restrict__ A, const h16* __restrict__ Bt, int K, int ld, int brow, int bcol, h16* shm, Acc& acc) {
;     ...
;   int wid = TID >> 6, lane = TID & 63, wr = wid >> 2, wc = wid & 3, fr = lane & 15, fq = lane >> 4;
;   int vo0, vo1;
;   {
;     int r, c;
;     stage_rc(TID * 16, r, c);
;     vo0 = (r * ld + c) * 2;
;     stage_rc(TID * 16 + 8192, r, c);
;     vo1 = (r * ld + c) * 2;
;   }
;   __amdgpu_buffer_rsrc_t rsA = __builtin_amdgcn_make_buffer_rsrc((void*)A, (short)0, 0x7fffffff, 0x00020000);
;   __amdgpu_buffer_rsrc_t rsB = __builtin_amdgcn_make_buffer_rsrc((void*)Bt, (short)0, 0x7fffffff, 0x00020000);
; #pragma unroll
;   for (int a = 0; a < 2; ++a)
; #pragma unroll
;     for (int b = 0; b < 2; ++b)
; #pragma unroll
;       for (int m = 0; m < 4; ++m)
; #pragma unroll
;         for (int n = 0; n < 2; ++n) acc[a][b][m][n] = f32x4{0.f, 0.f, 0.f, 0.f};
;   h16x8 At[4][2], B0[2][2], B1[2][2];
;   int nt = K / BK;
;   STAGE(SB(0, 0), rsB, bcol, 0); STAGE(SA(0, 0), rsA, brow, 0);
;   STAGE(SB(0, 1), rsB, bcol + HALF_, 0); STAGE(SA(0, 1), rsA, brow + HALF_, 0);
;   if (wr == 1) BAR;
;   WAIT_V(4); BAR;
;   STAGE(SB(1, 0), rsB, bcol, 1); STAGE(SA(1, 0), rsA, brow, 1); STAGE(SB(1, 1), rsB, bcol + HALF_, 1);
;   WAIT_V(6); BAR;
; template <int EPI> __device__ __forceinline__ void gemm_phase(const h16* A, const h16* Bt, int M, int N, int K, const GE& e, h16* shm) {
;     ...
;       int q = nwg / NXCD, r = nwg % NXCD, xcd = wgid % NXCD, off = wgid / NXCD;
;       wgid = (xcd < r ? xcd * (q + 1) : r * (q + 1) + (xcd - r) * q) + off;
;     }
;     int nig = WGM * nN, gid = wgid / nig, fm = gid * WGM, gsz = min(nM - fm, WGM);
;     int pm = fm + ((wgid % nig) % gsz), pn = (wgid % nig) / gsz, brow = pm * BM, bcol = pn * BM;
.LBB0_2175:
	v_mov_b32_e32 v0, v172
	s_ashr_i32 s4, s14, 31
	v_bfe_i32 v4, v0, 27, 1
	v_lshlrev_b32_e32 v2, 4, v0
	v_lshrrev_b32_e32 v4, 22, v4
	v_add_u32_e32 v4, v2, v4
	v_and_b32_e32 v4, 0xfffffc00, v4
	v_ashrrev_i32_e32 v3, 31, v0
	v_sub_u32_e32 v4, v2, v4
	s_lshr_b32 s4, s4, 29
	v_lshrrev_b32_e32 v3, 26, v3
	v_lshrrev_b32_e32 v5, 4, v4
	s_add_i32 s4, s14, s4
	v_add_u32_e32 v3, v0, v3
	v_bitop3_b32 v5, v5, v4, 32 bitop3:0x6c
	v_ashrrev_i32_e32 v4, 31, v4
	s_ashr_i32 s5, s4, 3
	s_and_b32 s4, s4, -8
	v_ashrrev_i32_e32 v3, 6, v3
	v_lshrrev_b32_e32 v4, 26, v4
	s_sub_i32 s4, s14, s4
	v_lshlrev_b32_e32 v6, 3, v3
	v_add_u32_e32 v4, v5, v4
	s_cmp_lt_i32 s4, 0
	s_movk_i32 s10, 0x61
	v_and_b32_e32 v6, 0x1ffff0, v6
	v_ashrrev_i32_e32 v4, 6, v4
	s_cselect_b32 s10, s10, 0x60
	v_add_u32_e32 v6, v4, v6
	v_lshlrev_b32_e32 v3, 5, v3
	v_mul_i32_i24_e32 v4, 64, v4
	s_mul_i32 s4, s10, s4
	v_and_b32_e32 v3, 32, v3
	v_sub_u32_e32 v4, v5, v4
	v_add_u32_e32 v5, 0x2000, v2
	s_add_i32 s4, s4, s5
	v_lshl_or_b32 v3, v6, 10, v3
	v_ashrrev_i32_e32 v6, 31, v5
	s_ashr_i32 s5, s4, 31
	v_lshrrev_b32_e32 v6, 22, v6
	s_lshr_b32 s5, s5, 27
	v_add_u32_e32 v6, v5, v6
	s_add_i32 s5, s4, s5
	v_ashrrev_i32_e32 v6, 10, v6
	s_ashr_i32 s20, s5, 5
	s_and_b32 s5, s5, 0xffe0
	v_mul_i32_i24_e32 v7, 0x400, v6
	s_sub_i32 s4, s4, s5
	v_sub_u32_e32 v5, v5, v7
	s_bfe_i32 s5, s4, 0x80000
	v_lshrrev_b32_e32 v7, 4, v5
	s_bfe_u32 s5, s5, 0x3000c
	v_bitop3_b32 v5, v7, v5, 32 bitop3:0x6c
	s_add_i32 s5, s4, s5
	v_ashrrev_i32_e32 v8, 31, v5
	s_bfe_i32 s10, s5, 0x80000
	s_and_b32 s5, s5, 0xf8
	v_lshrrev_b32_e32 v8, 26, v8
	s_sub_i32 s4, s4, s5
	v_add_u32_e32 v8, v5, v8
	s_sext_i32_i8 s21, s4
	v_lshlrev_b32_e32 v7, 3, v6
	v_lshrrev_b32_e32 v9, 6, v8
	v_and_b32_e32 v8, 0xc0, v8
	s_add_i32 s22, s68, 0x110
	s_sext_i32_i16 s10, s10
	s_lshl_b32 s4, s20, 11
	s_lshl_b32 s15, s21, 8
	v_ashrrev_i16_sdwa v4, v187, sext(v4) dst_sel:DWORD dst_unused:UNUSED_PAD src0_sel:DWORD src1_sel:BYTE_0
	v_and_b32_e32 v7, 0x1ffff0, v7
	v_lshlrev_b32_e32 v6, 5, v6
	v_sub_u32_e32 v5, v5, v8
	v_add_u32_e32 v137, s22, v2
	s_ashr_i32 s17, s10, 3
	s_add_i32 s15, s15, s4
	v_bfe_i32 v4, v4, 0, 16
	v_add_u32_e32 v7, v9, v7
	v_and_b32_e32 v6, 32, v6
	v_ashrrev_i16_sdwa v5, v187, sext(v5) dst_sel:DWORD dst_unused:UNUSED_PAD src0_sel:DWORD src1_sel:BYTE_0
	v_readfirstlane_b32 s4, v137
	v_add_u32_e32 v139, 0x2000, v137
	v_bfe_i32 v5, v5, 0, 16
	v_lshl_or_b32 v6, v7, 10, v6
	v_add_lshl_u32 v136, v3, v4, 1
	s_lshl_b32 s18, s17, 19
	s_mov_b32 s10, s78
	s_mov_b32 s11, s79
	s_mov_b32 m0, s4
	v_readfirstlane_b32 s4, v139
	v_add_u32_e32 v140, 0x110, v2
	v_add_lshl_u32 v135, v6, v5, 1
	buffer_load_dwordx4 v136, s[8:11], s18 offen lds
	s_mov_b32 m0, s4
	v_readfirstlane_b32 s4, v140
	v_add_u32_e32 v141, 0x2000, v140
	buffer_load_dwordx4 v135, s[8:11], s18 offen lds
	s_lshl_b32 s23, s15, 11
	s_mov_b32 m0, s4
	v_readfirstlane_b32 s4, v141
	buffer_load_dwordx4 v136, s[76:79], s23 offen lds
	s_mov_b32 m0, s4
	v_readlane_b32 s4, v254, 11
	buffer_load_dwordx4 v135, s[76:79], s23 offen lds
	s_or_b32 s24, s18, 0x40000
	v_add_u32_e32 v142, s4, v2
	v_add_u32_e32 v143, 0x2000, v142
	v_readfirstlane_b32 s4, v142
	s_mov_b32 m0, s4
	v_readfirstlane_b32 s4, v143
	v_add_u32_e32 v144, 0x4000, v140
	buffer_load_dwordx4 v136, s[8:11], s24 offen lds
	s_mov_b32 m0, s4
	s_or_b32 s16, s15, 0x80
	v_readfirstlane_b32 s4, v144
	v_add_u32_e32 v145, 0x6000, v140
	buffer_load_dwordx4 v135, s[8:11], s24 offen lds
	s_lshl_b32 s19, s16, 11
	s_mov_b32 m0, s4
	v_readfirstlane_b32 s4, v145
	buffer_load_dwordx4 v136, s[76:79], s19 offen lds
	s_mov_b32 m0, s4
	v_ashrrev_i32_e32 v3, 8, v0
	buffer_load_dwordx4 v135, s[76:79], s19 offen lds
	v_cmp_eq_u32_e32 vcc, 1, v3
	s_and_saveexec_b64 s[4:5], vcc
	s_cbranch_execz .LBB0_2177
	s_barrier
	s_setprio 1

; #define WAIT_L(n) asm volatile("s_waitcnt lgkmcnt(" #n ")" ::: "memory")
; #define BAR __builtin_amdgcn_s_barrier()
; #define SCHED __builtin_amdgcn_sched_barrier(0)
; DEV void gemm_tile(const h16* __restrict__ A, const h16* __restrict__ Bt, int K, int ld, int brow, int bcol, h16* shm, Acc& acc) {
;     ...
;     LDB(B0, 0, 0); SCHED; LDA(At, 0, 0); STAGE(SA(1, 1), rsA, brow + HALF_, t + 1);
;     WAIT_L(8); BAR; WAIT_L(0); MMA(0, 0, At, B0); BAR; SCHED;
;     LDB(B1, 0, 1); STAGE(SB(0, 0), rsB, bcol, t + 2);
;     BAR; WAIT_L(0); MMA(0, 1, At, B1); BAR;
;     LDA(At, 0, 1); STAGE(SA(0, 0), rsA, brow, t + 2);
;     BAR; WAIT_L(0); MMA(1, 0, At, B0); BAR; SCHED;
.LBB0_2178:
	ds_read_b128 v[156:159], v155
	ds_read_b128 v[160:163], v155 offset:1024
	ds_read_b128 v[164:167], v155 offset:2048
	ds_read_b128 v[168:171], v155 offset:3072
	s_add_i32 s21, s4, s20
	v_readfirstlane_b32 s11, v153
	s_add_i32 s10, s21, 0x40080
	s_mov_b32 m0, s11
	v_readfirstlane_b32 s11, v152
	ds_read_b128 v[174:177], v133
	ds_read_b128 v[178:181], v133 offset:1024
	ds_read_b128 v[198:201], v132
	ds_read_b128 v[202:205], v132 offset:1024
	ds_read_b128 v[206:209], v131
	ds_read_b128 v[210:213], v131 offset:1024
	ds_read_b128 v[214:217], v130
	ds_read_b128 v[218:221], v130 offset:1024
	buffer_load_dwordx4 v136, s[76:79], s10 offen lds
	s_mov_b32 m0, s11
	s_nop 0
	buffer_load_dwordx4 v135, s[76:79], s10 offen lds
	s_waitcnt lgkmcnt(8)
	s_barrier
	s_waitcnt lgkmcnt(0)
	s_waitcnt lgkmcnt(7)
	v_mfma_f32_16x16x32_f16 v[126:129], v[174:177], v[156:159], v[126:129]
	v_mfma_f32_16x16x32_f16 v[122:125], v[174:177], v[164:167], v[122:125]
	s_waitcnt lgkmcnt(5)
	v_mfma_f32_16x16x32_f16 v[118:121], v[198:201], v[156:159], v[118:121]
	v_mfma_f32_16x16x32_f16 v[114:117], v[198:201], v[164:167], v[114:117]
	s_waitcnt lgkmcnt(3)
	v_mfma_f32_16x16x32_f16 v[110:113], v[206:209], v[156:159], v[110:113]
	v_mfma_f32_16x16x32_f16 v[106:109], v[206:209], v[164:167], v[106:109]
	s_waitcnt lgkmcnt(1)
	v_mfma_f32_16x16x32_f16 v[102:105], v[214:217], v[156:159], v[102:105]
	v_mfma_f32_16x16x32_f16 v[98:101], v[214:217], v[164:167], v[98:101]
	v_mfma_f32_16x16x32_f16 v[126:129], v[178:181], v[160:163], v[126:129]
	v_mfma_f32_16x16x32_f16 v[122:125], v[178:181], v[168:171], v[122:125]
	v_mfma_f32_16x16x32_f16 v[118:121], v[202:205], v[160:163], v[118:121]
	v_mfma_f32_16x16x32_f16 v[114:117], v[202:205], v[168:171], v[114:117]
	v_mfma_f32_16x16x32_f16 v[110:113], v[210:213], v[160:163], v[110:113]
	v_mfma_f32_16x16x32_f16 v[106:109], v[210:213], v[168:171], v[106:109]
	s_waitcnt lgkmcnt(0)
	v_mfma_f32_16x16x32_f16 v[102:105], v[218:221], v[160:163], v[102:105]
	v_mfma_f32_16x16x32_f16 v[98:101], v[218:221], v[168:171], v[98:101]
	s_barrier
	s_add_i32 s22, s18, s20
	v_readfirstlane_b32 s24, v137
	s_add_i32 s23, s22, 0x100
	s_mov_b32 s10, s78
	s_mov_b32 s11, s79
	s_mov_b32 m0, s24
	v_readfirstlane_b32 s24, v139
	ds_read_b128 v[222:225], v150
	ds_read_b128 v[226:229], v150 offset:1024
	ds_read_b128 v[230:233], v150 offset:2048
	ds_read_b128 v[234:237], v150 offset:3072
	buffer_load_dwordx4 v136, s[8:11], s23 offen lds
	s_mov_b32 m0, s24
	s_nop 0
	buffer_load_dwordx4 v135, s[8:11], s23 offen lds
	s_barrier
	s_waitcnt lgkmcnt(0)
	s_waitcnt lgkmcnt(3)
	v_mfma_f32_16x16x32_f16 v[94:97], v[174:177], v[222:225], v[94:97]
	s_waitcnt lgkmcnt(1)
	v_mfma_f32_16x16x32_f16 v[90:93], v[174:177], v[230:233], v[90:93]
	v_mfma_f32_16x16x32_f16 v[86:89], v[198:201], v[222:225], v[86:89]
	v_mfma_f32_16x16x32_f16 v[82:85], v[198:201], v[230:233], v[82:85]
	v_mfma_f32_16x16x32_f16 v[78:81], v[206:209], v[222:225], v[78:81]
	v_mfma_f32_16x16x32_f16 v[74:77], v[206:209], v[230:233], v[74:77]
	v_mfma_f32_16x16x32_f16 v[70:73], v[214:217], v[222:225], v[70:73]
	v_mfma_f32_16x16x32_f16 v[66:69], v[214:217], v[230:233], v[66:69]
	v_mfma_f32_16x16x32_f16 v[94:97], v[178:181], v[226:229], v[94:97]
	s_waitcnt lgkmcnt(0)
	v_mfma_f32_16x16x32_f16 v[90:93], v[178:181], v[234:237], v[90:93]
	v_mfma_f32_16x16x32_f16 v[86:89], v[202:205], v[226:229], v[86:89]
	v_mfma_f32_16x16x32_f16 v[82:85], v[202:205], v[234:237], v[82:85]
	v_mfma_f32_16x16x32_f16 v[78:81], v[210:213], v[226:229], v[78:81]
	v_mfma_f32_16x16x32_f16 v[74:77], v[210:213], v[234:237], v[74:77]
	v_mfma_f32_16x16x32_f16 v[70:73], v[218:221], v[226:229], v[70:73]
	v_mfma_f32_16x16x32_f16 v[66:69], v[218:221], v[234:237], v[66:69]
	v_readfirstlane_b32 s24, v140
	s_add_i32 s23, s21, 0x100
	s_mov_b32 m0, s24
	v_readfirstlane_b32 s24, v141
	s_barrier
	ds_read_b128 v[174:177], v133 offset:16384
	ds_read_b128 v[178:181], v133 offset:17408
	ds_read_b128 v[198:201], v132 offset:16384
	ds_read_b128 v[202:205], v132 offset:17408
	ds_read_b128 v[206:209], v131 offset:16384
	ds_read_b128 v[210:213], v131 offset:17408
	ds_read_b128 v[214:217], v130 offset:16384
	ds_read_b128 v[218:221], v130 offset:17408
	buffer_load_dwordx4 v136, s[76:79], s23 offen lds
	s_mov_b32 m0, s24
	s_nop 0
	buffer_load_dwordx4 v135, s[76:79], s23 offen lds
	s_barrier
	s_waitcnt lgkmcnt(0)
	s_waitcnt lgkmcnt(7)
	v_mfma_f32_16x16x32_f16 v[62:65], v[174:177], v[156:159], v[62:65]
	v_mfma_f32_16x16x32_f16 v[58:61], v[174:177], v[164:167], v[58:61]
	s_waitcnt lgkmcnt(5)
	v_mfma_f32_16x16x32_f16 v[54:57], v[198:201], v[156:159], v[54:57]
	v_mfma_f32_16x16x32_f16 v[50:53], v[198:201], v[164:167], v[50:53]
	s_waitcnt lgkmcnt(3)
	v_mfma_f32_16x16x32_f16 v[46:49], v[206:209], v[156:159], v[46:49]
	v_mfma_f32_16x16x32_f16 v[42:45], v[206:209], v[164:167], v[42:45]
	s_waitcnt lgkmcnt(1)
	v_mfma_f32_16x16x32_f16 v[38:41], v[214:217], v[156:159], v[38:41]
	v_mfma_f32_16x16x32_f16 v[34:37], v[214:217], v[164:167], v[34:37]
	v_mfma_f32_16x16x32_f16 v[62:65], v[178:181], v[160:163], v[62:65]
	v_mfma_f32_16x16x32_f16 v[58:61], v[178:181], v[168:171], v[58:61]
	v_mfma_f32_16x16x32_f16 v[54:57], v[202:205], v[160:163], v[54:57]
	v_mfma_f32_16x16x32_f16 v[50:53], v[202:205], v[168:171], v[50:53]
	v_mfma_f32_16x16x32_f16 v[46:49], v[210:213], v[160:163], v[46:49]
	v_mfma_f32_16x16x32_f16 v[42:45], v[210:213], v[168:171], v[42:45]
	s_waitcnt lgkmcnt(0)
	v_mfma_f32_16x16x32_f16 v[38:41], v[218:221], v[160:163], v[38:41]
	v_mfma_f32_16x16x32_f16 v[34:37], v[218:221], v[168:171], v[34:37]
	s_barrier
; #define WAIT_V(n) asm volatile("s_waitcnt vmcnt(" #n ")" ::: "memory")
; #define WAIT_L(n) asm volatile("s_waitcnt lgkmcnt(" #n ")" ::: "memory")
; #define BAR __builtin_amdgcn_s_barrier()
; #define SCHED __builtin_amdgcn_sched_barrier(0)
; DEV void gemm_tile(const h16* __restrict__ A, const h16* __restrict__ Bt, int K, int ld, int brow, int bcol, h16* shm, Acc& acc) {
;     ...
;     STAGE(SB(0, 1), rsB, bcol + HALF_, t + 2);
;     WAIT_V(6); BAR; MMA(1, 1, At, B1); BAR;
;     LDB(B0, 1, 0); SCHED; LDA(At, 1, 0); STAGE(SA(0, 1), rsA, brow + HALF_, t + 2);
;     WAIT_L(8); BAR; WAIT_L(0); MMA(0, 0, At, B0); BAR; SCHED;
;     LDB(B1, 1, 1); STAGE(SB(1, 0), rsB, bcol, t + 3);
;     BAR; WAIT_L(0); MMA(0, 1, At, B1); BAR;
;     LDA(At, 1, 1); STAGE(SA(1, 0), rsA, brow, t + 3);
	v_readfirstlane_b32 s24, v142
	s_add_i32 s23, s22, 0x40100
	s_mov_b32 m0, s24
	v_readfirstlane_b32 s24, v143
	buffer_load_dwordx4 v136, s[8:11], s23 offen lds
	s_mov_b32 m0, s24
	s_nop 0
	buffer_load_dwordx4 v135, s[8:11], s23 offen lds
	s_waitcnt vmcnt(6)
	s_barrier
	v_mfma_f32_16x16x32_f16 v[30:33], v[174:177], v[222:225], v[30:33]
	v_mfma_f32_16x16x32_f16 v[26:29], v[174:177], v[230:233], v[26:29]
	v_mfma_f32_16x16x32_f16 v[22:25], v[198:201], v[222:225], v[22:25]
	v_mfma_f32_16x16x32_f16 v[18:21], v[198:201], v[230:233], v[18:21]
	v_mfma_f32_16x16x32_f16 v[14:17], v[206:209], v[222:225], v[14:17]
	v_mfma_f32_16x16x32_f16 v[10:13], v[206:209], v[230:233], v[10:13]
	v_mfma_f32_16x16x32_f16 v[6:9], v[214:217], v[222:225], v[6:9]
	v_mfma_f32_16x16x32_f16 v[2:5], v[214:217], v[230:233], v[2:5]
	v_mfma_f32_16x16x32_f16 v[30:33], v[178:181], v[226:229], v[30:33]
	v_mfma_f32_16x16x32_f16 v[26:29], v[178:181], v[234:237], v[26:29]
	v_mfma_f32_16x16x32_f16 v[22:25], v[202:205], v[226:229], v[22:25]
	v_mfma_f32_16x16x32_f16 v[18:21], v[202:205], v[234:237], v[18:21]
	v_mfma_f32_16x16x32_f16 v[14:17], v[210:213], v[226:229], v[14:17]
	v_mfma_f32_16x16x32_f16 v[10:13], v[210:213], v[234:237], v[10:13]
	v_mfma_f32_16x16x32_f16 v[6:9], v[218:221], v[226:229], v[6:9]
	v_mfma_f32_16x16x32_f16 v[2:5], v[218:221], v[234:237], v[2:5]
	s_barrier
	ds_read_b128 v[156:159], v138
	ds_read_b128 v[160:163], v138 offset:1024
	ds_read_b128 v[164:167], v138 offset:2048
	ds_read_b128 v[168:171], v138 offset:3072
	v_readfirstlane_b32 s24, v144
	s_add_i32 s23, s21, 0x40100
	s_mov_b32 m0, s24
	v_readfirstlane_b32 s24, v145
	ds_read_b128 v[174:177], v133 offset:32768
	ds_read_b128 v[178:181], v133 offset:33792
	ds_read_b128 v[198:201], v132 offset:32768
	ds_read_b128 v[202:205], v132 offset:33792
	ds_read_b128 v[206:209], v131 offset:32768
	ds_read_b128 v[210:213], v131 offset:33792
	ds_read_b128 v[214:217], v130 offset:32768
	ds_read_b128 v[218:221], v130 offset:33792
	buffer_load_dwordx4 v136, s[76:79], s23 offen lds
	s_mov_b32 m0, s24
	s_nop 0
	buffer_load_dwordx4 v135, s[76:79], s23 offen lds
	s_waitcnt lgkmcnt(8)
	s_barrier
	s_waitcnt lgkmcnt(0)
	s_waitcnt lgkmcnt(7)
	v_mfma_f32_16x16x32_f16 v[126:129], v[174:177], v[156:159], v[126:129]
	v_mfma_f32_16x16x32_f16 v[122:125], v[174:177], v[164:167], v[122:125]
	s_waitcnt lgkmcnt(5)
	v_mfma_f32_16x16x32_f16 v[118:121], v[198:201], v[156:159], v[118:121]
	v_mfma_f32_16x16x32_f16 v[114:117], v[198:201], v[164:167], v[114:117]
	s_waitcnt lgkmcnt(3)
	v_mfma_f32_16x16x32_f16 v[110:113], v[206:209], v[156:159], v[110:113]
	v_mfma_f32_16x16x32_f16 v[106:109], v[206:209], v[164:167], v[106:109]
	s_waitcnt lgkmcnt(1)
	v_mfma_f32_16x16x32_f16 v[102:105], v[214:217], v[156:159], v[102:105]
	v_mfma_f32_16x16x32_f16 v[98:101], v[214:217], v[164:167], v[98:101]
	v_mfma_f32_16x16x32_f16 v[126:129], v[178:181], v[160:163], v[126:129]
	v_mfma_f32_16x16x32_f16 v[122:125], v[178:181], v[168:171], v[122:125]
	v_mfma_f32_16x16x32_f16 v[118:121], v[202:205], v[160:163], v[118:121]
	v_mfma_f32_16x16x32_f16 v[114:117], v[202:205], v[168:171], v[114:117]
	v_mfma_f32_16x16x32_f16 v[110:113], v[210:213], v[160:163], v[110:113]
	v_mfma_f32_16x16x32_f16 v[106:109], v[210:213], v[168:171], v[106:109]
	s_waitcnt lgkmcnt(0)
	v_mfma_f32_16x16x32_f16 v[102:105], v[218:221], v[160:163], v[102:105]
	v_mfma_f32_16x16x32_f16 v[98:101], v[218:221], v[168:171], v[98:101]
	s_barrier
	v_readfirstlane_b32 s24, v146
	s_add_i32 s23, s22, 0x180
	s_mov_b32 m0, s24
	v_readfirstlane_b32 s24, v147
	ds_read_b128 v[222:225], v134
	ds_read_b128 v[226:229], v134 offset:1024
	ds_read_b128 v[230:233], v134 offset:2048
	ds_read_b128 v[234:237], v134 offset:3072
	buffer_load_dwordx4 v136, s[8:11], s23 offen lds
	s_mov_b32 m0, s24
	s_nop 0
	buffer_load_dwordx4 v135, s[8:11], s23 offen lds
	s_barrier
	s_waitcnt lgkmcnt(0)
	s_waitcnt lgkmcnt(3)
	v_mfma_f32_16x16x32_f16 v[94:97], v[174:177], v[222:225], v[94:97]
	s_waitcnt lgkmcnt(1)
	v_mfma_f32_16x16x32_f16 v[90:93], v[174:177], v[230:233], v[90:93]
	v_mfma_f32_16x16x32_f16 v[86:89], v[198:201], v[222:225], v[86:89]
	v_mfma_f32_16x16x32_f16 v[82:85], v[198:201], v[230:233], v[82:85]
	v_mfma_f32_16x16x32_f16 v[78:81], v[206:209], v[222:225], v[78:81]
	v_mfma_f32_16x16x32_f16 v[74:77], v[206:209], v[230:233], v[74:77]
	v_mfma_f32_16x16x32_f16 v[70:73], v[214:217], v[222:225], v[70:73]
	v_mfma_f32_16x16x32_f16 v[66:69], v[214:217], v[230:233], v[66:69]
	v_mfma_f32_16x16x32_f16 v[94:97], v[178:181], v[226:229], v[94:97]
	s_waitcnt lgkmcnt(0)
	v_mfma_f32_16x16x32_f16 v[90:93], v[178:181], v[234:237], v[90:93]
	v_mfma_f32_16x16x32_f16 v[86:89], v[202:205], v[226:229], v[86:89]
	v_mfma_f32_16x16x32_f16 v[82:85], v[202:205], v[234:237], v[82:85]
	v_mfma_f32_16x16x32_f16 v[78:81], v[210:213], v[226:229], v[78:81]
	v_mfma_f32_16x16x32_f16 v[74:77], v[210:213], v[234:237], v[74:77]
	v_mfma_f32_16x16x32_f16 v[70:73], v[218:221], v[226:229], v[70:73]
	v_mfma_f32_16x16x32_f16 v[66:69], v[218:221], v[234:237], v[66:69]
	v_readfirstlane_b32 s23, v148
	s_addk_i32 s21, 0x180
	s_mov_b32 m0, s23
	v_readfirstlane_b32 s23, v149
	s_barrier
	ds_read_b128 v[174:177], v133 offset:49152
	ds_read_b128 v[178:181], v133 offset:50176
	ds_read_b128 v[198:201], v132 offset:49152
	ds_read_b128 v[202:205], v132 offset:50176
	ds_read_b128 v[206:209], v131 offset:49152
	ds_read_b128 v[210:213], v131 offset:50176
	ds_read_b128 v[214:217], v130 offset:49152
	ds_read_b128 v[218:221], v130 offset:50176
	buffer_load_dwordx4 v136, s[76:79], s21 offen lds
	s_mov_b32 m0, s23
	s_nop 0
	buffer_load_dwordx4 v135, s[76:79], s21 offen lds
	s_barrier
; #define WAIT_V(n) asm volatile("s_waitcnt vmcnt(" #n ")" ::: "memory")
; #define WAIT_L(n) asm volatile("s_waitcnt lgkmcnt(" #n ")" ::: "memory")
; #define BAR __builtin_amdgcn_s_barrier()
; #define SCHED __builtin_amdgcn_sched_barrier(0)
; DEV void gemm_tile(const h16* __restrict__ A, const h16* __restrict__ Bt, int K, int ld, int brow, int bcol, h16* shm, Acc& acc) {
;     ...
;     BAR; WAIT_L(0); MMA(1, 0, At, B0); BAR; SCHED;
;     STAGE(SB(1, 1), rsB, bcol + HALF_, t + 3);
;     WAIT_V(6); BAR; MMA(1, 1, At, B1); BAR;
;   }
;   { LDB(B0, 0, 0); LDA(At, 0, 0); STAGE(SA(1, 1), rsA, brow + HALF_, nt - 1);
;     BAR; WAIT_L(0); MMA(0, 0, At, B0); BAR;
;     LDB(B1, 0, 1); BAR; WAIT_L(0); MMA(0, 1, At, B1); BAR;
	s_waitcnt lgkmcnt(0)
	s_waitcnt lgkmcnt(7)
	v_mfma_f32_16x16x32_f16 v[62:65], v[174:177], v[156:159], v[62:65]
	v_mfma_f32_16x16x32_f16 v[58:61], v[174:177], v[164:167], v[58:61]
	s_waitcnt lgkmcnt(5)
	v_mfma_f32_16x16x32_f16 v[54:57], v[198:201], v[156:159], v[54:57]
	v_mfma_f32_16x16x32_f16 v[50:53], v[198:201], v[164:167], v[50:53]
	s_waitcnt lgkmcnt(3)
	v_mfma_f32_16x16x32_f16 v[46:49], v[206:209], v[156:159], v[46:49]
	v_mfma_f32_16x16x32_f16 v[42:45], v[206:209], v[164:167], v[42:45]
	s_waitcnt lgkmcnt(1)
	v_mfma_f32_16x16x32_f16 v[38:41], v[214:217], v[156:159], v[38:41]
	v_mfma_f32_16x16x32_f16 v[34:37], v[214:217], v[164:167], v[34:37]
	v_mfma_f32_16x16x32_f16 v[62:65], v[178:181], v[160:163], v[62:65]
	v_mfma_f32_16x16x32_f16 v[58:61], v[178:181], v[168:171], v[58:61]
	v_mfma_f32_16x16x32_f16 v[54:57], v[202:205], v[160:163], v[54:57]
	v_mfma_f32_16x16x32_f16 v[50:53], v[202:205], v[168:171], v[50:53]
	v_mfma_f32_16x16x32_f16 v[46:49], v[210:213], v[160:163], v[46:49]
	v_mfma_f32_16x16x32_f16 v[42:45], v[210:213], v[168:171], v[42:45]
	s_waitcnt lgkmcnt(0)
	v_mfma_f32_16x16x32_f16 v[38:41], v[218:221], v[160:163], v[38:41]
	v_mfma_f32_16x16x32_f16 v[34:37], v[218:221], v[168:171], v[34:37]
	s_barrier
	v_readfirstlane_b32 s21, v151
	s_add_i32 s22, s22, 0x40180
	s_mov_b32 m0, s21
	v_readfirstlane_b32 s21, v154
	buffer_load_dwordx4 v136, s[8:11], s22 offen lds
	s_mov_b32 m0, s21
	s_nop 0
	buffer_load_dwordx4 v135, s[8:11], s22 offen lds
	s_waitcnt vmcnt(6)
	s_barrier
	v_mfma_f32_16x16x32_f16 v[30:33], v[174:177], v[222:225], v[30:33]
	v_mfma_f32_16x16x32_f16 v[26:29], v[174:177], v[230:233], v[26:29]
	v_mfma_f32_16x16x32_f16 v[22:25], v[198:201], v[222:225], v[22:25]
	v_mfma_f32_16x16x32_f16 v[18:21], v[198:201], v[230:233], v[18:21]
	v_mfma_f32_16x16x32_f16 v[14:17], v[206:209], v[222:225], v[14:17]
	v_mfma_f32_16x16x32_f16 v[10:13], v[206:209], v[230:233], v[10:13]
	v_mfma_f32_16x16x32_f16 v[6:9], v[214:217], v[222:225], v[6:9]
	v_mfma_f32_16x16x32_f16 v[2:5], v[214:217], v[230:233], v[2:5]
	v_mfma_f32_16x16x32_f16 v[30:33], v[178:181], v[226:229], v[30:33]
	v_mfma_f32_16x16x32_f16 v[26:29], v[178:181], v[234:237], v[26:29]
	v_mfma_f32_16x16x32_f16 v[22:25], v[202:205], v[226:229], v[22:25]
	v_mfma_f32_16x16x32_f16 v[18:21], v[202:205], v[234:237], v[18:21]
	v_mfma_f32_16x16x32_f16 v[14:17], v[210:213], v[226:229], v[14:17]
	v_mfma_f32_16x16x32_f16 v[10:13], v[210:213], v[234:237], v[10:13]
	v_mfma_f32_16x16x32_f16 v[6:9], v[218:221], v[226:229], v[6:9]
	v_mfma_f32_16x16x32_f16 v[2:5], v[218:221], v[234:237], v[2:5]
	s_add_i32 s5, s5, 2
	s_addk_i32 s20, 0x100
	s_cmp_lt_u32 s5, 12
	s_barrier
	s_cbranch_scc1 .LBB0_2178
	v_readfirstlane_b32 s5, v153
	s_or_b32 s4, s19, 0x780
	s_mov_b32 m0, s5
	v_readfirstlane_b32 s5, v152
	ds_read_b128 v[140:143], v155
	ds_read_b128 v[144:147], v155 offset:1024
	ds_read_b128 v[156:159], v155 offset:2048
	ds_read_b128 v[160:163], v155 offset:3072
	ds_read_b128 v[164:167], v133
	ds_read_b128 v[168:171], v133 offset:1024
	ds_read_b128 v[174:177], v132
	ds_read_b128 v[178:181], v132 offset:1024
	ds_read_b128 v[198:201], v131
	ds_read_b128 v[202:205], v131 offset:1024
	ds_read_b128 v[206:209], v130
	ds_read_b128 v[210:213], v130 offset:1024
	buffer_load_dwordx4 v136, s[76:79], s4 offen lds
	s_mov_b32 m0, s5
	s_nop 0
	buffer_load_dwordx4 v135, s[76:79], s4 offen lds
	s_barrier
	s_waitcnt lgkmcnt(0)
	s_waitcnt lgkmcnt(7)
	v_mfma_f32_16x16x32_f16 v[126:129], v[164:167], v[140:143], v[126:129]
	v_mfma_f32_16x16x32_f16 v[122:125], v[164:167], v[156:159], v[122:125]
	s_waitcnt lgkmcnt(5)
	v_mfma_f32_16x16x32_f16 v[118:121], v[174:177], v[140:143], v[118:121]
	v_mfma_f32_16x16x32_f16 v[114:117], v[174:177], v[156:159], v[114:117]
	v_mfma_f32_16x16x32_f16 v[126:129], v[168:171], v[144:147], v[126:129]
	v_mfma_f32_16x16x32_f16 v[122:125], v[168:171], v[160:163], v[122:125]
	s_waitcnt lgkmcnt(4)
	v_mfma_f32_16x16x32_f16 v[118:121], v[178:181], v[144:147], v[118:121]
	v_mfma_f32_16x16x32_f16 v[114:117], v[178:181], v[160:163], v[114:117]
	s_waitcnt lgkmcnt(3)
	v_mfma_f32_16x16x32_f16 v[110:113], v[198:201], v[140:143], v[110:113]
	v_mfma_f32_16x16x32_f16 v[106:109], v[198:201], v[156:159], v[106:109]
	s_waitcnt lgkmcnt(1)
	v_mfma_f32_16x16x32_f16 v[102:105], v[206:209], v[140:143], v[102:105]
	v_mfma_f32_16x16x32_f16 v[98:101], v[206:209], v[156:159], v[98:101]
	v_mfma_f32_16x16x32_f16 v[152:155], v[202:205], v[144:147], v[110:113]
	v_mfma_f32_16x16x32_f16 v[214:217], v[202:205], v[160:163], v[106:109]
	s_waitcnt lgkmcnt(0)
	v_mfma_f32_16x16x32_f16 v[218:221], v[210:213], v[144:147], v[102:105]
	v_mfma_f32_16x16x32_f16 v[222:225], v[210:213], v[160:163], v[98:101]
	s_barrier
	s_nop 0
	ds_read_b128 v[98:101], v150
	ds_read_b128 v[102:105], v150 offset:1024
	ds_read_b128 v[106:109], v150 offset:2048
	ds_read_b128 v[110:113], v150 offset:3072
	s_barrier
	s_waitcnt lgkmcnt(0)
	s_waitcnt lgkmcnt(3)
	v_mfma_f32_16x16x32_f16 v[94:97], v[164:167], v[98:101], v[94:97]
	s_waitcnt lgkmcnt(1)
	v_mfma_f32_16x16x32_f16 v[90:93], v[164:167], v[106:109], v[90:93]
	v_mfma_f32_16x16x32_f16 v[86:89], v[174:177], v[98:101], v[86:89]
	v_mfma_f32_16x16x32_f16 v[82:85], v[174:177], v[106:109], v[82:85]
	v_mfma_f32_16x16x32_f16 v[94:97], v[168:171], v[102:105], v[94:97]
	s_waitcnt lgkmcnt(0)
	v_mfma_f32_16x16x32_f16 v[90:93], v[168:171], v[110:113], v[90:93]
	v_mfma_f32_16x16x32_f16 v[86:89], v[178:181], v[102:105], v[86:89]
	v_mfma_f32_16x16x32_f16 v[82:85], v[178:181], v[110:113], v[82:85]
	v_mfma_f32_16x16x32_f16 v[78:81], v[198:201], v[98:101], v[78:81]
	v_mfma_f32_16x16x32_f16 v[74:77], v[198:201], v[106:109], v[74:77]
	v_mfma_f32_16x16x32_f16 v[70:73], v[206:209], v[98:101], v[70:73]
	v_mfma_f32_16x16x32_f16 v[66:69], v[206:209], v[106:109], v[66:69]
	v_mfma_f32_16x16x32_f16 v[148:151], v[202:205], v[102:105], v[78:81]
	v_mfma_f32_16x16x32_f16 v[164:167], v[202:205], v[110:113], v[74:77]
	v_mfma_f32_16x16x32_f16 v[168:171], v[210:213], v[102:105], v[70:73]
	v_mfma_f32_16x16x32_f16 v[174:177], v[210:213], v[110:113], v[66:69]
	s_barrier
; #define WAIT_V(n) asm volatile("s_waitcnt vmcnt(" #n ")" ::: "memory")
; #define WAIT_L(n) asm volatile("s_waitcnt lgkmcnt(" #n ")" ::: "memory")
; #define BAR __builtin_amdgcn_s_barrier()
; DEV void gemm_tile(const h16* __restrict__ A, const h16* __restrict__ Bt, int K, int ld, int brow, int bcol, h16* shm, Acc& acc) {
;     ...
;     LDA(At, 0, 1); WAIT_V(4); BAR; WAIT_L(0); MMA(1, 0, At, B0); MMA(1, 1, At, B1); BAR; }
;   { LDB(B0, 1, 0); LDA(At, 1, 0); WAIT_V(2); BAR; WAIT_L(0); MMA(0, 0, At, B0); BAR;
	s_nop 1
	ds_read_b128 v[66:69], v133 offset:16384
	ds_read_b128 v[70:73], v133 offset:17408
	ds_read_b128 v[74:77], v132 offset:16384
	ds_read_b128 v[78:81], v132 offset:17408
	ds_read_b128 v[178:181], v131 offset:16384
	ds_read_b128 v[198:201], v131 offset:17408
	ds_read_b128 v[202:205], v130 offset:16384
	ds_read_b128 v[206:209], v130 offset:17408
	s_waitcnt vmcnt(4)
	s_barrier
	s_waitcnt lgkmcnt(0)
	s_waitcnt lgkmcnt(7)
	v_mfma_f32_16x16x32_f16 v[62:65], v[66:69], v[140:143], v[62:65]
	v_mfma_f32_16x16x32_f16 v[58:61], v[66:69], v[156:159], v[58:61]
	s_waitcnt lgkmcnt(5)
	v_mfma_f32_16x16x32_f16 v[54:57], v[74:77], v[140:143], v[54:57]
	v_mfma_f32_16x16x32_f16 v[50:53], v[74:77], v[156:159], v[50:53]
	v_mfma_f32_16x16x32_f16 v[62:65], v[70:73], v[144:147], v[62:65]
	v_mfma_f32_16x16x32_f16 v[58:61], v[70:73], v[160:163], v[58:61]
	s_waitcnt lgkmcnt(4)
	v_mfma_f32_16x16x32_f16 v[54:57], v[78:81], v[144:147], v[54:57]
	v_mfma_f32_16x16x32_f16 v[50:53], v[78:81], v[160:163], v[50:53]
	s_waitcnt lgkmcnt(3)
	v_mfma_f32_16x16x32_f16 v[46:49], v[178:181], v[140:143], v[46:49]
	v_mfma_f32_16x16x32_f16 v[42:45], v[178:181], v[156:159], v[42:45]
	s_waitcnt lgkmcnt(1)
	v_mfma_f32_16x16x32_f16 v[38:41], v[202:205], v[140:143], v[38:41]
	v_mfma_f32_16x16x32_f16 v[34:37], v[202:205], v[156:159], v[34:37]
	v_mfma_f32_16x16x32_f16 v[210:213], v[198:201], v[144:147], v[46:49]
	v_mfma_f32_16x16x32_f16 v[226:229], v[198:201], v[160:163], v[42:45]
	s_waitcnt lgkmcnt(0)
	v_mfma_f32_16x16x32_f16 v[140:143], v[206:209], v[144:147], v[38:41]
	v_mfma_f32_16x16x32_f16 v[144:147], v[206:209], v[160:163], v[34:37]
	v_mfma_f32_16x16x32_f16 v[30:33], v[66:69], v[98:101], v[30:33]
	v_mfma_f32_16x16x32_f16 v[26:29], v[66:69], v[106:109], v[26:29]
	v_mfma_f32_16x16x32_f16 v[22:25], v[74:77], v[98:101], v[22:25]
	v_mfma_f32_16x16x32_f16 v[18:21], v[74:77], v[106:109], v[18:21]
	v_mfma_f32_16x16x32_f16 v[30:33], v[70:73], v[102:105], v[30:33]
	v_mfma_f32_16x16x32_f16 v[26:29], v[70:73], v[110:113], v[26:29]
	v_mfma_f32_16x16x32_f16 v[22:25], v[78:81], v[102:105], v[22:25]
	v_mfma_f32_16x16x32_f16 v[18:21], v[78:81], v[110:113], v[18:21]
	v_mfma_f32_16x16x32_f16 v[14:17], v[178:181], v[98:101], v[14:17]
	v_mfma_f32_16x16x32_f16 v[10:13], v[178:181], v[106:109], v[10:13]
	v_mfma_f32_16x16x32_f16 v[6:9], v[202:205], v[98:101], v[6:9]
	v_mfma_f32_16x16x32_f16 v[2:5], v[202:205], v[106:109], v[2:5]
	v_mfma_f32_16x16x32_f16 v[156:159], v[198:201], v[102:105], v[14:17]
	v_mfma_f32_16x16x32_f16 v[160:163], v[198:201], v[110:113], v[10:13]
	v_mfma_f32_16x16x32_f16 v[178:181], v[206:209], v[102:105], v[6:9]
	v_mfma_f32_16x16x32_f16 v[198:201], v[206:209], v[110:113], v[2:5]
	s_barrier
	s_nop 1
	ds_read_b128 v[2:5], v138
	ds_read_b128 v[6:9], v138 offset:1024
	ds_read_b128 v[202:205], v138 offset:2048
	ds_read_b128 v[136:139], v138 offset:3072
	ds_read_b128 v[10:13], v133 offset:32768
	ds_read_b128 v[14:17], v133 offset:33792
	ds_read_b128 v[34:37], v132 offset:32768
	ds_read_b128 v[38:41], v132 offset:33792
	ds_read_b128 v[42:45], v131 offset:32768
	ds_read_b128 v[46:49], v131 offset:33792
	ds_read_b128 v[206:209], v130 offset:32768
	ds_read_b128 v[230:233], v130 offset:33792
	s_waitcnt vmcnt(2)
	s_barrier
	s_waitcnt lgkmcnt(0)
	s_waitcnt lgkmcnt(7)
	v_mfma_f32_16x16x32_f16 v[66:69], v[10:13], v[2:5], v[126:129]
	s_waitcnt lgkmcnt(6)
	v_mfma_f32_16x16x32_f16 v[106:109], v[14:17], v[6:9], v[66:69]
	v_mfma_f32_16x16x32_f16 v[66:69], v[10:13], v[202:205], v[122:125]
	v_mfma_f32_16x16x32_f16 v[110:113], v[14:17], v[136:139], v[66:69]
	s_waitcnt lgkmcnt(5)
	v_mfma_f32_16x16x32_f16 v[66:69], v[34:37], v[2:5], v[118:121]
	s_waitcnt lgkmcnt(4)
	v_mfma_f32_16x16x32_f16 v[98:101], v[38:41], v[6:9], v[66:69]
	v_mfma_f32_16x16x32_f16 v[66:69], v[34:37], v[202:205], v[114:117]
	v_mfma_f32_16x16x32_f16 v[102:105], v[38:41], v[136:139], v[66:69]
	s_waitcnt lgkmcnt(3)
	v_mfma_f32_16x16x32_f16 v[66:69], v[42:45], v[2:5], v[152:155]
	s_waitcnt lgkmcnt(2)
	v_mfma_f32_16x16x32_f16 v[74:77], v[46:49], v[6:9], v[66:69]
	v_mfma_f32_16x16x32_f16 v[66:69], v[42:45], v[202:205], v[214:217]
	v_mfma_f32_16x16x32_f16 v[78:81], v[46:49], v[136:139], v[66:69]
	s_waitcnt lgkmcnt(1)
	v_mfma_f32_16x16x32_f16 v[66:69], v[206:209], v[2:5], v[218:221]
	v_mfma_f32_16x16x32_f16 v[70:73], v[206:209], v[202:205], v[222:225]
	s_waitcnt lgkmcnt(0)
	v_mfma_f32_16x16x32_f16 v[66:69], v[230:233], v[6:9], v[66:69]
	v_mfma_f32_16x16x32_f16 v[70:73], v[230:233], v[136:139], v[70:73]
	s_barrier
; #define WAIT_V(n) asm volatile("s_waitcnt vmcnt(" #n ")" ::: "memory")
; #define WAIT_L(n) asm volatile("s_waitcnt lgkmcnt(" #n ")" ::: "memory")
; #define BAR __builtin_amdgcn_s_barrier()
; DEV void gemm_tile(const h16* __restrict__ A, const h16* __restrict__ Bt, int K, int ld, int brow, int bcol, h16* shm, Acc& acc) {
;     ...
;     LDB(B1, 1, 1); WAIT_V(0); BAR; WAIT_L(0); MMA(0, 1, At, B1); BAR;
;     LDA(At, 1, 1); BAR; WAIT_L(0); MMA(1, 0, At, B0); MMA(1, 1, At, B1); BAR; }
;   if (wr == 0) BAR;
	ds_read_b128 v[152:155], v134
	ds_read_b128 v[214:217], v134 offset:1024
	ds_read_b128 v[218:221], v134 offset:2048
	ds_read_b128 v[222:225], v134 offset:3072
	s_waitcnt vmcnt(0)
	s_barrier
	s_waitcnt lgkmcnt(0)
	s_waitcnt lgkmcnt(3)
	v_mfma_f32_16x16x32_f16 v[94:97], v[10:13], v[152:155], v[94:97]
	s_waitcnt lgkmcnt(1)
	v_mfma_f32_16x16x32_f16 v[10:13], v[10:13], v[218:221], v[90:93]
	s_waitcnt lgkmcnt(0)
	v_mfma_f32_16x16x32_f16 v[126:129], v[14:17], v[222:225], v[10:13]
	v_mfma_f32_16x16x32_f16 v[10:13], v[34:37], v[152:155], v[86:89]
	v_mfma_f32_16x16x32_f16 v[114:117], v[38:41], v[214:217], v[10:13]
	v_mfma_f32_16x16x32_f16 v[10:13], v[34:37], v[218:221], v[82:85]
	v_mfma_f32_16x16x32_f16 v[118:121], v[38:41], v[222:225], v[10:13]
	v_mfma_f32_16x16x32_f16 v[10:13], v[42:45], v[152:155], v[148:151]
	v_mfma_f32_16x16x32_f16 v[90:93], v[46:49], v[214:217], v[10:13]
	v_mfma_f32_16x16x32_f16 v[10:13], v[42:45], v[218:221], v[164:167]
	v_mfma_f32_16x16x32_f16 v[122:125], v[14:17], v[214:217], v[94:97]
	v_mfma_f32_16x16x32_f16 v[94:97], v[46:49], v[222:225], v[10:13]
	v_mfma_f32_16x16x32_f16 v[10:13], v[206:209], v[152:155], v[168:171]
	v_mfma_f32_16x16x32_f16 v[82:85], v[230:233], v[214:217], v[10:13]
	v_mfma_f32_16x16x32_f16 v[10:13], v[206:209], v[218:221], v[174:177]
	v_mfma_f32_16x16x32_f16 v[86:89], v[230:233], v[222:225], v[10:13]
	s_barrier
	ds_read_b128 v[148:151], v133 offset:49152
	ds_read_b128 v[164:167], v133 offset:50176
	ds_read_b128 v[168:171], v132 offset:49152
	ds_read_b128 v[132:135], v132 offset:50176
	ds_read_b128 v[174:177], v131 offset:49152
	ds_read_b128 v[206:209], v131 offset:50176
	ds_read_b128 v[230:233], v130 offset:49152
	ds_read_b128 v[234:237], v130 offset:50176
	s_barrier
	s_waitcnt lgkmcnt(0)
	s_waitcnt lgkmcnt(7)
	v_mfma_f32_16x16x32_f16 v[10:13], v[148:151], v[2:5], v[62:65]
	s_waitcnt lgkmcnt(6)
	v_mfma_f32_16x16x32_f16 v[42:45], v[164:167], v[6:9], v[10:13]
	v_mfma_f32_16x16x32_f16 v[10:13], v[148:151], v[202:205], v[58:61]
	v_mfma_f32_16x16x32_f16 v[46:49], v[164:167], v[136:139], v[10:13]
	s_waitcnt lgkmcnt(5)
	v_mfma_f32_16x16x32_f16 v[10:13], v[168:171], v[2:5], v[54:57]
	s_waitcnt lgkmcnt(4)
	v_mfma_f32_16x16x32_f16 v[34:37], v[132:135], v[6:9], v[10:13]
	v_mfma_f32_16x16x32_f16 v[10:13], v[168:171], v[202:205], v[50:53]
	v_mfma_f32_16x16x32_f16 v[38:41], v[132:135], v[136:139], v[10:13]
	s_waitcnt lgkmcnt(3)
	v_mfma_f32_16x16x32_f16 v[10:13], v[174:177], v[2:5], v[210:213]
	s_waitcnt lgkmcnt(1)
	v_mfma_f32_16x16x32_f16 v[2:5], v[230:233], v[2:5], v[140:143]
	v_mfma_f32_16x16x32_f16 v[10:13], v[206:209], v[6:9], v[10:13]
	v_mfma_f32_16x16x32_f16 v[14:17], v[174:177], v[202:205], v[226:229]
	s_waitcnt lgkmcnt(0)
	v_mfma_f32_16x16x32_f16 v[2:5], v[234:237], v[6:9], v[2:5]
	v_mfma_f32_16x16x32_f16 v[6:9], v[230:233], v[202:205], v[144:147]
	v_mfma_f32_16x16x32_f16 v[14:17], v[206:209], v[136:139], v[14:17]
	v_mfma_f32_16x16x32_f16 v[6:9], v[234:237], v[136:139], v[6:9]
	v_mfma_f32_16x16x32_f16 v[18:21], v[168:171], v[218:221], v[18:21]
	v_mfma_f32_16x16x32_f16 v[26:29], v[148:151], v[218:221], v[26:29]
	v_mfma_f32_16x16x32_f16 v[54:57], v[132:135], v[222:225], v[18:21]
	v_mfma_f32_16x16x32_f16 v[18:21], v[174:177], v[152:155], v[156:159]
	v_mfma_f32_16x16x32_f16 v[30:33], v[148:151], v[152:155], v[30:33]
	v_mfma_f32_16x16x32_f16 v[62:65], v[164:167], v[222:225], v[26:29]
	v_mfma_f32_16x16x32_f16 v[22:25], v[168:171], v[152:155], v[22:25]
	v_mfma_f32_16x16x32_f16 v[26:29], v[206:209], v[214:217], v[18:21]
	v_mfma_f32_16x16x32_f16 v[18:21], v[174:177], v[218:221], v[160:163]
	v_mfma_f32_16x16x32_f16 v[58:61], v[164:167], v[214:217], v[30:33]
	v_mfma_f32_16x16x32_f16 v[50:53], v[132:135], v[214:217], v[22:25]
	v_mfma_f32_16x16x32_f16 v[30:33], v[206:209], v[222:225], v[18:21]
	v_mfma_f32_16x16x32_f16 v[18:21], v[230:233], v[152:155], v[178:181]
	v_mfma_f32_16x16x32_f16 v[22:25], v[230:233], v[218:221], v[198:201]
	v_mfma_f32_16x16x32_f16 v[18:21], v[234:237], v[214:217], v[18:21]
	v_mfma_f32_16x16x32_f16 v[22:25], v[234:237], v[222:225], v[22:25]
	s_setprio 0
	s_movk_i32 s4, 0x100
	v_cmp_gt_u32_e32 vcc, s4, v0
	s_barrier
	s_and_saveexec_b64 s[4:5], vcc
	s_cbranch_execz .LBB0_2174
	s_barrier
	s_branch .LBB0_2174
